# EpiUp v2 (DPP-fused conv, scalar gelu, halo rows last) + safe-register EpiOut pipeline + early L1 invalidate in grid barrier + write-through sample ACT hand-off
# speedup vs baseline: 1.0655x; 1.0325x over previous
; __device__ __forceinline__ unsigned xb_ld(unsigned* p)              { return __hip_atomic_load(p, __ATOMIC_RELAXED, __HIP_MEMORY_SCOPE_AGENT); }
; __device__ __forceinline__ unsigned xb_add(unsigned* p, unsigned v) { return __hip_atomic_fetch_add(p, v, __ATOMIC_RELAXED, __HIP_MEMORY_SCOPE_AGENT); }
; #define XB_SPIN(cond, bar) do { unsigned _sp = 0; while (cond) { __builtin_amdgcn_s_sleep(1); \
;     if ((++_sp & 255u) == 0u) { if (xb_ld(&(bar)[XB_TMO])) break; if (_sp > XB_SPIN_CAP) { atomicAdd(&(bar)[XB_TMO], 1u); break; } } } } while (0)
; __device__ __forceinline__ void xcd_barrier(const XcdBarrier& b) {
;     ...
;         const unsigned old = xb_add(&bar[XB_XSUB(b.x)], 1u);
;         const unsigned gen = old / nloc;
;         if (old + 1u == (gen + 1u) * nloc) {
;             __builtin_amdgcn_fence(__ATOMIC_RELEASE, "agent");
;             asm volatile("s_waitcnt vmcnt(0)" ::: "memory");
;             const unsigned og = xb_add(&bar[XB_TOP], 1u);
;             const unsigned tg = og / nx;
;             if (og + 1u == (tg + 1u) * nx) xb_add(&bar[XB_TOPGEN], 1u);
;             else XB_SPIN(xb_ld(&bar[XB_TOPGEN]) == tg, bar);
;             __builtin_amdgcn_fence(__ATOMIC_ACQUIRE, "agent");
;             xb_add(&bar[XB_XGEN(b.x)], 1u);
;             asm volatile("s_waitcnt vmcnt(0)" ::: "memory");
;         } else {
;             XB_SPIN(xb_ld(&bar[XB_XGEN(b.x)]) == gen, bar);
;             __builtin_amdgcn_fence(__ATOMIC_ACQUIRE, "agent");
;             asm volatile("s_waitcnt vmcnt(0)" ::: "memory");
.LBB0_68:
	s_or_b64 exec, exec, s[14:15]
	v_cvt_f32_u32_e32 v4, v2
	s_waitcnt vmcnt(0)
	v_readfirstlane_b32 s0, v3
	v_sub_u32_e32 v3, 0, v2
	v_rcp_iflag_f32_e32 v4, v4
	v_add_u32_e32 v5, s0, v1
	v_mul_f32_e32 v4, 0x4f7ffffe, v4
	v_cvt_u32_f32_e32 v4, v4
	v_mul_lo_u32 v1, v3, v4
	v_mul_hi_u32 v1, v4, v1
	v_add_u32_e32 v1, v4, v1
	v_mul_hi_u32 v1, v5, v1
	v_mul_lo_u32 v3, v1, v2
	v_sub_u32_e32 v3, v5, v3
	v_add_u32_e32 v4, 1, v1
	v_cmp_ge_u32_e32 vcc, v3, v2
	s_nop 1
	v_cndmask_b32_e32 v1, v1, v4, vcc
	v_sub_u32_e32 v4, v3, v2
	v_cndmask_b32_e32 v3, v3, v4, vcc
	v_add_u32_e32 v4, 1, v1
	v_cmp_ge_u32_e32 vcc, v3, v2
	v_add_u32_e32 v3, 1, v5
	s_nop 0
	v_cndmask_b32_e32 v1, v1, v4, vcc
	v_mul_lo_u32 v4, v2, v1
	v_add_u32_e32 v2, v4, v2
	v_cmp_ne_u32_e32 vcc, v3, v2
	s_and_saveexec_b64 s[0:1], vcc
	s_xor_b64 s[12:13], exec, s[0:1]
	s_cbranch_execz .LBB0_82
	s_waitcnt lgkmcnt(0)
	buffer_inv sc1
	v_mov_b32_e32 v0, 0x2000
	global_load_dword v0, v0, s[8:9] offset:1024 sc1
	s_add_u32 s18, s8, 0x2400
	s_addc_u32 s19, s9, 0
	s_waitcnt vmcnt(0)
	v_cmp_eq_u32_e32 vcc, v0, v1
	s_and_saveexec_b64 s[14:15], vcc
	s_cbranch_execz .LBB0_81
	s_add_u32 s16, s80, 0x1a20200
	s_addc_u32 s17, s81, 0
	s_mov_b32 s0, 1
	s_mov_b64 s[20:21], 0
	v_mov_b32_e32 v0, 0
	s_branch .LBB0_72

; __device__ __forceinline__ unsigned xb_ld(unsigned* p)              { return __hip_atomic_load(p, __ATOMIC_RELAXED, __HIP_MEMORY_SCOPE_AGENT); }
; #define XB_SPIN(cond, bar) do { unsigned _sp = 0; while (cond) { __builtin_amdgcn_s_sleep(1); \
;     if ((++_sp & 255u) == 0u) { if (xb_ld(&(bar)[XB_TMO])) break; if (_sp > XB_SPIN_CAP) { atomicAdd(&(bar)[XB_TMO], 1u); break; } } } } while (0)
; __device__ __forceinline__ void xcd_barrier(const XcdBarrier& b) {
;     ...
;             XB_SPIN(xb_ld(&bar[XB_XGEN(b.x)]) == gen, bar);
;             __builtin_amdgcn_fence(__ATOMIC_ACQUIRE, "agent");
;             asm volatile("s_waitcnt vmcnt(0)" ::: "memory");
.LBB0_81:
	s_or_b64 exec, exec, s[14:15]
	s_waitcnt vmcnt(0)
	s_waitcnt vmcnt(0)

; __device__ __forceinline__ unsigned xb_ld(unsigned* p)              { return __hip_atomic_load(p, __ATOMIC_RELAXED, __HIP_MEMORY_SCOPE_AGENT); }
; __device__ __forceinline__ unsigned xb_add(unsigned* p, unsigned v) { return __hip_atomic_fetch_add(p, v, __ATOMIC_RELAXED, __HIP_MEMORY_SCOPE_AGENT); }
; #define XB_SPIN(cond, bar) do { unsigned _sp = 0; while (cond) { __builtin_amdgcn_s_sleep(1); \
;     if ((++_sp & 255u) == 0u) { if (xb_ld(&(bar)[XB_TMO])) break; if (_sp > XB_SPIN_CAP) { atomicAdd(&(bar)[XB_TMO], 1u); break; } } } } while (0)
; __device__ __forceinline__ void xcd_barrier(const XcdBarrier& b) {
;     ...
;         const unsigned old = xb_add(&bar[XB_XSUB(b.x)], 1u);
;         const unsigned gen = old / nloc;
;         if (old + 1u == (gen + 1u) * nloc) {
;             __builtin_amdgcn_fence(__ATOMIC_RELEASE, "agent");
;             asm volatile("s_waitcnt vmcnt(0)" ::: "memory");
;             const unsigned og = xb_add(&bar[XB_TOP], 1u);
;             const unsigned tg = og / nx;
;             if (og + 1u == (tg + 1u) * nx) xb_add(&bar[XB_TOPGEN], 1u);
;             else XB_SPIN(xb_ld(&bar[XB_TOPGEN]) == tg, bar);
;             __builtin_amdgcn_fence(__ATOMIC_ACQUIRE, "agent");
;             xb_add(&bar[XB_XGEN(b.x)], 1u);
;             asm volatile("s_waitcnt vmcnt(0)" ::: "memory");
;         } else {
;             XB_SPIN(xb_ld(&bar[XB_XGEN(b.x)]) == gen, bar);
;             __builtin_amdgcn_fence(__ATOMIC_ACQUIRE, "agent");
;             asm volatile("s_waitcnt vmcnt(0)" ::: "memory");
.LBB0_242:
	s_or_b64 exec, exec, s[16:17]
	v_cvt_f32_u32_e32 v4, v2
	s_waitcnt vmcnt(0)
	v_readfirstlane_b32 s0, v3
	v_sub_u32_e32 v3, 0, v2
	v_rcp_iflag_f32_e32 v4, v4
	v_add_u32_e32 v5, s0, v1
	v_mul_f32_e32 v4, 0x4f7ffffe, v4
	v_cvt_u32_f32_e32 v4, v4
	v_mul_lo_u32 v1, v3, v4
	v_mul_hi_u32 v1, v4, v1
	v_add_u32_e32 v1, v4, v1
	v_mul_hi_u32 v1, v5, v1
	v_mul_lo_u32 v3, v1, v2
	v_sub_u32_e32 v3, v5, v3
	v_add_u32_e32 v4, 1, v1
	v_cmp_ge_u32_e32 vcc, v3, v2
	s_nop 1
	v_cndmask_b32_e32 v1, v1, v4, vcc
	v_sub_u32_e32 v4, v3, v2
	v_cndmask_b32_e32 v3, v3, v4, vcc
	v_add_u32_e32 v4, 1, v1
	v_cmp_ge_u32_e32 vcc, v3, v2
	v_add_u32_e32 v3, 1, v5
	s_nop 0
	v_cndmask_b32_e32 v1, v1, v4, vcc
	v_mul_lo_u32 v4, v2, v1
	v_add_u32_e32 v2, v4, v2
	v_cmp_ne_u32_e32 vcc, v3, v2
	s_and_saveexec_b64 s[0:1], vcc
	s_xor_b64 s[14:15], exec, s[0:1]
	s_cbranch_execz .LBB0_256
	s_waitcnt lgkmcnt(0)
	buffer_inv sc1
	v_mov_b32_e32 v0, 0x2000
	global_load_dword v0, v0, s[12:13] offset:1024 sc1
	s_add_u32 s20, s12, 0x2400
	s_addc_u32 s21, s13, 0
	s_waitcnt vmcnt(0)
	v_cmp_eq_u32_e32 vcc, v0, v1
	s_and_saveexec_b64 s[16:17], vcc
	s_cbranch_execz .LBB0_255
	s_add_u32 s18, s80, 0x1a20200
	s_addc_u32 s19, s81, 0
	s_mov_b32 s0, 1
	s_mov_b64 s[22:23], 0
	v_mov_b32_e32 v0, 0
	s_branch .LBB0_246

; __device__ __forceinline__ unsigned xb_ld(unsigned* p)              { return __hip_atomic_load(p, __ATOMIC_RELAXED, __HIP_MEMORY_SCOPE_AGENT); }
; #define XB_SPIN(cond, bar) do { unsigned _sp = 0; while (cond) { __builtin_amdgcn_s_sleep(1); \
;     if ((++_sp & 255u) == 0u) { if (xb_ld(&(bar)[XB_TMO])) break; if (_sp > XB_SPIN_CAP) { atomicAdd(&(bar)[XB_TMO], 1u); break; } } } } while (0)
; __device__ __forceinline__ void xcd_barrier(const XcdBarrier& b) {
;     ...
;             XB_SPIN(xb_ld(&bar[XB_XGEN(b.x)]) == gen, bar);
;             __builtin_amdgcn_fence(__ATOMIC_ACQUIRE, "agent");
;             asm volatile("s_waitcnt vmcnt(0)" ::: "memory");
.LBB0_255:
	s_or_b64 exec, exec, s[16:17]
	s_waitcnt vmcnt(0)
	s_waitcnt vmcnt(0)

; __device__ __forceinline__ unsigned xb_ld(unsigned* p)              { return __hip_atomic_load(p, __ATOMIC_RELAXED, __HIP_MEMORY_SCOPE_AGENT); }
; __device__ __forceinline__ unsigned xb_add(unsigned* p, unsigned v) { return __hip_atomic_fetch_add(p, v, __ATOMIC_RELAXED, __HIP_MEMORY_SCOPE_AGENT); }
; #define XB_SPIN(cond, bar) do { unsigned _sp = 0; while (cond) { __builtin_amdgcn_s_sleep(1); \
;     if ((++_sp & 255u) == 0u) { if (xb_ld(&(bar)[XB_TMO])) break; if (_sp > XB_SPIN_CAP) { atomicAdd(&(bar)[XB_TMO], 1u); break; } } } } while (0)
; __device__ __forceinline__ void xcd_barrier(const XcdBarrier& b) {
;     ...
;         const unsigned old = xb_add(&bar[XB_XSUB(b.x)], 1u);
;         const unsigned gen = old / nloc;
;         if (old + 1u == (gen + 1u) * nloc) {
;             __builtin_amdgcn_fence(__ATOMIC_RELEASE, "agent");
;             asm volatile("s_waitcnt vmcnt(0)" ::: "memory");
;             const unsigned og = xb_add(&bar[XB_TOP], 1u);
;             const unsigned tg = og / nx;
;             if (og + 1u == (tg + 1u) * nx) xb_add(&bar[XB_TOPGEN], 1u);
;             else XB_SPIN(xb_ld(&bar[XB_TOPGEN]) == tg, bar);
;             __builtin_amdgcn_fence(__ATOMIC_ACQUIRE, "agent");
;             xb_add(&bar[XB_XGEN(b.x)], 1u);
;             asm volatile("s_waitcnt vmcnt(0)" ::: "memory");
;         } else {
;             XB_SPIN(xb_ld(&bar[XB_XGEN(b.x)]) == gen, bar);
;             __builtin_amdgcn_fence(__ATOMIC_ACQUIRE, "agent");
;             asm volatile("s_waitcnt vmcnt(0)" ::: "memory");
.LBB0_378:
	s_or_b64 exec, exec, s[14:15]
	v_cvt_f32_u32_e32 v4, v2
	s_waitcnt vmcnt(0)
	v_readfirstlane_b32 s0, v3
	v_sub_u32_e32 v3, 0, v2
	v_rcp_iflag_f32_e32 v4, v4
	v_add_u32_e32 v5, s0, v1
	v_mul_f32_e32 v4, 0x4f7ffffe, v4
	v_cvt_u32_f32_e32 v4, v4
	v_mul_lo_u32 v1, v3, v4
	v_mul_hi_u32 v1, v4, v1
	v_add_u32_e32 v1, v4, v1
	v_mul_hi_u32 v1, v5, v1
	v_mul_lo_u32 v3, v1, v2
	v_sub_u32_e32 v3, v5, v3
	v_add_u32_e32 v4, 1, v1
	v_cmp_ge_u32_e32 vcc, v3, v2
	s_nop 1
	v_cndmask_b32_e32 v1, v1, v4, vcc
	v_sub_u32_e32 v4, v3, v2
	v_cndmask_b32_e32 v3, v3, v4, vcc
	v_add_u32_e32 v4, 1, v1
	v_cmp_ge_u32_e32 vcc, v3, v2
	v_add_u32_e32 v3, 1, v5
	s_nop 0
	v_cndmask_b32_e32 v1, v1, v4, vcc
	v_mul_lo_u32 v4, v2, v1
	v_add_u32_e32 v2, v4, v2
	v_cmp_ne_u32_e32 vcc, v3, v2
	s_and_saveexec_b64 s[0:1], vcc
	s_xor_b64 s[12:13], exec, s[0:1]
	s_cbranch_execz .LBB0_392
	s_waitcnt lgkmcnt(0)
	buffer_inv sc1
	v_mov_b32_e32 v0, 0x2000
	global_load_dword v0, v0, s[10:11] offset:1024 sc1
	s_add_u32 s18, s10, 0x2400
	s_addc_u32 s19, s11, 0
	s_waitcnt vmcnt(0)
	v_cmp_eq_u32_e32 vcc, v0, v1
	s_and_saveexec_b64 s[14:15], vcc
	s_cbranch_execz .LBB0_391
	s_add_u32 s16, s80, 0x1a20200
	s_addc_u32 s17, s81, 0
	s_mov_b32 s0, 1
	s_mov_b64 s[20:21], 0
	v_mov_b32_e32 v0, 0
	s_branch .LBB0_382

; __device__ __forceinline__ float bf2f(unsigned b) { return __uint_as_float(b << 16); }
;     __device__ __forceinline__ void operator()(const f32x4 (&acc)[2][2][4][2], const Unit& u, int wr, int wc, int fr, int fq) const {
;         const bool recon = (XN != nullptr) && (u.pm < 64);
;         f32x4 gi[2][2];
;         if (recon) {
; #pragma unroll
;             for (int bj = 0; bj < 2; ++bj) { const int col0 = u.pn * 256 + bj * 128 + wc * 32 + fq * 8;
; #pragma unroll
;                 for (int n = 0; n < 2; ++n) { const f32x4 gq = *(const f32x4*)(gmix + col0 + 4 * n);
;                     gi[bj][n] = (f32x4){__builtin_amdgcn_rcpf(gq[0]), __builtin_amdgcn_rcpf(gq[1]), __builtin_amdgcn_rcpf(gq[2]), __builtin_amdgcn_rcpf(gq[3])}; } }
;         }
; #pragma unroll
;         for (int ai = 0; ai < 2; ++ai)
; #pragma unroll
;             for (int m = 0; m < 4; ++m) {
;                 const int row = u.pm * 256 + ai * 128 + wr * 64 + m * 16 + fr;
;                 const bool valid = row < MTOT;
;                 const float* xr = row < MP ? xp + (size_t)row * D : xs + (size_t)(valid ? row - MP : 0) * D;
;                 const float ri = recon ? RINV[row] : 0.f;
;                 float ss = 0.f;
; #pragma unroll
;                 for (int bj = 0; bj < 2; ++bj) {
;                     const int col0 = u.pn * 256 + bj * 128 + wc * 32 + fq * 8;
;                     f32x4 x0 = (f32x4){0.f, 0.f, 0.f, 0.f}, x1 = x0;
;                     if (recon) {
;                         const v4u xb = __builtin_nontemporal_load((const v4u*)(XN + (size_t)row * D + col0));
;                         x0 = (f32x4){bf2f(xb.x & 0xffffu), bf2f(xb.x >> 16), bf2f(xb.y & 0xffffu), bf2f(xb.y >> 16)} * gi[bj][0] * ri;
;                         x1 = (f32x4){bf2f(xb.z & 0xffffu), bf2f(xb.z >> 16), bf2f(xb.w & 0xffffu), bf2f(xb.w >> 16)} * gi[bj][1] * ri;
;                     } else if (valid) { x0 = *(const f32x4*)(xr + col0); x1 = *(const f32x4*)(xr + col0 + 4); }
;                     const f32x4 v0 = acc[ai][bj][m][0] + x0, v1 = acc[ai][bj][m][1] + x1;
;                     ss += (v0[0] * v0[0] + v0[1] * v0[1]) + (v0[2] * v0[2] + v0[3] * v0[3]) + (v1[0] * v1[0] + v1[1] * v1[1]) + (v1[2] * v1[2] + v1[3] * v1[3]);
;                     if (valid && row >= MP) { *(f32x4*)(out + (size_t)row * D + col0) = v0; *(f32x4*)(out + (size_t)row * D + col0 + 4) = v1; }
.LBB0_526:
	s_branch .Lfo_begin
	s_lshl_b32 s47, s10, 8
	v_lshl_or_b32 v162, s12, 8, v187
	s_add_i32 s47, s47, s35
	v_ashrrev_i32_e32 v163, 31, v162
	v_or_b32_e32 v176, s47, v153
	v_lshl_add_u64 v[132:133], v[162:163], 2, s[14:15]
	v_ashrrev_i32_e32 v177, 31, v176
	global_load_dwordx4 v[172:175], v[132:133], off offset:16
	global_load_dwordx4 v[166:169], v[132:133], off
	v_lshlrev_b64 v[164:165], 11, v[176:177]
	v_lshl_add_u64 v[128:129], s[26:27], 0, v[164:165]
	v_lshl_add_u64 v[136:137], v[162:163], 1, v[128:129]
	global_load_dwordx4 v[192:195], v[136:137], off nt
	v_lshl_add_u64 v[128:129], v[176:177], 2, s[18:19]
	global_load_dword v178, v[128:129], off
	s_nop 0
	global_load_dwordx4 v[128:131], v[132:133], off offset:528
	s_nop 0
	global_load_dwordx4 v[132:135], v[132:133], off offset:512
	s_and_b32 s10, s47, 0xffffff80
	s_cmpk_eq_i32 s10, 0x4000
	s_cselect_b64 s[54:55], -1, 0
	s_cmpk_lg_i32 s10, 0x4000
	v_lshlrev_b32_e32 v148, 10, v176
	s_cselect_b64 s[56:57], -1, 0
	v_lshl_add_u64 v[182:183], v[148:149], 2, s[16:17]
	s_and_b64 vcc, exec, s[56:57]
	s_waitcnt vmcnt(0)
	v_rcp_f32_e32 v172, v172
	v_rcp_f32_e32 v166, v166
	v_rcp_f32_e32 v167, v167
	v_rcp_f32_e32 v168, v168
	v_rcp_f32_e32 v169, v169
	v_rcp_f32_e32 v173, v173
	v_rcp_f32_e32 v174, v174
	v_rcp_f32_e32 v175, v175
	v_lshlrev_b32_e32 v138, 16, v194
	v_and_b32_e32 v139, 0xffff0000, v194
	v_lshlrev_b32_e32 v170, 16, v195
	v_and_b32_e32 v171, 0xffff0000, v195
	v_lshlrev_b32_e32 v180, 16, v192
	v_and_b32_e32 v181, 0xffff0000, v192
	v_lshlrev_b32_e32 v192, 16, v193
	v_and_b32_e32 v193, 0xffff0000, v193
	v_pk_mul_f32 v[138:139], v[172:173], v[138:139]
	v_pk_mul_f32 v[170:171], v[174:175], v[170:171]
	v_pk_mul_f32 v[180:181], v[166:167], v[180:181]
	v_pk_mul_f32 v[192:193], v[168:169], v[192:193]
	v_pk_fma_f32 v[124:125], v[178:179], v[180:181], v[124:125] op_sel_hi:[0,1,1]
	v_pk_fma_f32 v[126:127], v[178:179], v[192:193], v[126:127] op_sel_hi:[0,1,1]
	v_pk_fma_f32 v[122:123], v[178:179], v[170:171], v[122:123] op_sel_hi:[0,1,1]
	v_pk_fma_f32 v[120:121], v[178:179], v[138:139], v[120:121] op_sel_hi:[0,1,1]
	s_cbranch_vccnz .LBB0_528
	v_lshl_add_u64 v[138:139], v[162:163], 2, v[182:183]
	global_store_dwordx4 v[138:139], v[124:127], off
	global_store_dwordx4 v[138:139], v[120:123], off offset:16

;     __device__ __forceinline__ void operator()(const f32x4 (&acc)[2][2][4][2], const Unit& u, int wr, int wc, int fr, int fq) const {
;     ...
;         if (recon) {
; #pragma unroll
;             for (int bj = 0; bj < 2; ++bj) { const int col0 = u.pn * 256 + bj * 128 + wc * 32 + fq * 8;
; #pragma unroll
;                 for (int n = 0; n < 2; ++n) { const f32x4 gq = *(const f32x4*)(gmix + col0 + 4 * n);
;                     gi[bj][n] = (f32x4){__builtin_amdgcn_rcpf(gq[0]), __builtin_amdgcn_rcpf(gq[1]), __builtin_amdgcn_rcpf(gq[2]), __builtin_amdgcn_rcpf(gq[3])}; } }
;         }
; #pragma unroll
;         for (int ai = 0; ai < 2; ++ai)
; #pragma unroll
;             for (int m = 0; m < 4; ++m) {
;                 const int row = u.pm * 256 + ai * 128 + wr * 64 + m * 16 + fr;
;                 const bool valid = row < MTOT;
;                 const float* xr = row < MP ? xp + (size_t)row * D : xs + (size_t)(valid ? row - MP : 0) * D;
;                 const float ri = recon ? RINV[row] : 0.f;
;                 float ss = 0.f;
; #pragma unroll
;                 for (int bj = 0; bj < 2; ++bj) {
;                     const int col0 = u.pn * 256 + bj * 128 + wc * 32 + fq * 8;
;                     f32x4 x0 = (f32x4){0.f, 0.f, 0.f, 0.f}, x1 = x0;
;                     if (recon) {
;                         const v4u xb = __builtin_nontemporal_load((const v4u*)(XN + (size_t)row * D + col0));
;                         x0 = (f32x4){bf2f(xb.x & 0xffffu), bf2f(xb.x >> 16), bf2f(xb.y & 0xffffu), bf2f(xb.y >> 16)} * gi[bj][0] * ri;
;                         x1 = (f32x4){bf2f(xb.z & 0xffffu), bf2f(xb.z >> 16), bf2f(xb.w & 0xffffu), bf2f(xb.w >> 16)} * gi[bj][1] * ri;
;                     } else if (valid) { x0 = *(const f32x4*)(xr + col0); x1 = *(const f32x4*)(xr + col0 + 4); }
;                     const f32x4 v0 = acc[ai][bj][m][0] + x0, v1 = acc[ai][bj][m][1] + x1;
;                     ss += (v0[0] * v0[0] + v0[1] * v0[1]) + (v0[2] * v0[2] + v0[3] * v0[3]) + (v1[0] * v1[0] + v1[1] * v1[1]) + (v1[2] * v1[2] + v1[3] * v1[3]);
;                     if (valid && row >= MP) { *(f32x4*)(out + (size_t)row * D + col0) = v0; *(f32x4*)(out + (size_t)row * D + col0 + 4) = v1; }
;                     v4u w; w.x = cvt_pk_bf16(v0[0], v0[1]); w.y = cvt_pk_bf16(v0[2], v0[3]); w.z = cvt_pk_bf16(v1[0], v1[1]); w.w = cvt_pk_bf16(v1[2], v1[3]);
.Lfo_begin:
	s_lshl_b32 s47, s10, 8
	s_add_i32 s47, s47, s35
	v_or_b32_e32 v137, s47, v153
	v_lshl_or_b32 v138, s12, 8, v187
	v_lshlrev_b32_e32 v136, 11, v137
	v_lshl_add_u32 v136, v138, 1, v136
	v_lshlrev_b32_e32 v137, 2, v137
	v_lshlrev_b32_e32 v138, 2, v138
	global_load_dwordx4 v[162:165], v138, s[14:15]
	global_load_dwordx4 v[166:169], v138, s[14:15] offset:16
	global_load_dwordx4 v[170:173], v138, s[14:15] offset:512
	global_load_dwordx4 v[174:177], v138, s[14:15] offset:528
	global_load_dword v128, v137, s[18:19]
	global_load_dwordx4 v[178:181], v136, s[26:27] nt
	global_load_dwordx4 v[192:195], v136, s[26:27] offset:256 nt
	v_xor_b32_e32 v139, 16, v191
	v_xor_b32_e32 v148, 32, v191
	v_lshlrev_b32_e32 v139, 2, v139
	v_lshlrev_b32_e32 v148, 2, v148
	s_waitcnt vmcnt(3)
	v_rcp_f32_e32 v162, v162
	v_rcp_f32_e32 v163, v163
	v_rcp_f32_e32 v164, v164
	v_rcp_f32_e32 v165, v165
	v_rcp_f32_e32 v166, v166
	v_rcp_f32_e32 v167, v167
	v_rcp_f32_e32 v168, v168
	v_rcp_f32_e32 v169, v169
	v_rcp_f32_e32 v170, v170
	v_rcp_f32_e32 v171, v171
	v_rcp_f32_e32 v172, v172
	v_rcp_f32_e32 v173, v173
	v_rcp_f32_e32 v174, v174
	v_rcp_f32_e32 v175, v175
	v_rcp_f32_e32 v176, v176
	v_rcp_f32_e32 v177, v177
	global_load_dword v129, v137, s[18:19] offset:64
	s_add_u32 s0, s26, 0x8000
	s_addc_u32 s1, s27, 0
	global_load_dwordx4 v[250:253], v136, s[0:1] nt
	global_load_dwordx4 v[132:135], v136, s[0:1] offset:256 nt
	s_waitcnt vmcnt(3)
	v_lshlrev_b32_e32 v238, 16, v178
	v_and_b32_e32 v239, 0xffff0000, v178
	v_lshlrev_b32_e32 v240, 16, v179
	v_and_b32_e32 v241, 0xffff0000, v179
	v_lshlrev_b32_e32 v242, 16, v180
	v_and_b32_e32 v243, 0xffff0000, v180
	v_lshlrev_b32_e32 v244, 16, v181
	v_and_b32_e32 v245, 0xffff0000, v181
	v_pk_mul_f32 v[238:239], v[162:163], v[238:239]
	v_pk_mul_f32 v[240:241], v[164:165], v[240:241]
	v_pk_mul_f32 v[242:243], v[166:167], v[242:243]
	v_pk_mul_f32 v[244:245], v[168:169], v[244:245]
	v_pk_fma_f32 v[124:125], v[128:129], v[238:239], v[124:125] op_sel_hi:[0,1,1]
	v_pk_fma_f32 v[126:127], v[128:129], v[240:241], v[126:127] op_sel_hi:[0,1,1]
	v_pk_fma_f32 v[120:121], v[128:129], v[242:243], v[120:121] op_sel_hi:[0,1,1]
	v_pk_fma_f32 v[122:123], v[128:129], v[244:245], v[122:123] op_sel_hi:[0,1,1]
	v_pk_mul_f32 v[246:247], v[124:125], v[124:125]
	v_pk_fma_f32 v[246:247], v[126:127], v[126:127], v[246:247]
	v_pk_fma_f32 v[246:247], v[120:121], v[120:121], v[246:247]
	v_pk_fma_f32 v[246:247], v[122:123], v[122:123], v[246:247]
	v_cvt_pk_bf16_f32 v238, v124, v125
	v_cvt_pk_bf16_f32 v239, v126, v127
	v_cvt_pk_bf16_f32 v240, v120, v121
	v_cvt_pk_bf16_f32 v241, v122, v123
	global_store_dwordx4 v136, v[238:241], s[22:23]
	s_nop 1
	v_lshlrev_b32_e32 v238, 16, v192
	v_and_b32_e32 v239, 0xffff0000, v192
	v_lshlrev_b32_e32 v240, 16, v193
	v_and_b32_e32 v241, 0xffff0000, v193
	v_lshlrev_b32_e32 v242, 16, v194
	v_and_b32_e32 v243, 0xffff0000, v194
	v_lshlrev_b32_e32 v244, 16, v195
	v_and_b32_e32 v245, 0xffff0000, v195
	v_pk_mul_f32 v[238:239], v[170:171], v[238:239]
	v_pk_mul_f32 v[240:241], v[172:173], v[240:241]
	v_pk_mul_f32 v[242:243], v[174:175], v[242:243]
	v_pk_mul_f32 v[244:245], v[176:177], v[244:245]
	v_pk_fma_f32 v[116:117], v[128:129], v[238:239], v[116:117] op_sel_hi:[0,1,1]
	v_pk_fma_f32 v[118:119], v[128:129], v[240:241], v[118:119] op_sel_hi:[0,1,1]
	v_pk_fma_f32 v[112:113], v[128:129], v[242:243], v[112:113] op_sel_hi:[0,1,1]
	v_pk_fma_f32 v[114:115], v[128:129], v[244:245], v[114:115] op_sel_hi:[0,1,1]
	v_pk_fma_f32 v[246:247], v[116:117], v[116:117], v[246:247]
	v_pk_fma_f32 v[246:247], v[118:119], v[118:119], v[246:247]
	v_pk_fma_f32 v[246:247], v[112:113], v[112:113], v[246:247]
	v_pk_fma_f32 v[246:247], v[114:115], v[114:115], v[246:247]
	v_cvt_pk_bf16_f32 v242, v116, v117
	v_cvt_pk_bf16_f32 v243, v118, v119
	v_cvt_pk_bf16_f32 v244, v112, v113
	v_cvt_pk_bf16_f32 v245, v114, v115
	global_store_dwordx4 v136, v[242:245], s[22:23] offset:256
	s_nop 1
	v_add_f32_e32 v248, v246, v247
	ds_bpermute_b32 v249, v139, v248
	s_waitcnt lgkmcnt(0)
	v_add_f32_e32 v248, v248, v249
	ds_bpermute_b32 v249, v148, v248
	s_waitcnt lgkmcnt(0)
	v_add_f32_e32 v248, v248, v249
	s_mov_b64 s[12:13], exec
	s_mov_b64 exec, s[8:9]
	global_atomic_add_f32 v137, v248, s[24:25]
	s_mov_b64 exec, s[12:13]
	s_nop 1
	global_load_dword v128, v137, s[18:19] offset:128
	s_add_u32 s0, s26, 0x10000
	s_addc_u32 s1, s27, 0
	global_load_dwordx4 v[178:181], v136, s[0:1] nt
	global_load_dwordx4 v[192:195], v136, s[0:1] offset:256 nt
	s_waitcnt vmcnt(6)
; __device__ __forceinline__ unsigned cvt_pk_bf16(float lo, float hi) { unsigned r; asm volatile("v_cvt_pk_bf16_f32 %0, %1, %2" : "=v"(r) : "v"(lo), "v"(hi)); return r; }
; __device__ __forceinline__ float bf2f(unsigned b) { return __uint_as_float(b << 16); }
;     __device__ __forceinline__ void operator()(const f32x4 (&acc)[2][2][4][2], const Unit& u, int wr, int wc, int fr, int fq) const {
;     ...
;             for (int m = 0; m < 4; ++m) {
;                 const int row = u.pm * 256 + ai * 128 + wr * 64 + m * 16 + fr;
;                 const bool valid = row < MTOT;
;                 const float* xr = row < MP ? xp + (size_t)row * D : xs + (size_t)(valid ? row - MP : 0) * D;
;                 const float ri = recon ? RINV[row] : 0.f;
;                 float ss = 0.f;
; #pragma unroll
;                 for (int bj = 0; bj < 2; ++bj) {
;                     const int col0 = u.pn * 256 + bj * 128 + wc * 32 + fq * 8;
;                     f32x4 x0 = (f32x4){0.f, 0.f, 0.f, 0.f}, x1 = x0;
;                     if (recon) {
;                         const v4u xb = __builtin_nontemporal_load((const v4u*)(XN + (size_t)row * D + col0));
;                         x0 = (f32x4){bf2f(xb.x & 0xffffu), bf2f(xb.x >> 16), bf2f(xb.y & 0xffffu), bf2f(xb.y >> 16)} * gi[bj][0] * ri;
;                         x1 = (f32x4){bf2f(xb.z & 0xffffu), bf2f(xb.z >> 16), bf2f(xb.w & 0xffffu), bf2f(xb.w >> 16)} * gi[bj][1] * ri;
;                     } else if (valid) { x0 = *(const f32x4*)(xr + col0); x1 = *(const f32x4*)(xr + col0 + 4); }
;                     const f32x4 v0 = acc[ai][bj][m][0] + x0, v1 = acc[ai][bj][m][1] + x1;
;                     ss += (v0[0] * v0[0] + v0[1] * v0[1]) + (v0[2] * v0[2] + v0[3] * v0[3]) + (v1[0] * v1[0] + v1[1] * v1[1]) + (v1[2] * v1[2] + v1[3] * v1[3]);
;                     if (valid && row >= MP) { *(f32x4*)(out + (size_t)row * D + col0) = v0; *(f32x4*)(out + (size_t)row * D + col0 + 4) = v1; }
;                     v4u w; w.x = cvt_pk_bf16(v0[0], v0[1]); w.y = cvt_pk_bf16(v0[2], v0[3]); w.z = cvt_pk_bf16(v1[0], v1[1]); w.w = cvt_pk_bf16(v1[2], v1[3]);
;                     *(v4u*)(XMIDB + (size_t)row * D + col0) = w;
;                 }
;                 ss += __shfl_xor(ss, 16); ss += __shfl_xor(ss, 32);
;                 if (fq == 0) atomicAdd(SS + row, ss);
;                 if (m & 1) asm volatile("" ::: "memory");
	v_lshlrev_b32_e32 v238, 16, v250
	v_and_b32_e32 v239, 0xffff0000, v250
	v_lshlrev_b32_e32 v240, 16, v251
	v_and_b32_e32 v241, 0xffff0000, v251
	v_lshlrev_b32_e32 v242, 16, v252
	v_and_b32_e32 v243, 0xffff0000, v252
	v_lshlrev_b32_e32 v244, 16, v253
	v_and_b32_e32 v245, 0xffff0000, v253
	v_pk_mul_f32 v[238:239], v[162:163], v[238:239]
	v_pk_mul_f32 v[240:241], v[164:165], v[240:241]
	v_pk_mul_f32 v[242:243], v[166:167], v[242:243]
	v_pk_mul_f32 v[244:245], v[168:169], v[244:245]
	v_pk_fma_f32 v[108:109], v[128:129], v[238:239], v[108:109] op_sel:[1,0,0] op_sel_hi:[1,1,1]
	v_pk_fma_f32 v[110:111], v[128:129], v[240:241], v[110:111] op_sel:[1,0,0] op_sel_hi:[1,1,1]
	v_pk_fma_f32 v[104:105], v[128:129], v[242:243], v[104:105] op_sel:[1,0,0] op_sel_hi:[1,1,1]
	v_pk_fma_f32 v[106:107], v[128:129], v[244:245], v[106:107] op_sel:[1,0,0] op_sel_hi:[1,1,1]
	v_pk_mul_f32 v[246:247], v[108:109], v[108:109]
	v_pk_fma_f32 v[246:247], v[110:111], v[110:111], v[246:247]
	v_pk_fma_f32 v[246:247], v[104:105], v[104:105], v[246:247]
	v_pk_fma_f32 v[246:247], v[106:107], v[106:107], v[246:247]
	v_cvt_pk_bf16_f32 v238, v108, v109
	v_cvt_pk_bf16_f32 v239, v110, v111
	v_cvt_pk_bf16_f32 v240, v104, v105
	v_cvt_pk_bf16_f32 v241, v106, v107
	s_add_u32 s4, s22, 0x8000
	s_addc_u32 s5, s23, 0
	global_store_dwordx4 v136, v[238:241], s[4:5]
	s_nop 1
	v_lshlrev_b32_e32 v238, 16, v132
	v_and_b32_e32 v239, 0xffff0000, v132
	v_lshlrev_b32_e32 v240, 16, v133
	v_and_b32_e32 v241, 0xffff0000, v133
	v_lshlrev_b32_e32 v242, 16, v134
	v_and_b32_e32 v243, 0xffff0000, v134
	v_lshlrev_b32_e32 v244, 16, v135
	v_and_b32_e32 v245, 0xffff0000, v135
	v_pk_mul_f32 v[238:239], v[170:171], v[238:239]
	v_pk_mul_f32 v[240:241], v[172:173], v[240:241]
	v_pk_mul_f32 v[242:243], v[174:175], v[242:243]
	v_pk_mul_f32 v[244:245], v[176:177], v[244:245]
	v_pk_fma_f32 v[100:101], v[128:129], v[238:239], v[100:101] op_sel:[1,0,0] op_sel_hi:[1,1,1]
	v_pk_fma_f32 v[102:103], v[128:129], v[240:241], v[102:103] op_sel:[1,0,0] op_sel_hi:[1,1,1]
	v_pk_fma_f32 v[96:97], v[128:129], v[242:243], v[96:97] op_sel:[1,0,0] op_sel_hi:[1,1,1]
	v_pk_fma_f32 v[98:99], v[128:129], v[244:245], v[98:99] op_sel:[1,0,0] op_sel_hi:[1,1,1]
	v_pk_fma_f32 v[246:247], v[100:101], v[100:101], v[246:247]
	v_pk_fma_f32 v[246:247], v[102:103], v[102:103], v[246:247]
	v_pk_fma_f32 v[246:247], v[96:97], v[96:97], v[246:247]
	v_pk_fma_f32 v[246:247], v[98:99], v[98:99], v[246:247]
	v_cvt_pk_bf16_f32 v242, v100, v101
	v_cvt_pk_bf16_f32 v243, v102, v103
	v_cvt_pk_bf16_f32 v244, v96, v97
	v_cvt_pk_bf16_f32 v245, v98, v99
	global_store_dwordx4 v136, v[242:245], s[4:5] offset:256
	s_nop 1
	v_add_f32_e32 v248, v246, v247
	ds_bpermute_b32 v249, v139, v248
	s_waitcnt lgkmcnt(0)
	v_add_f32_e32 v248, v248, v249
	ds_bpermute_b32 v249, v148, v248
	s_waitcnt lgkmcnt(0)
	v_add_f32_e32 v248, v248, v249
	s_mov_b64 s[12:13], exec
	s_mov_b64 exec, s[8:9]
	global_atomic_add_f32 v137, v248, s[24:25] offset:64
	s_mov_b64 exec, s[12:13]
	s_nop 1
	global_load_dword v129, v137, s[18:19] offset:192
	s_add_u32 s0, s26, 0x18000
	s_addc_u32 s1, s27, 0
	global_load_dwordx4 v[250:253], v136, s[0:1] nt
	global_load_dwordx4 v[132:135], v136, s[0:1] offset:256 nt
	s_waitcnt vmcnt(6)
	v_lshlrev_b32_e32 v238, 16, v178
	v_and_b32_e32 v239, 0xffff0000, v178
	v_lshlrev_b32_e32 v240, 16, v179
	v_and_b32_e32 v241, 0xffff0000, v179
	v_lshlrev_b32_e32 v242, 16, v180
	v_and_b32_e32 v243, 0xffff0000, v180
	v_lshlrev_b32_e32 v244, 16, v181
	v_and_b32_e32 v245, 0xffff0000, v181
	v_pk_mul_f32 v[238:239], v[162:163], v[238:239]
	v_pk_mul_f32 v[240:241], v[164:165], v[240:241]
	v_pk_mul_f32 v[242:243], v[166:167], v[242:243]
	v_pk_mul_f32 v[244:245], v[168:169], v[244:245]
	v_pk_fma_f32 v[92:93], v[128:129], v[238:239], v[92:93] op_sel_hi:[0,1,1]
	v_pk_fma_f32 v[94:95], v[128:129], v[240:241], v[94:95] op_sel_hi:[0,1,1]
	v_pk_fma_f32 v[88:89], v[128:129], v[242:243], v[88:89] op_sel_hi:[0,1,1]
	v_pk_fma_f32 v[90:91], v[128:129], v[244:245], v[90:91] op_sel_hi:[0,1,1]
	v_pk_mul_f32 v[246:247], v[92:93], v[92:93]
	v_pk_fma_f32 v[246:247], v[94:95], v[94:95], v[246:247]
	v_pk_fma_f32 v[246:247], v[88:89], v[88:89], v[246:247]
	v_pk_fma_f32 v[246:247], v[90:91], v[90:91], v[246:247]
	v_cvt_pk_bf16_f32 v238, v92, v93
	v_cvt_pk_bf16_f32 v239, v94, v95
	v_cvt_pk_bf16_f32 v240, v88, v89
	v_cvt_pk_bf16_f32 v241, v90, v91
	s_add_u32 s4, s22, 0x10000
	s_addc_u32 s5, s23, 0
	global_store_dwordx4 v136, v[238:241], s[4:5]
	s_nop 1
	v_lshlrev_b32_e32 v238, 16, v192
	v_and_b32_e32 v239, 0xffff0000, v192
	v_lshlrev_b32_e32 v240, 16, v193
	v_and_b32_e32 v241, 0xffff0000, v193
	v_lshlrev_b32_e32 v242, 16, v194
	v_and_b32_e32 v243, 0xffff0000, v194
	v_lshlrev_b32_e32 v244, 16, v195
	v_and_b32_e32 v245, 0xffff0000, v195
	v_pk_mul_f32 v[238:239], v[170:171], v[238:239]
	v_pk_mul_f32 v[240:241], v[172:173], v[240:241]
	v_pk_mul_f32 v[242:243], v[174:175], v[242:243]
	v_pk_mul_f32 v[244:245], v[176:177], v[244:245]
	v_pk_fma_f32 v[84:85], v[128:129], v[238:239], v[84:85] op_sel_hi:[0,1,1]
	v_pk_fma_f32 v[86:87], v[128:129], v[240:241], v[86:87] op_sel_hi:[0,1,1]
	v_pk_fma_f32 v[80:81], v[128:129], v[242:243], v[80:81] op_sel_hi:[0,1,1]
	v_pk_fma_f32 v[82:83], v[128:129], v[244:245], v[82:83] op_sel_hi:[0,1,1]
	v_pk_fma_f32 v[246:247], v[84:85], v[84:85], v[246:247]
	v_pk_fma_f32 v[246:247], v[86:87], v[86:87], v[246:247]
	v_pk_fma_f32 v[246:247], v[80:81], v[80:81], v[246:247]
	v_pk_fma_f32 v[246:247], v[82:83], v[82:83], v[246:247]
	v_cvt_pk_bf16_f32 v242, v84, v85
	v_cvt_pk_bf16_f32 v243, v86, v87
	v_cvt_pk_bf16_f32 v244, v80, v81
	v_cvt_pk_bf16_f32 v245, v82, v83
	global_store_dwordx4 v136, v[242:245], s[4:5] offset:256
	s_nop 1
	v_add_f32_e32 v248, v246, v247
	ds_bpermute_b32 v249, v139, v248
	s_waitcnt lgkmcnt(0)
; __device__ __forceinline__ unsigned cvt_pk_bf16(float lo, float hi) { unsigned r; asm volatile("v_cvt_pk_bf16_f32 %0, %1, %2" : "=v"(r) : "v"(lo), "v"(hi)); return r; }
; __device__ __forceinline__ float bf2f(unsigned b) { return __uint_as_float(b << 16); }
;     __device__ __forceinline__ void operator()(const f32x4 (&acc)[2][2][4][2], const Unit& u, int wr, int wc, int fr, int fq) const {
;     ...
;             for (int m = 0; m < 4; ++m) {
;                 const int row = u.pm * 256 + ai * 128 + wr * 64 + m * 16 + fr;
;                 const bool valid = row < MTOT;
;                 const float* xr = row < MP ? xp + (size_t)row * D : xs + (size_t)(valid ? row - MP : 0) * D;
;                 const float ri = recon ? RINV[row] : 0.f;
;                 float ss = 0.f;
; #pragma unroll
;                 for (int bj = 0; bj < 2; ++bj) {
;                     const int col0 = u.pn * 256 + bj * 128 + wc * 32 + fq * 8;
;                     f32x4 x0 = (f32x4){0.f, 0.f, 0.f, 0.f}, x1 = x0;
;                     if (recon) {
;                         const v4u xb = __builtin_nontemporal_load((const v4u*)(XN + (size_t)row * D + col0));
;                         x0 = (f32x4){bf2f(xb.x & 0xffffu), bf2f(xb.x >> 16), bf2f(xb.y & 0xffffu), bf2f(xb.y >> 16)} * gi[bj][0] * ri;
;                         x1 = (f32x4){bf2f(xb.z & 0xffffu), bf2f(xb.z >> 16), bf2f(xb.w & 0xffffu), bf2f(xb.w >> 16)} * gi[bj][1] * ri;
;                     } else if (valid) { x0 = *(const f32x4*)(xr + col0); x1 = *(const f32x4*)(xr + col0 + 4); }
;                     const f32x4 v0 = acc[ai][bj][m][0] + x0, v1 = acc[ai][bj][m][1] + x1;
;                     ss += (v0[0] * v0[0] + v0[1] * v0[1]) + (v0[2] * v0[2] + v0[3] * v0[3]) + (v1[0] * v1[0] + v1[1] * v1[1]) + (v1[2] * v1[2] + v1[3] * v1[3]);
;                     if (valid && row >= MP) { *(f32x4*)(out + (size_t)row * D + col0) = v0; *(f32x4*)(out + (size_t)row * D + col0 + 4) = v1; }
;                     v4u w; w.x = cvt_pk_bf16(v0[0], v0[1]); w.y = cvt_pk_bf16(v0[2], v0[3]); w.z = cvt_pk_bf16(v1[0], v1[1]); w.w = cvt_pk_bf16(v1[2], v1[3]);
;                     *(v4u*)(XMIDB + (size_t)row * D + col0) = w;
;                 }
;                 ss += __shfl_xor(ss, 16); ss += __shfl_xor(ss, 32);
;                 if (fq == 0) atomicAdd(SS + row, ss);
;                 if (m & 1) asm volatile("" ::: "memory");
	v_add_f32_e32 v248, v248, v249
	ds_bpermute_b32 v249, v148, v248
	s_waitcnt lgkmcnt(0)
	v_add_f32_e32 v248, v248, v249
	s_mov_b64 s[12:13], exec
	s_mov_b64 exec, s[8:9]
	global_atomic_add_f32 v137, v248, s[24:25] offset:128
	s_mov_b64 exec, s[12:13]
	s_nop 1
	global_load_dword v128, v137, s[18:19] offset:512
	s_add_u32 s0, s26, 0x40000
	s_addc_u32 s1, s27, 0
	global_load_dwordx4 v[178:181], v136, s[0:1] nt
	global_load_dwordx4 v[192:195], v136, s[0:1] offset:256 nt
	s_waitcnt vmcnt(6)
	v_lshlrev_b32_e32 v238, 16, v250
	v_and_b32_e32 v239, 0xffff0000, v250
	v_lshlrev_b32_e32 v240, 16, v251
	v_and_b32_e32 v241, 0xffff0000, v251
	v_lshlrev_b32_e32 v242, 16, v252
	v_and_b32_e32 v243, 0xffff0000, v252
	v_lshlrev_b32_e32 v244, 16, v253
	v_and_b32_e32 v245, 0xffff0000, v253
	v_pk_mul_f32 v[238:239], v[162:163], v[238:239]
	v_pk_mul_f32 v[240:241], v[164:165], v[240:241]
	v_pk_mul_f32 v[242:243], v[166:167], v[242:243]
	v_pk_mul_f32 v[244:245], v[168:169], v[244:245]
	v_pk_fma_f32 v[76:77], v[128:129], v[238:239], v[76:77] op_sel:[1,0,0] op_sel_hi:[1,1,1]
	v_pk_fma_f32 v[78:79], v[128:129], v[240:241], v[78:79] op_sel:[1,0,0] op_sel_hi:[1,1,1]
	v_pk_fma_f32 v[72:73], v[128:129], v[242:243], v[72:73] op_sel:[1,0,0] op_sel_hi:[1,1,1]
	v_pk_fma_f32 v[74:75], v[128:129], v[244:245], v[74:75] op_sel:[1,0,0] op_sel_hi:[1,1,1]
	v_pk_mul_f32 v[246:247], v[76:77], v[76:77]
	v_pk_fma_f32 v[246:247], v[78:79], v[78:79], v[246:247]
	v_pk_fma_f32 v[246:247], v[72:73], v[72:73], v[246:247]
	v_pk_fma_f32 v[246:247], v[74:75], v[74:75], v[246:247]
	v_cvt_pk_bf16_f32 v238, v76, v77
	v_cvt_pk_bf16_f32 v239, v78, v79
	v_cvt_pk_bf16_f32 v240, v72, v73
	v_cvt_pk_bf16_f32 v241, v74, v75
	s_add_u32 s4, s22, 0x18000
	s_addc_u32 s5, s23, 0
	global_store_dwordx4 v136, v[238:241], s[4:5]
	s_nop 1
	v_lshlrev_b32_e32 v238, 16, v132
	v_and_b32_e32 v239, 0xffff0000, v132
	v_lshlrev_b32_e32 v240, 16, v133
	v_and_b32_e32 v241, 0xffff0000, v133
	v_lshlrev_b32_e32 v242, 16, v134
	v_and_b32_e32 v243, 0xffff0000, v134
	v_lshlrev_b32_e32 v244, 16, v135
	v_and_b32_e32 v245, 0xffff0000, v135
	v_pk_mul_f32 v[238:239], v[170:171], v[238:239]
	v_pk_mul_f32 v[240:241], v[172:173], v[240:241]
	v_pk_mul_f32 v[242:243], v[174:175], v[242:243]
	v_pk_mul_f32 v[244:245], v[176:177], v[244:245]
	v_pk_fma_f32 v[68:69], v[128:129], v[238:239], v[68:69] op_sel:[1,0,0] op_sel_hi:[1,1,1]
	v_pk_fma_f32 v[70:71], v[128:129], v[240:241], v[70:71] op_sel:[1,0,0] op_sel_hi:[1,1,1]
	v_pk_fma_f32 v[64:65], v[128:129], v[242:243], v[64:65] op_sel:[1,0,0] op_sel_hi:[1,1,1]
	v_pk_fma_f32 v[66:67], v[128:129], v[244:245], v[66:67] op_sel:[1,0,0] op_sel_hi:[1,1,1]
	v_pk_fma_f32 v[246:247], v[68:69], v[68:69], v[246:247]
	v_pk_fma_f32 v[246:247], v[70:71], v[70:71], v[246:247]
	v_pk_fma_f32 v[246:247], v[64:65], v[64:65], v[246:247]
	v_pk_fma_f32 v[246:247], v[66:67], v[66:67], v[246:247]
	v_cvt_pk_bf16_f32 v242, v68, v69
	v_cvt_pk_bf16_f32 v243, v70, v71
	v_cvt_pk_bf16_f32 v244, v64, v65
	v_cvt_pk_bf16_f32 v245, v66, v67
	global_store_dwordx4 v136, v[242:245], s[4:5] offset:256
	s_nop 1
	v_add_f32_e32 v248, v246, v247
	ds_bpermute_b32 v249, v139, v248
	s_waitcnt lgkmcnt(0)
	v_add_f32_e32 v248, v248, v249
	ds_bpermute_b32 v249, v148, v248
	s_waitcnt lgkmcnt(0)
	v_add_f32_e32 v248, v248, v249
	s_mov_b64 s[12:13], exec
	s_mov_b64 exec, s[8:9]
	global_atomic_add_f32 v137, v248, s[24:25] offset:192
	s_mov_b64 exec, s[12:13]
	s_nop 1
	global_load_dword v129, v137, s[18:19] offset:576
	s_add_u32 s0, s26, 0x48000
	s_addc_u32 s1, s27, 0
	global_load_dwordx4 v[250:253], v136, s[0:1] nt
	global_load_dwordx4 v[132:135], v136, s[0:1] offset:256 nt
	s_waitcnt vmcnt(6)
	v_lshlrev_b32_e32 v238, 16, v178
	v_and_b32_e32 v239, 0xffff0000, v178
	v_lshlrev_b32_e32 v240, 16, v179
	v_and_b32_e32 v241, 0xffff0000, v179
	v_lshlrev_b32_e32 v242, 16, v180
	v_and_b32_e32 v243, 0xffff0000, v180
	v_lshlrev_b32_e32 v244, 16, v181
	v_and_b32_e32 v245, 0xffff0000, v181
	v_pk_mul_f32 v[238:239], v[162:163], v[238:239]
	v_pk_mul_f32 v[240:241], v[164:165], v[240:241]
	v_pk_mul_f32 v[242:243], v[166:167], v[242:243]
	v_pk_mul_f32 v[244:245], v[168:169], v[244:245]
	v_pk_fma_f32 v[60:61], v[128:129], v[238:239], v[60:61] op_sel_hi:[0,1,1]
	v_pk_fma_f32 v[62:63], v[128:129], v[240:241], v[62:63] op_sel_hi:[0,1,1]
	v_pk_fma_f32 v[56:57], v[128:129], v[242:243], v[56:57] op_sel_hi:[0,1,1]
	v_pk_fma_f32 v[58:59], v[128:129], v[244:245], v[58:59] op_sel_hi:[0,1,1]
	v_pk_mul_f32 v[246:247], v[60:61], v[60:61]
	v_pk_fma_f32 v[246:247], v[62:63], v[62:63], v[246:247]
	v_pk_fma_f32 v[246:247], v[56:57], v[56:57], v[246:247]
	v_pk_fma_f32 v[246:247], v[58:59], v[58:59], v[246:247]
	v_cvt_pk_bf16_f32 v238, v60, v61
	v_cvt_pk_bf16_f32 v239, v62, v63
	v_cvt_pk_bf16_f32 v240, v56, v57
	v_cvt_pk_bf16_f32 v241, v58, v59
	s_add_u32 s4, s22, 0x40000
	s_addc_u32 s5, s23, 0
	global_store_dwordx4 v136, v[238:241], s[4:5]
	s_nop 1
	v_lshlrev_b32_e32 v238, 16, v192
	v_and_b32_e32 v239, 0xffff0000, v192
	v_lshlrev_b32_e32 v240, 16, v193
	v_and_b32_e32 v241, 0xffff0000, v193
	v_lshlrev_b32_e32 v242, 16, v194
	v_and_b32_e32 v243, 0xffff0000, v194
	v_lshlrev_b32_e32 v244, 16, v195
	v_and_b32_e32 v245, 0xffff0000, v195
	v_pk_mul_f32 v[238:239], v[170:171], v[238:239]
	v_pk_mul_f32 v[240:241], v[172:173], v[240:241]
	v_pk_mul_f32 v[242:243], v[174:175], v[242:243]
	v_pk_mul_f32 v[244:245], v[176:177], v[244:245]
	v_pk_fma_f32 v[52:53], v[128:129], v[238:239], v[52:53] op_sel_hi:[0,1,1]
	v_pk_fma_f32 v[54:55], v[128:129], v[240:241], v[54:55] op_sel_hi:[0,1,1]
	v_pk_fma_f32 v[48:49], v[128:129], v[242:243], v[48:49] op_sel_hi:[0,1,1]
	v_pk_fma_f32 v[50:51], v[128:129], v[244:245], v[50:51] op_sel_hi:[0,1,1]
	v_pk_fma_f32 v[246:247], v[52:53], v[52:53], v[246:247]
	v_pk_fma_f32 v[246:247], v[54:55], v[54:55], v[246:247]
	v_pk_fma_f32 v[246:247], v[48:49], v[48:49], v[246:247]
	v_pk_fma_f32 v[246:247], v[50:51], v[50:51], v[246:247]
	v_cvt_pk_bf16_f32 v242, v52, v53
	v_cvt_pk_bf16_f32 v243, v54, v55
	v_cvt_pk_bf16_f32 v244, v48, v49
	v_cvt_pk_bf16_f32 v245, v50, v51
	global_store_dwordx4 v136, v[242:245], s[4:5] offset:256
	s_nop 1
	v_add_f32_e32 v248, v246, v247
	ds_bpermute_b32 v249, v139, v248
	s_waitcnt lgkmcnt(0)
; __device__ __forceinline__ unsigned cvt_pk_bf16(float lo, float hi) { unsigned r; asm volatile("v_cvt_pk_bf16_f32 %0, %1, %2" : "=v"(r) : "v"(lo), "v"(hi)); return r; }
; __device__ __forceinline__ float bf2f(unsigned b) { return __uint_as_float(b << 16); }
;     __device__ __forceinline__ void operator()(const f32x4 (&acc)[2][2][4][2], const Unit& u, int wr, int wc, int fr, int fq) const {
;     ...
;             for (int m = 0; m < 4; ++m) {
;                 const int row = u.pm * 256 + ai * 128 + wr * 64 + m * 16 + fr;
;                 const bool valid = row < MTOT;
;                 const float* xr = row < MP ? xp + (size_t)row * D : xs + (size_t)(valid ? row - MP : 0) * D;
;                 const float ri = recon ? RINV[row] : 0.f;
;                 float ss = 0.f;
; #pragma unroll
;                 for (int bj = 0; bj < 2; ++bj) {
;                     const int col0 = u.pn * 256 + bj * 128 + wc * 32 + fq * 8;
;                     f32x4 x0 = (f32x4){0.f, 0.f, 0.f, 0.f}, x1 = x0;
;                     if (recon) {
;                         const v4u xb = __builtin_nontemporal_load((const v4u*)(XN + (size_t)row * D + col0));
;                         x0 = (f32x4){bf2f(xb.x & 0xffffu), bf2f(xb.x >> 16), bf2f(xb.y & 0xffffu), bf2f(xb.y >> 16)} * gi[bj][0] * ri;
;                         x1 = (f32x4){bf2f(xb.z & 0xffffu), bf2f(xb.z >> 16), bf2f(xb.w & 0xffffu), bf2f(xb.w >> 16)} * gi[bj][1] * ri;
;                     } else if (valid) { x0 = *(const f32x4*)(xr + col0); x1 = *(const f32x4*)(xr + col0 + 4); }
;                     const f32x4 v0 = acc[ai][bj][m][0] + x0, v1 = acc[ai][bj][m][1] + x1;
;                     ss += (v0[0] * v0[0] + v0[1] * v0[1]) + (v0[2] * v0[2] + v0[3] * v0[3]) + (v1[0] * v1[0] + v1[1] * v1[1]) + (v1[2] * v1[2] + v1[3] * v1[3]);
;                     if (valid && row >= MP) { *(f32x4*)(out + (size_t)row * D + col0) = v0; *(f32x4*)(out + (size_t)row * D + col0 + 4) = v1; }
;                     v4u w; w.x = cvt_pk_bf16(v0[0], v0[1]); w.y = cvt_pk_bf16(v0[2], v0[3]); w.z = cvt_pk_bf16(v1[0], v1[1]); w.w = cvt_pk_bf16(v1[2], v1[3]);
;                     *(v4u*)(XMIDB + (size_t)row * D + col0) = w;
;                 }
;                 ss += __shfl_xor(ss, 16); ss += __shfl_xor(ss, 32);
;                 if (fq == 0) atomicAdd(SS + row, ss);
;                 if (m & 1) asm volatile("" ::: "memory");
	v_add_f32_e32 v248, v248, v249
	ds_bpermute_b32 v249, v148, v248
	s_waitcnt lgkmcnt(0)
	v_add_f32_e32 v248, v248, v249
	s_mov_b64 s[12:13], exec
	s_mov_b64 exec, s[8:9]
	global_atomic_add_f32 v137, v248, s[24:25] offset:512
	s_mov_b64 exec, s[12:13]
	s_nop 1
	global_load_dword v128, v137, s[18:19] offset:640
	s_add_u32 s0, s26, 0x50000
	s_addc_u32 s1, s27, 0
	global_load_dwordx4 v[178:181], v136, s[0:1] nt
	global_load_dwordx4 v[192:195], v136, s[0:1] offset:256 nt
	s_waitcnt vmcnt(6)
	v_lshlrev_b32_e32 v238, 16, v250
	v_and_b32_e32 v239, 0xffff0000, v250
	v_lshlrev_b32_e32 v240, 16, v251
	v_and_b32_e32 v241, 0xffff0000, v251
	v_lshlrev_b32_e32 v242, 16, v252
	v_and_b32_e32 v243, 0xffff0000, v252
	v_lshlrev_b32_e32 v244, 16, v253
	v_and_b32_e32 v245, 0xffff0000, v253
	v_pk_mul_f32 v[238:239], v[162:163], v[238:239]
	v_pk_mul_f32 v[240:241], v[164:165], v[240:241]
	v_pk_mul_f32 v[242:243], v[166:167], v[242:243]
	v_pk_mul_f32 v[244:245], v[168:169], v[244:245]
	v_pk_fma_f32 v[44:45], v[128:129], v[238:239], v[44:45] op_sel:[1,0,0] op_sel_hi:[1,1,1]
	v_pk_fma_f32 v[46:47], v[128:129], v[240:241], v[46:47] op_sel:[1,0,0] op_sel_hi:[1,1,1]
	v_pk_fma_f32 v[40:41], v[128:129], v[242:243], v[40:41] op_sel:[1,0,0] op_sel_hi:[1,1,1]
	v_pk_fma_f32 v[42:43], v[128:129], v[244:245], v[42:43] op_sel:[1,0,0] op_sel_hi:[1,1,1]
	v_pk_mul_f32 v[246:247], v[44:45], v[44:45]
	v_pk_fma_f32 v[246:247], v[46:47], v[46:47], v[246:247]
	v_pk_fma_f32 v[246:247], v[40:41], v[40:41], v[246:247]
	v_pk_fma_f32 v[246:247], v[42:43], v[42:43], v[246:247]
	v_cvt_pk_bf16_f32 v238, v44, v45
	v_cvt_pk_bf16_f32 v239, v46, v47
	v_cvt_pk_bf16_f32 v240, v40, v41
	v_cvt_pk_bf16_f32 v241, v42, v43
	s_add_u32 s4, s22, 0x48000
	s_addc_u32 s5, s23, 0
	global_store_dwordx4 v136, v[238:241], s[4:5]
	s_nop 1
	v_lshlrev_b32_e32 v238, 16, v132
	v_and_b32_e32 v239, 0xffff0000, v132
	v_lshlrev_b32_e32 v240, 16, v133
	v_and_b32_e32 v241, 0xffff0000, v133
	v_lshlrev_b32_e32 v242, 16, v134
	v_and_b32_e32 v243, 0xffff0000, v134
	v_lshlrev_b32_e32 v244, 16, v135
	v_and_b32_e32 v245, 0xffff0000, v135
	v_pk_mul_f32 v[238:239], v[170:171], v[238:239]
	v_pk_mul_f32 v[240:241], v[172:173], v[240:241]
	v_pk_mul_f32 v[242:243], v[174:175], v[242:243]
	v_pk_mul_f32 v[244:245], v[176:177], v[244:245]
	v_pk_fma_f32 v[36:37], v[128:129], v[238:239], v[36:37] op_sel:[1,0,0] op_sel_hi:[1,1,1]
	v_pk_fma_f32 v[38:39], v[128:129], v[240:241], v[38:39] op_sel:[1,0,0] op_sel_hi:[1,1,1]
	v_pk_fma_f32 v[32:33], v[128:129], v[242:243], v[32:33] op_sel:[1,0,0] op_sel_hi:[1,1,1]
	v_pk_fma_f32 v[34:35], v[128:129], v[244:245], v[34:35] op_sel:[1,0,0] op_sel_hi:[1,1,1]
	v_pk_fma_f32 v[246:247], v[36:37], v[36:37], v[246:247]
	v_pk_fma_f32 v[246:247], v[38:39], v[38:39], v[246:247]
	v_pk_fma_f32 v[246:247], v[32:33], v[32:33], v[246:247]
	v_pk_fma_f32 v[246:247], v[34:35], v[34:35], v[246:247]
	v_cvt_pk_bf16_f32 v242, v36, v37
	v_cvt_pk_bf16_f32 v243, v38, v39
	v_cvt_pk_bf16_f32 v244, v32, v33
	v_cvt_pk_bf16_f32 v245, v34, v35
	global_store_dwordx4 v136, v[242:245], s[4:5] offset:256
	s_nop 1
	v_add_f32_e32 v248, v246, v247
	ds_bpermute_b32 v249, v139, v248
	s_waitcnt lgkmcnt(0)
	v_add_f32_e32 v248, v248, v249
	ds_bpermute_b32 v249, v148, v248
	s_waitcnt lgkmcnt(0)
	v_add_f32_e32 v248, v248, v249
	s_mov_b64 s[12:13], exec
	s_mov_b64 exec, s[8:9]
	global_atomic_add_f32 v137, v248, s[24:25] offset:576
	s_mov_b64 exec, s[12:13]
	s_nop 1
	global_load_dword v129, v137, s[18:19] offset:704
	s_add_u32 s0, s26, 0x58000
	s_addc_u32 s1, s27, 0
	global_load_dwordx4 v[250:253], v136, s[0:1] nt
	global_load_dwordx4 v[132:135], v136, s[0:1] offset:256 nt
	s_waitcnt vmcnt(6)
; __device__ __forceinline__ unsigned cvt_pk_bf16(float lo, float hi) { unsigned r; asm volatile("v_cvt_pk_bf16_f32 %0, %1, %2" : "=v"(r) : "v"(lo), "v"(hi)); return r; }
; __device__ __forceinline__ float bf2f(unsigned b) { return __uint_as_float(b << 16); }
;     __device__ __forceinline__ void operator()(const f32x4 (&acc)[2][2][4][2], const Unit& u, int wr, int wc, int fr, int fq) const {
;     ...
;                 for (int bj = 0; bj < 2; ++bj) {
;                     const int col0 = u.pn * 256 + bj * 128 + wc * 32 + fq * 8;
;                     f32x4 x0 = (f32x4){0.f, 0.f, 0.f, 0.f}, x1 = x0;
;                     if (recon) {
;                         const v4u xb = __builtin_nontemporal_load((const v4u*)(XN + (size_t)row * D + col0));
;                         x0 = (f32x4){bf2f(xb.x & 0xffffu), bf2f(xb.x >> 16), bf2f(xb.y & 0xffffu), bf2f(xb.y >> 16)} * gi[bj][0] * ri;
;                         x1 = (f32x4){bf2f(xb.z & 0xffffu), bf2f(xb.z >> 16), bf2f(xb.w & 0xffffu), bf2f(xb.w >> 16)} * gi[bj][1] * ri;
;                     } else if (valid) { x0 = *(const f32x4*)(xr + col0); x1 = *(const f32x4*)(xr + col0 + 4); }
;                     const f32x4 v0 = acc[ai][bj][m][0] + x0, v1 = acc[ai][bj][m][1] + x1;
;                     ss += (v0[0] * v0[0] + v0[1] * v0[1]) + (v0[2] * v0[2] + v0[3] * v0[3]) + (v1[0] * v1[0] + v1[1] * v1[1]) + (v1[2] * v1[2] + v1[3] * v1[3]);
;                     if (valid && row >= MP) { *(f32x4*)(out + (size_t)row * D + col0) = v0; *(f32x4*)(out + (size_t)row * D + col0 + 4) = v1; }
;                     v4u w; w.x = cvt_pk_bf16(v0[0], v0[1]); w.y = cvt_pk_bf16(v0[2], v0[3]); w.z = cvt_pk_bf16(v1[0], v1[1]); w.w = cvt_pk_bf16(v1[2], v1[3]);
;                     *(v4u*)(XMIDB + (size_t)row * D + col0) = w;
;                 }
;                 ss += __shfl_xor(ss, 16); ss += __shfl_xor(ss, 32);
;                 if (fq == 0) atomicAdd(SS + row, ss);
	v_lshlrev_b32_e32 v238, 16, v178
	v_and_b32_e32 v239, 0xffff0000, v178
	v_lshlrev_b32_e32 v240, 16, v179
	v_and_b32_e32 v241, 0xffff0000, v179
	v_lshlrev_b32_e32 v242, 16, v180
	v_and_b32_e32 v243, 0xffff0000, v180
	v_lshlrev_b32_e32 v244, 16, v181
	v_and_b32_e32 v245, 0xffff0000, v181
	v_pk_mul_f32 v[238:239], v[162:163], v[238:239]
	v_pk_mul_f32 v[240:241], v[164:165], v[240:241]
	v_pk_mul_f32 v[242:243], v[166:167], v[242:243]
	v_pk_mul_f32 v[244:245], v[168:169], v[244:245]
	v_pk_fma_f32 v[28:29], v[128:129], v[238:239], v[28:29] op_sel_hi:[0,1,1]
	v_pk_fma_f32 v[30:31], v[128:129], v[240:241], v[30:31] op_sel_hi:[0,1,1]
	v_pk_fma_f32 v[24:25], v[128:129], v[242:243], v[24:25] op_sel_hi:[0,1,1]
	v_pk_fma_f32 v[26:27], v[128:129], v[244:245], v[26:27] op_sel_hi:[0,1,1]
	v_pk_mul_f32 v[246:247], v[28:29], v[28:29]
	v_pk_fma_f32 v[246:247], v[30:31], v[30:31], v[246:247]
	v_pk_fma_f32 v[246:247], v[24:25], v[24:25], v[246:247]
	v_pk_fma_f32 v[246:247], v[26:27], v[26:27], v[246:247]
	v_cvt_pk_bf16_f32 v238, v28, v29
	v_cvt_pk_bf16_f32 v239, v30, v31
	v_cvt_pk_bf16_f32 v240, v24, v25
	v_cvt_pk_bf16_f32 v241, v26, v27
	s_add_u32 s4, s22, 0x50000
	s_addc_u32 s5, s23, 0
	global_store_dwordx4 v136, v[238:241], s[4:5]
	s_nop 1
	v_lshlrev_b32_e32 v238, 16, v192
	v_and_b32_e32 v239, 0xffff0000, v192
	v_lshlrev_b32_e32 v240, 16, v193
	v_and_b32_e32 v241, 0xffff0000, v193
	v_lshlrev_b32_e32 v242, 16, v194
	v_and_b32_e32 v243, 0xffff0000, v194
	v_lshlrev_b32_e32 v244, 16, v195
	v_and_b32_e32 v245, 0xffff0000, v195
	v_pk_mul_f32 v[238:239], v[170:171], v[238:239]
	v_pk_mul_f32 v[240:241], v[172:173], v[240:241]
	v_pk_mul_f32 v[242:243], v[174:175], v[242:243]
	v_pk_mul_f32 v[244:245], v[176:177], v[244:245]
	v_pk_fma_f32 v[20:21], v[128:129], v[238:239], v[20:21] op_sel_hi:[0,1,1]
	v_pk_fma_f32 v[22:23], v[128:129], v[240:241], v[22:23] op_sel_hi:[0,1,1]
	v_pk_fma_f32 v[16:17], v[128:129], v[242:243], v[16:17] op_sel_hi:[0,1,1]
	v_pk_fma_f32 v[18:19], v[128:129], v[244:245], v[18:19] op_sel_hi:[0,1,1]
	v_pk_fma_f32 v[246:247], v[20:21], v[20:21], v[246:247]
	v_pk_fma_f32 v[246:247], v[22:23], v[22:23], v[246:247]
	v_pk_fma_f32 v[246:247], v[16:17], v[16:17], v[246:247]
	v_pk_fma_f32 v[246:247], v[18:19], v[18:19], v[246:247]
	v_cvt_pk_bf16_f32 v242, v20, v21
	v_cvt_pk_bf16_f32 v243, v22, v23
	v_cvt_pk_bf16_f32 v244, v16, v17
	v_cvt_pk_bf16_f32 v245, v18, v19
	global_store_dwordx4 v136, v[242:245], s[4:5] offset:256
	s_nop 1
	v_add_f32_e32 v248, v246, v247
	ds_bpermute_b32 v249, v139, v248
	s_waitcnt lgkmcnt(0)
	v_add_f32_e32 v248, v248, v249
	ds_bpermute_b32 v249, v148, v248
	s_waitcnt lgkmcnt(0)
	v_add_f32_e32 v248, v248, v249
	s_mov_b64 s[12:13], exec
	s_mov_b64 exec, s[8:9]
	global_atomic_add_f32 v137, v248, s[24:25] offset:640
	s_mov_b64 exec, s[12:13]
	s_nop 1
	s_waitcnt vmcnt(3)
	v_lshlrev_b32_e32 v238, 16, v250
	v_and_b32_e32 v239, 0xffff0000, v250
	v_lshlrev_b32_e32 v240, 16, v251
	v_and_b32_e32 v241, 0xffff0000, v251
	v_lshlrev_b32_e32 v242, 16, v252
	v_and_b32_e32 v243, 0xffff0000, v252
	v_lshlrev_b32_e32 v244, 16, v253
	v_and_b32_e32 v245, 0xffff0000, v253
	v_pk_mul_f32 v[238:239], v[162:163], v[238:239]
	v_pk_mul_f32 v[240:241], v[164:165], v[240:241]
	v_pk_mul_f32 v[242:243], v[166:167], v[242:243]
	v_pk_mul_f32 v[244:245], v[168:169], v[244:245]
	v_pk_fma_f32 v[12:13], v[128:129], v[238:239], v[12:13] op_sel:[1,0,0] op_sel_hi:[1,1,1]
	v_pk_fma_f32 v[14:15], v[128:129], v[240:241], v[14:15] op_sel:[1,0,0] op_sel_hi:[1,1,1]
	v_pk_fma_f32 v[8:9], v[128:129], v[242:243], v[8:9] op_sel:[1,0,0] op_sel_hi:[1,1,1]
	v_pk_fma_f32 v[10:11], v[128:129], v[244:245], v[10:11] op_sel:[1,0,0] op_sel_hi:[1,1,1]
	v_pk_mul_f32 v[246:247], v[12:13], v[12:13]
	v_pk_fma_f32 v[246:247], v[14:15], v[14:15], v[246:247]
	v_pk_fma_f32 v[246:247], v[8:9], v[8:9], v[246:247]
	v_pk_fma_f32 v[246:247], v[10:11], v[10:11], v[246:247]
	v_cvt_pk_bf16_f32 v238, v12, v13
	v_cvt_pk_bf16_f32 v239, v14, v15
	v_cvt_pk_bf16_f32 v240, v8, v9
	v_cvt_pk_bf16_f32 v241, v10, v11
	s_add_u32 s4, s22, 0x58000
	s_addc_u32 s5, s23, 0
	global_store_dwordx4 v136, v[238:241], s[4:5]
	s_nop 1
	v_lshlrev_b32_e32 v238, 16, v132
	v_and_b32_e32 v239, 0xffff0000, v132
	v_lshlrev_b32_e32 v240, 16, v133
	v_and_b32_e32 v241, 0xffff0000, v133
	v_lshlrev_b32_e32 v242, 16, v134
	v_and_b32_e32 v243, 0xffff0000, v134
	v_lshlrev_b32_e32 v244, 16, v135
	v_and_b32_e32 v245, 0xffff0000, v135
	v_pk_mul_f32 v[238:239], v[170:171], v[238:239]
	v_pk_mul_f32 v[240:241], v[172:173], v[240:241]
	v_pk_mul_f32 v[242:243], v[174:175], v[242:243]
	v_pk_mul_f32 v[244:245], v[176:177], v[244:245]
	v_pk_fma_f32 v[4:5], v[128:129], v[238:239], v[4:5] op_sel:[1,0,0] op_sel_hi:[1,1,1]
	v_pk_fma_f32 v[6:7], v[128:129], v[240:241], v[6:7] op_sel:[1,0,0] op_sel_hi:[1,1,1]
	v_pk_fma_f32 v[0:1], v[128:129], v[242:243], v[0:1] op_sel:[1,0,0] op_sel_hi:[1,1,1]
	v_pk_fma_f32 v[2:3], v[128:129], v[244:245], v[2:3] op_sel:[1,0,0] op_sel_hi:[1,1,1]
	v_pk_fma_f32 v[246:247], v[4:5], v[4:5], v[246:247]
	v_pk_fma_f32 v[246:247], v[6:7], v[6:7], v[246:247]
	v_pk_fma_f32 v[246:247], v[0:1], v[0:1], v[246:247]
	v_pk_fma_f32 v[246:247], v[2:3], v[2:3], v[246:247]
	v_cvt_pk_bf16_f32 v242, v4, v5
	v_cvt_pk_bf16_f32 v243, v6, v7
	v_cvt_pk_bf16_f32 v244, v0, v1
	v_cvt_pk_bf16_f32 v245, v2, v3
	global_store_dwordx4 v136, v[242:245], s[4:5] offset:256
	s_nop 1
	v_add_f32_e32 v248, v246, v247
	ds_bpermute_b32 v249, v139, v248
	s_waitcnt lgkmcnt(0)
	v_add_f32_e32 v248, v248, v249
	ds_bpermute_b32 v249, v148, v248
	s_waitcnt lgkmcnt(0)
	v_add_f32_e32 v248, v248, v249
	s_mov_b64 s[12:13], exec
	s_mov_b64 exec, s[8:9]
	global_atomic_add_f32 v137, v248, s[24:25] offset:704
	s_mov_b64 exec, s[12:13]
	s_nop 1
	s_mov_b64 s[10:11], 0
	s_branch .LBB0_590

;     __device__ __forceinline__ void operator()(const f32x4 (&acc)[2][2][4][2], const Unit& u, int wr, int wc, int fr, int fq) const {
;         const int lane = threadIdx.x & 63;
;         if (!halo_ok) {
;             if (threadIdx.x < 64) { unsigned sp = 0;
;                 while ((unsigned)__builtin_amdgcn_readfirstlane(__hip_atomic_load(halo_ctr, __ATOMIC_RELAXED, __HIP_MEMORY_SCOPE_AGENT)) < halo_need) { __builtin_amdgcn_s_sleep(8); if (++sp > (1u << 20)) break; }
;                 __builtin_amdgcn_fence(__ATOMIC_ACQUIRE, "agent"); asm volatile("s_waitcnt vmcnt(0)" ::: "memory"); }
;             asm volatile("" ::: "memory"); __builtin_amdgcn_s_barrier(); asm volatile("" ::: "memory");
;             halo_ok = 1;
;         }
;         const bool samp = (u.pm == 64);
.LBB0_884:
	s_cmp_lg_u32 s88, 64
	s_cbranch_scc1 .Lfe_begin
	s_andn2_b64 vcc, exec, s[86:87]
	s_cbranch_vccnz .LBB0_892
	s_and_saveexec_b64 s[14:15], s[8:9]
	s_cbranch_execz .LBB0_891
	s_mov_b32 s13, 0x100001
	s_branch .LBB0_888

; __device__ __forceinline__ unsigned cvt_pk_bf16(float lo, float hi) { unsigned r; asm volatile("v_cvt_pk_bf16_f32 %0, %1, %2" : "=v"(r) : "v"(lo), "v"(hi)); return r; }
;     __device__ __forceinline__ void operator()(const f32x4 (&acc)[2][2][4][2], const Unit& u, int wr, int wc, int fr, int fq) const {
;     ...
; #pragma unroll
;                     for (int m = 0; m < 4; ++m) {
;                         f32x4 cv;
;                         if (!samp) {
;                             const f32x4 prev = m ? v[m - 1] : hv;
; #pragma unroll
;                             for (int e = 0; e < 4; ++e) {
;                                 const int vi = __float_as_int(v[m][e]), pi = __float_as_int(prev[e]);
;                                 const int o1 = __builtin_amdgcn_mov_dpp(pi, 0x121, 0xf, 0xf, false);
;                                 const int o2 = __builtin_amdgcn_mov_dpp(pi, 0x122, 0xf, 0xf, false);
;                                 const float p1 = __int_as_float(__builtin_amdgcn_update_dpp(o1, vi, 0x111, 0xf, 0xf, false));
;                                 const float p2 = __int_as_float(__builtin_amdgcn_update_dpp(o2, vi, 0x112, 0xf, 0xf, false));
;                                 cv[e] = cb[e] + cw0[e] * p2 + cw1[e] * p1 + cw2[e] * v[m][e];
;                             }
;                         } else {
;                             const int ns = rowb + 16 * m + fr - MP;
;                             f32x4 s0 = (f32x4){0.f, 0.f, 0.f, 0.f}, s1 = s0;
;                             if (ns < NS) {
;                                 s0 = *(const f32x4*)(state + (size_t)(ns * 2 + 0) * FF2 + oc); s1 = *(const f32x4*)(state + (size_t)(ns * 2 + 1) * FF2 + oc);
;                                 *(f32x4*)(ncs + (size_t)(ns * 2 + 0) * FF2 + oc) = s1; *(f32x4*)(ncs + (size_t)(ns * 2 + 1) * FF2 + oc) = v[m];
;                             }
;                             cv = cb + cw0 * s0 + cw1 * s1 + cw2 * v[m];
;                         }
;                         if (bj == 0) cg[m] = gelu4(cv);
;                         else {
;                             const f32x4 r = cg[m] * cv;
;                             v2u w; w.x = cvt_pk_bf16(r[0], r[1]); w.y = cvt_pk_bf16(r[2], r[3]);
;                             *(v2u*)(ACT + (size_t)(rowb + 16 * m + fr) * FF + 128 * u.pn + 32 * wc + 8 * fq + 4 * n) = w;
;                         }
.LBB0_926:
	v_mov_b32_e32 v148, v212
	v_mov_b32_e32 v149, v212
	v_pk_mul_f32 v[106:107], v[106:107], v[148:149]
	v_and_b32_e32 v149, 0x7fffffff, v141
	v_and_b32_e32 v148, 0x7fffffff, v140
	v_pk_fma_f32 v[148:149], v[148:149], s[38:39], 1.0 op_sel_hi:[1,0,0]
	v_mov_b64_e32 v[150:151], s[64:65]
	v_rcp_f32_e32 v148, v148
	v_rcp_f32_e32 v149, v149
	v_pk_mul_f32 v[222:223], v[140:141], v[140:141]
	v_cmp_gt_f32_e32 vcc, 0, v140
	v_pk_mul_f32 v[222:223], v[222:223], s[72:73] op_sel_hi:[1,0]
	v_pk_fma_f32 v[220:221], v[148:149], s[62:63], v[150:151] op_sel_hi:[1,0,0]
	v_exp_f32_e32 v222, v222
	v_pk_fma_f32 v[220:221], v[148:149], v[220:221], s[66:67] op_sel_hi:[1,1,0]
	v_exp_f32_e32 v223, v223
	v_pk_fma_f32 v[220:221], v[148:149], v[220:221], s[68:69] op_sel_hi:[1,1,0]
	s_ashr_i32 s87, s86, 31
	v_pk_fma_f32 v[220:221], v[148:149], v[220:221], s[70:71] op_sel_hi:[1,1,0]
	v_pk_mul_f32 v[104:105], v[104:105], v[212:213]
	v_pk_mul_f32 v[148:149], v[148:149], v[220:221]
	v_pk_mul_f32 v[220:221], v[142:143], v[142:143]
	v_pk_mul_f32 v[148:149], v[222:223], v[148:149]
	s_nop 0
	v_pk_mul_f32 v[222:223], v[140:141], v[148:149]
	v_pk_fma_f32 v[148:149], v[140:141], v[148:149], v[140:141] neg_lo:[1,0,0] neg_hi:[1,0,0]
	s_nop 0
	v_cndmask_b32_e32 v140, v148, v222, vcc
	v_cmp_gt_f32_e32 vcc, 0, v141
	v_and_b32_e32 v148, 0x7fffffff, v142
	s_nop 0
	v_cndmask_b32_e32 v141, v149, v223, vcc
	v_and_b32_e32 v149, 0x7fffffff, v143
	v_pk_fma_f32 v[148:149], v[148:149], s[38:39], 1.0 op_sel_hi:[1,0,0]
	v_cmp_gt_f32_e32 vcc, 0, v142
	v_rcp_f32_e32 v148, v148
	v_rcp_f32_e32 v149, v149
	v_pk_mul_f32 v[140:141], v[140:141], v[144:145]
	v_pk_fma_f32 v[150:151], v[148:149], s[62:63], v[150:151] op_sel_hi:[1,0,0]
	s_nop 0
	v_pk_fma_f32 v[150:151], v[148:149], v[150:151], s[66:67] op_sel_hi:[1,1,0]
	v_cvt_pk_bf16_f32 v140, v140, v141
	s_nop 0
	v_pk_fma_f32 v[150:151], v[148:149], v[150:151], s[68:69] op_sel_hi:[1,1,0]
	s_nop 0
	v_pk_fma_f32 v[150:151], v[148:149], v[150:151], s[70:71] op_sel_hi:[1,1,0]
	s_nop 0
	v_pk_mul_f32 v[148:149], v[148:149], v[150:151]
	v_pk_mul_f32 v[150:151], v[220:221], s[72:73] op_sel_hi:[1,0]
	s_nop 0
	v_exp_f32_e32 v150, v150
	v_exp_f32_e32 v151, v151
	s_nop 0
	v_pk_mul_f32 v[148:149], v[150:151], v[148:149]
	s_nop 0
	v_pk_mul_f32 v[150:151], v[142:143], v[148:149]
	v_pk_fma_f32 v[148:149], v[142:143], v[148:149], v[142:143] neg_lo:[1,0,0] neg_hi:[1,0,0]
	s_nop 0
	v_cndmask_b32_e32 v142, v148, v150, vcc
	v_cmp_gt_f32_e32 vcc, 0, v143
	s_nop 1
	v_cndmask_b32_e32 v143, v149, v151, vcc
	v_pk_mul_f32 v[142:143], v[142:143], v[146:147]
	s_and_b64 vcc, exec, s[12:13]
	v_cvt_pk_bf16_f32 v141, v142, v143
	v_mov_b64_e32 v[142:143], s[46:47]
	v_mad_i64_i32 v[142:143], s[14:15], v202, s34, v[142:143]
	v_lshl_add_u64 v[142:143], s[86:87], 1, v[142:143]
	v_lshl_add_u64 v[142:143], v[142:143], 0, s[24:25]
	v_lshl_add_u64 v[144:145], v[142:143], 0, v[168:169]
	s_mov_b64 s[14:15], -1
	global_store_dwordx2 v[144:145], v[140:141], off sc1
	s_cbranch_vccnz .LBB0_928
	v_mov_b32_dpp v149, v111 row_ror:1 row_mask:0xf bank_mask:0xf
	v_mov_b32_dpp v140, v108 row_ror:1 row_mask:0xf bank_mask:0xf
	v_mov_b32_dpp v108, v108 row_ror:2 row_mask:0xf bank_mask:0xf
	v_mov_b32_dpp v141, v109 row_ror:1 row_mask:0xf bank_mask:0xf
	v_mov_b32_dpp v109, v109 row_ror:2 row_mask:0xf bank_mask:0xf
	v_mov_b32_dpp v142, v110 row_ror:1 row_mask:0xf bank_mask:0xf
	v_mov_b32_dpp v110, v110 row_ror:2 row_mask:0xf bank_mask:0xf
	v_mov_b32_dpp v111, v111 row_ror:2 row_mask:0xf bank_mask:0xf
	v_mov_b32_dpp v149, v107 row_shr:1 row_mask:0xf bank_mask:0xf
	v_mov_b32_e32 v150, v107
	s_waitcnt vmcnt(3)
	v_mov_b32_e32 v151, v127
	s_waitcnt vmcnt(2)
	v_mov_b32_e32 v148, v123
	v_mov_b32_dpp v108, v104 row_shr:2 row_mask:0xf bank_mask:0xf
	v_mov_b32_dpp v109, v105 row_shr:2 row_mask:0xf bank_mask:0xf
	v_mov_b32_dpp v142, v106 row_shr:1 row_mask:0xf bank_mask:0xf
	v_mov_b32_dpp v110, v106 row_shr:2 row_mask:0xf bank_mask:0xf
	v_mov_b32_dpp v111, v107 row_shr:2 row_mask:0xf bank_mask:0xf
	v_pk_mul_f32 v[148:149], v[150:151], v[148:149]
	v_mov_b32_dpp v140, v104 row_shr:1 row_mask:0xf bank_mask:0xf
	v_mov_b32_dpp v141, v105 row_shr:1 row_mask:0xf bank_mask:0xf
	v_mul_f32_e32 v142, v126, v142
	v_mov_b32_e32 v143, v149
	s_waitcnt vmcnt(1)
	v_pk_fma_f32 v[108:109], v[128:129], v[108:109], v[132:133]
	v_pk_fma_f32 v[110:111], v[130:131], v[110:111], v[134:135]
	v_mul_f32_e32 v146, v106, v122
	v_mov_b32_e32 v147, v148
	v_pk_add_f32 v[110:111], v[142:143], v[110:111]
	v_pk_fma_f32 v[108:109], v[124:125], v[140:141], v[108:109]
	v_pk_add_f32 v[142:143], v[146:147], v[110:111]
	v_pk_fma_f32 v[140:141], v[104:105], v[120:121], v[108:109]
	s_mov_b64 s[14:15], 0

; __device__ __forceinline__ unsigned cvt_pk_bf16(float lo, float hi) { unsigned r; asm volatile("v_cvt_pk_bf16_f32 %0, %1, %2" : "=v"(r) : "v"(lo), "v"(hi)); return r; }
;     __device__ __forceinline__ void operator()(const f32x4 (&acc)[2][2][4][2], const Unit& u, int wr, int wc, int fr, int fq) const {
;     ...
; #pragma unroll
;                     for (int m = 0; m < 4; ++m) {
;                         f32x4 cv;
;                         if (!samp) {
;                             const f32x4 prev = m ? v[m - 1] : hv;
; #pragma unroll
;                             for (int e = 0; e < 4; ++e) {
;                                 const int vi = __float_as_int(v[m][e]), pi = __float_as_int(prev[e]);
;                                 const int o1 = __builtin_amdgcn_mov_dpp(pi, 0x121, 0xf, 0xf, false);
;                                 const int o2 = __builtin_amdgcn_mov_dpp(pi, 0x122, 0xf, 0xf, false);
;                                 const float p1 = __int_as_float(__builtin_amdgcn_update_dpp(o1, vi, 0x111, 0xf, 0xf, false));
;                                 const float p2 = __int_as_float(__builtin_amdgcn_update_dpp(o2, vi, 0x112, 0xf, 0xf, false));
;                                 cv[e] = cb[e] + cw0[e] * p2 + cw1[e] * p1 + cw2[e] * v[m][e];
;                             }
;                         } else {
;                             const int ns = rowb + 16 * m + fr - MP;
;                             f32x4 s0 = (f32x4){0.f, 0.f, 0.f, 0.f}, s1 = s0;
;                             if (ns < NS) {
;                                 s0 = *(const f32x4*)(state + (size_t)(ns * 2 + 0) * FF2 + oc); s1 = *(const f32x4*)(state + (size_t)(ns * 2 + 1) * FF2 + oc);
;                                 *(f32x4*)(ncs + (size_t)(ns * 2 + 0) * FF2 + oc) = s1; *(f32x4*)(ncs + (size_t)(ns * 2 + 1) * FF2 + oc) = v[m];
;                             }
;                             cv = cb + cw0 * s0 + cw1 * s1 + cw2 * v[m];
;                         }
;                         if (bj == 0) cg[m] = gelu4(cv);
;                         else {
;                             const f32x4 r = cg[m] * cv;
;                             v2u w; w.x = cvt_pk_bf16(r[0], r[1]); w.y = cvt_pk_bf16(r[2], r[3]);
;                             *(v2u*)(ACT + (size_t)(rowb + 16 * m + fr) * FF + 128 * u.pn + 32 * wc + 8 * fq + 4 * n) = w;
;                         }
.LBB0_932:
	v_mov_b32_e32 v108, v210
	v_mov_b32_e32 v109, v210
	v_pk_mul_f32 v[102:103], v[102:103], v[108:109]
	v_and_b32_e32 v109, 0x7fffffff, v137
	v_and_b32_e32 v108, 0x7fffffff, v136
	v_pk_fma_f32 v[108:109], v[108:109], s[38:39], 1.0 op_sel_hi:[1,0,0]
	v_mov_b64_e32 v[110:111], s[64:65]
	v_rcp_f32_e32 v108, v108
	v_rcp_f32_e32 v109, v109
	v_pk_mul_f32 v[148:149], v[136:137], v[136:137]
	v_cmp_gt_f32_e32 vcc, 0, v136
	v_pk_mul_f32 v[148:149], v[148:149], s[72:73] op_sel_hi:[1,0]
	v_pk_fma_f32 v[146:147], v[108:109], s[62:63], v[110:111] op_sel_hi:[1,0,0]
	v_exp_f32_e32 v148, v148
	v_pk_fma_f32 v[146:147], v[108:109], v[146:147], s[66:67] op_sel_hi:[1,1,0]
	v_exp_f32_e32 v149, v149
	v_pk_fma_f32 v[146:147], v[108:109], v[146:147], s[68:69] op_sel_hi:[1,1,0]
	v_pk_mul_f32 v[100:101], v[100:101], v[210:211]
	v_pk_fma_f32 v[146:147], v[108:109], v[146:147], s[70:71] op_sel_hi:[1,1,0]
	s_nop 0
	v_pk_mul_f32 v[108:109], v[108:109], v[146:147]
	v_pk_mul_f32 v[146:147], v[138:139], v[138:139]
	v_pk_mul_f32 v[108:109], v[148:149], v[108:109]
	s_nop 0
	v_pk_mul_f32 v[148:149], v[136:137], v[108:109]
	v_pk_fma_f32 v[108:109], v[136:137], v[108:109], v[136:137] neg_lo:[1,0,0] neg_hi:[1,0,0]
	v_and_b32_e32 v136, 0x7fffffff, v138
	v_cndmask_b32_e32 v108, v108, v148, vcc
	v_cmp_gt_f32_e32 vcc, 0, v137
	v_and_b32_e32 v137, 0x7fffffff, v139
	v_pk_fma_f32 v[136:137], v[136:137], s[38:39], 1.0 op_sel_hi:[1,0,0]
	v_cndmask_b32_e32 v109, v109, v149, vcc
	v_rcp_f32_e32 v136, v136
	v_rcp_f32_e32 v137, v137
	v_cmp_gt_f32_e32 vcc, 0, v138
	v_pk_mul_f32 v[108:109], v[108:109], v[140:141]
	v_pk_fma_f32 v[110:111], v[136:137], s[62:63], v[110:111] op_sel_hi:[1,0,0]
	s_nop 0
	v_pk_fma_f32 v[110:111], v[136:137], v[110:111], s[66:67] op_sel_hi:[1,1,0]
	v_cvt_pk_bf16_f32 v108, v108, v109
	s_nop 0
	v_pk_fma_f32 v[110:111], v[136:137], v[110:111], s[68:69] op_sel_hi:[1,1,0]
	s_nop 0
	v_pk_fma_f32 v[110:111], v[136:137], v[110:111], s[70:71] op_sel_hi:[1,1,0]
	s_nop 0
	v_pk_mul_f32 v[110:111], v[136:137], v[110:111]
	v_pk_mul_f32 v[136:137], v[146:147], s[72:73] op_sel_hi:[1,0]
	s_nop 0
	v_exp_f32_e32 v136, v136
	v_exp_f32_e32 v137, v137
	s_nop 0
	v_pk_mul_f32 v[110:111], v[136:137], v[110:111]
	s_nop 0
	v_pk_mul_f32 v[136:137], v[138:139], v[110:111]
	v_pk_fma_f32 v[110:111], v[138:139], v[110:111], v[138:139] neg_lo:[1,0,0] neg_hi:[1,0,0]
	s_nop 0
	v_cndmask_b32_e32 v110, v110, v136, vcc
	v_cmp_gt_f32_e32 vcc, 0, v139
	s_nop 1
	v_cndmask_b32_e32 v111, v111, v137, vcc
	v_pk_mul_f32 v[110:111], v[110:111], v[142:143]
	s_and_b64 vcc, exec, s[12:13]
	v_cvt_pk_bf16_f32 v109, v110, v111
	v_mov_b64_e32 v[110:111], s[46:47]
	v_mad_i64_i32 v[110:111], s[14:15], v200, s34, v[110:111]
	v_lshl_add_u64 v[110:111], s[86:87], 1, v[110:111]
	v_lshl_add_u64 v[110:111], v[110:111], 0, s[24:25]
	v_lshl_add_u64 v[138:139], v[110:111], 0, v[168:169]
	s_mov_b64 s[14:15], -1
	global_store_dwordx2 v[138:139], v[108:109], off sc1
	s_cbranch_vccnz .LBB0_934
	v_mov_b32_dpp v141, v107 row_ror:1 row_mask:0xf bank_mask:0xf
	v_mov_b32_dpp v108, v104 row_ror:1 row_mask:0xf bank_mask:0xf
	v_mov_b32_dpp v104, v104 row_ror:2 row_mask:0xf bank_mask:0xf
	v_mov_b32_dpp v109, v105 row_ror:1 row_mask:0xf bank_mask:0xf
	v_mov_b32_dpp v105, v105 row_ror:2 row_mask:0xf bank_mask:0xf
	v_mov_b32_dpp v110, v106 row_ror:1 row_mask:0xf bank_mask:0xf
	v_mov_b32_dpp v106, v106 row_ror:2 row_mask:0xf bank_mask:0xf
	v_mov_b32_dpp v107, v107 row_ror:2 row_mask:0xf bank_mask:0xf
	v_mov_b32_dpp v141, v103 row_shr:1 row_mask:0xf bank_mask:0xf
	v_mov_b32_e32 v142, v103
	s_waitcnt vmcnt(4)
	v_mov_b32_e32 v143, v127
	s_waitcnt vmcnt(3)
	v_mov_b32_e32 v140, v123
	v_mov_b32_dpp v104, v100 row_shr:2 row_mask:0xf bank_mask:0xf
	v_mov_b32_dpp v105, v101 row_shr:2 row_mask:0xf bank_mask:0xf
	v_mov_b32_dpp v110, v102 row_shr:1 row_mask:0xf bank_mask:0xf
	v_mov_b32_dpp v106, v102 row_shr:2 row_mask:0xf bank_mask:0xf
	v_mov_b32_dpp v107, v103 row_shr:2 row_mask:0xf bank_mask:0xf
	v_pk_mul_f32 v[140:141], v[142:143], v[140:141]
	v_mov_b32_dpp v108, v100 row_shr:1 row_mask:0xf bank_mask:0xf
	v_mov_b32_dpp v109, v101 row_shr:1 row_mask:0xf bank_mask:0xf
	v_mul_f32_e32 v110, v126, v110
	v_mov_b32_e32 v111, v141
	s_waitcnt vmcnt(2)
	v_pk_fma_f32 v[104:105], v[128:129], v[104:105], v[132:133]
	v_pk_fma_f32 v[106:107], v[130:131], v[106:107], v[134:135]
	v_mul_f32_e32 v136, v102, v122
	v_mov_b32_e32 v137, v140
	v_pk_add_f32 v[106:107], v[110:111], v[106:107]
	v_pk_fma_f32 v[104:105], v[124:125], v[108:109], v[104:105]
	v_pk_add_f32 v[110:111], v[136:137], v[106:107]
	v_pk_fma_f32 v[108:109], v[100:101], v[120:121], v[104:105]
	s_mov_b64 s[14:15], 0

; __device__ __forceinline__ unsigned cvt_pk_bf16(float lo, float hi) { unsigned r; asm volatile("v_cvt_pk_bf16_f32 %0, %1, %2" : "=v"(r) : "v"(lo), "v"(hi)); return r; }
;     __device__ __forceinline__ void operator()(const f32x4 (&acc)[2][2][4][2], const Unit& u, int wr, int wc, int fr, int fq) const {
;     ...
; #pragma unroll
;                     for (int m = 0; m < 4; ++m) {
;                         f32x4 cv;
;                         if (!samp) {
;                             const f32x4 prev = m ? v[m - 1] : hv;
; #pragma unroll
;                             for (int e = 0; e < 4; ++e) {
;                                 const int vi = __float_as_int(v[m][e]), pi = __float_as_int(prev[e]);
;                                 const int o1 = __builtin_amdgcn_mov_dpp(pi, 0x121, 0xf, 0xf, false);
;                                 const int o2 = __builtin_amdgcn_mov_dpp(pi, 0x122, 0xf, 0xf, false);
;                                 const float p1 = __int_as_float(__builtin_amdgcn_update_dpp(o1, vi, 0x111, 0xf, 0xf, false));
;                                 const float p2 = __int_as_float(__builtin_amdgcn_update_dpp(o2, vi, 0x112, 0xf, 0xf, false));
;                                 cv[e] = cb[e] + cw0[e] * p2 + cw1[e] * p1 + cw2[e] * v[m][e];
;                             }
;                         } else {
;                             const int ns = rowb + 16 * m + fr - MP;
;                             f32x4 s0 = (f32x4){0.f, 0.f, 0.f, 0.f}, s1 = s0;
;                             if (ns < NS) {
;                                 s0 = *(const f32x4*)(state + (size_t)(ns * 2 + 0) * FF2 + oc); s1 = *(const f32x4*)(state + (size_t)(ns * 2 + 1) * FF2 + oc);
;                                 *(f32x4*)(ncs + (size_t)(ns * 2 + 0) * FF2 + oc) = s1; *(f32x4*)(ncs + (size_t)(ns * 2 + 1) * FF2 + oc) = v[m];
;                             }
;                             cv = cb + cw0 * s0 + cw1 * s1 + cw2 * v[m];
;                         }
;                         if (bj == 0) cg[m] = gelu4(cv);
;                         else {
;                             const f32x4 r = cg[m] * cv;
;                             v2u w; w.x = cvt_pk_bf16(r[0], r[1]); w.y = cvt_pk_bf16(r[2], r[3]);
;                             *(v2u*)(ACT + (size_t)(rowb + 16 * m + fr) * FF + 128 * u.pn + 32 * wc + 8 * fq + 4 * n) = w;
;                         }
.LBB0_938:
	v_mov_b32_e32 v104, v204
	v_mov_b32_e32 v105, v204
	v_pk_mul_f32 v[98:99], v[98:99], v[104:105]
	v_and_b32_e32 v105, 0x7fffffff, v117
	v_and_b32_e32 v104, 0x7fffffff, v116
	v_pk_fma_f32 v[104:105], v[104:105], s[38:39], 1.0 op_sel_hi:[1,0,0]
	v_mov_b64_e32 v[106:107], s[64:65]
	v_rcp_f32_e32 v104, v104
	v_rcp_f32_e32 v105, v105
	v_pk_mul_f32 v[140:141], v[116:117], v[116:117]
	v_cmp_gt_f32_e32 vcc, 0, v116
	v_pk_mul_f32 v[140:141], v[140:141], s[72:73] op_sel_hi:[1,0]
	v_pk_fma_f32 v[136:137], v[104:105], s[62:63], v[106:107] op_sel_hi:[1,0,0]
	v_exp_f32_e32 v140, v140
	v_pk_fma_f32 v[136:137], v[104:105], v[136:137], s[66:67] op_sel_hi:[1,1,0]
	v_exp_f32_e32 v141, v141
	v_pk_fma_f32 v[136:137], v[104:105], v[136:137], s[68:69] op_sel_hi:[1,1,0]
	v_pk_mul_f32 v[96:97], v[96:97], v[204:205]
	v_pk_fma_f32 v[136:137], v[104:105], v[136:137], s[70:71] op_sel_hi:[1,1,0]
	s_nop 0
	v_pk_mul_f32 v[104:105], v[104:105], v[136:137]
	v_pk_mul_f32 v[136:137], v[118:119], v[118:119]
	v_pk_mul_f32 v[104:105], v[140:141], v[104:105]
	s_nop 0
	v_pk_mul_f32 v[140:141], v[116:117], v[104:105]
	v_pk_fma_f32 v[104:105], v[116:117], v[104:105], v[116:117] neg_lo:[1,0,0] neg_hi:[1,0,0]
	v_and_b32_e32 v116, 0x7fffffff, v118
	v_cndmask_b32_e32 v104, v104, v140, vcc
	v_cmp_gt_f32_e32 vcc, 0, v117
	v_and_b32_e32 v117, 0x7fffffff, v119
	v_pk_fma_f32 v[116:117], v[116:117], s[38:39], 1.0 op_sel_hi:[1,0,0]
	v_cndmask_b32_e32 v105, v105, v141, vcc
	v_rcp_f32_e32 v116, v116
	v_rcp_f32_e32 v117, v117
	v_cmp_gt_f32_e32 vcc, 0, v118
	v_pk_mul_f32 v[104:105], v[104:105], v[108:109]
	v_pk_fma_f32 v[106:107], v[116:117], s[62:63], v[106:107] op_sel_hi:[1,0,0]
	s_nop 0
	v_pk_fma_f32 v[106:107], v[116:117], v[106:107], s[66:67] op_sel_hi:[1,1,0]
	v_cvt_pk_bf16_f32 v104, v104, v105
	s_nop 0
	v_pk_fma_f32 v[106:107], v[116:117], v[106:107], s[68:69] op_sel_hi:[1,1,0]
	s_nop 0
	v_pk_fma_f32 v[106:107], v[116:117], v[106:107], s[70:71] op_sel_hi:[1,1,0]
	s_nop 0
	v_pk_mul_f32 v[106:107], v[116:117], v[106:107]
	v_pk_mul_f32 v[116:117], v[136:137], s[72:73] op_sel_hi:[1,0]
	s_nop 0
	v_exp_f32_e32 v116, v116
	v_exp_f32_e32 v117, v117
	s_nop 0
	v_pk_mul_f32 v[106:107], v[116:117], v[106:107]
	s_nop 0
	v_pk_mul_f32 v[116:117], v[118:119], v[106:107]
	v_pk_fma_f32 v[106:107], v[118:119], v[106:107], v[118:119] neg_lo:[1,0,0] neg_hi:[1,0,0]
	s_nop 0
	v_cndmask_b32_e32 v106, v106, v116, vcc
	v_cmp_gt_f32_e32 vcc, 0, v119
	s_nop 1
	v_cndmask_b32_e32 v107, v107, v117, vcc
	v_pk_mul_f32 v[106:107], v[106:107], v[110:111]
	s_and_b64 vcc, exec, s[12:13]
	v_cvt_pk_bf16_f32 v105, v106, v107
	v_mov_b64_e32 v[106:107], s[46:47]
	v_mad_i64_i32 v[106:107], s[14:15], v198, s34, v[106:107]
	v_lshl_add_u64 v[106:107], s[86:87], 1, v[106:107]
	v_lshl_add_u64 v[106:107], v[106:107], 0, s[24:25]
	v_lshl_add_u64 v[140:141], v[106:107], 0, v[168:169]
	s_mov_b64 s[14:15], -1
	global_store_dwordx2 v[140:141], v[104:105], off sc1
	s_cbranch_vccnz .LBB0_940
	v_mov_b32_dpp v111, v103 row_ror:1 row_mask:0xf bank_mask:0xf
	v_mov_b32_dpp v104, v100 row_ror:1 row_mask:0xf bank_mask:0xf
	v_mov_b32_dpp v100, v100 row_ror:2 row_mask:0xf bank_mask:0xf
	v_mov_b32_dpp v105, v101 row_ror:1 row_mask:0xf bank_mask:0xf
	v_mov_b32_dpp v101, v101 row_ror:2 row_mask:0xf bank_mask:0xf
	v_mov_b32_dpp v106, v102 row_ror:1 row_mask:0xf bank_mask:0xf
	v_mov_b32_dpp v102, v102 row_ror:2 row_mask:0xf bank_mask:0xf
	v_mov_b32_dpp v103, v103 row_ror:2 row_mask:0xf bank_mask:0xf
	v_mov_b32_dpp v111, v99 row_shr:1 row_mask:0xf bank_mask:0xf
	v_mov_b32_e32 v116, v99
	s_waitcnt vmcnt(5)
	v_mov_b32_e32 v117, v127
	s_waitcnt vmcnt(4)
	v_mov_b32_e32 v110, v123
	v_mov_b32_dpp v100, v96 row_shr:2 row_mask:0xf bank_mask:0xf
	v_mov_b32_dpp v101, v97 row_shr:2 row_mask:0xf bank_mask:0xf
	v_mov_b32_dpp v106, v98 row_shr:1 row_mask:0xf bank_mask:0xf
	v_mov_b32_dpp v102, v98 row_shr:2 row_mask:0xf bank_mask:0xf
	v_mov_b32_dpp v103, v99 row_shr:2 row_mask:0xf bank_mask:0xf
	v_pk_mul_f32 v[110:111], v[116:117], v[110:111]
	v_mov_b32_dpp v104, v96 row_shr:1 row_mask:0xf bank_mask:0xf
	v_mov_b32_dpp v105, v97 row_shr:1 row_mask:0xf bank_mask:0xf
	v_mul_f32_e32 v106, v126, v106
	v_mov_b32_e32 v107, v111
	s_waitcnt vmcnt(3)
	v_pk_fma_f32 v[100:101], v[128:129], v[100:101], v[132:133]
	v_pk_fma_f32 v[102:103], v[130:131], v[102:103], v[134:135]
	v_mul_f32_e32 v108, v98, v122
	v_mov_b32_e32 v109, v110
	v_pk_add_f32 v[102:103], v[106:107], v[102:103]
	v_pk_fma_f32 v[100:101], v[124:125], v[104:105], v[100:101]
	v_pk_add_f32 v[106:107], v[108:109], v[102:103]
	v_pk_fma_f32 v[104:105], v[96:97], v[120:121], v[100:101]
	s_mov_b64 s[14:15], 0

;     __device__ __forceinline__ void operator()(const f32x4 (&acc)[2][2][4][2], const Unit& u, int wr, int wc, int fr, int fq) const {
;     ...
;                     const int oc = (bj ? FF : 0) + 128 * u.pn + 32 * wc + 8 * fq + 4 * n;
;                     const int cgc = 256 * u.pn + 128 * bj + 32 * wc + 8 * fq + 4 * n;
;                     const f32x4 cw0 = *(const f32x4*)(convw + oc), cw1 = *(const f32x4*)(convw + FF2 + oc), cw2 = *(const f32x4*)(convw + 2 * FF2 + oc), cb = *(const f32x4*)(convb + oc);
;                     f32x4 v[4];
; #pragma unroll
;                     for (int m = 0; m < 4; ++m) v[m] = acc[ai][bj][m][n] * rs[m];
;                     f32x4 hv = (f32x4){0.f, 0.f, 0.f, 0.f};
;                     if (!samp) {
;                         if ((blk & 31) != 0 && fr >= 14) hv = *(const f32x4*)(HALO + (size_t)(2 * blk + fr - 14) * FF2 + cgc);
;                         if ((u.pm & 7) == 7 && ai == 1 && wr == 1 && fr >= 14) *(f32x4*)(ncp + (size_t)((u.pm >> 3) * 2 + (fr - 14)) * FF2 + oc) = v[3];
;                     }
; #pragma unroll
;                     for (int m = 0; m < 4; ++m) {
;                         f32x4 cv;
;                         if (!samp) {
;                             const f32x4 prev = m ? v[m - 1] : hv;
; #pragma unroll
;                             for (int e = 0; e < 4; ++e) {
;                                 const int vi = __float_as_int(v[m][e]), pi = __float_as_int(prev[e]);
;                                 const int o1 = __builtin_amdgcn_mov_dpp(pi, 0x121, 0xf, 0xf, false);
;                                 const int o2 = __builtin_amdgcn_mov_dpp(pi, 0x122, 0xf, 0xf, false);
;                                 const float p1 = __int_as_float(__builtin_amdgcn_update_dpp(o1, vi, 0x111, 0xf, 0xf, false));
;                                 const float p2 = __int_as_float(__builtin_amdgcn_update_dpp(o2, vi, 0x112, 0xf, 0xf, false));
;                                 cv[e] = cb[e] + cw0[e] * p2 + cw1[e] * p1 + cw2[e] * v[m][e];
;                             }
;                         } else {
;                             const int ns = rowb + 16 * m + fr - MP;
;                             f32x4 s0 = (f32x4){0.f, 0.f, 0.f, 0.f}, s1 = s0;
;                             if (ns < NS) {
.LBB0_944:
	v_and_b32_e32 v97, 0x7fffffff, v113
	v_and_b32_e32 v96, 0x7fffffff, v112
	v_pk_fma_f32 v[96:97], v[96:97], s[38:39], 1.0 op_sel_hi:[1,0,0]
	v_mov_b64_e32 v[98:99], s[64:65]
	v_rcp_f32_e32 v96, v96
	v_rcp_f32_e32 v97, v97
	v_and_b32_e32 v109, 0x7fffffff, v115
	v_and_b32_e32 v108, 0x7fffffff, v114
	v_pk_fma_f32 v[108:109], v[108:109], s[38:39], 1.0 op_sel_hi:[1,0,0]
	v_pk_fma_f32 v[100:101], v[96:97], s[62:63], v[98:99] op_sel_hi:[1,0,0]
	v_rcp_f32_e32 v108, v108
	v_pk_fma_f32 v[100:101], v[96:97], v[100:101], s[66:67] op_sel_hi:[1,1,0]
	v_rcp_f32_e32 v109, v109
	v_pk_fma_f32 v[100:101], v[96:97], v[100:101], s[68:69] op_sel_hi:[1,1,0]
	v_pk_mul_f32 v[102:103], v[112:113], v[112:113]
	v_pk_fma_f32 v[100:101], v[96:97], v[100:101], s[70:71] op_sel_hi:[1,1,0]
	v_pk_mul_f32 v[102:103], v[102:103], s[72:73] op_sel_hi:[1,0]
	v_pk_mul_f32 v[96:97], v[96:97], v[100:101]
	v_exp_f32_e32 v102, v102
	v_exp_f32_e32 v103, v103
	v_pk_mul_f32 v[100:101], v[114:115], v[114:115]
	v_pk_fma_f32 v[98:99], v[108:109], s[62:63], v[98:99] op_sel_hi:[1,0,0]
	v_pk_mul_f32 v[100:101], v[100:101], s[72:73] op_sel_hi:[1,0]
	v_pk_fma_f32 v[98:99], v[108:109], v[98:99], s[66:67] op_sel_hi:[1,1,0]
	v_exp_f32_e32 v100, v100
	v_exp_f32_e32 v101, v101
	v_pk_fma_f32 v[98:99], v[108:109], v[98:99], s[68:69] op_sel_hi:[1,1,0]
	v_pk_mul_f32 v[96:97], v[102:103], v[96:97]
	v_pk_fma_f32 v[98:99], v[108:109], v[98:99], s[70:71] op_sel_hi:[1,1,0]
	v_pk_mul_f32 v[102:103], v[112:113], v[96:97]
	v_pk_fma_f32 v[96:97], v[112:113], v[96:97], v[112:113] neg_lo:[1,0,0] neg_hi:[1,0,0]
	v_cmp_gt_f32_e32 vcc, 0, v112
	v_pk_mul_f32 v[98:99], v[108:109], v[98:99]
	v_pk_mul_f32 v[92:93], v[92:93], v[206:207]
	v_cndmask_b32_e32 v96, v96, v102, vcc
	v_cmp_gt_f32_e32 vcc, 0, v113
	v_pk_mul_f32 v[98:99], v[100:101], v[98:99]
	s_nop 0
	v_cndmask_b32_e32 v97, v97, v103, vcc
	v_pk_mul_f32 v[100:101], v[114:115], v[98:99]
	v_pk_fma_f32 v[98:99], v[114:115], v[98:99], v[114:115] neg_lo:[1,0,0] neg_hi:[1,0,0]
	v_cmp_gt_f32_e32 vcc, 0, v114
	v_pk_mul_f32 v[96:97], v[96:97], v[104:105]
	v_mov_b32_e32 v104, v206
	v_cndmask_b32_e32 v98, v98, v100, vcc
	v_cmp_gt_f32_e32 vcc, 0, v115
	v_cvt_pk_bf16_f32 v96, v96, v97
	v_mov_b32_e32 v105, v206
	v_pk_mul_f32 v[94:95], v[94:95], v[104:105]
	v_cndmask_b32_e32 v99, v99, v101, vcc
	v_pk_mul_f32 v[98:99], v[98:99], v[106:107]
	s_and_b64 vcc, exec, s[12:13]
	v_cvt_pk_bf16_f32 v97, v98, v99
	v_mov_b64_e32 v[98:99], s[46:47]
	v_mad_i64_i32 v[98:99], s[14:15], v196, s34, v[98:99]
	v_lshl_add_u64 v[98:99], s[86:87], 1, v[98:99]
	v_lshl_add_u64 v[98:99], v[98:99], 0, s[24:25]
	v_lshl_add_u64 v[136:137], v[98:99], 0, v[168:169]
	global_store_dwordx2 v[136:137], v[96:97], off sc1
	v_or_b32_e32 v96, 4, v174
	v_ashrrev_i32_e32 v97, 31, v96
	v_lshlrev_b64 v[96:97], 2, v[96:97]
	s_waitcnt vmcnt(4)
	v_lshl_add_u64 v[132:133], s[58:59], 0, v[96:97]
	global_load_dwordx4 v[112:115], v[176:177], off offset:16
	v_lshl_add_u64 v[134:135], s[60:61], 0, v[96:97]
	global_load_dwordx4 v[100:103], v[132:133], off
	global_load_dwordx4 v[96:99], v[134:135], off
	global_load_dwordx4 v[116:119], v[178:179], off offset:16
	s_mov_b64 s[14:15], -1
	s_cbranch_vccnz .LBB0_948
	v_mov_b32_e32 v104, 0
	v_mov_b32_e32 v105, 0
	v_mov_b32_e32 v106, 0
	v_mov_b32_e32 v107, 0
	s_and_saveexec_b64 s[14:15], s[90:91]
	s_cbranch_execz .LBB0_947
	v_lshl_add_u64 v[104:105], s[44:45], 0, v[208:209]
	v_ashrrev_i32_e32 v171, 31, v170
	v_lshl_add_u64 v[104:105], v[170:171], 2, v[104:105]
	global_load_dwordx4 v[104:107], v[104:105], off offset:16

; __device__ __forceinline__ unsigned cvt_pk_bf16(float lo, float hi) { unsigned r; asm volatile("v_cvt_pk_bf16_f32 %0, %1, %2" : "=v"(r) : "v"(lo), "v"(hi)); return r; }
;     __device__ __forceinline__ void operator()(const f32x4 (&acc)[2][2][4][2], const Unit& u, int wr, int wc, int fr, int fq) const {
;     ...
; #pragma unroll
;                     for (int m = 0; m < 4; ++m) {
;                         f32x4 cv;
;                         if (!samp) {
;                             const f32x4 prev = m ? v[m - 1] : hv;
; #pragma unroll
;                             for (int e = 0; e < 4; ++e) {
;                                 const int vi = __float_as_int(v[m][e]), pi = __float_as_int(prev[e]);
;                                 const int o1 = __builtin_amdgcn_mov_dpp(pi, 0x121, 0xf, 0xf, false);
;                                 const int o2 = __builtin_amdgcn_mov_dpp(pi, 0x122, 0xf, 0xf, false);
;                                 const float p1 = __int_as_float(__builtin_amdgcn_update_dpp(o1, vi, 0x111, 0xf, 0xf, false));
;                                 const float p2 = __int_as_float(__builtin_amdgcn_update_dpp(o2, vi, 0x112, 0xf, 0xf, false));
;                                 cv[e] = cb[e] + cw0[e] * p2 + cw1[e] * p1 + cw2[e] * v[m][e];
;                             }
;                         } else {
;                             const int ns = rowb + 16 * m + fr - MP;
;                             f32x4 s0 = (f32x4){0.f, 0.f, 0.f, 0.f}, s1 = s0;
;                             if (ns < NS) {
;                                 s0 = *(const f32x4*)(state + (size_t)(ns * 2 + 0) * FF2 + oc); s1 = *(const f32x4*)(state + (size_t)(ns * 2 + 1) * FF2 + oc);
;                                 *(f32x4*)(ncs + (size_t)(ns * 2 + 0) * FF2 + oc) = s1; *(f32x4*)(ncs + (size_t)(ns * 2 + 1) * FF2 + oc) = v[m];
;                             }
;                             cv = cb + cw0 * s0 + cw1 * s1 + cw2 * v[m];
;                         }
;                         if (bj == 0) cg[m] = gelu4(cv);
;                         else {
;                             const f32x4 r = cg[m] * cv;
;                             v2u w; w.x = cvt_pk_bf16(r[0], r[1]); w.y = cvt_pk_bf16(r[2], r[3]);
;                             *(v2u*)(ACT + (size_t)(rowb + 16 * m + fr) * FF + 128 * u.pn + 32 * wc + 8 * fq + 4 * n) = w;
;                         }
.LBB0_978:
	s_waitcnt vmcnt(4)
	v_mov_b32_e32 v116, v212
	v_mov_b32_e32 v117, v212
	v_pk_mul_f32 v[74:75], v[74:75], v[116:117]
	v_and_b32_e32 v117, 0x7fffffff, v109
	v_and_b32_e32 v116, 0x7fffffff, v108
	v_pk_fma_f32 v[116:117], v[116:117], s[38:39], 1.0 op_sel_hi:[1,0,0]
	v_mov_b64_e32 v[118:119], s[64:65]
	v_rcp_f32_e32 v116, v116
	v_rcp_f32_e32 v117, v117
	v_pk_mul_f32 v[146:147], v[108:109], v[108:109]
	v_cmp_gt_f32_e32 vcc, 0, v108
	v_pk_mul_f32 v[146:147], v[146:147], s[72:73] op_sel_hi:[1,0]
	v_pk_fma_f32 v[142:143], v[116:117], s[62:63], v[118:119] op_sel_hi:[1,0,0]
	v_exp_f32_e32 v146, v146
	v_pk_fma_f32 v[142:143], v[116:117], v[142:143], s[66:67] op_sel_hi:[1,1,0]
	v_exp_f32_e32 v147, v147
	v_pk_fma_f32 v[142:143], v[116:117], v[142:143], s[68:69] op_sel_hi:[1,1,0]
	v_pk_mul_f32 v[72:73], v[72:73], v[212:213]
	v_pk_fma_f32 v[142:143], v[116:117], v[142:143], s[70:71] op_sel_hi:[1,1,0]
	s_mov_b64 s[14:15], -1
	v_pk_mul_f32 v[116:117], v[116:117], v[142:143]
	v_pk_mul_f32 v[142:143], v[110:111], v[110:111]
	v_pk_mul_f32 v[116:117], v[146:147], v[116:117]
	s_nop 0
	v_pk_mul_f32 v[146:147], v[108:109], v[116:117]
	v_pk_fma_f32 v[116:117], v[108:109], v[116:117], v[108:109] neg_lo:[1,0,0] neg_hi:[1,0,0]
	s_nop 0
	v_cndmask_b32_e32 v108, v116, v146, vcc
	v_cmp_gt_f32_e32 vcc, 0, v109
	v_and_b32_e32 v116, 0x7fffffff, v110
	s_nop 0
	v_cndmask_b32_e32 v109, v117, v147, vcc
	v_and_b32_e32 v117, 0x7fffffff, v111
	v_pk_fma_f32 v[116:117], v[116:117], s[38:39], 1.0 op_sel_hi:[1,0,0]
	v_cmp_gt_f32_e32 vcc, 0, v110
	v_rcp_f32_e32 v116, v116
	v_rcp_f32_e32 v117, v117
	v_pk_mul_f32 v[108:109], v[108:109], v[112:113]
	v_pk_fma_f32 v[118:119], v[116:117], s[62:63], v[118:119] op_sel_hi:[1,0,0]
	s_nop 0
	v_pk_fma_f32 v[118:119], v[116:117], v[118:119], s[66:67] op_sel_hi:[1,1,0]
	v_cvt_pk_bf16_f32 v108, v108, v109
	s_nop 0
	v_pk_fma_f32 v[118:119], v[116:117], v[118:119], s[68:69] op_sel_hi:[1,1,0]
	s_nop 0
	v_pk_fma_f32 v[118:119], v[116:117], v[118:119], s[70:71] op_sel_hi:[1,1,0]
	s_nop 0
	v_pk_mul_f32 v[116:117], v[116:117], v[118:119]
	v_pk_mul_f32 v[118:119], v[142:143], s[72:73] op_sel_hi:[1,0]
	s_nop 0
	v_exp_f32_e32 v118, v118
	v_exp_f32_e32 v119, v119
	s_nop 0
	v_pk_mul_f32 v[116:117], v[118:119], v[116:117]
	s_nop 0
	v_pk_mul_f32 v[118:119], v[110:111], v[116:117]
	v_pk_fma_f32 v[116:117], v[110:111], v[116:117], v[110:111] neg_lo:[1,0,0] neg_hi:[1,0,0]
	s_nop 0
	v_cndmask_b32_e32 v110, v116, v118, vcc
	v_cmp_gt_f32_e32 vcc, 0, v111
	s_nop 1
	v_cndmask_b32_e32 v111, v117, v119, vcc
	v_pk_mul_f32 v[110:111], v[110:111], v[114:115]
	s_and_b64 vcc, exec, s[12:13]
	v_cvt_pk_bf16_f32 v109, v110, v111
	global_store_dwordx2 v[144:145], v[108:109], off offset:8 sc1
	s_cbranch_vccnz .LBB0_980
	v_mov_b32_dpp v115, v79 row_ror:1 row_mask:0xf bank_mask:0xf
	v_mov_b32_dpp v108, v76 row_ror:1 row_mask:0xf bank_mask:0xf
	v_mov_b32_dpp v76, v76 row_ror:2 row_mask:0xf bank_mask:0xf
	v_mov_b32_dpp v109, v77 row_ror:1 row_mask:0xf bank_mask:0xf
	v_mov_b32_dpp v77, v77 row_ror:2 row_mask:0xf bank_mask:0xf
	v_mov_b32_dpp v110, v78 row_ror:1 row_mask:0xf bank_mask:0xf
	v_mov_b32_dpp v78, v78 row_ror:2 row_mask:0xf bank_mask:0xf
	v_mov_b32_dpp v79, v79 row_ror:2 row_mask:0xf bank_mask:0xf
	v_mov_b32_dpp v115, v75 row_shr:1 row_mask:0xf bank_mask:0xf
	v_mov_b32_e32 v116, v75
	s_waitcnt vmcnt(3)
	v_mov_b32_e32 v117, v95
	s_waitcnt vmcnt(2)
	v_mov_b32_e32 v114, v91
	v_mov_b32_dpp v76, v72 row_shr:2 row_mask:0xf bank_mask:0xf
	v_mov_b32_dpp v77, v73 row_shr:2 row_mask:0xf bank_mask:0xf
	v_mov_b32_dpp v110, v74 row_shr:1 row_mask:0xf bank_mask:0xf
	v_mov_b32_dpp v78, v74 row_shr:2 row_mask:0xf bank_mask:0xf
	v_mov_b32_dpp v79, v75 row_shr:2 row_mask:0xf bank_mask:0xf
	v_pk_mul_f32 v[114:115], v[116:117], v[114:115]
	v_mov_b32_dpp v108, v72 row_shr:1 row_mask:0xf bank_mask:0xf
	v_mov_b32_dpp v109, v73 row_shr:1 row_mask:0xf bank_mask:0xf
	v_mul_f32_e32 v110, v94, v110
	v_mov_b32_e32 v111, v115
	s_waitcnt vmcnt(1)
	v_pk_fma_f32 v[76:77], v[96:97], v[76:77], v[100:101]
	v_pk_fma_f32 v[78:79], v[98:99], v[78:79], v[102:103]
	v_mul_f32_e32 v112, v74, v90
	v_mov_b32_e32 v113, v114
	v_pk_add_f32 v[78:79], v[110:111], v[78:79]
	v_pk_fma_f32 v[76:77], v[92:93], v[108:109], v[76:77]
	v_pk_add_f32 v[110:111], v[112:113], v[78:79]
	v_pk_fma_f32 v[108:109], v[72:73], v[88:89], v[76:77]
	s_mov_b64 s[14:15], 0

; __device__ __forceinline__ unsigned cvt_pk_bf16(float lo, float hi) { unsigned r; asm volatile("v_cvt_pk_bf16_f32 %0, %1, %2" : "=v"(r) : "v"(lo), "v"(hi)); return r; }
;     __device__ __forceinline__ void operator()(const f32x4 (&acc)[2][2][4][2], const Unit& u, int wr, int wc, int fr, int fq) const {
;     ...
; #pragma unroll
;                     for (int m = 0; m < 4; ++m) {
;                         f32x4 cv;
;                         if (!samp) {
;                             const f32x4 prev = m ? v[m - 1] : hv;
; #pragma unroll
;                             for (int e = 0; e < 4; ++e) {
;                                 const int vi = __float_as_int(v[m][e]), pi = __float_as_int(prev[e]);
;                                 const int o1 = __builtin_amdgcn_mov_dpp(pi, 0x121, 0xf, 0xf, false);
;                                 const int o2 = __builtin_amdgcn_mov_dpp(pi, 0x122, 0xf, 0xf, false);
;                                 const float p1 = __int_as_float(__builtin_amdgcn_update_dpp(o1, vi, 0x111, 0xf, 0xf, false));
;                                 const float p2 = __int_as_float(__builtin_amdgcn_update_dpp(o2, vi, 0x112, 0xf, 0xf, false));
;                                 cv[e] = cb[e] + cw0[e] * p2 + cw1[e] * p1 + cw2[e] * v[m][e];
;                             }
;                         } else {
;                             const int ns = rowb + 16 * m + fr - MP;
;                             f32x4 s0 = (f32x4){0.f, 0.f, 0.f, 0.f}, s1 = s0;
;                             if (ns < NS) {
;                                 s0 = *(const f32x4*)(state + (size_t)(ns * 2 + 0) * FF2 + oc); s1 = *(const f32x4*)(state + (size_t)(ns * 2 + 1) * FF2 + oc);
;                                 *(f32x4*)(ncs + (size_t)(ns * 2 + 0) * FF2 + oc) = s1; *(f32x4*)(ncs + (size_t)(ns * 2 + 1) * FF2 + oc) = v[m];
;                             }
;                             cv = cb + cw0 * s0 + cw1 * s1 + cw2 * v[m];
;                         }
;                         if (bj == 0) cg[m] = gelu4(cv);
;                         else {
;                             const f32x4 r = cg[m] * cv;
;                             v2u w; w.x = cvt_pk_bf16(r[0], r[1]); w.y = cvt_pk_bf16(r[2], r[3]);
;                             *(v2u*)(ACT + (size_t)(rowb + 16 * m + fr) * FF + 128 * u.pn + 32 * wc + 8 * fq + 4 * n) = w;
;                         }
.LBB0_984:
	v_mov_b32_e32 v76, v210
	v_mov_b32_e32 v77, v210
	v_pk_mul_f32 v[70:71], v[70:71], v[76:77]
	v_and_b32_e32 v77, 0x7fffffff, v105
	v_and_b32_e32 v76, 0x7fffffff, v104
	v_pk_fma_f32 v[76:77], v[76:77], s[38:39], 1.0 op_sel_hi:[1,0,0]
	v_mov_b64_e32 v[78:79], s[64:65]
	v_rcp_f32_e32 v76, v76
	v_rcp_f32_e32 v77, v77
	v_pk_mul_f32 v[114:115], v[104:105], v[104:105]
	v_cmp_gt_f32_e32 vcc, 0, v104
	v_pk_mul_f32 v[114:115], v[114:115], s[72:73] op_sel_hi:[1,0]
	v_pk_fma_f32 v[112:113], v[76:77], s[62:63], v[78:79] op_sel_hi:[1,0,0]
	v_exp_f32_e32 v114, v114
	v_pk_fma_f32 v[112:113], v[76:77], v[112:113], s[66:67] op_sel_hi:[1,1,0]
	v_exp_f32_e32 v115, v115
	v_pk_fma_f32 v[112:113], v[76:77], v[112:113], s[68:69] op_sel_hi:[1,1,0]
	v_pk_mul_f32 v[68:69], v[68:69], v[210:211]
	v_pk_fma_f32 v[112:113], v[76:77], v[112:113], s[70:71] op_sel_hi:[1,1,0]
	s_mov_b64 s[14:15], -1
	v_pk_mul_f32 v[76:77], v[76:77], v[112:113]
	v_pk_mul_f32 v[112:113], v[106:107], v[106:107]
	v_pk_mul_f32 v[76:77], v[114:115], v[76:77]
	s_nop 0
	v_pk_mul_f32 v[114:115], v[104:105], v[76:77]
	v_pk_fma_f32 v[76:77], v[104:105], v[76:77], v[104:105] neg_lo:[1,0,0] neg_hi:[1,0,0]
	v_and_b32_e32 v104, 0x7fffffff, v106
	v_cndmask_b32_e32 v76, v76, v114, vcc
	v_cmp_gt_f32_e32 vcc, 0, v105
	v_and_b32_e32 v105, 0x7fffffff, v107
	v_pk_fma_f32 v[104:105], v[104:105], s[38:39], 1.0 op_sel_hi:[1,0,0]
	v_cndmask_b32_e32 v77, v77, v115, vcc
	v_rcp_f32_e32 v104, v104
	v_rcp_f32_e32 v105, v105
	v_cmp_gt_f32_e32 vcc, 0, v106
	v_pk_mul_f32 v[76:77], v[76:77], v[108:109]
	v_pk_fma_f32 v[78:79], v[104:105], s[62:63], v[78:79] op_sel_hi:[1,0,0]
	s_nop 0
	v_pk_fma_f32 v[78:79], v[104:105], v[78:79], s[66:67] op_sel_hi:[1,1,0]
	v_cvt_pk_bf16_f32 v76, v76, v77
	s_nop 0
	v_pk_fma_f32 v[78:79], v[104:105], v[78:79], s[68:69] op_sel_hi:[1,1,0]
	s_nop 0
	v_pk_fma_f32 v[78:79], v[104:105], v[78:79], s[70:71] op_sel_hi:[1,1,0]
	s_nop 0
	v_pk_mul_f32 v[78:79], v[104:105], v[78:79]
	v_pk_mul_f32 v[104:105], v[112:113], s[72:73] op_sel_hi:[1,0]
	s_nop 0
	v_exp_f32_e32 v104, v104
	v_exp_f32_e32 v105, v105
	s_nop 0
	v_pk_mul_f32 v[78:79], v[104:105], v[78:79]
	s_nop 0
	v_pk_mul_f32 v[104:105], v[106:107], v[78:79]
	v_pk_fma_f32 v[78:79], v[106:107], v[78:79], v[106:107] neg_lo:[1,0,0] neg_hi:[1,0,0]
	s_nop 0
	v_cndmask_b32_e32 v78, v78, v104, vcc
	v_cmp_gt_f32_e32 vcc, 0, v107
	s_nop 1
	v_cndmask_b32_e32 v79, v79, v105, vcc
	v_pk_mul_f32 v[78:79], v[78:79], v[110:111]
	s_and_b64 vcc, exec, s[12:13]
	v_cvt_pk_bf16_f32 v77, v78, v79
	global_store_dwordx2 v[138:139], v[76:77], off offset:8 sc1
	s_cbranch_vccnz .LBB0_986
	v_mov_b32_dpp v107, v75 row_ror:1 row_mask:0xf bank_mask:0xf
	v_mov_b32_dpp v76, v72 row_ror:1 row_mask:0xf bank_mask:0xf
	v_mov_b32_dpp v72, v72 row_ror:2 row_mask:0xf bank_mask:0xf
	v_mov_b32_dpp v77, v73 row_ror:1 row_mask:0xf bank_mask:0xf
	v_mov_b32_dpp v73, v73 row_ror:2 row_mask:0xf bank_mask:0xf
	v_mov_b32_dpp v78, v74 row_ror:1 row_mask:0xf bank_mask:0xf
	v_mov_b32_dpp v74, v74 row_ror:2 row_mask:0xf bank_mask:0xf
	v_mov_b32_dpp v75, v75 row_ror:2 row_mask:0xf bank_mask:0xf
	v_mov_b32_dpp v107, v71 row_shr:1 row_mask:0xf bank_mask:0xf
	v_mov_b32_e32 v108, v71
	s_waitcnt vmcnt(4)
	v_mov_b32_e32 v109, v95
	s_waitcnt vmcnt(3)
	v_mov_b32_e32 v106, v91
	v_mov_b32_dpp v72, v68 row_shr:2 row_mask:0xf bank_mask:0xf
	v_mov_b32_dpp v73, v69 row_shr:2 row_mask:0xf bank_mask:0xf
	v_mov_b32_dpp v78, v70 row_shr:1 row_mask:0xf bank_mask:0xf
	v_mov_b32_dpp v74, v70 row_shr:2 row_mask:0xf bank_mask:0xf
	v_mov_b32_dpp v75, v71 row_shr:2 row_mask:0xf bank_mask:0xf
	v_pk_mul_f32 v[106:107], v[108:109], v[106:107]
	v_mov_b32_dpp v76, v68 row_shr:1 row_mask:0xf bank_mask:0xf
	v_mov_b32_dpp v77, v69 row_shr:1 row_mask:0xf bank_mask:0xf
	v_mul_f32_e32 v78, v94, v78
	v_mov_b32_e32 v79, v107
	s_waitcnt vmcnt(2)
	v_pk_fma_f32 v[72:73], v[96:97], v[72:73], v[100:101]
	v_pk_fma_f32 v[74:75], v[98:99], v[74:75], v[102:103]
	v_mul_f32_e32 v104, v70, v90
	v_mov_b32_e32 v105, v106
	v_pk_add_f32 v[74:75], v[78:79], v[74:75]
	v_pk_fma_f32 v[72:73], v[92:93], v[76:77], v[72:73]
	v_pk_add_f32 v[78:79], v[104:105], v[74:75]
	v_pk_fma_f32 v[76:77], v[68:69], v[88:89], v[72:73]
	s_mov_b64 s[14:15], 0

; __device__ __forceinline__ unsigned cvt_pk_bf16(float lo, float hi) { unsigned r; asm volatile("v_cvt_pk_bf16_f32 %0, %1, %2" : "=v"(r) : "v"(lo), "v"(hi)); return r; }
;     __device__ __forceinline__ void operator()(const f32x4 (&acc)[2][2][4][2], const Unit& u, int wr, int wc, int fr, int fq) const {
;     ...
; #pragma unroll
;                     for (int m = 0; m < 4; ++m) {
;                         f32x4 cv;
;                         if (!samp) {
;                             const f32x4 prev = m ? v[m - 1] : hv;
; #pragma unroll
;                             for (int e = 0; e < 4; ++e) {
;                                 const int vi = __float_as_int(v[m][e]), pi = __float_as_int(prev[e]);
;                                 const int o1 = __builtin_amdgcn_mov_dpp(pi, 0x121, 0xf, 0xf, false);
;                                 const int o2 = __builtin_amdgcn_mov_dpp(pi, 0x122, 0xf, 0xf, false);
;                                 const float p1 = __int_as_float(__builtin_amdgcn_update_dpp(o1, vi, 0x111, 0xf, 0xf, false));
;                                 const float p2 = __int_as_float(__builtin_amdgcn_update_dpp(o2, vi, 0x112, 0xf, 0xf, false));
;                                 cv[e] = cb[e] + cw0[e] * p2 + cw1[e] * p1 + cw2[e] * v[m][e];
;                             }
;                         } else {
;                             const int ns = rowb + 16 * m + fr - MP;
;                             f32x4 s0 = (f32x4){0.f, 0.f, 0.f, 0.f}, s1 = s0;
;                             if (ns < NS) {
;                                 s0 = *(const f32x4*)(state + (size_t)(ns * 2 + 0) * FF2 + oc); s1 = *(const f32x4*)(state + (size_t)(ns * 2 + 1) * FF2 + oc);
;                                 *(f32x4*)(ncs + (size_t)(ns * 2 + 0) * FF2 + oc) = s1; *(f32x4*)(ncs + (size_t)(ns * 2 + 1) * FF2 + oc) = v[m];
;                             }
;                             cv = cb + cw0 * s0 + cw1 * s1 + cw2 * v[m];
;                         }
;                         if (bj == 0) cg[m] = gelu4(cv);
;                         else {
;                             const f32x4 r = cg[m] * cv;
;                             v2u w; w.x = cvt_pk_bf16(r[0], r[1]); w.y = cvt_pk_bf16(r[2], r[3]);
;                             *(v2u*)(ACT + (size_t)(rowb + 16 * m + fr) * FF + 128 * u.pn + 32 * wc + 8 * fq + 4 * n) = w;
;                         }
.LBB0_990:
	v_mov_b32_e32 v72, v204
	v_mov_b32_e32 v73, v204
	v_pk_mul_f32 v[66:67], v[66:67], v[72:73]
	v_and_b32_e32 v73, 0x7fffffff, v85
	v_and_b32_e32 v72, 0x7fffffff, v84
	v_pk_fma_f32 v[72:73], v[72:73], s[38:39], 1.0 op_sel_hi:[1,0,0]
	v_mov_b64_e32 v[74:75], s[64:65]
	v_rcp_f32_e32 v72, v72
	v_rcp_f32_e32 v73, v73
	v_pk_mul_f32 v[106:107], v[84:85], v[84:85]
	v_cmp_gt_f32_e32 vcc, 0, v84
	v_pk_mul_f32 v[106:107], v[106:107], s[72:73] op_sel_hi:[1,0]
	v_pk_fma_f32 v[104:105], v[72:73], s[62:63], v[74:75] op_sel_hi:[1,0,0]
	v_exp_f32_e32 v106, v106
	v_pk_fma_f32 v[104:105], v[72:73], v[104:105], s[66:67] op_sel_hi:[1,1,0]
	v_exp_f32_e32 v107, v107
	v_pk_fma_f32 v[104:105], v[72:73], v[104:105], s[68:69] op_sel_hi:[1,1,0]
	v_pk_mul_f32 v[64:65], v[64:65], v[204:205]
	v_pk_fma_f32 v[104:105], v[72:73], v[104:105], s[70:71] op_sel_hi:[1,1,0]
	s_mov_b64 s[14:15], -1
	v_pk_mul_f32 v[72:73], v[72:73], v[104:105]
	v_pk_mul_f32 v[104:105], v[86:87], v[86:87]
	v_pk_mul_f32 v[72:73], v[106:107], v[72:73]
	s_nop 0
	v_pk_mul_f32 v[106:107], v[84:85], v[72:73]
	v_pk_fma_f32 v[72:73], v[84:85], v[72:73], v[84:85] neg_lo:[1,0,0] neg_hi:[1,0,0]
	v_and_b32_e32 v84, 0x7fffffff, v86
	v_cndmask_b32_e32 v72, v72, v106, vcc
	v_cmp_gt_f32_e32 vcc, 0, v85
	v_and_b32_e32 v85, 0x7fffffff, v87
	v_pk_fma_f32 v[84:85], v[84:85], s[38:39], 1.0 op_sel_hi:[1,0,0]
	v_cndmask_b32_e32 v73, v73, v107, vcc
	v_rcp_f32_e32 v84, v84
	v_rcp_f32_e32 v85, v85
	v_cmp_gt_f32_e32 vcc, 0, v86
	v_pk_mul_f32 v[72:73], v[72:73], v[76:77]
	v_pk_fma_f32 v[74:75], v[84:85], s[62:63], v[74:75] op_sel_hi:[1,0,0]
	s_nop 0
	v_pk_fma_f32 v[74:75], v[84:85], v[74:75], s[66:67] op_sel_hi:[1,1,0]
	v_cvt_pk_bf16_f32 v72, v72, v73
	s_nop 0
	v_pk_fma_f32 v[74:75], v[84:85], v[74:75], s[68:69] op_sel_hi:[1,1,0]
	s_nop 0
	v_pk_fma_f32 v[74:75], v[84:85], v[74:75], s[70:71] op_sel_hi:[1,1,0]
	s_nop 0
	v_pk_mul_f32 v[74:75], v[84:85], v[74:75]
	v_pk_mul_f32 v[84:85], v[104:105], s[72:73] op_sel_hi:[1,0]
	s_nop 0
	v_exp_f32_e32 v84, v84
	v_exp_f32_e32 v85, v85
	s_nop 0
	v_pk_mul_f32 v[74:75], v[84:85], v[74:75]
	s_nop 0
	v_pk_mul_f32 v[84:85], v[86:87], v[74:75]
	v_pk_fma_f32 v[74:75], v[86:87], v[74:75], v[86:87] neg_lo:[1,0,0] neg_hi:[1,0,0]
	s_nop 0
	v_cndmask_b32_e32 v74, v74, v84, vcc
	v_cmp_gt_f32_e32 vcc, 0, v87
	s_nop 1
	v_cndmask_b32_e32 v75, v75, v85, vcc
	v_pk_mul_f32 v[74:75], v[74:75], v[78:79]
	s_and_b64 vcc, exec, s[12:13]
	v_cvt_pk_bf16_f32 v73, v74, v75
	global_store_dwordx2 v[140:141], v[72:73], off offset:8 sc1
	s_cbranch_vccnz .LBB0_992
	v_mov_b32_dpp v79, v71 row_ror:1 row_mask:0xf bank_mask:0xf
	v_mov_b32_dpp v72, v68 row_ror:1 row_mask:0xf bank_mask:0xf
	v_mov_b32_dpp v68, v68 row_ror:2 row_mask:0xf bank_mask:0xf
	v_mov_b32_dpp v73, v69 row_ror:1 row_mask:0xf bank_mask:0xf
	v_mov_b32_dpp v69, v69 row_ror:2 row_mask:0xf bank_mask:0xf
	v_mov_b32_dpp v74, v70 row_ror:1 row_mask:0xf bank_mask:0xf
	v_mov_b32_dpp v70, v70 row_ror:2 row_mask:0xf bank_mask:0xf
	v_mov_b32_dpp v71, v71 row_ror:2 row_mask:0xf bank_mask:0xf
	v_mov_b32_dpp v79, v67 row_shr:1 row_mask:0xf bank_mask:0xf
	v_mov_b32_e32 v84, v67
	s_waitcnt vmcnt(5)
	v_mov_b32_e32 v85, v95
	s_waitcnt vmcnt(4)
	v_mov_b32_e32 v78, v91
	v_mov_b32_dpp v68, v64 row_shr:2 row_mask:0xf bank_mask:0xf
	v_mov_b32_dpp v69, v65 row_shr:2 row_mask:0xf bank_mask:0xf
	v_mov_b32_dpp v74, v66 row_shr:1 row_mask:0xf bank_mask:0xf
	v_mov_b32_dpp v70, v66 row_shr:2 row_mask:0xf bank_mask:0xf
	v_mov_b32_dpp v71, v67 row_shr:2 row_mask:0xf bank_mask:0xf
	v_pk_mul_f32 v[78:79], v[84:85], v[78:79]
	v_mov_b32_dpp v72, v64 row_shr:1 row_mask:0xf bank_mask:0xf
	v_mov_b32_dpp v73, v65 row_shr:1 row_mask:0xf bank_mask:0xf
	v_mul_f32_e32 v74, v94, v74
	v_mov_b32_e32 v75, v79
	s_waitcnt vmcnt(3)
	v_pk_fma_f32 v[68:69], v[96:97], v[68:69], v[100:101]
	v_pk_fma_f32 v[70:71], v[98:99], v[70:71], v[102:103]
	v_mul_f32_e32 v76, v66, v90
	v_mov_b32_e32 v77, v78
	v_pk_add_f32 v[70:71], v[74:75], v[70:71]
	v_pk_fma_f32 v[68:69], v[92:93], v[72:73], v[68:69]
	v_pk_add_f32 v[74:75], v[76:77], v[70:71]
	v_pk_fma_f32 v[72:73], v[64:65], v[88:89], v[68:69]
	s_mov_b64 s[14:15], 0

;     __device__ __forceinline__ void operator()(const f32x4 (&acc)[2][2][4][2], const Unit& u, int wr, int wc, int fr, int fq) const {
;     ...
;             for (int m = 0; m < 4; ++m) rs[m] = rsqrtf(SS[rowb + 16 * m + fr] * (1.0f / D) + EPS);
; #pragma unroll
;             for (int n = 0; n < 2; ++n) {
;                 f32x4 cg[4];
; #pragma unroll
;                 for (int bj = 0; bj < 2; ++bj) {
;                     const int oc = (bj ? FF : 0) + 128 * u.pn + 32 * wc + 8 * fq + 4 * n;
;                     const int cgc = 256 * u.pn + 128 * bj + 32 * wc + 8 * fq + 4 * n;
;                     const f32x4 cw0 = *(const f32x4*)(convw + oc), cw1 = *(const f32x4*)(convw + FF2 + oc), cw2 = *(const f32x4*)(convw + 2 * FF2 + oc), cb = *(const f32x4*)(convb + oc);
;                     f32x4 v[4];
; #pragma unroll
;                     for (int m = 0; m < 4; ++m) v[m] = acc[ai][bj][m][n] * rs[m];
;                     f32x4 hv = (f32x4){0.f, 0.f, 0.f, 0.f};
;                     if (!samp) {
;                         if ((blk & 31) != 0 && fr >= 14) hv = *(const f32x4*)(HALO + (size_t)(2 * blk + fr - 14) * FF2 + cgc);
;                         if ((u.pm & 7) == 7 && ai == 1 && wr == 1 && fr >= 14) *(f32x4*)(ncp + (size_t)((u.pm >> 3) * 2 + (fr - 14)) * FF2 + oc) = v[3];
;                     }
; #pragma unroll
;                     for (int m = 0; m < 4; ++m) {
;                         f32x4 cv;
;                         if (!samp) {
;                             const f32x4 prev = m ? v[m - 1] : hv;
; #pragma unroll
;                             for (int e = 0; e < 4; ++e) {
;                                 const int vi = __float_as_int(v[m][e]), pi = __float_as_int(prev[e]);
;                                 const int o1 = __builtin_amdgcn_mov_dpp(pi, 0x121, 0xf, 0xf, false);
;                                 const int o2 = __builtin_amdgcn_mov_dpp(pi, 0x122, 0xf, 0xf, false);
;                                 const float p1 = __int_as_float(__builtin_amdgcn_update_dpp(o1, vi, 0x111, 0xf, 0xf, false));
;                                 const float p2 = __int_as_float(__builtin_amdgcn_update_dpp(o2, vi, 0x112, 0xf, 0xf, false));
;                                 cv[e] = cb[e] + cw0[e] * p2 + cw1[e] * p1 + cw2[e] * v[m][e];
;                             }
;                         } else {
;                             const int ns = rowb + 16 * m + fr - MP;
.LBB0_996:
	v_and_b32_e32 v65, 0x7fffffff, v81
	v_and_b32_e32 v64, 0x7fffffff, v80
	v_pk_fma_f32 v[64:65], v[64:65], s[38:39], 1.0 op_sel_hi:[1,0,0]
	v_mov_b64_e32 v[66:67], s[64:65]
	v_rcp_f32_e32 v64, v64
	v_rcp_f32_e32 v65, v65
	v_pk_mul_f32 v[70:71], v[80:81], v[80:81]
	v_cmp_gt_f32_e32 vcc, 0, v80
	v_pk_mul_f32 v[70:71], v[70:71], s[72:73] op_sel_hi:[1,0]
	v_pk_fma_f32 v[68:69], v[64:65], s[62:63], v[66:67] op_sel_hi:[1,0,0]
	v_exp_f32_e32 v70, v70
	v_pk_fma_f32 v[68:69], v[64:65], v[68:69], s[66:67] op_sel_hi:[1,1,0]
	v_exp_f32_e32 v71, v71
	v_pk_fma_f32 v[68:69], v[64:65], v[68:69], s[68:69] op_sel_hi:[1,1,0]
	s_waitcnt vmcnt(6)
	v_add_u32_e32 v98, s77, v214
	v_pk_fma_f32 v[68:69], v[64:65], v[68:69], s[70:71] op_sel_hi:[1,1,0]
	v_ashrrev_i32_e32 v99, 31, v98
	v_pk_mul_f32 v[64:65], v[64:65], v[68:69]
	v_pk_mul_f32 v[68:69], v[82:83], v[82:83]
	v_pk_mul_f32 v[64:65], v[70:71], v[64:65]
	v_pk_mul_f32 v[68:69], v[68:69], s[72:73] op_sel_hi:[1,0]
	v_pk_mul_f32 v[70:71], v[80:81], v[64:65]
	v_pk_fma_f32 v[64:65], v[80:81], v[64:65], v[80:81] neg_lo:[1,0,0] neg_hi:[1,0,0]
	v_exp_f32_e32 v68, v68
	v_cndmask_b32_e32 v64, v64, v70, vcc
	v_cmp_gt_f32_e32 vcc, 0, v81
	v_and_b32_e32 v70, 0x7fffffff, v82
	v_exp_f32_e32 v69, v69
	v_cndmask_b32_e32 v65, v65, v71, vcc
	v_and_b32_e32 v71, 0x7fffffff, v83
	v_pk_fma_f32 v[70:71], v[70:71], s[38:39], 1.0 op_sel_hi:[1,0,0]
	v_cmp_gt_f32_e32 vcc, 0, v82
	v_rcp_f32_e32 v70, v70
	v_rcp_f32_e32 v71, v71
	v_pk_mul_f32 v[64:65], v[64:65], v[72:73]
	v_or_b32_e32 v96, 16, v98
	v_cvt_pk_bf16_f32 v64, v64, v65
	v_pk_fma_f32 v[66:67], v[70:71], s[62:63], v[66:67] op_sel_hi:[1,0,0]
	v_ashrrev_i32_e32 v97, 31, v96
	v_pk_fma_f32 v[66:67], v[70:71], v[66:67], s[66:67] op_sel_hi:[1,1,0]
	s_waitcnt vmcnt(5)
	v_or_b32_e32 v94, 32, v98
	v_pk_fma_f32 v[66:67], v[70:71], v[66:67], s[68:69] op_sel_hi:[1,1,0]
	v_ashrrev_i32_e32 v95, 31, v94
	v_pk_fma_f32 v[66:67], v[70:71], v[66:67], s[70:71] op_sel_hi:[1,1,0]
	v_or_b32_e32 v92, 48, v98
	v_pk_mul_f32 v[66:67], v[70:71], v[66:67]
	v_ashrrev_i32_e32 v93, 31, v92
	v_pk_mul_f32 v[66:67], v[68:69], v[66:67]
	s_and_b32 s14, s88, 7
	v_pk_mul_f32 v[68:69], v[82:83], v[66:67]
	v_pk_fma_f32 v[66:67], v[82:83], v[66:67], v[82:83] neg_lo:[1,0,0] neg_hi:[1,0,0]
	s_cmp_eq_u32 s14, 7
	v_cndmask_b32_e32 v66, v66, v68, vcc
	v_cmp_gt_f32_e32 vcc, 0, v83
	s_cselect_b64 s[14:15], -1, 0
	s_ashr_i32 s48, s88, 2
	v_cndmask_b32_e32 v67, v67, v69, vcc
	v_pk_mul_f32 v[66:67], v[66:67], v[74:75]
	s_and_b32 s48, s48, -2
	v_cvt_pk_bf16_f32 v65, v66, v67
	global_store_dwordx2 v[136:137], v[64:65], off offset:8 sc1
	v_lshl_add_u64 v[64:65], v[98:99], 2, s[42:43]
	global_load_dword v64, v[64:65], off
	s_add_i32 s75, s75, 2
	s_and_b64 s[14:15], s[26:27], s[14:15]
	v_add_u32_e32 v68, s48, v216
	s_and_b32 s48, s75, 31
	s_waitcnt vmcnt(5)
	v_mad_i64_i32 v[100:101], s[56:57], v68, s4, 0
	s_cmp_lg_u32 s48, 0
	s_cselect_b64 s[56:57], -1, 0
	s_and_b64 s[90:91], s[56:57], s[10:11]
	s_and_b64 s[88:89], s[14:15], s[10:11]
	s_mov_b64 s[14:15], -1
	s_waitcnt vmcnt(0)
	v_fmamk_f32 v64, v64, 0x3a800000, v218
	v_cmp_gt_f32_e32 vcc, s1, v64
	v_mul_f32_e32 v65, 0x4b800000, v64
	s_nop 0
	v_cndmask_b32_e32 v64, v64, v65, vcc
	v_rsq_f32_e32 v64, v64
	s_nop 0
	v_mul_f32_e32 v65, 0x45800000, v64
	v_cndmask_b32_e32 v102, v64, v65, vcc
	v_lshl_add_u64 v[64:65], v[96:97], 2, s[42:43]
	global_load_dword v88, v[64:65], off
	v_lshl_add_u64 v[64:65], v[94:95], 2, s[42:43]
	global_load_dword v95, v[64:65], off
	v_lshl_add_u64 v[64:65], v[92:93], 2, s[42:43]
	global_load_dword v64, v[64:65], off
	v_pk_mul_f32 v[62:63], v[62:63], v[102:103] op_sel_hi:[1,0]
	v_pk_mul_f32 v[60:61], v[60:61], v[102:103] op_sel_hi:[1,0]
	s_waitcnt vmcnt(0)
	v_fmamk_f32 v64, v64, 0x3a800000, v218
	v_cmp_gt_f32_e32 vcc, s1, v64
	v_mul_f32_e32 v65, 0x4b800000, v64
	s_nop 0
	v_cndmask_b32_e32 v64, v64, v65, vcc
	v_rsq_f32_e32 v64, v64
	s_nop 0
	v_mul_f32_e32 v65, 0x45800000, v64
	v_cndmask_b32_e32 v106, v64, v65, vcc
	v_lshl_add_u32 v64, s75, 1, v216
	v_mad_i64_i32 v[104:105], s[56:57], v64, s4, 0
	global_load_dwordx4 v[80:83], v[176:177], off
	global_load_dwordx4 v[68:71], v[192:193], off
	global_load_dwordx4 v[64:67], v[194:195], off
	global_load_dwordx4 v[84:87], v[178:179], off
	v_pk_mul_f32 v[58:59], v[58:59], v[106:107] op_sel_hi:[1,0]
	v_pk_mul_f32 v[56:57], v[56:57], v[106:107] op_sel_hi:[1,0]
	s_and_b64 vcc, exec, s[12:13]
	s_cbranch_vccnz .LBB0_1002
	v_mov_b32_e32 v72, 0
	v_mov_b32_e32 v73, 0
	v_mov_b32_e32 v74, 0
	v_mov_b32_e32 v75, 0
	s_and_saveexec_b64 s[14:15], s[90:91]
	s_cbranch_execz .LBB0_999
	v_lshl_add_u64 v[72:73], s[44:45], 0, v[104:105]
	v_ashrrev_i32_e32 v171, 31, v170
	v_lshl_add_u64 v[72:73], v[170:171], 2, v[72:73]
	global_load_dwordx4 v[72:75], v[72:73], off

; __device__ __forceinline__ unsigned cvt_pk_bf16(float lo, float hi) { unsigned r; asm volatile("v_cvt_pk_bf16_f32 %0, %1, %2" : "=v"(r) : "v"(lo), "v"(hi)); return r; }
;     __device__ __forceinline__ void operator()(const f32x4 (&acc)[2][2][4][2], const Unit& u, int wr, int wc, int fr, int fq) const {
;     ...
; #pragma unroll
;                     for (int m = 0; m < 4; ++m) {
;                         f32x4 cv;
;                         if (!samp) {
;                             const f32x4 prev = m ? v[m - 1] : hv;
; #pragma unroll
;                             for (int e = 0; e < 4; ++e) {
;                                 const int vi = __float_as_int(v[m][e]), pi = __float_as_int(prev[e]);
;                                 const int o1 = __builtin_amdgcn_mov_dpp(pi, 0x121, 0xf, 0xf, false);
;                                 const int o2 = __builtin_amdgcn_mov_dpp(pi, 0x122, 0xf, 0xf, false);
;                                 const float p1 = __int_as_float(__builtin_amdgcn_update_dpp(o1, vi, 0x111, 0xf, 0xf, false));
;                                 const float p2 = __int_as_float(__builtin_amdgcn_update_dpp(o2, vi, 0x112, 0xf, 0xf, false));
;                                 cv[e] = cb[e] + cw0[e] * p2 + cw1[e] * p1 + cw2[e] * v[m][e];
;                             }
;                         } else {
;                             const int ns = rowb + 16 * m + fr - MP;
;                             f32x4 s0 = (f32x4){0.f, 0.f, 0.f, 0.f}, s1 = s0;
;                             if (ns < NS) {
;                                 s0 = *(const f32x4*)(state + (size_t)(ns * 2 + 0) * FF2 + oc); s1 = *(const f32x4*)(state + (size_t)(ns * 2 + 1) * FF2 + oc);
;                                 *(f32x4*)(ncs + (size_t)(ns * 2 + 0) * FF2 + oc) = s1; *(f32x4*)(ncs + (size_t)(ns * 2 + 1) * FF2 + oc) = v[m];
;                             }
;                             cv = cb + cw0 * s0 + cw1 * s1 + cw2 * v[m];
;                         }
;                         if (bj == 0) cg[m] = gelu4(cv);
;                         else {
;                             const f32x4 r = cg[m] * cv;
;                             v2u w; w.x = cvt_pk_bf16(r[0], r[1]); w.y = cvt_pk_bf16(r[2], r[3]);
;                             *(v2u*)(ACT + (size_t)(rowb + 16 * m + fr) * FF + 128 * u.pn + 32 * wc + 8 * fq + 4 * n) = w;
;                         }
.LBB0_1034:
	s_waitcnt vmcnt(4)
	v_mov_b32_e32 v84, v110
	v_mov_b32_e32 v85, v110
	v_pk_mul_f32 v[38:39], v[38:39], v[84:85]
	v_and_b32_e32 v85, 0x7fffffff, v77
	v_and_b32_e32 v84, 0x7fffffff, v76
	v_pk_fma_f32 v[84:85], v[84:85], s[38:39], 1.0 op_sel_hi:[1,0,0]
	v_mov_b64_e32 v[86:87], s[64:65]
	v_rcp_f32_e32 v84, v84
	v_rcp_f32_e32 v85, v85
	v_pk_mul_f32 v[90:91], v[76:77], v[76:77]
	v_cmp_gt_f32_e32 vcc, 0, v76
	v_pk_mul_f32 v[90:91], v[90:91], s[72:73] op_sel_hi:[1,0]
	v_pk_fma_f32 v[88:89], v[84:85], s[62:63], v[86:87] op_sel_hi:[1,0,0]
	v_exp_f32_e32 v90, v90
	v_pk_fma_f32 v[88:89], v[84:85], v[88:89], s[66:67] op_sel_hi:[1,1,0]
	v_exp_f32_e32 v91, v91
	v_pk_fma_f32 v[88:89], v[84:85], v[88:89], s[68:69] op_sel_hi:[1,1,0]
	v_pk_mul_f32 v[36:37], v[36:37], v[110:111]
	v_pk_fma_f32 v[88:89], v[84:85], v[88:89], s[70:71] op_sel_hi:[1,1,0]
	s_nop 0
	v_pk_mul_f32 v[84:85], v[84:85], v[88:89]
	v_pk_mul_f32 v[88:89], v[78:79], v[78:79]
	v_pk_mul_f32 v[84:85], v[90:91], v[84:85]
	s_nop 0
	v_pk_mul_f32 v[90:91], v[76:77], v[84:85]
	v_pk_fma_f32 v[84:85], v[76:77], v[84:85], v[76:77] neg_lo:[1,0,0] neg_hi:[1,0,0]
	s_nop 0
	v_cndmask_b32_e32 v76, v84, v90, vcc
	v_cmp_gt_f32_e32 vcc, 0, v77
	v_and_b32_e32 v84, 0x7fffffff, v78
	s_nop 0
	v_cndmask_b32_e32 v77, v85, v91, vcc
	v_and_b32_e32 v85, 0x7fffffff, v79
	v_pk_fma_f32 v[84:85], v[84:85], s[38:39], 1.0 op_sel_hi:[1,0,0]
	v_cmp_gt_f32_e32 vcc, 0, v78
	v_rcp_f32_e32 v84, v84
	v_rcp_f32_e32 v85, v85
	v_pk_mul_f32 v[76:77], v[76:77], v[80:81]
	v_pk_fma_f32 v[86:87], v[84:85], s[62:63], v[86:87] op_sel_hi:[1,0,0]
	s_nop 0
	v_pk_fma_f32 v[86:87], v[84:85], v[86:87], s[66:67] op_sel_hi:[1,1,0]
	v_cvt_pk_bf16_f32 v76, v76, v77
	s_nop 0
	v_pk_fma_f32 v[86:87], v[84:85], v[86:87], s[68:69] op_sel_hi:[1,1,0]
	s_nop 0
	v_pk_fma_f32 v[86:87], v[84:85], v[86:87], s[70:71] op_sel_hi:[1,1,0]
	s_nop 0
	v_pk_mul_f32 v[84:85], v[84:85], v[86:87]
	v_pk_mul_f32 v[86:87], v[88:89], s[72:73] op_sel_hi:[1,0]
	s_nop 0
	v_exp_f32_e32 v86, v86
	v_exp_f32_e32 v87, v87
	s_nop 0
	v_pk_mul_f32 v[84:85], v[86:87], v[84:85]
	s_nop 0
	v_pk_mul_f32 v[86:87], v[78:79], v[84:85]
	v_pk_fma_f32 v[84:85], v[78:79], v[84:85], v[78:79] neg_lo:[1,0,0] neg_hi:[1,0,0]
	s_nop 0
	v_cndmask_b32_e32 v78, v84, v86, vcc
	v_cmp_gt_f32_e32 vcc, 0, v79
	s_nop 1
	v_cndmask_b32_e32 v79, v85, v87, vcc
	v_pk_mul_f32 v[78:79], v[78:79], v[82:83]
	s_and_b64 vcc, exec, s[12:13]
	v_cvt_pk_bf16_f32 v77, v78, v79
	v_mov_b64_e32 v[78:79], s[46:47]
	v_mad_i64_i32 v[78:79], s[14:15], v98, s34, v[78:79]
	v_lshl_add_u64 v[78:79], s[86:87], 1, v[78:79]
	v_lshl_add_u64 v[78:79], v[78:79], 0, s[24:25]
	v_lshl_add_u64 v[80:81], v[78:79], 0, v[168:169]
	s_mov_b64 s[14:15], -1
	global_store_dwordx2 v[80:81], v[76:77], off sc1
	s_cbranch_vccnz .LBB0_1036
	v_mov_b32_dpp v85, v47 row_ror:1 row_mask:0xf bank_mask:0xf
	v_mov_b32_dpp v76, v44 row_ror:1 row_mask:0xf bank_mask:0xf
	v_mov_b32_dpp v44, v44 row_ror:2 row_mask:0xf bank_mask:0xf
	v_mov_b32_dpp v77, v45 row_ror:1 row_mask:0xf bank_mask:0xf
	v_mov_b32_dpp v45, v45 row_ror:2 row_mask:0xf bank_mask:0xf
	v_mov_b32_dpp v78, v46 row_ror:1 row_mask:0xf bank_mask:0xf
	v_mov_b32_dpp v46, v46 row_ror:2 row_mask:0xf bank_mask:0xf
	v_mov_b32_dpp v47, v47 row_ror:2 row_mask:0xf bank_mask:0xf
	v_mov_b32_dpp v85, v39 row_shr:1 row_mask:0xf bank_mask:0xf
	v_mov_b32_e32 v86, v39
	s_waitcnt vmcnt(3)
	v_mov_b32_e32 v87, v63
	s_waitcnt vmcnt(2)
	v_mov_b32_e32 v84, v59
	v_mov_b32_dpp v44, v36 row_shr:2 row_mask:0xf bank_mask:0xf
	v_mov_b32_dpp v45, v37 row_shr:2 row_mask:0xf bank_mask:0xf
	v_mov_b32_dpp v78, v38 row_shr:1 row_mask:0xf bank_mask:0xf
	v_mov_b32_dpp v46, v38 row_shr:2 row_mask:0xf bank_mask:0xf
	v_mov_b32_dpp v47, v39 row_shr:2 row_mask:0xf bank_mask:0xf
	v_pk_mul_f32 v[84:85], v[86:87], v[84:85]
	v_mov_b32_dpp v76, v36 row_shr:1 row_mask:0xf bank_mask:0xf
	v_mov_b32_dpp v77, v37 row_shr:1 row_mask:0xf bank_mask:0xf
	v_mul_f32_e32 v78, v62, v78
	v_mov_b32_e32 v79, v85
	s_waitcnt vmcnt(1)
	v_pk_fma_f32 v[44:45], v[64:65], v[44:45], v[68:69]
	v_pk_fma_f32 v[46:47], v[66:67], v[46:47], v[70:71]
	v_mul_f32_e32 v82, v38, v58
	v_mov_b32_e32 v83, v84
	v_pk_add_f32 v[46:47], v[78:79], v[46:47]
	v_pk_fma_f32 v[44:45], v[60:61], v[76:77], v[44:45]
	v_pk_add_f32 v[78:79], v[82:83], v[46:47]
	v_pk_fma_f32 v[76:77], v[36:37], v[56:57], v[44:45]
	s_mov_b64 s[14:15], 0

; __device__ __forceinline__ unsigned cvt_pk_bf16(float lo, float hi) { unsigned r; asm volatile("v_cvt_pk_bf16_f32 %0, %1, %2" : "=v"(r) : "v"(lo), "v"(hi)); return r; }
;     __device__ __forceinline__ void operator()(const f32x4 (&acc)[2][2][4][2], const Unit& u, int wr, int wc, int fr, int fq) const {
;     ...
; #pragma unroll
;                     for (int m = 0; m < 4; ++m) {
;                         f32x4 cv;
;                         if (!samp) {
;                             const f32x4 prev = m ? v[m - 1] : hv;
; #pragma unroll
;                             for (int e = 0; e < 4; ++e) {
;                                 const int vi = __float_as_int(v[m][e]), pi = __float_as_int(prev[e]);
;                                 const int o1 = __builtin_amdgcn_mov_dpp(pi, 0x121, 0xf, 0xf, false);
;                                 const int o2 = __builtin_amdgcn_mov_dpp(pi, 0x122, 0xf, 0xf, false);
;                                 const float p1 = __int_as_float(__builtin_amdgcn_update_dpp(o1, vi, 0x111, 0xf, 0xf, false));
;                                 const float p2 = __int_as_float(__builtin_amdgcn_update_dpp(o2, vi, 0x112, 0xf, 0xf, false));
;                                 cv[e] = cb[e] + cw0[e] * p2 + cw1[e] * p1 + cw2[e] * v[m][e];
;                             }
;                         } else {
;                             const int ns = rowb + 16 * m + fr - MP;
;                             f32x4 s0 = (f32x4){0.f, 0.f, 0.f, 0.f}, s1 = s0;
;                             if (ns < NS) {
;                                 s0 = *(const f32x4*)(state + (size_t)(ns * 2 + 0) * FF2 + oc); s1 = *(const f32x4*)(state + (size_t)(ns * 2 + 1) * FF2 + oc);
;                                 *(f32x4*)(ncs + (size_t)(ns * 2 + 0) * FF2 + oc) = s1; *(f32x4*)(ncs + (size_t)(ns * 2 + 1) * FF2 + oc) = v[m];
;                             }
;                             cv = cb + cw0 * s0 + cw1 * s1 + cw2 * v[m];
;                         }
;                         if (bj == 0) cg[m] = gelu4(cv);
;                         else {
;                             const f32x4 r = cg[m] * cv;
;                             v2u w; w.x = cvt_pk_bf16(r[0], r[1]); w.y = cvt_pk_bf16(r[2], r[3]);
;                             *(v2u*)(ACT + (size_t)(rowb + 16 * m + fr) * FF + 128 * u.pn + 32 * wc + 8 * fq + 4 * n) = w;
;                         }
.LBB0_1040:
	v_mov_b32_e32 v44, v108
	v_mov_b32_e32 v45, v108
	v_pk_mul_f32 v[34:35], v[34:35], v[44:45]
	v_and_b32_e32 v45, 0x7fffffff, v73
	v_and_b32_e32 v44, 0x7fffffff, v72
	v_pk_fma_f32 v[44:45], v[44:45], s[38:39], 1.0 op_sel_hi:[1,0,0]
	v_mov_b64_e32 v[46:47], s[64:65]
	v_rcp_f32_e32 v44, v44
	v_rcp_f32_e32 v45, v45
	v_pk_mul_f32 v[84:85], v[72:73], v[72:73]
	v_cmp_gt_f32_e32 vcc, 0, v72
	v_pk_mul_f32 v[84:85], v[84:85], s[72:73] op_sel_hi:[1,0]
	v_pk_fma_f32 v[82:83], v[44:45], s[62:63], v[46:47] op_sel_hi:[1,0,0]
	v_exp_f32_e32 v84, v84
	v_pk_fma_f32 v[82:83], v[44:45], v[82:83], s[66:67] op_sel_hi:[1,1,0]
	v_exp_f32_e32 v85, v85
	v_pk_fma_f32 v[82:83], v[44:45], v[82:83], s[68:69] op_sel_hi:[1,1,0]
	v_pk_mul_f32 v[32:33], v[32:33], v[108:109]
	v_pk_fma_f32 v[82:83], v[44:45], v[82:83], s[70:71] op_sel_hi:[1,1,0]
	s_nop 0
	v_pk_mul_f32 v[44:45], v[44:45], v[82:83]
	v_pk_mul_f32 v[82:83], v[74:75], v[74:75]
	v_pk_mul_f32 v[44:45], v[84:85], v[44:45]
	s_nop 0
	v_pk_mul_f32 v[84:85], v[72:73], v[44:45]
	v_pk_fma_f32 v[44:45], v[72:73], v[44:45], v[72:73] neg_lo:[1,0,0] neg_hi:[1,0,0]
	v_and_b32_e32 v72, 0x7fffffff, v74
	v_cndmask_b32_e32 v44, v44, v84, vcc
	v_cmp_gt_f32_e32 vcc, 0, v73
	v_and_b32_e32 v73, 0x7fffffff, v75
	v_pk_fma_f32 v[72:73], v[72:73], s[38:39], 1.0 op_sel_hi:[1,0,0]
	v_cndmask_b32_e32 v45, v45, v85, vcc
	v_rcp_f32_e32 v72, v72
	v_rcp_f32_e32 v73, v73
	v_cmp_gt_f32_e32 vcc, 0, v74
	v_pk_mul_f32 v[44:45], v[44:45], v[76:77]
	v_pk_fma_f32 v[46:47], v[72:73], s[62:63], v[46:47] op_sel_hi:[1,0,0]
	s_nop 0
	v_pk_fma_f32 v[46:47], v[72:73], v[46:47], s[66:67] op_sel_hi:[1,1,0]
	v_cvt_pk_bf16_f32 v44, v44, v45
	s_nop 0
	v_pk_fma_f32 v[46:47], v[72:73], v[46:47], s[68:69] op_sel_hi:[1,1,0]
	s_nop 0
	v_pk_fma_f32 v[46:47], v[72:73], v[46:47], s[70:71] op_sel_hi:[1,1,0]
	s_nop 0
	v_pk_mul_f32 v[46:47], v[72:73], v[46:47]
	v_pk_mul_f32 v[72:73], v[82:83], s[72:73] op_sel_hi:[1,0]
	s_nop 0
	v_exp_f32_e32 v72, v72
	v_exp_f32_e32 v73, v73
	s_nop 0
	v_pk_mul_f32 v[46:47], v[72:73], v[46:47]
	s_nop 0
	v_pk_mul_f32 v[72:73], v[74:75], v[46:47]
	v_pk_fma_f32 v[46:47], v[74:75], v[46:47], v[74:75] neg_lo:[1,0,0] neg_hi:[1,0,0]
	s_nop 0
	v_cndmask_b32_e32 v46, v46, v72, vcc
	v_cmp_gt_f32_e32 vcc, 0, v75
	s_nop 1
	v_cndmask_b32_e32 v47, v47, v73, vcc
	v_pk_mul_f32 v[46:47], v[46:47], v[78:79]
	s_and_b64 vcc, exec, s[12:13]
	v_cvt_pk_bf16_f32 v45, v46, v47
	v_mov_b64_e32 v[46:47], s[46:47]
	v_mad_i64_i32 v[46:47], s[14:15], v96, s34, v[46:47]
	v_lshl_add_u64 v[46:47], s[86:87], 1, v[46:47]
	v_lshl_add_u64 v[46:47], v[46:47], 0, s[24:25]
	v_lshl_add_u64 v[72:73], v[46:47], 0, v[168:169]
	s_mov_b64 s[14:15], -1
	global_store_dwordx2 v[72:73], v[44:45], off sc1
	s_cbranch_vccnz .LBB0_1042
	v_mov_b32_dpp v77, v39 row_ror:1 row_mask:0xf bank_mask:0xf
	v_mov_b32_dpp v44, v36 row_ror:1 row_mask:0xf bank_mask:0xf
	v_mov_b32_dpp v36, v36 row_ror:2 row_mask:0xf bank_mask:0xf
	v_mov_b32_dpp v45, v37 row_ror:1 row_mask:0xf bank_mask:0xf
	v_mov_b32_dpp v37, v37 row_ror:2 row_mask:0xf bank_mask:0xf
	v_mov_b32_dpp v46, v38 row_ror:1 row_mask:0xf bank_mask:0xf
	v_mov_b32_dpp v38, v38 row_ror:2 row_mask:0xf bank_mask:0xf
	v_mov_b32_dpp v39, v39 row_ror:2 row_mask:0xf bank_mask:0xf
	v_mov_b32_dpp v77, v35 row_shr:1 row_mask:0xf bank_mask:0xf
	v_mov_b32_e32 v78, v35
	s_waitcnt vmcnt(4)
	v_mov_b32_e32 v79, v63
	s_waitcnt vmcnt(3)
	v_mov_b32_e32 v76, v59
	v_mov_b32_dpp v36, v32 row_shr:2 row_mask:0xf bank_mask:0xf
	v_mov_b32_dpp v37, v33 row_shr:2 row_mask:0xf bank_mask:0xf
	v_mov_b32_dpp v46, v34 row_shr:1 row_mask:0xf bank_mask:0xf
	v_mov_b32_dpp v38, v34 row_shr:2 row_mask:0xf bank_mask:0xf
	v_mov_b32_dpp v39, v35 row_shr:2 row_mask:0xf bank_mask:0xf
	v_pk_mul_f32 v[76:77], v[78:79], v[76:77]
	v_mov_b32_dpp v44, v32 row_shr:1 row_mask:0xf bank_mask:0xf
	v_mov_b32_dpp v45, v33 row_shr:1 row_mask:0xf bank_mask:0xf
	v_mul_f32_e32 v46, v62, v46
	v_mov_b32_e32 v47, v77
	s_waitcnt vmcnt(2)
	v_pk_fma_f32 v[36:37], v[64:65], v[36:37], v[68:69]
	v_pk_fma_f32 v[38:39], v[66:67], v[38:39], v[70:71]
	v_mul_f32_e32 v74, v34, v58
	v_mov_b32_e32 v75, v76
	v_pk_add_f32 v[38:39], v[46:47], v[38:39]
	v_pk_fma_f32 v[36:37], v[60:61], v[44:45], v[36:37]
	v_pk_add_f32 v[46:47], v[74:75], v[38:39]
	v_pk_fma_f32 v[44:45], v[32:33], v[56:57], v[36:37]
	s_mov_b64 s[14:15], 0

; __device__ __forceinline__ unsigned cvt_pk_bf16(float lo, float hi) { unsigned r; asm volatile("v_cvt_pk_bf16_f32 %0, %1, %2" : "=v"(r) : "v"(lo), "v"(hi)); return r; }
;     __device__ __forceinline__ void operator()(const f32x4 (&acc)[2][2][4][2], const Unit& u, int wr, int wc, int fr, int fq) const {
;     ...
; #pragma unroll
;                     for (int m = 0; m < 4; ++m) {
;                         f32x4 cv;
;                         if (!samp) {
;                             const f32x4 prev = m ? v[m - 1] : hv;
; #pragma unroll
;                             for (int e = 0; e < 4; ++e) {
;                                 const int vi = __float_as_int(v[m][e]), pi = __float_as_int(prev[e]);
;                                 const int o1 = __builtin_amdgcn_mov_dpp(pi, 0x121, 0xf, 0xf, false);
;                                 const int o2 = __builtin_amdgcn_mov_dpp(pi, 0x122, 0xf, 0xf, false);
;                                 const float p1 = __int_as_float(__builtin_amdgcn_update_dpp(o1, vi, 0x111, 0xf, 0xf, false));
;                                 const float p2 = __int_as_float(__builtin_amdgcn_update_dpp(o2, vi, 0x112, 0xf, 0xf, false));
;                                 cv[e] = cb[e] + cw0[e] * p2 + cw1[e] * p1 + cw2[e] * v[m][e];
;                             }
;                         } else {
;                             const int ns = rowb + 16 * m + fr - MP;
;                             f32x4 s0 = (f32x4){0.f, 0.f, 0.f, 0.f}, s1 = s0;
;                             if (ns < NS) {
;                                 s0 = *(const f32x4*)(state + (size_t)(ns * 2 + 0) * FF2 + oc); s1 = *(const f32x4*)(state + (size_t)(ns * 2 + 1) * FF2 + oc);
;                                 *(f32x4*)(ncs + (size_t)(ns * 2 + 0) * FF2 + oc) = s1; *(f32x4*)(ncs + (size_t)(ns * 2 + 1) * FF2 + oc) = v[m];
;                             }
;                             cv = cb + cw0 * s0 + cw1 * s1 + cw2 * v[m];
;                         }
;                         if (bj == 0) cg[m] = gelu4(cv);
;                         else {
;                             const f32x4 r = cg[m] * cv;
;                             v2u w; w.x = cvt_pk_bf16(r[0], r[1]); w.y = cvt_pk_bf16(r[2], r[3]);
;                             *(v2u*)(ACT + (size_t)(rowb + 16 * m + fr) * FF + 128 * u.pn + 32 * wc + 8 * fq + 4 * n) = w;
;                         }
.LBB0_1046:
	v_and_b32_e32 v37, 0x7fffffff, v53
	v_and_b32_e32 v36, 0x7fffffff, v52
	v_pk_fma_f32 v[36:37], v[36:37], s[38:39], 1.0 op_sel_hi:[1,0,0]
	v_mov_b64_e32 v[38:39], s[64:65]
	v_rcp_f32_e32 v36, v36
	v_rcp_f32_e32 v37, v37
	v_pk_mul_f32 v[76:77], v[52:53], v[52:53]
	v_cmp_gt_f32_e32 vcc, 0, v52
	v_pk_mul_f32 v[76:77], v[76:77], s[72:73] op_sel_hi:[1,0]
	v_pk_fma_f32 v[74:75], v[36:37], s[62:63], v[38:39] op_sel_hi:[1,0,0]
	v_exp_f32_e32 v76, v76
	v_pk_fma_f32 v[74:75], v[36:37], v[74:75], s[66:67] op_sel_hi:[1,1,0]
	v_exp_f32_e32 v77, v77
	v_pk_fma_f32 v[74:75], v[36:37], v[74:75], s[68:69] op_sel_hi:[1,1,0]
	s_nop 0
	v_pk_fma_f32 v[74:75], v[36:37], v[74:75], s[70:71] op_sel_hi:[1,1,0]
	s_nop 0
	v_pk_mul_f32 v[36:37], v[36:37], v[74:75]
	v_pk_mul_f32 v[74:75], v[54:55], v[54:55]
	v_pk_mul_f32 v[36:37], v[76:77], v[36:37]
	s_nop 0
	v_pk_mul_f32 v[76:77], v[52:53], v[36:37]
	v_pk_fma_f32 v[36:37], v[52:53], v[36:37], v[52:53] neg_lo:[1,0,0] neg_hi:[1,0,0]
	v_and_b32_e32 v52, 0x7fffffff, v54
	v_cndmask_b32_e32 v36, v36, v76, vcc
	v_cmp_gt_f32_e32 vcc, 0, v53
	v_and_b32_e32 v53, 0x7fffffff, v55
	v_pk_fma_f32 v[52:53], v[52:53], s[38:39], 1.0 op_sel_hi:[1,0,0]
	v_cndmask_b32_e32 v37, v37, v77, vcc
	v_rcp_f32_e32 v52, v52
	v_rcp_f32_e32 v53, v53
	v_cmp_gt_f32_e32 vcc, 0, v54
	v_pk_mul_f32 v[36:37], v[36:37], v[44:45]
	v_pk_fma_f32 v[38:39], v[52:53], s[62:63], v[38:39] op_sel_hi:[1,0,0]
	s_nop 0
	v_pk_fma_f32 v[38:39], v[52:53], v[38:39], s[66:67] op_sel_hi:[1,1,0]
	v_cvt_pk_bf16_f32 v36, v36, v37
	s_nop 0
	v_pk_fma_f32 v[38:39], v[52:53], v[38:39], s[68:69] op_sel_hi:[1,1,0]
	s_nop 0
	v_pk_fma_f32 v[38:39], v[52:53], v[38:39], s[70:71] op_sel_hi:[1,1,0]
	s_nop 0
	v_pk_mul_f32 v[38:39], v[52:53], v[38:39]
	v_pk_mul_f32 v[52:53], v[74:75], s[72:73] op_sel_hi:[1,0]
	s_nop 0
	v_exp_f32_e32 v52, v52
	v_exp_f32_e32 v53, v53
	s_nop 0
	v_pk_mul_f32 v[38:39], v[52:53], v[38:39]
	s_nop 0
	v_pk_mul_f32 v[52:53], v[54:55], v[38:39]
	v_pk_fma_f32 v[38:39], v[54:55], v[38:39], v[54:55] neg_lo:[1,0,0] neg_hi:[1,0,0]
	s_nop 0
	v_cndmask_b32_e32 v38, v38, v52, vcc
	v_cmp_gt_f32_e32 vcc, 0, v55
	s_nop 1
	v_cndmask_b32_e32 v39, v39, v53, vcc
	v_pk_mul_f32 v[38:39], v[38:39], v[46:47]
	s_and_b64 vcc, exec, s[12:13]
	v_cvt_pk_bf16_f32 v37, v38, v39
	v_mov_b64_e32 v[38:39], s[46:47]
	v_mad_i64_i32 v[38:39], s[14:15], v94, s34, v[38:39]
	v_lshl_add_u64 v[38:39], s[86:87], 1, v[38:39]
	v_lshl_add_u64 v[38:39], v[38:39], 0, s[24:25]
	v_lshl_add_u64 v[74:75], v[38:39], 0, v[168:169]
	s_mov_b64 s[14:15], -1
	global_store_dwordx2 v[74:75], v[36:37], off sc1
	s_cbranch_vccnz .LBB0_1048
	v_mov_b32_dpp v47, v35 row_ror:1 row_mask:0xf bank_mask:0xf
	v_mov_b32_dpp v36, v32 row_ror:1 row_mask:0xf bank_mask:0xf
	v_mov_b32_dpp v32, v32 row_ror:2 row_mask:0xf bank_mask:0xf
	v_mov_b32_dpp v37, v33 row_ror:1 row_mask:0xf bank_mask:0xf
	v_mov_b32_dpp v33, v33 row_ror:2 row_mask:0xf bank_mask:0xf
	v_mov_b32_dpp v38, v34 row_ror:1 row_mask:0xf bank_mask:0xf
	v_mov_b32_dpp v34, v34 row_ror:2 row_mask:0xf bank_mask:0xf
	v_mov_b32_dpp v35, v35 row_ror:2 row_mask:0xf bank_mask:0xf
	v_mov_b32_dpp v47, v43 row_shr:1 row_mask:0xf bank_mask:0xf
	v_mov_b32_e32 v52, v43
	s_waitcnt vmcnt(5)
	v_mov_b32_e32 v53, v63
	s_waitcnt vmcnt(4)
	v_mov_b32_e32 v46, v59
	v_mov_b32_dpp v32, v40 row_shr:2 row_mask:0xf bank_mask:0xf
	v_mov_b32_dpp v33, v41 row_shr:2 row_mask:0xf bank_mask:0xf
	v_mov_b32_dpp v38, v42 row_shr:1 row_mask:0xf bank_mask:0xf
	v_mov_b32_dpp v34, v42 row_shr:2 row_mask:0xf bank_mask:0xf
	v_mov_b32_dpp v35, v43 row_shr:2 row_mask:0xf bank_mask:0xf
	v_pk_mul_f32 v[46:47], v[52:53], v[46:47]
	v_mov_b32_dpp v36, v40 row_shr:1 row_mask:0xf bank_mask:0xf
	v_mov_b32_dpp v37, v41 row_shr:1 row_mask:0xf bank_mask:0xf
	v_mul_f32_e32 v38, v62, v38
	v_mov_b32_e32 v39, v47
	s_waitcnt vmcnt(3)
	v_pk_fma_f32 v[32:33], v[64:65], v[32:33], v[68:69]
	v_pk_fma_f32 v[34:35], v[66:67], v[34:35], v[70:71]
	v_mul_f32_e32 v44, v42, v58
	v_mov_b32_e32 v45, v46
	v_pk_add_f32 v[34:35], v[38:39], v[34:35]
	v_pk_fma_f32 v[32:33], v[60:61], v[36:37], v[32:33]
	v_pk_add_f32 v[38:39], v[44:45], v[34:35]
	v_pk_fma_f32 v[36:37], v[40:41], v[56:57], v[32:33]
	s_mov_b64 s[14:15], 0

;     __device__ __forceinline__ void operator()(const f32x4 (&acc)[2][2][4][2], const Unit& u, int wr, int wc, int fr, int fq) const {
;     ...
;                     const f32x4 cw0 = *(const f32x4*)(convw + oc), cw1 = *(const f32x4*)(convw + FF2 + oc), cw2 = *(const f32x4*)(convw + 2 * FF2 + oc), cb = *(const f32x4*)(convb + oc);
;                     f32x4 v[4];
; #pragma unroll
;                     for (int m = 0; m < 4; ++m) v[m] = acc[ai][bj][m][n] * rs[m];
;                     f32x4 hv = (f32x4){0.f, 0.f, 0.f, 0.f};
;                     if (!samp) {
;                         if ((blk & 31) != 0 && fr >= 14) hv = *(const f32x4*)(HALO + (size_t)(2 * blk + fr - 14) * FF2 + cgc);
;                         if ((u.pm & 7) == 7 && ai == 1 && wr == 1 && fr >= 14) *(f32x4*)(ncp + (size_t)((u.pm >> 3) * 2 + (fr - 14)) * FF2 + oc) = v[3];
;                     }
; #pragma unroll
;                     for (int m = 0; m < 4; ++m) {
;                         f32x4 cv;
;                         if (!samp) {
;                             const f32x4 prev = m ? v[m - 1] : hv;
; #pragma unroll
;                             for (int e = 0; e < 4; ++e) {
;                                 const int vi = __float_as_int(v[m][e]), pi = __float_as_int(prev[e]);
;                                 const int o1 = __builtin_amdgcn_mov_dpp(pi, 0x121, 0xf, 0xf, false);
;                                 const int o2 = __builtin_amdgcn_mov_dpp(pi, 0x122, 0xf, 0xf, false);
;                                 const float p1 = __int_as_float(__builtin_amdgcn_update_dpp(o1, vi, 0x111, 0xf, 0xf, false));
;                                 const float p2 = __int_as_float(__builtin_amdgcn_update_dpp(o2, vi, 0x112, 0xf, 0xf, false));
;                                 cv[e] = cb[e] + cw0[e] * p2 + cw1[e] * p1 + cw2[e] * v[m][e];
;                             }
;                         } else {
;                             const int ns = rowb + 16 * m + fr - MP;
;                             f32x4 s0 = (f32x4){0.f, 0.f, 0.f, 0.f}, s1 = s0;
;                             if (ns < NS) {
;                                 s0 = *(const f32x4*)(state + (size_t)(ns * 2 + 0) * FF2 + oc); s1 = *(const f32x4*)(state + (size_t)(ns * 2 + 1) * FF2 + oc);
;                                 *(f32x4*)(ncs + (size_t)(ns * 2 + 0) * FF2 + oc) = s1; *(f32x4*)(ncs + (size_t)(ns * 2 + 1) * FF2 + oc) = v[m];
.LBB0_1052:
	v_and_b32_e32 v33, 0x7fffffff, v49
	v_and_b32_e32 v32, 0x7fffffff, v48
	v_pk_fma_f32 v[32:33], v[32:33], s[38:39], 1.0 op_sel_hi:[1,0,0]
	v_mov_b64_e32 v[34:35], s[64:65]
	v_rcp_f32_e32 v32, v32
	v_rcp_f32_e32 v33, v33
	v_pk_mul_f32 v[42:43], v[48:49], v[48:49]
	v_cmp_gt_f32_e32 vcc, 0, v48
	v_pk_mul_f32 v[42:43], v[42:43], s[72:73] op_sel_hi:[1,0]
	v_pk_fma_f32 v[40:41], v[32:33], s[62:63], v[34:35] op_sel_hi:[1,0,0]
	v_exp_f32_e32 v42, v42
	v_pk_fma_f32 v[40:41], v[32:33], v[40:41], s[66:67] op_sel_hi:[1,1,0]
	v_exp_f32_e32 v43, v43
	v_pk_fma_f32 v[40:41], v[32:33], v[40:41], s[68:69] op_sel_hi:[1,1,0]
	v_pk_mul_f32 v[28:29], v[28:29], v[102:103]
	v_pk_fma_f32 v[40:41], v[32:33], v[40:41], s[70:71] op_sel_hi:[1,1,0]
	v_pk_mul_f32 v[24:25], v[24:25], v[106:107]
	v_pk_mul_f32 v[32:33], v[32:33], v[40:41]
	v_pk_mul_f32 v[40:41], v[50:51], v[50:51]
	v_pk_mul_f32 v[32:33], v[42:43], v[32:33]
	v_pk_mul_f32 v[40:41], v[40:41], s[72:73] op_sel_hi:[1,0]
	v_pk_mul_f32 v[42:43], v[48:49], v[32:33]
	v_pk_fma_f32 v[32:33], v[48:49], v[32:33], v[48:49] neg_lo:[1,0,0] neg_hi:[1,0,0]
	v_exp_f32_e32 v40, v40
	v_cndmask_b32_e32 v32, v32, v42, vcc
	v_cmp_gt_f32_e32 vcc, 0, v49
	v_and_b32_e32 v42, 0x7fffffff, v50
	v_exp_f32_e32 v41, v41
	v_cndmask_b32_e32 v33, v33, v43, vcc
	v_and_b32_e32 v43, 0x7fffffff, v51
	v_pk_fma_f32 v[42:43], v[42:43], s[38:39], 1.0 op_sel_hi:[1,0,0]
	v_cmp_gt_f32_e32 vcc, 0, v50
	v_rcp_f32_e32 v42, v42
	v_rcp_f32_e32 v43, v43
	v_pk_mul_f32 v[32:33], v[32:33], v[36:37]
	v_pk_fma_f32 v[34:35], v[42:43], s[62:63], v[34:35] op_sel_hi:[1,0,0]
	s_nop 0
	v_pk_fma_f32 v[34:35], v[42:43], v[34:35], s[66:67] op_sel_hi:[1,1,0]
	v_cvt_pk_bf16_f32 v32, v32, v33
	s_nop 0
	v_pk_fma_f32 v[34:35], v[42:43], v[34:35], s[68:69] op_sel_hi:[1,1,0]
	s_nop 0
	v_pk_fma_f32 v[34:35], v[42:43], v[34:35], s[70:71] op_sel_hi:[1,1,0]
	s_nop 0
	v_pk_mul_f32 v[34:35], v[42:43], v[34:35]
	s_nop 0
	v_pk_mul_f32 v[34:35], v[40:41], v[34:35]
	s_nop 0
	v_pk_mul_f32 v[40:41], v[50:51], v[34:35]
	v_pk_fma_f32 v[34:35], v[50:51], v[34:35], v[50:51] neg_lo:[1,0,0] neg_hi:[1,0,0]
	s_nop 0
	v_cndmask_b32_e32 v34, v34, v40, vcc
	v_cmp_gt_f32_e32 vcc, 0, v51
	v_mov_b32_e32 v40, v102
	s_nop 0
	v_cndmask_b32_e32 v35, v35, v41, vcc
	v_pk_mul_f32 v[34:35], v[34:35], v[38:39]
	v_mov_b32_e32 v41, v102
	v_cvt_pk_bf16_f32 v33, v34, v35
	v_mov_b64_e32 v[34:35], s[46:47]
	v_mad_i64_i32 v[34:35], s[14:15], v92, s34, v[34:35]
	v_lshl_add_u64 v[34:35], s[86:87], 1, v[34:35]
	v_lshl_add_u64 v[34:35], v[34:35], 0, s[24:25]
	s_waitcnt vmcnt(5)
	v_lshl_add_u64 v[60:61], v[34:35], 0, v[168:169]
	global_store_dwordx2 v[60:61], v[32:33], off sc1
	global_load_dwordx4 v[48:51], v[176:177], off offset:16
	global_load_dwordx4 v[36:39], v[132:133], off
	global_load_dwordx4 v[32:35], v[134:135], off
	global_load_dwordx4 v[52:55], v[178:179], off offset:16
	v_pk_mul_f32 v[30:31], v[30:31], v[40:41]
	v_mov_b32_e32 v40, v106
	v_mov_b32_e32 v41, v106
	v_pk_mul_f32 v[26:27], v[26:27], v[40:41]
	s_mov_b64 s[14:15], -1
	s_and_b64 vcc, exec, s[12:13]
	s_cbranch_vccnz .LBB0_1058
	v_mov_b32_e32 v40, 0
	v_mov_b32_e32 v41, 0
	v_mov_b32_e32 v42, 0
	v_mov_b32_e32 v43, 0
	s_and_saveexec_b64 s[14:15], s[90:91]
	s_cbranch_execz .LBB0_1055
	v_lshl_add_u64 v[40:41], s[44:45], 0, v[104:105]
	v_ashrrev_i32_e32 v171, 31, v170
	v_lshl_add_u64 v[40:41], v[170:171], 2, v[40:41]
	global_load_dwordx4 v[40:43], v[40:41], off offset:16

; __device__ __forceinline__ unsigned cvt_pk_bf16(float lo, float hi) { unsigned r; asm volatile("v_cvt_pk_bf16_f32 %0, %1, %2" : "=v"(r) : "v"(lo), "v"(hi)); return r; }
;     __device__ __forceinline__ void operator()(const f32x4 (&acc)[2][2][4][2], const Unit& u, int wr, int wc, int fr, int fq) const {
;     ...
; #pragma unroll
;                     for (int m = 0; m < 4; ++m) {
;                         f32x4 cv;
;                         if (!samp) {
;                             const f32x4 prev = m ? v[m - 1] : hv;
; #pragma unroll
;                             for (int e = 0; e < 4; ++e) {
;                                 const int vi = __float_as_int(v[m][e]), pi = __float_as_int(prev[e]);
;                                 const int o1 = __builtin_amdgcn_mov_dpp(pi, 0x121, 0xf, 0xf, false);
;                                 const int o2 = __builtin_amdgcn_mov_dpp(pi, 0x122, 0xf, 0xf, false);
;                                 const float p1 = __int_as_float(__builtin_amdgcn_update_dpp(o1, vi, 0x111, 0xf, 0xf, false));
;                                 const float p2 = __int_as_float(__builtin_amdgcn_update_dpp(o2, vi, 0x112, 0xf, 0xf, false));
;                                 cv[e] = cb[e] + cw0[e] * p2 + cw1[e] * p1 + cw2[e] * v[m][e];
;                             }
;                         } else {
;                             const int ns = rowb + 16 * m + fr - MP;
;                             f32x4 s0 = (f32x4){0.f, 0.f, 0.f, 0.f}, s1 = s0;
;                             if (ns < NS) {
;                                 s0 = *(const f32x4*)(state + (size_t)(ns * 2 + 0) * FF2 + oc); s1 = *(const f32x4*)(state + (size_t)(ns * 2 + 1) * FF2 + oc);
;                                 *(f32x4*)(ncs + (size_t)(ns * 2 + 0) * FF2 + oc) = s1; *(f32x4*)(ncs + (size_t)(ns * 2 + 1) * FF2 + oc) = v[m];
;                             }
;                             cv = cb + cw0 * s0 + cw1 * s1 + cw2 * v[m];
;                         }
;                         if (bj == 0) cg[m] = gelu4(cv);
;                         else {
;                             const f32x4 r = cg[m] * cv;
;                             v2u w; w.x = cvt_pk_bf16(r[0], r[1]); w.y = cvt_pk_bf16(r[2], r[3]);
;                             *(v2u*)(ACT + (size_t)(rowb + 16 * m + fr) * FF + 128 * u.pn + 32 * wc + 8 * fq + 4 * n) = w;
;                         }
.LBB0_1090:
	s_waitcnt vmcnt(4)
	v_mov_b32_e32 v52, v110
	v_mov_b32_e32 v53, v110
	v_pk_mul_f32 v[6:7], v[6:7], v[52:53]
	v_and_b32_e32 v53, 0x7fffffff, v45
	v_and_b32_e32 v52, 0x7fffffff, v44
	v_pk_fma_f32 v[52:53], v[52:53], s[38:39], 1.0 op_sel_hi:[1,0,0]
	v_mov_b64_e32 v[54:55], s[64:65]
	v_rcp_f32_e32 v52, v52
	v_rcp_f32_e32 v53, v53
	v_pk_mul_f32 v[58:59], v[44:45], v[44:45]
	v_cmp_gt_f32_e32 vcc, 0, v44
	v_pk_mul_f32 v[58:59], v[58:59], s[72:73] op_sel_hi:[1,0]
	v_pk_fma_f32 v[56:57], v[52:53], s[62:63], v[54:55] op_sel_hi:[1,0,0]
	v_exp_f32_e32 v58, v58
	v_pk_fma_f32 v[56:57], v[52:53], v[56:57], s[66:67] op_sel_hi:[1,1,0]
	v_exp_f32_e32 v59, v59
	v_pk_fma_f32 v[56:57], v[52:53], v[56:57], s[68:69] op_sel_hi:[1,1,0]
	v_pk_mul_f32 v[4:5], v[4:5], v[110:111]
	v_pk_fma_f32 v[56:57], v[52:53], v[56:57], s[70:71] op_sel_hi:[1,1,0]
	s_mov_b64 s[14:15], -1
	v_pk_mul_f32 v[52:53], v[52:53], v[56:57]
	v_pk_mul_f32 v[56:57], v[46:47], v[46:47]
	v_pk_mul_f32 v[52:53], v[58:59], v[52:53]
	s_nop 0
	v_pk_mul_f32 v[58:59], v[44:45], v[52:53]
	v_pk_fma_f32 v[52:53], v[44:45], v[52:53], v[44:45] neg_lo:[1,0,0] neg_hi:[1,0,0]
	s_nop 0
	v_cndmask_b32_e32 v44, v52, v58, vcc
	v_cmp_gt_f32_e32 vcc, 0, v45
	v_and_b32_e32 v52, 0x7fffffff, v46
	s_nop 0
	v_cndmask_b32_e32 v45, v53, v59, vcc
	v_and_b32_e32 v53, 0x7fffffff, v47
	v_pk_fma_f32 v[52:53], v[52:53], s[38:39], 1.0 op_sel_hi:[1,0,0]
	v_cmp_gt_f32_e32 vcc, 0, v46
	v_rcp_f32_e32 v52, v52
	v_rcp_f32_e32 v53, v53
	v_pk_mul_f32 v[44:45], v[44:45], v[48:49]
	v_pk_fma_f32 v[54:55], v[52:53], s[62:63], v[54:55] op_sel_hi:[1,0,0]
	s_nop 0
	v_pk_fma_f32 v[54:55], v[52:53], v[54:55], s[66:67] op_sel_hi:[1,1,0]
	v_cvt_pk_bf16_f32 v44, v44, v45
	s_nop 0
	v_pk_fma_f32 v[54:55], v[52:53], v[54:55], s[68:69] op_sel_hi:[1,1,0]
	s_nop 0
	v_pk_fma_f32 v[54:55], v[52:53], v[54:55], s[70:71] op_sel_hi:[1,1,0]
	s_nop 0
	v_pk_mul_f32 v[52:53], v[52:53], v[54:55]
	v_pk_mul_f32 v[54:55], v[56:57], s[72:73] op_sel_hi:[1,0]
	s_nop 0
	v_exp_f32_e32 v54, v54
	v_exp_f32_e32 v55, v55
	s_nop 0
	v_pk_mul_f32 v[52:53], v[54:55], v[52:53]
	s_nop 0
	v_pk_mul_f32 v[54:55], v[46:47], v[52:53]
	v_pk_fma_f32 v[52:53], v[46:47], v[52:53], v[46:47] neg_lo:[1,0,0] neg_hi:[1,0,0]
	s_nop 0
	v_cndmask_b32_e32 v46, v52, v54, vcc
	v_cmp_gt_f32_e32 vcc, 0, v47
	s_nop 1
	v_cndmask_b32_e32 v47, v53, v55, vcc
	v_pk_mul_f32 v[46:47], v[46:47], v[50:51]
	s_and_b64 vcc, exec, s[12:13]
	v_cvt_pk_bf16_f32 v45, v46, v47
	global_store_dwordx2 v[80:81], v[44:45], off offset:8 sc1
	s_cbranch_vccnz .LBB0_1092
	v_mov_b32_dpp v51, v15 row_ror:1 row_mask:0xf bank_mask:0xf
	v_mov_b32_dpp v44, v12 row_ror:1 row_mask:0xf bank_mask:0xf
	v_mov_b32_dpp v12, v12 row_ror:2 row_mask:0xf bank_mask:0xf
	v_mov_b32_dpp v45, v13 row_ror:1 row_mask:0xf bank_mask:0xf
	v_mov_b32_dpp v13, v13 row_ror:2 row_mask:0xf bank_mask:0xf
	v_mov_b32_dpp v46, v14 row_ror:1 row_mask:0xf bank_mask:0xf
	v_mov_b32_dpp v14, v14 row_ror:2 row_mask:0xf bank_mask:0xf
	v_mov_b32_dpp v15, v15 row_ror:2 row_mask:0xf bank_mask:0xf
	v_mov_b32_dpp v51, v7 row_shr:1 row_mask:0xf bank_mask:0xf
	v_mov_b32_e32 v52, v7
	s_waitcnt vmcnt(3)
	v_mov_b32_e32 v53, v31
	s_waitcnt vmcnt(2)
	v_mov_b32_e32 v50, v27
	v_mov_b32_dpp v12, v4 row_shr:2 row_mask:0xf bank_mask:0xf
	v_mov_b32_dpp v13, v5 row_shr:2 row_mask:0xf bank_mask:0xf
	v_mov_b32_dpp v46, v6 row_shr:1 row_mask:0xf bank_mask:0xf
	v_mov_b32_dpp v14, v6 row_shr:2 row_mask:0xf bank_mask:0xf
	v_mov_b32_dpp v15, v7 row_shr:2 row_mask:0xf bank_mask:0xf
	v_pk_mul_f32 v[50:51], v[52:53], v[50:51]
	v_mov_b32_dpp v44, v4 row_shr:1 row_mask:0xf bank_mask:0xf
	v_mov_b32_dpp v45, v5 row_shr:1 row_mask:0xf bank_mask:0xf
	v_mul_f32_e32 v46, v30, v46
	v_mov_b32_e32 v47, v51
	s_waitcnt vmcnt(1)
	v_pk_fma_f32 v[12:13], v[32:33], v[12:13], v[36:37]
	v_pk_fma_f32 v[14:15], v[34:35], v[14:15], v[38:39]
	v_mul_f32_e32 v48, v6, v26
	v_mov_b32_e32 v49, v50
	v_pk_add_f32 v[14:15], v[46:47], v[14:15]
	v_pk_fma_f32 v[12:13], v[28:29], v[44:45], v[12:13]
	v_pk_add_f32 v[46:47], v[48:49], v[14:15]
	v_pk_fma_f32 v[44:45], v[4:5], v[24:25], v[12:13]
	s_mov_b64 s[14:15], 0

; __device__ __forceinline__ unsigned cvt_pk_bf16(float lo, float hi) { unsigned r; asm volatile("v_cvt_pk_bf16_f32 %0, %1, %2" : "=v"(r) : "v"(lo), "v"(hi)); return r; }
;     __device__ __forceinline__ void operator()(const f32x4 (&acc)[2][2][4][2], const Unit& u, int wr, int wc, int fr, int fq) const {
;     ...
; #pragma unroll
;                     for (int m = 0; m < 4; ++m) {
;                         f32x4 cv;
;                         if (!samp) {
;                             const f32x4 prev = m ? v[m - 1] : hv;
; #pragma unroll
;                             for (int e = 0; e < 4; ++e) {
;                                 const int vi = __float_as_int(v[m][e]), pi = __float_as_int(prev[e]);
;                                 const int o1 = __builtin_amdgcn_mov_dpp(pi, 0x121, 0xf, 0xf, false);
;                                 const int o2 = __builtin_amdgcn_mov_dpp(pi, 0x122, 0xf, 0xf, false);
;                                 const float p1 = __int_as_float(__builtin_amdgcn_update_dpp(o1, vi, 0x111, 0xf, 0xf, false));
;                                 const float p2 = __int_as_float(__builtin_amdgcn_update_dpp(o2, vi, 0x112, 0xf, 0xf, false));
;                                 cv[e] = cb[e] + cw0[e] * p2 + cw1[e] * p1 + cw2[e] * v[m][e];
;                             }
;                         } else {
;                             const int ns = rowb + 16 * m + fr - MP;
;                             f32x4 s0 = (f32x4){0.f, 0.f, 0.f, 0.f}, s1 = s0;
;                             if (ns < NS) {
;                                 s0 = *(const f32x4*)(state + (size_t)(ns * 2 + 0) * FF2 + oc); s1 = *(const f32x4*)(state + (size_t)(ns * 2 + 1) * FF2 + oc);
;                                 *(f32x4*)(ncs + (size_t)(ns * 2 + 0) * FF2 + oc) = s1; *(f32x4*)(ncs + (size_t)(ns * 2 + 1) * FF2 + oc) = v[m];
;                             }
;                             cv = cb + cw0 * s0 + cw1 * s1 + cw2 * v[m];
;                         }
;                         if (bj == 0) cg[m] = gelu4(cv);
;                         else {
;                             const f32x4 r = cg[m] * cv;
;                             v2u w; w.x = cvt_pk_bf16(r[0], r[1]); w.y = cvt_pk_bf16(r[2], r[3]);
;                             *(v2u*)(ACT + (size_t)(rowb + 16 * m + fr) * FF + 128 * u.pn + 32 * wc + 8 * fq + 4 * n) = w;
;                         }
.LBB0_1096:
	v_mov_b32_e32 v12, v108
	v_mov_b32_e32 v13, v108
	v_pk_mul_f32 v[2:3], v[2:3], v[12:13]
	v_and_b32_e32 v13, 0x7fffffff, v41
	v_and_b32_e32 v12, 0x7fffffff, v40
	v_pk_fma_f32 v[12:13], v[12:13], s[38:39], 1.0 op_sel_hi:[1,0,0]
	v_mov_b64_e32 v[14:15], s[64:65]
	v_rcp_f32_e32 v12, v12
	v_rcp_f32_e32 v13, v13
	v_pk_mul_f32 v[50:51], v[40:41], v[40:41]
	v_cmp_gt_f32_e32 vcc, 0, v40
	v_pk_mul_f32 v[50:51], v[50:51], s[72:73] op_sel_hi:[1,0]
	v_pk_fma_f32 v[48:49], v[12:13], s[62:63], v[14:15] op_sel_hi:[1,0,0]
	v_exp_f32_e32 v50, v50
	v_pk_fma_f32 v[48:49], v[12:13], v[48:49], s[66:67] op_sel_hi:[1,1,0]
	v_exp_f32_e32 v51, v51
	v_pk_fma_f32 v[48:49], v[12:13], v[48:49], s[68:69] op_sel_hi:[1,1,0]
	v_pk_mul_f32 v[0:1], v[0:1], v[108:109]
	v_pk_fma_f32 v[48:49], v[12:13], v[48:49], s[70:71] op_sel_hi:[1,1,0]
	s_mov_b64 s[14:15], -1
	v_pk_mul_f32 v[12:13], v[12:13], v[48:49]
	v_pk_mul_f32 v[48:49], v[42:43], v[42:43]
	v_pk_mul_f32 v[12:13], v[50:51], v[12:13]
	s_nop 0
	v_pk_mul_f32 v[50:51], v[40:41], v[12:13]
	v_pk_fma_f32 v[12:13], v[40:41], v[12:13], v[40:41] neg_lo:[1,0,0] neg_hi:[1,0,0]
	v_and_b32_e32 v40, 0x7fffffff, v42
	v_cndmask_b32_e32 v12, v12, v50, vcc
	v_cmp_gt_f32_e32 vcc, 0, v41
	v_and_b32_e32 v41, 0x7fffffff, v43
	v_pk_fma_f32 v[40:41], v[40:41], s[38:39], 1.0 op_sel_hi:[1,0,0]
	v_cndmask_b32_e32 v13, v13, v51, vcc
	v_rcp_f32_e32 v40, v40
	v_rcp_f32_e32 v41, v41
	v_cmp_gt_f32_e32 vcc, 0, v42
	v_pk_mul_f32 v[12:13], v[12:13], v[44:45]
	v_pk_fma_f32 v[14:15], v[40:41], s[62:63], v[14:15] op_sel_hi:[1,0,0]
	s_nop 0
	v_pk_fma_f32 v[14:15], v[40:41], v[14:15], s[66:67] op_sel_hi:[1,1,0]
	v_cvt_pk_bf16_f32 v12, v12, v13
	s_nop 0
	v_pk_fma_f32 v[14:15], v[40:41], v[14:15], s[68:69] op_sel_hi:[1,1,0]
	s_nop 0
	v_pk_fma_f32 v[14:15], v[40:41], v[14:15], s[70:71] op_sel_hi:[1,1,0]
	s_nop 0
	v_pk_mul_f32 v[14:15], v[40:41], v[14:15]
	v_pk_mul_f32 v[40:41], v[48:49], s[72:73] op_sel_hi:[1,0]
	s_nop 0
	v_exp_f32_e32 v40, v40
	v_exp_f32_e32 v41, v41
	s_nop 0
	v_pk_mul_f32 v[14:15], v[40:41], v[14:15]
	s_nop 0
	v_pk_mul_f32 v[40:41], v[42:43], v[14:15]
	v_pk_fma_f32 v[14:15], v[42:43], v[14:15], v[42:43] neg_lo:[1,0,0] neg_hi:[1,0,0]
	s_nop 0
	v_cndmask_b32_e32 v14, v14, v40, vcc
	v_cmp_gt_f32_e32 vcc, 0, v43
	s_nop 1
	v_cndmask_b32_e32 v15, v15, v41, vcc
	v_pk_mul_f32 v[14:15], v[14:15], v[46:47]
	s_and_b64 vcc, exec, s[12:13]
	v_cvt_pk_bf16_f32 v13, v14, v15
	global_store_dwordx2 v[72:73], v[12:13], off offset:8 sc1
	s_cbranch_vccnz .LBB0_1098
	v_mov_b32_dpp v43, v7 row_ror:1 row_mask:0xf bank_mask:0xf
	v_mov_b32_dpp v12, v4 row_ror:1 row_mask:0xf bank_mask:0xf
	v_mov_b32_dpp v4, v4 row_ror:2 row_mask:0xf bank_mask:0xf
	v_mov_b32_dpp v13, v5 row_ror:1 row_mask:0xf bank_mask:0xf
	v_mov_b32_dpp v5, v5 row_ror:2 row_mask:0xf bank_mask:0xf
	v_mov_b32_dpp v14, v6 row_ror:1 row_mask:0xf bank_mask:0xf
	v_mov_b32_dpp v6, v6 row_ror:2 row_mask:0xf bank_mask:0xf
	v_mov_b32_dpp v7, v7 row_ror:2 row_mask:0xf bank_mask:0xf
	v_mov_b32_dpp v43, v3 row_shr:1 row_mask:0xf bank_mask:0xf
	v_mov_b32_e32 v44, v3
	s_waitcnt vmcnt(4)
	v_mov_b32_e32 v45, v31
	s_waitcnt vmcnt(3)
	v_mov_b32_e32 v42, v27
	v_mov_b32_dpp v4, v0 row_shr:2 row_mask:0xf bank_mask:0xf
	v_mov_b32_dpp v5, v1 row_shr:2 row_mask:0xf bank_mask:0xf
	v_mov_b32_dpp v14, v2 row_shr:1 row_mask:0xf bank_mask:0xf
	v_mov_b32_dpp v6, v2 row_shr:2 row_mask:0xf bank_mask:0xf
	v_mov_b32_dpp v7, v3 row_shr:2 row_mask:0xf bank_mask:0xf
	v_pk_mul_f32 v[42:43], v[44:45], v[42:43]
	v_mov_b32_dpp v12, v0 row_shr:1 row_mask:0xf bank_mask:0xf
	v_mov_b32_dpp v13, v1 row_shr:1 row_mask:0xf bank_mask:0xf
	v_mul_f32_e32 v14, v30, v14
	v_mov_b32_e32 v15, v43
	s_waitcnt vmcnt(2)
	v_pk_fma_f32 v[4:5], v[32:33], v[4:5], v[36:37]
	v_pk_fma_f32 v[6:7], v[34:35], v[6:7], v[38:39]
	v_mul_f32_e32 v40, v2, v26
	v_mov_b32_e32 v41, v42
	v_pk_add_f32 v[6:7], v[14:15], v[6:7]
	v_pk_fma_f32 v[4:5], v[28:29], v[12:13], v[4:5]
	v_pk_add_f32 v[14:15], v[40:41], v[6:7]
	v_pk_fma_f32 v[12:13], v[0:1], v[24:25], v[4:5]
	s_mov_b64 s[14:15], 0

; __device__ __forceinline__ unsigned cvt_pk_bf16(float lo, float hi) { unsigned r; asm volatile("v_cvt_pk_bf16_f32 %0, %1, %2" : "=v"(r) : "v"(lo), "v"(hi)); return r; }
;     __device__ __forceinline__ void operator()(const f32x4 (&acc)[2][2][4][2], const Unit& u, int wr, int wc, int fr, int fq) const {
;     ...
; #pragma unroll
;                     for (int m = 0; m < 4; ++m) {
;                         f32x4 cv;
;                         if (!samp) {
;                             const f32x4 prev = m ? v[m - 1] : hv;
; #pragma unroll
;                             for (int e = 0; e < 4; ++e) {
;                                 const int vi = __float_as_int(v[m][e]), pi = __float_as_int(prev[e]);
;                                 const int o1 = __builtin_amdgcn_mov_dpp(pi, 0x121, 0xf, 0xf, false);
;                                 const int o2 = __builtin_amdgcn_mov_dpp(pi, 0x122, 0xf, 0xf, false);
;                                 const float p1 = __int_as_float(__builtin_amdgcn_update_dpp(o1, vi, 0x111, 0xf, 0xf, false));
;                                 const float p2 = __int_as_float(__builtin_amdgcn_update_dpp(o2, vi, 0x112, 0xf, 0xf, false));
;                                 cv[e] = cb[e] + cw0[e] * p2 + cw1[e] * p1 + cw2[e] * v[m][e];
;                             }
;                         } else {
;                             const int ns = rowb + 16 * m + fr - MP;
;                             f32x4 s0 = (f32x4){0.f, 0.f, 0.f, 0.f}, s1 = s0;
;                             if (ns < NS) {
;                                 s0 = *(const f32x4*)(state + (size_t)(ns * 2 + 0) * FF2 + oc); s1 = *(const f32x4*)(state + (size_t)(ns * 2 + 1) * FF2 + oc);
;                                 *(f32x4*)(ncs + (size_t)(ns * 2 + 0) * FF2 + oc) = s1; *(f32x4*)(ncs + (size_t)(ns * 2 + 1) * FF2 + oc) = v[m];
;                             }
;                             cv = cb + cw0 * s0 + cw1 * s1 + cw2 * v[m];
;                         }
;                         if (bj == 0) cg[m] = gelu4(cv);
;                         else {
;                             const f32x4 r = cg[m] * cv;
;                             v2u w; w.x = cvt_pk_bf16(r[0], r[1]); w.y = cvt_pk_bf16(r[2], r[3]);
;                             *(v2u*)(ACT + (size_t)(rowb + 16 * m + fr) * FF + 128 * u.pn + 32 * wc + 8 * fq + 4 * n) = w;
;                         }
.LBB0_1102:
	v_and_b32_e32 v5, 0x7fffffff, v21
	v_and_b32_e32 v4, 0x7fffffff, v20
	v_pk_fma_f32 v[4:5], v[4:5], s[38:39], 1.0 op_sel_hi:[1,0,0]
	v_mov_b64_e32 v[6:7], s[64:65]
	v_rcp_f32_e32 v4, v4
	v_rcp_f32_e32 v5, v5
	v_pk_mul_f32 v[42:43], v[20:21], v[20:21]
	v_cmp_gt_f32_e32 vcc, 0, v20
	v_pk_mul_f32 v[42:43], v[42:43], s[72:73] op_sel_hi:[1,0]
	v_pk_fma_f32 v[40:41], v[4:5], s[62:63], v[6:7] op_sel_hi:[1,0,0]
	v_exp_f32_e32 v42, v42
	v_pk_fma_f32 v[40:41], v[4:5], v[40:41], s[66:67] op_sel_hi:[1,1,0]
	v_exp_f32_e32 v43, v43
	v_pk_fma_f32 v[40:41], v[4:5], v[40:41], s[68:69] op_sel_hi:[1,1,0]
	s_mov_b64 s[14:15], -1
	v_pk_fma_f32 v[40:41], v[4:5], v[40:41], s[70:71] op_sel_hi:[1,1,0]
	s_nop 0
	v_pk_mul_f32 v[4:5], v[4:5], v[40:41]
	v_pk_mul_f32 v[40:41], v[22:23], v[22:23]
	v_pk_mul_f32 v[4:5], v[42:43], v[4:5]
	s_nop 0
	v_pk_mul_f32 v[42:43], v[20:21], v[4:5]
	v_pk_fma_f32 v[4:5], v[20:21], v[4:5], v[20:21] neg_lo:[1,0,0] neg_hi:[1,0,0]
	v_and_b32_e32 v20, 0x7fffffff, v22
	v_cndmask_b32_e32 v4, v4, v42, vcc
	v_cmp_gt_f32_e32 vcc, 0, v21
	v_and_b32_e32 v21, 0x7fffffff, v23
	v_pk_fma_f32 v[20:21], v[20:21], s[38:39], 1.0 op_sel_hi:[1,0,0]
	v_cndmask_b32_e32 v5, v5, v43, vcc
	v_rcp_f32_e32 v20, v20
	v_rcp_f32_e32 v21, v21
	v_cmp_gt_f32_e32 vcc, 0, v22
	v_pk_mul_f32 v[4:5], v[4:5], v[12:13]
	v_pk_fma_f32 v[6:7], v[20:21], s[62:63], v[6:7] op_sel_hi:[1,0,0]
	s_nop 0
	v_pk_fma_f32 v[6:7], v[20:21], v[6:7], s[66:67] op_sel_hi:[1,1,0]
	v_cvt_pk_bf16_f32 v4, v4, v5
	s_nop 0
	v_pk_fma_f32 v[6:7], v[20:21], v[6:7], s[68:69] op_sel_hi:[1,1,0]
	s_nop 0
	v_pk_fma_f32 v[6:7], v[20:21], v[6:7], s[70:71] op_sel_hi:[1,1,0]
	s_nop 0
	v_pk_mul_f32 v[6:7], v[20:21], v[6:7]
	v_pk_mul_f32 v[20:21], v[40:41], s[72:73] op_sel_hi:[1,0]
	s_nop 0
	v_exp_f32_e32 v20, v20
	v_exp_f32_e32 v21, v21
	s_nop 0
	v_pk_mul_f32 v[6:7], v[20:21], v[6:7]
	s_nop 0
	v_pk_mul_f32 v[20:21], v[22:23], v[6:7]
	v_pk_fma_f32 v[6:7], v[22:23], v[6:7], v[22:23] neg_lo:[1,0,0] neg_hi:[1,0,0]
	s_nop 0
	v_cndmask_b32_e32 v6, v6, v20, vcc
	v_cmp_gt_f32_e32 vcc, 0, v23
	s_nop 1
	v_cndmask_b32_e32 v7, v7, v21, vcc
	v_pk_mul_f32 v[6:7], v[6:7], v[14:15]
	s_and_b64 vcc, exec, s[12:13]
	v_cvt_pk_bf16_f32 v5, v6, v7
	global_store_dwordx2 v[74:75], v[4:5], off offset:8 sc1
	s_cbranch_vccnz .LBB0_1104
	v_mov_b32_dpp v15, v3 row_ror:1 row_mask:0xf bank_mask:0xf
	v_mov_b32_dpp v4, v0 row_ror:1 row_mask:0xf bank_mask:0xf
	v_mov_b32_dpp v0, v0 row_ror:2 row_mask:0xf bank_mask:0xf
	v_mov_b32_dpp v5, v1 row_ror:1 row_mask:0xf bank_mask:0xf
	v_mov_b32_dpp v1, v1 row_ror:2 row_mask:0xf bank_mask:0xf
	v_mov_b32_dpp v6, v2 row_ror:1 row_mask:0xf bank_mask:0xf
	v_mov_b32_dpp v2, v2 row_ror:2 row_mask:0xf bank_mask:0xf
	v_mov_b32_dpp v3, v3 row_ror:2 row_mask:0xf bank_mask:0xf
	v_mov_b32_dpp v15, v11 row_shr:1 row_mask:0xf bank_mask:0xf
	v_mov_b32_e32 v20, v11
	s_waitcnt vmcnt(5)
	v_mov_b32_e32 v21, v31
	s_waitcnt vmcnt(4)
	v_mov_b32_e32 v14, v27
	v_mov_b32_dpp v0, v8 row_shr:2 row_mask:0xf bank_mask:0xf
	v_mov_b32_dpp v1, v9 row_shr:2 row_mask:0xf bank_mask:0xf
	v_mov_b32_dpp v6, v10 row_shr:1 row_mask:0xf bank_mask:0xf
	v_mov_b32_dpp v2, v10 row_shr:2 row_mask:0xf bank_mask:0xf
	v_mov_b32_dpp v3, v11 row_shr:2 row_mask:0xf bank_mask:0xf
	v_pk_mul_f32 v[14:15], v[20:21], v[14:15]
	v_mov_b32_dpp v4, v8 row_shr:1 row_mask:0xf bank_mask:0xf
	v_mov_b32_dpp v5, v9 row_shr:1 row_mask:0xf bank_mask:0xf
	v_mul_f32_e32 v6, v30, v6
	v_mov_b32_e32 v7, v15
	s_waitcnt vmcnt(3)
	v_pk_fma_f32 v[0:1], v[32:33], v[0:1], v[36:37]
	v_pk_fma_f32 v[2:3], v[34:35], v[2:3], v[38:39]
	v_mul_f32_e32 v12, v10, v26
	v_mov_b32_e32 v13, v14
	v_pk_add_f32 v[2:3], v[6:7], v[2:3]
	v_pk_fma_f32 v[0:1], v[28:29], v[4:5], v[0:1]
	v_pk_add_f32 v[6:7], v[12:13], v[2:3]
	v_pk_fma_f32 v[4:5], v[8:9], v[24:25], v[0:1]
	s_mov_b64 s[14:15], 0

; __device__ __forceinline__ unsigned cvt_pk_bf16(float lo, float hi) { unsigned r; asm volatile("v_cvt_pk_bf16_f32 %0, %1, %2" : "=v"(r) : "v"(lo), "v"(hi)); return r; }
; __device__ __forceinline__ f32x4 gelu4(f32x4 v) { f32x2 a = gelu_pk((f32x2){v[0], v[1]}), b = gelu_pk((f32x2){v[2], v[3]}); return (f32x4){a.x, a.y, b.x, b.y}; }
;     __device__ __forceinline__ void operator()(const f32x4 (&acc)[2][2][4][2], const Unit& u, int wr, int wc, int fr, int fq) const {
;     ...
;                         if (bj == 0) cg[m] = gelu4(cv);
;                         else {
;                             const f32x4 r = cg[m] * cv;
;                             v2u w; w.x = cvt_pk_bf16(r[0], r[1]); w.y = cvt_pk_bf16(r[2], r[3]);
;                             *(v2u*)(ACT + (size_t)(rowb + 16 * m + fr) * FF + 128 * u.pn + 32 * wc + 8 * fq + 4 * n) = w;
;                         }
;     __device__ __forceinline__ void done(const Unit& u) const {
;         if (done_pm == -2 || (done_pm >= 0 && u.pm != done_pm)) return;
;         asm volatile("s_waitcnt vmcnt(0)" ::: "memory");
;         asm volatile("" ::: "memory"); __builtin_amdgcn_s_barrier(); asm volatile("" ::: "memory");
;         if (threadIdx.x < 64) {
;             if (done_rel) { __builtin_amdgcn_fence(__ATOMIC_RELEASE, "agent"); asm volatile("s_waitcnt vmcnt(0)" ::: "memory"); }
;             if (threadIdx.x == 0) __hip_atomic_fetch_add(done_ctr, 1u, __ATOMIC_RELAXED, __HIP_MEMORY_SCOPE_AGENT);
;         }
.LBB0_1108:
	v_and_b32_e32 v9, 0x7fffffff, v19
	v_and_b32_e32 v8, 0x7fffffff, v18
	v_pk_fma_f32 v[8:9], v[8:9], s[38:39], 1.0 op_sel_hi:[1,0,0]
	v_pk_mul_f32 v[0:1], v[18:19], v[18:19]
	v_rcp_f32_e32 v8, v8
	v_rcp_f32_e32 v9, v9
	v_mov_b64_e32 v[10:11], s[64:65]
	v_pk_mul_f32 v[0:1], v[0:1], s[72:73] op_sel_hi:[1,0]
	v_cmp_gt_f32_e32 vcc, 0, v19
	v_pk_fma_f32 v[12:13], v[8:9], s[62:63], v[10:11] op_sel_hi:[1,0,0]
	v_exp_f32_e32 v0, v0
	v_exp_f32_e32 v1, v1
	v_pk_fma_f32 v[12:13], v[8:9], v[12:13], s[66:67] op_sel_hi:[1,1,0]
	v_pk_mul_f32 v[2:3], v[16:17], v[16:17]
	v_pk_fma_f32 v[12:13], v[8:9], v[12:13], s[68:69] op_sel_hi:[1,1,0]
	v_pk_mul_f32 v[2:3], v[2:3], s[72:73] op_sel_hi:[1,0]
	v_pk_fma_f32 v[12:13], v[8:9], v[12:13], s[70:71] op_sel_hi:[1,1,0]
	v_exp_f32_e32 v2, v2
	v_pk_mul_f32 v[8:9], v[8:9], v[12:13]
	v_exp_f32_e32 v3, v3
	v_pk_mul_f32 v[0:1], v[0:1], v[8:9]
	s_nop 0
	v_pk_mul_f32 v[8:9], v[18:19], v[0:1]
	v_pk_fma_f32 v[0:1], v[18:19], v[0:1], v[18:19] neg_lo:[1,0,0] neg_hi:[1,0,0]
	s_nop 0
	v_cndmask_b32_e32 v1, v1, v9, vcc
	v_cmp_gt_f32_e32 vcc, 0, v18
	v_and_b32_e32 v9, 0x7fffffff, v17
	s_nop 0
	v_cndmask_b32_e32 v0, v0, v8, vcc
	v_and_b32_e32 v8, 0x7fffffff, v16
	v_pk_fma_f32 v[8:9], v[8:9], s[38:39], 1.0 op_sel_hi:[1,0,0]
	v_cmp_gt_f32_e32 vcc, 0, v17
	v_rcp_f32_e32 v8, v8
	v_rcp_f32_e32 v9, v9
	v_pk_mul_f32 v[0:1], v[0:1], v[6:7]
	v_pk_fma_f32 v[10:11], v[8:9], s[62:63], v[10:11] op_sel_hi:[1,0,0]
	s_nop 0
	v_pk_fma_f32 v[10:11], v[8:9], v[10:11], s[66:67] op_sel_hi:[1,1,0]
	s_nop 0
	v_pk_fma_f32 v[10:11], v[8:9], v[10:11], s[68:69] op_sel_hi:[1,1,0]
	s_nop 0
	v_pk_fma_f32 v[10:11], v[8:9], v[10:11], s[70:71] op_sel_hi:[1,1,0]
	s_nop 0
	v_pk_mul_f32 v[8:9], v[8:9], v[10:11]
	s_nop 0
	v_pk_mul_f32 v[2:3], v[2:3], v[8:9]
	s_nop 0
	v_pk_mul_f32 v[8:9], v[16:17], v[2:3]
	v_pk_fma_f32 v[2:3], v[16:17], v[2:3], v[16:17] neg_lo:[1,0,0] neg_hi:[1,0,0]
	s_nop 0
	v_cndmask_b32_e32 v3, v3, v9, vcc
	v_cmp_gt_f32_e32 vcc, 0, v16
	s_nop 1
	v_cndmask_b32_e32 v2, v2, v8, vcc
	v_pk_mul_f32 v[2:3], v[2:3], v[4:5]
	s_andn2_b64 vcc, exec, s[84:85]
	v_cvt_pk_bf16_f32 v2, v2, v3
	v_cvt_pk_bf16_f32 v3, v0, v1
	global_store_dwordx2 v[60:61], v[2:3], off offset:8 sc1
	s_cbranch_vccnz .LBB0_1114
	s_waitcnt vmcnt(0)
	s_barrier
	s_and_saveexec_b64 s[12:13], s[8:9]
	s_cbranch_execz .LBB0_1113
	s_waitcnt vmcnt(0)
	s_waitcnt vmcnt(0)
	s_and_b64 exec, exec, s[90:91]
	s_cbranch_execz .LBB0_1113
	s_mov_b64 s[14:15], exec
	v_mbcnt_lo_u32_b32 v0, s14, 0
	v_mbcnt_hi_u32_b32 v0, s15, v0
	v_cmp_eq_u32_e32 vcc, 0, v0
	s_and_b64 s[56:57], exec, vcc
	s_mov_b64 exec, s[56:57]
	s_cbranch_execz .LBB0_1113
	s_bcnt1_i32_b64 s14, s[14:15]
	v_mov_b32_e32 v0, s14
	v_readlane_b32 s14, v236, 17
	v_readlane_b32 s15, v236, 18
	s_nop 4
	global_atomic_add v169, v0, s[14:15]

;     __device__ __forceinline__ void operator()(const f32x4 (&acc)[2][2][4][2], const Unit& u, int wr, int wc, int fr, int fq) const {
;     ...
;             const int rowb = u.pm * 256 + ai * 128 + wr * 64;
;             const int blk = 4 * u.pm + 2 * ai + wr;
;             float rs[4];
; #pragma unroll
;             for (int m = 0; m < 4; ++m) rs[m] = rsqrtf(SS[rowb + 16 * m + fr] * (1.0f / D) + EPS);
; #pragma unroll
;             for (int n = 0; n < 2; ++n) {
;                 f32x4 cg[4];
; #pragma unroll
;                 for (int bj = 0; bj < 2; ++bj) {
;                     const int oc = (bj ? FF : 0) + 128 * u.pn + 32 * wc + 8 * fq + 4 * n;
;                     const int cgc = 256 * u.pn + 128 * bj + 32 * wc + 8 * fq + 4 * n;
;                     const f32x4 cw0 = *(const f32x4*)(convw + oc), cw1 = *(const f32x4*)(convw + FF2 + oc), cw2 = *(const f32x4*)(convw + 2 * FF2 + oc), cb = *(const f32x4*)(convb + oc);
.Lfe_begin:
	v_readlane_b32 s13, v236, 19
	s_lshl_b32 s77, s88, 8
	s_lshl_b32 s89, s12, 7
	s_lshl_b32 s75, s88, 2
	s_add_i32 s75, s75, s73
	s_add_i32 s77, s77, s13
	v_add_u32_e32 v246, s77, v153
	v_lshlrev_b32_e32 v247, 2, v246
	global_load_dword v238, v247, s[42:43]
	global_load_dword v239, v247, s[42:43] offset:64
	global_load_dword v240, v247, s[42:43] offset:128
	global_load_dword v241, v247, s[42:43] offset:192
	global_load_dword v242, v247, s[42:43] offset:512
	global_load_dword v243, v247, s[42:43] offset:576
	global_load_dword v244, v247, s[42:43] offset:640
	global_load_dword v245, v247, s[42:43] offset:704
	v_add_u32_e32 v248, s89, v215
	v_lshlrev_b32_e32 v237, 2, v248
	v_add_u32_e32 v250, 0x2c00, v237
	global_load_dwordx4 v[170:173], v237, s[16:17]
	global_load_dwordx4 v[174:177], v237, s[16:17] offset:16
	global_load_dwordx4 v[178:181], v250, s[16:17]
	global_load_dwordx4 v[182:185], v250, s[16:17] offset:16
	global_load_dwordx4 v[186:189], v237, s[58:59]
	global_load_dwordx4 v[190:193], v237, s[58:59] offset:16
	global_load_dwordx4 v[194:197], v250, s[58:59]
	global_load_dwordx4 v[198:201], v250, s[58:59] offset:16
	global_load_dwordx4 v[202:205], v237, s[60:61]
	global_load_dwordx4 v[206:209], v237, s[60:61] offset:16
	global_load_dwordx4 v[210:213], v250, s[60:61]
	global_load_dwordx4 v[128:131], v250, s[60:61] offset:16
	global_load_dwordx4 v[132:135], v237, s[18:19]
	global_load_dwordx4 v[136:139], v237, s[18:19] offset:16
	global_load_dwordx4 v[140:143], v250, s[18:19]
	global_load_dwordx4 v[144:147], v250, s[18:19] offset:16
	v_mul_u32_u24_e32 v151, 0x1600, v246
	v_lshl_add_u32 v151, v248, 1, v151
	v_mov_b32_e32 v219, s64
	v_mov_b32_e32 v220, 0
	v_mov_b32_e32 v221, 0
	v_mov_b32_e32 v222, 0
	v_mov_b32_e32 v223, 0
	v_mov_b32_e32 v224, 0
	v_mov_b32_e32 v225, 0
	v_mov_b32_e32 v226, 0
	v_mov_b32_e32 v227, 0
	v_mov_b32_e32 v228, 0
	v_mov_b32_e32 v229, 0
	v_mov_b32_e32 v230, 0
	v_mov_b32_e32 v231, 0
	v_mov_b32_e32 v232, 0
	v_mov_b32_e32 v233, 0
	v_mov_b32_e32 v234, 0
	v_mov_b32_e32 v235, 0
	s_mul_i32 s56, s75, 0xb000
	s_lshl_b32 s57, s12, 10
	s_add_i32 s56, s56, s57
	v_mul_i32_i24_e32 v150, 0x5800, v216
	v_lshl_add_u32 v150, v215, 2, v150
	v_add_u32_e32 v150, s56, v150
	s_waitcnt vmcnt(16)
	v_fmamk_f32 v238, v238, 0x3a800000, v218
	v_fmamk_f32 v239, v239, 0x3a800000, v218
	v_fmamk_f32 v240, v240, 0x3a800000, v218
	v_fmamk_f32 v241, v241, 0x3a800000, v218
	v_fmamk_f32 v242, v242, 0x3a800000, v218
	v_fmamk_f32 v243, v243, 0x3a800000, v218
	v_fmamk_f32 v244, v244, 0x3a800000, v218
	v_fmamk_f32 v245, v245, 0x3a800000, v218
	v_rsq_f32_e32 v238, v238
	v_rsq_f32_e32 v239, v239
	v_rsq_f32_e32 v240, v240
	v_rsq_f32_e32 v241, v241
	v_rsq_f32_e32 v242, v242
	v_rsq_f32_e32 v243, v243
	v_rsq_f32_e32 v244, v244
	v_rsq_f32_e32 v245, v245
	v_pk_mul_f32 v[124:125], v[124:125], v[238:239] op_sel_hi:[1,0]
	v_pk_mul_f32 v[126:127], v[126:127], v[238:239] op_sel_hi:[1,0]
	v_pk_mul_f32 v[92:93], v[92:93], v[238:239] op_sel_hi:[1,0]
	v_pk_mul_f32 v[94:95], v[94:95], v[238:239] op_sel_hi:[1,0]
	v_pk_mul_f32 v[108:109], v[108:109], v[238:239] op_sel_hi:[1,0]
	v_pk_mul_f32 v[110:111], v[110:111], v[238:239] op_sel_hi:[1,0]
	v_pk_mul_f32 v[76:77], v[76:77], v[238:239] op_sel_hi:[1,0]
	v_pk_mul_f32 v[78:79], v[78:79], v[238:239] op_sel_hi:[1,0]
	v_pk_mul_f32 v[120:121], v[120:121], v[238:239] op_sel:[0,1] op_sel_hi:[1,1]
	v_pk_mul_f32 v[122:123], v[122:123], v[238:239] op_sel:[0,1] op_sel_hi:[1,1]
	v_pk_mul_f32 v[88:89], v[88:89], v[238:239] op_sel:[0,1] op_sel_hi:[1,1]
	v_pk_mul_f32 v[90:91], v[90:91], v[238:239] op_sel:[0,1] op_sel_hi:[1,1]
	v_pk_mul_f32 v[104:105], v[104:105], v[238:239] op_sel:[0,1] op_sel_hi:[1,1]
	v_pk_mul_f32 v[106:107], v[106:107], v[238:239] op_sel:[0,1] op_sel_hi:[1,1]
	v_pk_mul_f32 v[72:73], v[72:73], v[238:239] op_sel:[0,1] op_sel_hi:[1,1]
	v_pk_mul_f32 v[74:75], v[74:75], v[238:239] op_sel:[0,1] op_sel_hi:[1,1]
	v_pk_mul_f32 v[116:117], v[116:117], v[240:241] op_sel_hi:[1,0]
	v_pk_mul_f32 v[118:119], v[118:119], v[240:241] op_sel_hi:[1,0]
	v_pk_mul_f32 v[84:85], v[84:85], v[240:241] op_sel_hi:[1,0]
	v_pk_mul_f32 v[86:87], v[86:87], v[240:241] op_sel_hi:[1,0]
	v_pk_mul_f32 v[100:101], v[100:101], v[240:241] op_sel_hi:[1,0]
	v_pk_mul_f32 v[102:103], v[102:103], v[240:241] op_sel_hi:[1,0]
	v_pk_mul_f32 v[68:69], v[68:69], v[240:241] op_sel_hi:[1,0]
	v_pk_mul_f32 v[70:71], v[70:71], v[240:241] op_sel_hi:[1,0]
	v_pk_mul_f32 v[112:113], v[112:113], v[240:241] op_sel:[0,1] op_sel_hi:[1,1]
	v_pk_mul_f32 v[114:115], v[114:115], v[240:241] op_sel:[0,1] op_sel_hi:[1,1]
	v_pk_mul_f32 v[80:81], v[80:81], v[240:241] op_sel:[0,1] op_sel_hi:[1,1]
	v_pk_mul_f32 v[82:83], v[82:83], v[240:241] op_sel:[0,1] op_sel_hi:[1,1]
	v_pk_mul_f32 v[96:97], v[96:97], v[240:241] op_sel:[0,1] op_sel_hi:[1,1]
	v_pk_mul_f32 v[98:99], v[98:99], v[240:241] op_sel:[0,1] op_sel_hi:[1,1]
	v_pk_mul_f32 v[64:65], v[64:65], v[240:241] op_sel:[0,1] op_sel_hi:[1,1]
	v_pk_mul_f32 v[66:67], v[66:67], v[240:241] op_sel:[0,1] op_sel_hi:[1,1]
	v_pk_mul_f32 v[60:61], v[60:61], v[242:243] op_sel_hi:[1,0]
	v_pk_mul_f32 v[62:63], v[62:63], v[242:243] op_sel_hi:[1,0]
	v_pk_mul_f32 v[28:29], v[28:29], v[242:243] op_sel_hi:[1,0]
	v_pk_mul_f32 v[30:31], v[30:31], v[242:243] op_sel_hi:[1,0]
	v_pk_mul_f32 v[44:45], v[44:45], v[242:243] op_sel_hi:[1,0]
	v_pk_mul_f32 v[46:47], v[46:47], v[242:243] op_sel_hi:[1,0]
	v_pk_mul_f32 v[12:13], v[12:13], v[242:243] op_sel_hi:[1,0]
	v_pk_mul_f32 v[14:15], v[14:15], v[242:243] op_sel_hi:[1,0]
	v_pk_mul_f32 v[52:53], v[52:53], v[242:243] op_sel:[0,1] op_sel_hi:[1,1]
	v_pk_mul_f32 v[54:55], v[54:55], v[242:243] op_sel:[0,1] op_sel_hi:[1,1]
; __device__ __forceinline__ f32x4 gelu4(f32x4 v) { f32x2 a = gelu_pk((f32x2){v[0], v[1]}), b = gelu_pk((f32x2){v[2], v[3]}); return (f32x4){a.x, a.y, b.x, b.y}; }
;     __device__ __forceinline__ void operator()(const f32x4 (&acc)[2][2][4][2], const Unit& u, int wr, int wc, int fr, int fq) const {
;     ...
; #pragma unroll
;                     for (int m = 0; m < 4; ++m) {
;                         f32x4 cv;
;                         if (!samp) {
;                             const f32x4 prev = m ? v[m - 1] : hv;
; #pragma unroll
;                             for (int e = 0; e < 4; ++e) {
;                                 const int vi = __float_as_int(v[m][e]), pi = __float_as_int(prev[e]);
;                                 const int o1 = __builtin_amdgcn_mov_dpp(pi, 0x121, 0xf, 0xf, false);
;                                 const int o2 = __builtin_amdgcn_mov_dpp(pi, 0x122, 0xf, 0xf, false);
;                                 const float p1 = __int_as_float(__builtin_amdgcn_update_dpp(o1, vi, 0x111, 0xf, 0xf, false));
;                                 const float p2 = __int_as_float(__builtin_amdgcn_update_dpp(o2, vi, 0x112, 0xf, 0xf, false));
;                                 cv[e] = cb[e] + cw0[e] * p2 + cw1[e] * p1 + cw2[e] * v[m][e];
;                             }
;                         } else {
;                             const int ns = rowb + 16 * m + fr - MP;
;                             f32x4 s0 = (f32x4){0.f, 0.f, 0.f, 0.f}, s1 = s0;
;                             if (ns < NS) {
;                                 s0 = *(const f32x4*)(state + (size_t)(ns * 2 + 0) * FF2 + oc); s1 = *(const f32x4*)(state + (size_t)(ns * 2 + 1) * FF2 + oc);
;                                 *(f32x4*)(ncs + (size_t)(ns * 2 + 0) * FF2 + oc) = s1; *(f32x4*)(ncs + (size_t)(ns * 2 + 1) * FF2 + oc) = v[m];
;                             }
;                             cv = cb + cw0 * s0 + cw1 * s1 + cw2 * v[m];
;                         }
;                         if (bj == 0) cg[m] = gelu4(cv);
	v_pk_mul_f32 v[20:21], v[20:21], v[242:243] op_sel:[0,1] op_sel_hi:[1,1]
	v_pk_mul_f32 v[22:23], v[22:23], v[242:243] op_sel:[0,1] op_sel_hi:[1,1]
	v_pk_mul_f32 v[36:37], v[36:37], v[242:243] op_sel:[0,1] op_sel_hi:[1,1]
	v_pk_mul_f32 v[38:39], v[38:39], v[242:243] op_sel:[0,1] op_sel_hi:[1,1]
	v_pk_mul_f32 v[4:5], v[4:5], v[242:243] op_sel:[0,1] op_sel_hi:[1,1]
	v_pk_mul_f32 v[6:7], v[6:7], v[242:243] op_sel:[0,1] op_sel_hi:[1,1]
	v_pk_mul_f32 v[48:49], v[48:49], v[244:245] op_sel_hi:[1,0]
	v_pk_mul_f32 v[50:51], v[50:51], v[244:245] op_sel_hi:[1,0]
	v_pk_mul_f32 v[16:17], v[16:17], v[244:245] op_sel_hi:[1,0]
	v_pk_mul_f32 v[18:19], v[18:19], v[244:245] op_sel_hi:[1,0]
	v_pk_mul_f32 v[32:33], v[32:33], v[244:245] op_sel_hi:[1,0]
	v_pk_mul_f32 v[34:35], v[34:35], v[244:245] op_sel_hi:[1,0]
	v_pk_mul_f32 v[0:1], v[0:1], v[244:245] op_sel_hi:[1,0]
	v_pk_mul_f32 v[2:3], v[2:3], v[244:245] op_sel_hi:[1,0]
	v_pk_mul_f32 v[56:57], v[56:57], v[244:245] op_sel:[0,1] op_sel_hi:[1,1]
	v_pk_mul_f32 v[58:59], v[58:59], v[244:245] op_sel:[0,1] op_sel_hi:[1,1]
	v_pk_mul_f32 v[24:25], v[24:25], v[244:245] op_sel:[0,1] op_sel_hi:[1,1]
	v_pk_mul_f32 v[26:27], v[26:27], v[244:245] op_sel:[0,1] op_sel_hi:[1,1]
	v_pk_mul_f32 v[40:41], v[40:41], v[244:245] op_sel:[0,1] op_sel_hi:[1,1]
	v_pk_mul_f32 v[42:43], v[42:43], v[244:245] op_sel:[0,1] op_sel_hi:[1,1]
	v_pk_mul_f32 v[8:9], v[8:9], v[244:245] op_sel:[0,1] op_sel_hi:[1,1]
	v_pk_mul_f32 v[10:11], v[10:11], v[244:245] op_sel:[0,1] op_sel_hi:[1,1]
	s_waitcnt vmcnt(0)
	v_mov_b32_dpp v220, v116 quad_perm:[0,1,2,3] row_mask:0xf bank_mask:0x8
	v_mov_b32_dpp v221, v117 quad_perm:[0,1,2,3] row_mask:0xf bank_mask:0x8
	v_mov_b32_dpp v222, v118 quad_perm:[0,1,2,3] row_mask:0xf bank_mask:0x8
	v_mov_b32_dpp v223, v119 quad_perm:[0,1,2,3] row_mask:0xf bank_mask:0x8
	v_pk_fma_f32 v[254:255], v[202:203], v[112:113], v[132:133]
	v_pk_fma_f32 v[148:149], v[204:205], v[114:115], v[134:135]
	v_fmac_f32_dpp v254, v112, v186 row_shr:1 row_mask:0xf bank_mask:0xf
	v_fmac_f32_dpp v255, v113, v187 row_shr:1 row_mask:0xf bank_mask:0xf
	v_fmac_f32_dpp v148, v114, v188 row_shr:1 row_mask:0xf bank_mask:0xf
	v_fmac_f32_dpp v149, v115, v189 row_shr:1 row_mask:0xf bank_mask:0xf
	v_fmac_f32_dpp v254, v112, v170 row_shr:2 row_mask:0xf bank_mask:0xf
	v_fmac_f32_dpp v255, v113, v171 row_shr:2 row_mask:0xf bank_mask:0xf
	v_fmac_f32_dpp v148, v114, v172 row_shr:2 row_mask:0xf bank_mask:0xf
	v_fmac_f32_dpp v149, v115, v173 row_shr:2 row_mask:0xf bank_mask:0xf
	v_fmac_f32_dpp v254, v220, v186 row_ror:1 row_mask:0xf bank_mask:0x1
	v_fmac_f32_dpp v255, v221, v187 row_ror:1 row_mask:0xf bank_mask:0x1
	v_fmac_f32_dpp v148, v222, v188 row_ror:1 row_mask:0xf bank_mask:0x1
	v_fmac_f32_dpp v149, v223, v189 row_ror:1 row_mask:0xf bank_mask:0x1
	v_fmac_f32_dpp v254, v220, v170 row_ror:2 row_mask:0xf bank_mask:0x1
	v_fmac_f32_dpp v255, v221, v171 row_ror:2 row_mask:0xf bank_mask:0x1
	v_fmac_f32_dpp v148, v222, v172 row_ror:2 row_mask:0xf bank_mask:0x1
	v_fmac_f32_dpp v149, v223, v173 row_ror:2 row_mask:0xf bank_mask:0x1
	v_fma_f32 v246, |v254|, s38, 1.0
	v_fma_f32 v247, |v255|, s38, 1.0
	v_fma_f32 v248, |v148|, s38, 1.0
	v_fma_f32 v249, |v149|, s38, 1.0
	v_mul_f32_e32 v250, v254, v254
	v_mul_f32_e32 v251, v255, v255
	v_mul_f32_e32 v252, v148, v148
	v_mul_f32_e32 v253, v149, v149
	v_rcp_f32_e32 v246, v246
	v_rcp_f32_e32 v247, v247
	v_rcp_f32_e32 v248, v248
	v_rcp_f32_e32 v249, v249
	v_mul_f32_e32 v250, s72, v250
	v_mul_f32_e32 v251, s72, v251
	v_mul_f32_e32 v252, s72, v252
	v_mul_f32_e32 v253, s72, v253
	v_exp_f32_e32 v250, v250
	v_exp_f32_e32 v251, v251
	v_exp_f32_e32 v252, v252
	v_exp_f32_e32 v253, v253
	v_fmamk_f32 v238, v246, 0x3f07dc22, v219
	v_fmamk_f32 v239, v247, 0x3f07dc22, v219
	v_fmamk_f32 v240, v248, 0x3f07dc22, v219
	v_fmamk_f32 v241, v249, 0x3f07dc22, v219
	v_fma_f32 v238, v246, v238, s66
	v_fma_f32 v239, v247, v239, s66
	v_fma_f32 v240, v248, v240, s66
	v_fma_f32 v241, v249, v241, s66
	v_fma_f32 v238, v246, v238, s68
	v_fma_f32 v239, v247, v239, s68
	v_fma_f32 v240, v248, v240, s68
	v_fma_f32 v241, v249, v241, s68
	v_fma_f32 v238, v246, v238, s70
	v_fma_f32 v239, v247, v239, s70
	v_fma_f32 v240, v248, v240, s70
	v_fma_f32 v241, v249, v241, s70
	v_mul_f32_e32 v238, v246, v238
	v_mul_f32_e32 v239, v247, v239
	v_mul_f32_e32 v240, v248, v240
	v_mul_f32_e32 v241, v249, v241
	v_mul_f32_e32 v238, v250, v238
	v_mul_f32_e32 v239, v251, v239
	v_mul_f32_e32 v240, v252, v240
	v_mul_f32_e32 v241, v253, v241
	v_max_f32_e32 v246, 0, v254
	v_max_f32_e32 v247, 0, v255
	v_max_f32_e32 v248, 0, v148
	v_max_f32_e32 v249, 0, v149
	v_fma_f32 v238, -|v254|, v238, v246
	v_fma_f32 v239, -|v255|, v239, v247
	v_fma_f32 v240, -|v148|, v240, v248
	v_fma_f32 v241, -|v149|, v241, v249
	v_mov_b32_dpp v220, v100 quad_perm:[0,1,2,3] row_mask:0xf bank_mask:0x8
	v_mov_b32_dpp v221, v101 quad_perm:[0,1,2,3] row_mask:0xf bank_mask:0x8
	v_mov_b32_dpp v222, v102 quad_perm:[0,1,2,3] row_mask:0xf bank_mask:0x8
	v_mov_b32_dpp v223, v103 quad_perm:[0,1,2,3] row_mask:0xf bank_mask:0x8
	v_pk_fma_f32 v[254:255], v[210:211], v[96:97], v[140:141]
	v_pk_fma_f32 v[148:149], v[212:213], v[98:99], v[142:143]
	v_fmac_f32_dpp v254, v96, v194 row_shr:1 row_mask:0xf bank_mask:0xf
	v_fmac_f32_dpp v255, v97, v195 row_shr:1 row_mask:0xf bank_mask:0xf
	v_fmac_f32_dpp v148, v98, v196 row_shr:1 row_mask:0xf bank_mask:0xf
	v_fmac_f32_dpp v149, v99, v197 row_shr:1 row_mask:0xf bank_mask:0xf
	v_fmac_f32_dpp v254, v96, v178 row_shr:2 row_mask:0xf bank_mask:0xf
	v_fmac_f32_dpp v255, v97, v179 row_shr:2 row_mask:0xf bank_mask:0xf
	v_fmac_f32_dpp v148, v98, v180 row_shr:2 row_mask:0xf bank_mask:0xf
; __device__ __forceinline__ unsigned cvt_pk_bf16(float lo, float hi) { unsigned r; asm volatile("v_cvt_pk_bf16_f32 %0, %1, %2" : "=v"(r) : "v"(lo), "v"(hi)); return r; }
;     __device__ __forceinline__ void operator()(const f32x4 (&acc)[2][2][4][2], const Unit& u, int wr, int wc, int fr, int fq) const {
;     ...
; #pragma unroll
;                     for (int m = 0; m < 4; ++m) {
;                         f32x4 cv;
;                         if (!samp) {
;                             const f32x4 prev = m ? v[m - 1] : hv;
; #pragma unroll
;                             for (int e = 0; e < 4; ++e) {
;                                 const int vi = __float_as_int(v[m][e]), pi = __float_as_int(prev[e]);
;                                 const int o1 = __builtin_amdgcn_mov_dpp(pi, 0x121, 0xf, 0xf, false);
;                                 const int o2 = __builtin_amdgcn_mov_dpp(pi, 0x122, 0xf, 0xf, false);
;                                 const float p1 = __int_as_float(__builtin_amdgcn_update_dpp(o1, vi, 0x111, 0xf, 0xf, false));
;                                 const float p2 = __int_as_float(__builtin_amdgcn_update_dpp(o2, vi, 0x112, 0xf, 0xf, false));
;                                 cv[e] = cb[e] + cw0[e] * p2 + cw1[e] * p1 + cw2[e] * v[m][e];
;                             }
;                         } else {
;                             const int ns = rowb + 16 * m + fr - MP;
;                             f32x4 s0 = (f32x4){0.f, 0.f, 0.f, 0.f}, s1 = s0;
;                             if (ns < NS) {
;                                 s0 = *(const f32x4*)(state + (size_t)(ns * 2 + 0) * FF2 + oc); s1 = *(const f32x4*)(state + (size_t)(ns * 2 + 1) * FF2 + oc);
;                                 *(f32x4*)(ncs + (size_t)(ns * 2 + 0) * FF2 + oc) = s1; *(f32x4*)(ncs + (size_t)(ns * 2 + 1) * FF2 + oc) = v[m];
;                             }
;                             cv = cb + cw0 * s0 + cw1 * s1 + cw2 * v[m];
;                         }
;                         if (bj == 0) cg[m] = gelu4(cv);
;                         else {
;                             const f32x4 r = cg[m] * cv;
;                             v2u w; w.x = cvt_pk_bf16(r[0], r[1]); w.y = cvt_pk_bf16(r[2], r[3]);
;                             *(v2u*)(ACT + (size_t)(rowb + 16 * m + fr) * FF + 128 * u.pn + 32 * wc + 8 * fq + 4 * n) = w;
;                         }
	v_fmac_f32_dpp v149, v99, v181 row_shr:2 row_mask:0xf bank_mask:0xf
	v_fmac_f32_dpp v254, v220, v194 row_ror:1 row_mask:0xf bank_mask:0x1
	v_fmac_f32_dpp v255, v221, v195 row_ror:1 row_mask:0xf bank_mask:0x1
	v_fmac_f32_dpp v148, v222, v196 row_ror:1 row_mask:0xf bank_mask:0x1
	v_fmac_f32_dpp v149, v223, v197 row_ror:1 row_mask:0xf bank_mask:0x1
	v_fmac_f32_dpp v254, v220, v178 row_ror:2 row_mask:0xf bank_mask:0x1
	v_fmac_f32_dpp v255, v221, v179 row_ror:2 row_mask:0xf bank_mask:0x1
	v_fmac_f32_dpp v148, v222, v180 row_ror:2 row_mask:0xf bank_mask:0x1
	v_fmac_f32_dpp v149, v223, v181 row_ror:2 row_mask:0xf bank_mask:0x1
	v_pk_mul_f32 v[254:255], v[238:239], v[254:255]
	v_pk_mul_f32 v[148:149], v[240:241], v[148:149]
	v_cvt_pk_bf16_f32 v242, v254, v255
	v_cvt_pk_bf16_f32 v243, v148, v149
	v_mov_b32_dpp v220, v84 quad_perm:[0,1,2,3] row_mask:0xf bank_mask:0x8
	v_mov_b32_dpp v221, v85 quad_perm:[0,1,2,3] row_mask:0xf bank_mask:0x8
	v_mov_b32_dpp v222, v86 quad_perm:[0,1,2,3] row_mask:0xf bank_mask:0x8
	v_mov_b32_dpp v223, v87 quad_perm:[0,1,2,3] row_mask:0xf bank_mask:0x8
	v_pk_fma_f32 v[254:255], v[206:207], v[80:81], v[136:137]
	v_pk_fma_f32 v[148:149], v[208:209], v[82:83], v[138:139]
	v_fmac_f32_dpp v254, v80, v190 row_shr:1 row_mask:0xf bank_mask:0xf
	v_fmac_f32_dpp v255, v81, v191 row_shr:1 row_mask:0xf bank_mask:0xf
	v_fmac_f32_dpp v148, v82, v192 row_shr:1 row_mask:0xf bank_mask:0xf
	v_fmac_f32_dpp v149, v83, v193 row_shr:1 row_mask:0xf bank_mask:0xf
	v_fmac_f32_dpp v254, v80, v174 row_shr:2 row_mask:0xf bank_mask:0xf
	v_fmac_f32_dpp v255, v81, v175 row_shr:2 row_mask:0xf bank_mask:0xf
	v_fmac_f32_dpp v148, v82, v176 row_shr:2 row_mask:0xf bank_mask:0xf
	v_fmac_f32_dpp v149, v83, v177 row_shr:2 row_mask:0xf bank_mask:0xf
	v_fmac_f32_dpp v254, v220, v190 row_ror:1 row_mask:0xf bank_mask:0x1
	v_fmac_f32_dpp v255, v221, v191 row_ror:1 row_mask:0xf bank_mask:0x1
	v_fmac_f32_dpp v148, v222, v192 row_ror:1 row_mask:0xf bank_mask:0x1
	v_fmac_f32_dpp v149, v223, v193 row_ror:1 row_mask:0xf bank_mask:0x1
	v_fmac_f32_dpp v254, v220, v174 row_ror:2 row_mask:0xf bank_mask:0x1
	v_fmac_f32_dpp v255, v221, v175 row_ror:2 row_mask:0xf bank_mask:0x1
	v_fmac_f32_dpp v148, v222, v176 row_ror:2 row_mask:0xf bank_mask:0x1
	v_fmac_f32_dpp v149, v223, v177 row_ror:2 row_mask:0xf bank_mask:0x1
	v_fma_f32 v246, |v254|, s38, 1.0
	v_fma_f32 v247, |v255|, s38, 1.0
	v_fma_f32 v248, |v148|, s38, 1.0
	v_fma_f32 v249, |v149|, s38, 1.0
	v_mul_f32_e32 v250, v254, v254
	v_mul_f32_e32 v251, v255, v255
	v_mul_f32_e32 v252, v148, v148
	v_mul_f32_e32 v253, v149, v149
	v_rcp_f32_e32 v246, v246
	v_rcp_f32_e32 v247, v247
	v_rcp_f32_e32 v248, v248
	v_rcp_f32_e32 v249, v249
	v_mul_f32_e32 v250, s72, v250
	v_mul_f32_e32 v251, s72, v251
	v_mul_f32_e32 v252, s72, v252
	v_mul_f32_e32 v253, s72, v253
	v_exp_f32_e32 v250, v250
	v_exp_f32_e32 v251, v251
	v_exp_f32_e32 v252, v252
	v_exp_f32_e32 v253, v253
	v_fmamk_f32 v238, v246, 0x3f07dc22, v219
	v_fmamk_f32 v239, v247, 0x3f07dc22, v219
	v_fmamk_f32 v240, v248, 0x3f07dc22, v219
	v_fmamk_f32 v241, v249, 0x3f07dc22, v219
	v_fma_f32 v238, v246, v238, s66
	v_fma_f32 v239, v247, v239, s66
	v_fma_f32 v240, v248, v240, s66
	v_fma_f32 v241, v249, v241, s66
	v_fma_f32 v238, v246, v238, s68
	v_fma_f32 v239, v247, v239, s68
	v_fma_f32 v240, v248, v240, s68
	v_fma_f32 v241, v249, v241, s68
	v_fma_f32 v238, v246, v238, s70
	v_fma_f32 v239, v247, v239, s70
	v_fma_f32 v240, v248, v240, s70
	v_fma_f32 v241, v249, v241, s70
	v_mul_f32_e32 v238, v246, v238
	v_mul_f32_e32 v239, v247, v239
	v_mul_f32_e32 v240, v248, v240
	v_mul_f32_e32 v241, v249, v241
	v_mul_f32_e32 v238, v250, v238
	v_mul_f32_e32 v239, v251, v239
	v_mul_f32_e32 v240, v252, v240
	v_mul_f32_e32 v241, v253, v241
	v_max_f32_e32 v246, 0, v254
	v_max_f32_e32 v247, 0, v255
	v_max_f32_e32 v248, 0, v148
	v_max_f32_e32 v249, 0, v149
	v_fma_f32 v238, -|v254|, v238, v246
	v_fma_f32 v239, -|v255|, v239, v247
	v_fma_f32 v240, -|v148|, v240, v248
	v_fma_f32 v241, -|v149|, v241, v249
	v_mov_b32_dpp v220, v68 quad_perm:[0,1,2,3] row_mask:0xf bank_mask:0x8
	v_mov_b32_dpp v221, v69 quad_perm:[0,1,2,3] row_mask:0xf bank_mask:0x8
	v_mov_b32_dpp v222, v70 quad_perm:[0,1,2,3] row_mask:0xf bank_mask:0x8
	v_mov_b32_dpp v223, v71 quad_perm:[0,1,2,3] row_mask:0xf bank_mask:0x8
	v_pk_fma_f32 v[254:255], v[128:129], v[64:65], v[144:145]
	v_pk_fma_f32 v[148:149], v[130:131], v[66:67], v[146:147]
	v_fmac_f32_dpp v254, v64, v198 row_shr:1 row_mask:0xf bank_mask:0xf
	v_fmac_f32_dpp v255, v65, v199 row_shr:1 row_mask:0xf bank_mask:0xf
	v_fmac_f32_dpp v148, v66, v200 row_shr:1 row_mask:0xf bank_mask:0xf
	v_fmac_f32_dpp v149, v67, v201 row_shr:1 row_mask:0xf bank_mask:0xf
	v_fmac_f32_dpp v254, v64, v182 row_shr:2 row_mask:0xf bank_mask:0xf
	v_fmac_f32_dpp v255, v65, v183 row_shr:2 row_mask:0xf bank_mask:0xf
	v_fmac_f32_dpp v148, v66, v184 row_shr:2 row_mask:0xf bank_mask:0xf
	v_fmac_f32_dpp v149, v67, v185 row_shr:2 row_mask:0xf bank_mask:0xf
	v_fmac_f32_dpp v254, v220, v198 row_ror:1 row_mask:0xf bank_mask:0x1
	v_fmac_f32_dpp v255, v221, v199 row_ror:1 row_mask:0xf bank_mask:0x1
	v_fmac_f32_dpp v148, v222, v200 row_ror:1 row_mask:0xf bank_mask:0x1
	v_fmac_f32_dpp v149, v223, v201 row_ror:1 row_mask:0xf bank_mask:0x1
	v_fmac_f32_dpp v254, v220, v182 row_ror:2 row_mask:0xf bank_mask:0x1
	v_fmac_f32_dpp v255, v221, v183 row_ror:2 row_mask:0xf bank_mask:0x1
	v_fmac_f32_dpp v148, v222, v184 row_ror:2 row_mask:0xf bank_mask:0x1
	v_fmac_f32_dpp v149, v223, v185 row_ror:2 row_mask:0xf bank_mask:0x1
	v_pk_mul_f32 v[254:255], v[238:239], v[254:255]
	v_pk_mul_f32 v[148:149], v[240:241], v[148:149]
	v_cvt_pk_bf16_f32 v244, v254, v255
; __device__ __forceinline__ unsigned cvt_pk_bf16(float lo, float hi) { unsigned r; asm volatile("v_cvt_pk_bf16_f32 %0, %1, %2" : "=v"(r) : "v"(lo), "v"(hi)); return r; }
;     __device__ __forceinline__ void operator()(const f32x4 (&acc)[2][2][4][2], const Unit& u, int wr, int wc, int fr, int fq) const {
;     ...
; #pragma unroll
;                     for (int m = 0; m < 4; ++m) {
;                         f32x4 cv;
;                         if (!samp) {
;                             const f32x4 prev = m ? v[m - 1] : hv;
; #pragma unroll
;                             for (int e = 0; e < 4; ++e) {
;                                 const int vi = __float_as_int(v[m][e]), pi = __float_as_int(prev[e]);
;                                 const int o1 = __builtin_amdgcn_mov_dpp(pi, 0x121, 0xf, 0xf, false);
;                                 const int o2 = __builtin_amdgcn_mov_dpp(pi, 0x122, 0xf, 0xf, false);
;                                 const float p1 = __int_as_float(__builtin_amdgcn_update_dpp(o1, vi, 0x111, 0xf, 0xf, false));
;                                 const float p2 = __int_as_float(__builtin_amdgcn_update_dpp(o2, vi, 0x112, 0xf, 0xf, false));
;                                 cv[e] = cb[e] + cw0[e] * p2 + cw1[e] * p1 + cw2[e] * v[m][e];
;                             }
;                         } else {
;                             const int ns = rowb + 16 * m + fr - MP;
;                             f32x4 s0 = (f32x4){0.f, 0.f, 0.f, 0.f}, s1 = s0;
;                             if (ns < NS) {
;                                 s0 = *(const f32x4*)(state + (size_t)(ns * 2 + 0) * FF2 + oc); s1 = *(const f32x4*)(state + (size_t)(ns * 2 + 1) * FF2 + oc);
;                                 *(f32x4*)(ncs + (size_t)(ns * 2 + 0) * FF2 + oc) = s1; *(f32x4*)(ncs + (size_t)(ns * 2 + 1) * FF2 + oc) = v[m];
;                             }
;                             cv = cb + cw0 * s0 + cw1 * s1 + cw2 * v[m];
;                         }
;                         if (bj == 0) cg[m] = gelu4(cv);
;                         else {
;                             const f32x4 r = cg[m] * cv;
;                             v2u w; w.x = cvt_pk_bf16(r[0], r[1]); w.y = cvt_pk_bf16(r[2], r[3]);
;                             *(v2u*)(ACT + (size_t)(rowb + 16 * m + fr) * FF + 128 * u.pn + 32 * wc + 8 * fq + 4 * n) = w;
;                         }
;                     }
	v_cvt_pk_bf16_f32 v245, v148, v149
	s_add_u32 s56, s46, 0x42000
	s_addc_u32 s57, s47, 0
	global_store_dwordx4 v151, v[242:245], s[56:57]
	v_mov_b32_e32 v112, 0
	v_mov_b32_e32 v113, 0
	v_mov_b32_e32 v114, 0
	v_mov_b32_e32 v115, 0
	v_mov_b32_dpp v112, v120 quad_perm:[0,1,2,3] row_mask:0xf bank_mask:0x8
	v_mov_b32_dpp v113, v121 quad_perm:[0,1,2,3] row_mask:0xf bank_mask:0x8
	v_mov_b32_dpp v114, v122 quad_perm:[0,1,2,3] row_mask:0xf bank_mask:0x8
	v_mov_b32_dpp v115, v123 quad_perm:[0,1,2,3] row_mask:0xf bank_mask:0x8
	v_pk_fma_f32 v[254:255], v[202:203], v[116:117], v[132:133]
	v_pk_fma_f32 v[148:149], v[204:205], v[118:119], v[134:135]
	v_fmac_f32_dpp v254, v116, v186 row_shr:1 row_mask:0xf bank_mask:0xf
	v_fmac_f32_dpp v255, v117, v187 row_shr:1 row_mask:0xf bank_mask:0xf
	v_fmac_f32_dpp v148, v118, v188 row_shr:1 row_mask:0xf bank_mask:0xf
	v_fmac_f32_dpp v149, v119, v189 row_shr:1 row_mask:0xf bank_mask:0xf
	v_fmac_f32_dpp v254, v116, v170 row_shr:2 row_mask:0xf bank_mask:0xf
	v_fmac_f32_dpp v255, v117, v171 row_shr:2 row_mask:0xf bank_mask:0xf
	v_fmac_f32_dpp v148, v118, v172 row_shr:2 row_mask:0xf bank_mask:0xf
	v_fmac_f32_dpp v149, v119, v173 row_shr:2 row_mask:0xf bank_mask:0xf
	v_fmac_f32_dpp v254, v112, v186 row_ror:1 row_mask:0xf bank_mask:0x1
	v_fmac_f32_dpp v255, v113, v187 row_ror:1 row_mask:0xf bank_mask:0x1
	v_fmac_f32_dpp v148, v114, v188 row_ror:1 row_mask:0xf bank_mask:0x1
	v_fmac_f32_dpp v149, v115, v189 row_ror:1 row_mask:0xf bank_mask:0x1
	v_fmac_f32_dpp v254, v112, v170 row_ror:2 row_mask:0xf bank_mask:0x1
	v_fmac_f32_dpp v255, v113, v171 row_ror:2 row_mask:0xf bank_mask:0x1
	v_fmac_f32_dpp v148, v114, v172 row_ror:2 row_mask:0xf bank_mask:0x1
	v_fmac_f32_dpp v149, v115, v173 row_ror:2 row_mask:0xf bank_mask:0x1
	v_fma_f32 v246, |v254|, s38, 1.0
	v_fma_f32 v247, |v255|, s38, 1.0
	v_fma_f32 v248, |v148|, s38, 1.0
	v_fma_f32 v249, |v149|, s38, 1.0
	v_mul_f32_e32 v250, v254, v254
	v_mul_f32_e32 v251, v255, v255
	v_mul_f32_e32 v252, v148, v148
	v_mul_f32_e32 v253, v149, v149
	v_rcp_f32_e32 v246, v246
	v_rcp_f32_e32 v247, v247
	v_rcp_f32_e32 v248, v248
	v_rcp_f32_e32 v249, v249
	v_mul_f32_e32 v250, s72, v250
	v_mul_f32_e32 v251, s72, v251
	v_mul_f32_e32 v252, s72, v252
	v_mul_f32_e32 v253, s72, v253
	v_exp_f32_e32 v250, v250
	v_exp_f32_e32 v251, v251
	v_exp_f32_e32 v252, v252
	v_exp_f32_e32 v253, v253
	v_fmamk_f32 v238, v246, 0x3f07dc22, v219
	v_fmamk_f32 v239, v247, 0x3f07dc22, v219
	v_fmamk_f32 v240, v248, 0x3f07dc22, v219
	v_fmamk_f32 v241, v249, 0x3f07dc22, v219
	v_fma_f32 v238, v246, v238, s66
	v_fma_f32 v239, v247, v239, s66
	v_fma_f32 v240, v248, v240, s66
	v_fma_f32 v241, v249, v241, s66
	v_fma_f32 v238, v246, v238, s68
	v_fma_f32 v239, v247, v239, s68
	v_fma_f32 v240, v248, v240, s68
	v_fma_f32 v241, v249, v241, s68
	v_fma_f32 v238, v246, v238, s70
	v_fma_f32 v239, v247, v239, s70
	v_fma_f32 v240, v248, v240, s70
	v_fma_f32 v241, v249, v241, s70
	v_mul_f32_e32 v238, v246, v238
	v_mul_f32_e32 v239, v247, v239
	v_mul_f32_e32 v240, v248, v240
	v_mul_f32_e32 v241, v249, v241
	v_mul_f32_e32 v238, v250, v238
	v_mul_f32_e32 v239, v251, v239
	v_mul_f32_e32 v240, v252, v240
	v_mul_f32_e32 v241, v253, v241
	v_max_f32_e32 v246, 0, v254
	v_max_f32_e32 v247, 0, v255
	v_max_f32_e32 v248, 0, v148
	v_max_f32_e32 v249, 0, v149
	v_fma_f32 v238, -|v254|, v238, v246
	v_fma_f32 v239, -|v255|, v239, v247
	v_fma_f32 v240, -|v148|, v240, v248
	v_fma_f32 v241, -|v149|, v241, v249
	v_mov_b32_dpp v112, v104 quad_perm:[0,1,2,3] row_mask:0xf bank_mask:0x8
	v_mov_b32_dpp v113, v105 quad_perm:[0,1,2,3] row_mask:0xf bank_mask:0x8
	v_mov_b32_dpp v114, v106 quad_perm:[0,1,2,3] row_mask:0xf bank_mask:0x8
	v_mov_b32_dpp v115, v107 quad_perm:[0,1,2,3] row_mask:0xf bank_mask:0x8
	v_pk_fma_f32 v[254:255], v[210:211], v[100:101], v[140:141]
	v_pk_fma_f32 v[148:149], v[212:213], v[102:103], v[142:143]
	v_fmac_f32_dpp v254, v100, v194 row_shr:1 row_mask:0xf bank_mask:0xf
	v_fmac_f32_dpp v255, v101, v195 row_shr:1 row_mask:0xf bank_mask:0xf
	v_fmac_f32_dpp v148, v102, v196 row_shr:1 row_mask:0xf bank_mask:0xf
	v_fmac_f32_dpp v149, v103, v197 row_shr:1 row_mask:0xf bank_mask:0xf
	v_fmac_f32_dpp v254, v100, v178 row_shr:2 row_mask:0xf bank_mask:0xf
	v_fmac_f32_dpp v255, v101, v179 row_shr:2 row_mask:0xf bank_mask:0xf
	v_fmac_f32_dpp v148, v102, v180 row_shr:2 row_mask:0xf bank_mask:0xf
	v_fmac_f32_dpp v149, v103, v181 row_shr:2 row_mask:0xf bank_mask:0xf
	v_fmac_f32_dpp v254, v112, v194 row_ror:1 row_mask:0xf bank_mask:0x1
	v_fmac_f32_dpp v255, v113, v195 row_ror:1 row_mask:0xf bank_mask:0x1
	v_fmac_f32_dpp v148, v114, v196 row_ror:1 row_mask:0xf bank_mask:0x1
	v_fmac_f32_dpp v149, v115, v197 row_ror:1 row_mask:0xf bank_mask:0x1
	v_fmac_f32_dpp v254, v112, v178 row_ror:2 row_mask:0xf bank_mask:0x1
	v_fmac_f32_dpp v255, v113, v179 row_ror:2 row_mask:0xf bank_mask:0x1
	v_fmac_f32_dpp v148, v114, v180 row_ror:2 row_mask:0xf bank_mask:0x1
	v_fmac_f32_dpp v149, v115, v181 row_ror:2 row_mask:0xf bank_mask:0x1
	v_pk_mul_f32 v[254:255], v[238:239], v[254:255]
	v_pk_mul_f32 v[148:149], v[240:241], v[148:149]
	v_cvt_pk_bf16_f32 v242, v254, v255
	v_cvt_pk_bf16_f32 v243, v148, v149
	v_mov_b32_dpp v112, v88 quad_perm:[0,1,2,3] row_mask:0xf bank_mask:0x8
	v_mov_b32_dpp v113, v89 quad_perm:[0,1,2,3] row_mask:0xf bank_mask:0x8
	v_mov_b32_dpp v114, v90 quad_perm:[0,1,2,3] row_mask:0xf bank_mask:0x8
	v_mov_b32_dpp v115, v91 quad_perm:[0,1,2,3] row_mask:0xf bank_mask:0x8
	v_pk_fma_f32 v[254:255], v[206:207], v[84:85], v[136:137]
	v_pk_fma_f32 v[148:149], v[208:209], v[86:87], v[138:139]
	v_fmac_f32_dpp v254, v84, v190 row_shr:1 row_mask:0xf bank_mask:0xf
;     __device__ __forceinline__ void operator()(const f32x4 (&acc)[2][2][4][2], const Unit& u, int wr, int wc, int fr, int fq) const {
;     ...
;                     if (!samp) {
;                         if ((blk & 31) != 0 && fr >= 14) hv = *(const f32x4*)(HALO + (size_t)(2 * blk + fr - 14) * FF2 + cgc);
;                         if ((u.pm & 7) == 7 && ai == 1 && wr == 1 && fr >= 14) *(f32x4*)(ncp + (size_t)((u.pm >> 3) * 2 + (fr - 14)) * FF2 + oc) = v[3];
;                     }
; #pragma unroll
;                     for (int m = 0; m < 4; ++m) {
;                         f32x4 cv;
;                         if (!samp) {
;                             const f32x4 prev = m ? v[m - 1] : hv;
; #pragma unroll
;                             for (int e = 0; e < 4; ++e) {
;                                 const int vi = __float_as_int(v[m][e]), pi = __float_as_int(prev[e]);
;                                 const int o1 = __builtin_amdgcn_mov_dpp(pi, 0x121, 0xf, 0xf, false);
;                                 const int o2 = __builtin_amdgcn_mov_dpp(pi, 0x122, 0xf, 0xf, false);
;                                 const float p1 = __int_as_float(__builtin_amdgcn_update_dpp(o1, vi, 0x111, 0xf, 0xf, false));
;                                 const float p2 = __int_as_float(__builtin_amdgcn_update_dpp(o2, vi, 0x112, 0xf, 0xf, false));
;                                 cv[e] = cb[e] + cw0[e] * p2 + cw1[e] * p1 + cw2[e] * v[m][e];
;                             }
;                         } else {
;                             const int ns = rowb + 16 * m + fr - MP;
;                             f32x4 s0 = (f32x4){0.f, 0.f, 0.f, 0.f}, s1 = s0;
;                             if (ns < NS) {
;                                 s0 = *(const f32x4*)(state + (size_t)(ns * 2 + 0) * FF2 + oc); s1 = *(const f32x4*)(state + (size_t)(ns * 2 + 1) * FF2 + oc);
;                                 *(f32x4*)(ncs + (size_t)(ns * 2 + 0) * FF2 + oc) = s1; *(f32x4*)(ncs + (size_t)(ns * 2 + 1) * FF2 + oc) = v[m];
;                             }
;                             cv = cb + cw0 * s0 + cw1 * s1 + cw2 * v[m];
;                         }
;                         if (bj == 0) cg[m] = gelu4(cv);
;                         else {
;                             const f32x4 r = cg[m] * cv;
;                             v2u w; w.x = cvt_pk_bf16(r[0], r[1]); w.y = cvt_pk_bf16(r[2], r[3]);
	v_fmac_f32_dpp v255, v85, v191 row_shr:1 row_mask:0xf bank_mask:0xf
	v_fmac_f32_dpp v148, v86, v192 row_shr:1 row_mask:0xf bank_mask:0xf
	v_fmac_f32_dpp v149, v87, v193 row_shr:1 row_mask:0xf bank_mask:0xf
	v_fmac_f32_dpp v254, v84, v174 row_shr:2 row_mask:0xf bank_mask:0xf
	v_fmac_f32_dpp v255, v85, v175 row_shr:2 row_mask:0xf bank_mask:0xf
	v_fmac_f32_dpp v148, v86, v176 row_shr:2 row_mask:0xf bank_mask:0xf
	v_fmac_f32_dpp v149, v87, v177 row_shr:2 row_mask:0xf bank_mask:0xf
	v_fmac_f32_dpp v254, v112, v190 row_ror:1 row_mask:0xf bank_mask:0x1
	v_fmac_f32_dpp v255, v113, v191 row_ror:1 row_mask:0xf bank_mask:0x1
	v_fmac_f32_dpp v148, v114, v192 row_ror:1 row_mask:0xf bank_mask:0x1
	v_fmac_f32_dpp v149, v115, v193 row_ror:1 row_mask:0xf bank_mask:0x1
	v_fmac_f32_dpp v254, v112, v174 row_ror:2 row_mask:0xf bank_mask:0x1
	v_fmac_f32_dpp v255, v113, v175 row_ror:2 row_mask:0xf bank_mask:0x1
	v_fmac_f32_dpp v148, v114, v176 row_ror:2 row_mask:0xf bank_mask:0x1
	v_fmac_f32_dpp v149, v115, v177 row_ror:2 row_mask:0xf bank_mask:0x1
	v_fma_f32 v246, |v254|, s38, 1.0
	v_fma_f32 v247, |v255|, s38, 1.0
	v_fma_f32 v248, |v148|, s38, 1.0
	v_fma_f32 v249, |v149|, s38, 1.0
	v_mul_f32_e32 v250, v254, v254
	v_mul_f32_e32 v251, v255, v255
	v_mul_f32_e32 v252, v148, v148
	v_mul_f32_e32 v253, v149, v149
	v_rcp_f32_e32 v246, v246
	v_rcp_f32_e32 v247, v247
	v_rcp_f32_e32 v248, v248
	v_rcp_f32_e32 v249, v249
	v_mul_f32_e32 v250, s72, v250
	v_mul_f32_e32 v251, s72, v251
	v_mul_f32_e32 v252, s72, v252
	v_mul_f32_e32 v253, s72, v253
	v_exp_f32_e32 v250, v250
	v_exp_f32_e32 v251, v251
	v_exp_f32_e32 v252, v252
	v_exp_f32_e32 v253, v253
	v_fmamk_f32 v238, v246, 0x3f07dc22, v219
	v_fmamk_f32 v239, v247, 0x3f07dc22, v219
	v_fmamk_f32 v240, v248, 0x3f07dc22, v219
	v_fmamk_f32 v241, v249, 0x3f07dc22, v219
	v_fma_f32 v238, v246, v238, s66
	v_fma_f32 v239, v247, v239, s66
	v_fma_f32 v240, v248, v240, s66
	v_fma_f32 v241, v249, v241, s66
	v_fma_f32 v238, v246, v238, s68
	v_fma_f32 v239, v247, v239, s68
	v_fma_f32 v240, v248, v240, s68
	v_fma_f32 v241, v249, v241, s68
	v_fma_f32 v238, v246, v238, s70
	v_fma_f32 v239, v247, v239, s70
	v_fma_f32 v240, v248, v240, s70
	v_fma_f32 v241, v249, v241, s70
	v_mul_f32_e32 v238, v246, v238
	v_mul_f32_e32 v239, v247, v239
	v_mul_f32_e32 v240, v248, v240
	v_mul_f32_e32 v241, v249, v241
	v_mul_f32_e32 v238, v250, v238
	v_mul_f32_e32 v239, v251, v239
	v_mul_f32_e32 v240, v252, v240
	v_mul_f32_e32 v241, v253, v241
	v_max_f32_e32 v246, 0, v254
	v_max_f32_e32 v247, 0, v255
	v_max_f32_e32 v248, 0, v148
	v_max_f32_e32 v249, 0, v149
	v_fma_f32 v238, -|v254|, v238, v246
	v_fma_f32 v239, -|v255|, v239, v247
	v_fma_f32 v240, -|v148|, v240, v248
	v_fma_f32 v241, -|v149|, v241, v249
	v_mov_b32_dpp v112, v72 quad_perm:[0,1,2,3] row_mask:0xf bank_mask:0x8
	v_mov_b32_dpp v113, v73 quad_perm:[0,1,2,3] row_mask:0xf bank_mask:0x8
	v_mov_b32_dpp v114, v74 quad_perm:[0,1,2,3] row_mask:0xf bank_mask:0x8
	v_mov_b32_dpp v115, v75 quad_perm:[0,1,2,3] row_mask:0xf bank_mask:0x8
	v_pk_fma_f32 v[254:255], v[128:129], v[68:69], v[144:145]
	v_pk_fma_f32 v[148:149], v[130:131], v[70:71], v[146:147]
	v_fmac_f32_dpp v254, v68, v198 row_shr:1 row_mask:0xf bank_mask:0xf
	v_fmac_f32_dpp v255, v69, v199 row_shr:1 row_mask:0xf bank_mask:0xf
	v_fmac_f32_dpp v148, v70, v200 row_shr:1 row_mask:0xf bank_mask:0xf
	v_fmac_f32_dpp v149, v71, v201 row_shr:1 row_mask:0xf bank_mask:0xf
	v_fmac_f32_dpp v254, v68, v182 row_shr:2 row_mask:0xf bank_mask:0xf
	v_fmac_f32_dpp v255, v69, v183 row_shr:2 row_mask:0xf bank_mask:0xf
	v_fmac_f32_dpp v148, v70, v184 row_shr:2 row_mask:0xf bank_mask:0xf
	v_fmac_f32_dpp v149, v71, v185 row_shr:2 row_mask:0xf bank_mask:0xf
	v_fmac_f32_dpp v254, v112, v198 row_ror:1 row_mask:0xf bank_mask:0x1
	v_fmac_f32_dpp v255, v113, v199 row_ror:1 row_mask:0xf bank_mask:0x1
	v_fmac_f32_dpp v148, v114, v200 row_ror:1 row_mask:0xf bank_mask:0x1
	v_fmac_f32_dpp v149, v115, v201 row_ror:1 row_mask:0xf bank_mask:0x1
	v_fmac_f32_dpp v254, v112, v182 row_ror:2 row_mask:0xf bank_mask:0x1
	v_fmac_f32_dpp v255, v113, v183 row_ror:2 row_mask:0xf bank_mask:0x1
	v_fmac_f32_dpp v148, v114, v184 row_ror:2 row_mask:0xf bank_mask:0x1
	v_fmac_f32_dpp v149, v115, v185 row_ror:2 row_mask:0xf bank_mask:0x1
	v_pk_mul_f32 v[254:255], v[238:239], v[254:255]
	v_pk_mul_f32 v[148:149], v[240:241], v[148:149]
	v_cvt_pk_bf16_f32 v244, v254, v255
	v_cvt_pk_bf16_f32 v245, v148, v149
	s_add_u32 s56, s46, 0x2c000
	s_addc_u32 s57, s47, 0
	global_store_dwordx4 v151, v[242:245], s[56:57]
	v_mov_b32_e32 v220, 0
	v_mov_b32_e32 v221, 0
	v_mov_b32_e32 v222, 0
	v_mov_b32_e32 v223, 0
	s_and_b32 s14, s75, 31
	s_cselect_b64 s[92:93], -1, 0
	s_and_b64 vcc, exec, s[86:87]
	s_cbranch_vccnz .Lfe_h0a
	s_and_b64 vcc, exec, s[92:93]
	s_cbranch_vccz .Lfe_h0a
	s_mov_b64 s[14:15], exec
	s_mov_b64 exec, s[10:11]
	global_load_dwordx4 v[220:223], v150, s[44:45]
	global_load_dwordx4 v[224:227], v150, s[44:45] offset:16
	global_load_dwordx4 v[228:231], v150, s[44:45] offset:512
	global_load_dwordx4 v[232:235], v150, s[44:45] offset:528
	s_mov_b64 exec, s[14:15]
; __device__ __forceinline__ unsigned cvt_pk_bf16(float lo, float hi) { unsigned r; asm volatile("v_cvt_pk_bf16_f32 %0, %1, %2" : "=v"(r) : "v"(lo), "v"(hi)); return r; }
;     __device__ __forceinline__ void operator()(const f32x4 (&acc)[2][2][4][2], const Unit& u, int wr, int wc, int fr, int fq) const {
;     ...
; #pragma unroll
;                     for (int m = 0; m < 4; ++m) {
;                         f32x4 cv;
;                         if (!samp) {
;                             const f32x4 prev = m ? v[m - 1] : hv;
; #pragma unroll
;                             for (int e = 0; e < 4; ++e) {
;                                 const int vi = __float_as_int(v[m][e]), pi = __float_as_int(prev[e]);
;                                 const int o1 = __builtin_amdgcn_mov_dpp(pi, 0x121, 0xf, 0xf, false);
;                                 const int o2 = __builtin_amdgcn_mov_dpp(pi, 0x122, 0xf, 0xf, false);
;                                 const float p1 = __int_as_float(__builtin_amdgcn_update_dpp(o1, vi, 0x111, 0xf, 0xf, false));
;                                 const float p2 = __int_as_float(__builtin_amdgcn_update_dpp(o2, vi, 0x112, 0xf, 0xf, false));
;                                 cv[e] = cb[e] + cw0[e] * p2 + cw1[e] * p1 + cw2[e] * v[m][e];
;                             }
;                         } else {
;                             const int ns = rowb + 16 * m + fr - MP;
;                             f32x4 s0 = (f32x4){0.f, 0.f, 0.f, 0.f}, s1 = s0;
;                             if (ns < NS) {
;                                 s0 = *(const f32x4*)(state + (size_t)(ns * 2 + 0) * FF2 + oc); s1 = *(const f32x4*)(state + (size_t)(ns * 2 + 1) * FF2 + oc);
;                                 *(f32x4*)(ncs + (size_t)(ns * 2 + 0) * FF2 + oc) = s1; *(f32x4*)(ncs + (size_t)(ns * 2 + 1) * FF2 + oc) = v[m];
;                             }
;                             cv = cb + cw0 * s0 + cw1 * s1 + cw2 * v[m];
;                         }
;                         if (bj == 0) cg[m] = gelu4(cv);
;                         else {
;                             const f32x4 r = cg[m] * cv;
;                             v2u w; w.x = cvt_pk_bf16(r[0], r[1]); w.y = cvt_pk_bf16(r[2], r[3]);
;                             *(v2u*)(ACT + (size_t)(rowb + 16 * m + fr) * FF + 128 * u.pn + 32 * wc + 8 * fq + 4 * n) = w;
;                         }
.Lfe_h0a:
	v_mov_b32_dpp v112, v124 quad_perm:[0,1,2,3] row_mask:0xf bank_mask:0x8
	v_mov_b32_dpp v113, v125 quad_perm:[0,1,2,3] row_mask:0xf bank_mask:0x8
	v_mov_b32_dpp v114, v126 quad_perm:[0,1,2,3] row_mask:0xf bank_mask:0x8
	v_mov_b32_dpp v115, v127 quad_perm:[0,1,2,3] row_mask:0xf bank_mask:0x8
	v_pk_fma_f32 v[254:255], v[202:203], v[120:121], v[132:133]
	v_pk_fma_f32 v[148:149], v[204:205], v[122:123], v[134:135]
	v_fmac_f32_dpp v254, v120, v186 row_shr:1 row_mask:0xf bank_mask:0xf
	v_fmac_f32_dpp v255, v121, v187 row_shr:1 row_mask:0xf bank_mask:0xf
	v_fmac_f32_dpp v148, v122, v188 row_shr:1 row_mask:0xf bank_mask:0xf
	v_fmac_f32_dpp v149, v123, v189 row_shr:1 row_mask:0xf bank_mask:0xf
	v_fmac_f32_dpp v254, v120, v170 row_shr:2 row_mask:0xf bank_mask:0xf
	v_fmac_f32_dpp v255, v121, v171 row_shr:2 row_mask:0xf bank_mask:0xf
	v_fmac_f32_dpp v148, v122, v172 row_shr:2 row_mask:0xf bank_mask:0xf
	v_fmac_f32_dpp v149, v123, v173 row_shr:2 row_mask:0xf bank_mask:0xf
	v_fmac_f32_dpp v254, v112, v186 row_ror:1 row_mask:0xf bank_mask:0x1
	v_fmac_f32_dpp v255, v113, v187 row_ror:1 row_mask:0xf bank_mask:0x1
	v_fmac_f32_dpp v148, v114, v188 row_ror:1 row_mask:0xf bank_mask:0x1
	v_fmac_f32_dpp v149, v115, v189 row_ror:1 row_mask:0xf bank_mask:0x1
	v_fmac_f32_dpp v254, v112, v170 row_ror:2 row_mask:0xf bank_mask:0x1
	v_fmac_f32_dpp v255, v113, v171 row_ror:2 row_mask:0xf bank_mask:0x1
	v_fmac_f32_dpp v148, v114, v172 row_ror:2 row_mask:0xf bank_mask:0x1
	v_fmac_f32_dpp v149, v115, v173 row_ror:2 row_mask:0xf bank_mask:0x1
	v_fma_f32 v246, |v254|, s38, 1.0
	v_fma_f32 v247, |v255|, s38, 1.0
	v_fma_f32 v248, |v148|, s38, 1.0
	v_fma_f32 v249, |v149|, s38, 1.0
	v_mul_f32_e32 v250, v254, v254
	v_mul_f32_e32 v251, v255, v255
	v_mul_f32_e32 v252, v148, v148
	v_mul_f32_e32 v253, v149, v149
	v_rcp_f32_e32 v246, v246
	v_rcp_f32_e32 v247, v247
	v_rcp_f32_e32 v248, v248
	v_rcp_f32_e32 v249, v249
	v_mul_f32_e32 v250, s72, v250
	v_mul_f32_e32 v251, s72, v251
	v_mul_f32_e32 v252, s72, v252
	v_mul_f32_e32 v253, s72, v253
	v_exp_f32_e32 v250, v250
	v_exp_f32_e32 v251, v251
	v_exp_f32_e32 v252, v252
	v_exp_f32_e32 v253, v253
	v_fmamk_f32 v238, v246, 0x3f07dc22, v219
	v_fmamk_f32 v239, v247, 0x3f07dc22, v219
	v_fmamk_f32 v240, v248, 0x3f07dc22, v219
	v_fmamk_f32 v241, v249, 0x3f07dc22, v219
	v_fma_f32 v238, v246, v238, s66
	v_fma_f32 v239, v247, v239, s66
	v_fma_f32 v240, v248, v240, s66
	v_fma_f32 v241, v249, v241, s66
	v_fma_f32 v238, v246, v238, s68
	v_fma_f32 v239, v247, v239, s68
	v_fma_f32 v240, v248, v240, s68
	v_fma_f32 v241, v249, v241, s68
	v_fma_f32 v238, v246, v238, s70
	v_fma_f32 v239, v247, v239, s70
	v_fma_f32 v240, v248, v240, s70
	v_fma_f32 v241, v249, v241, s70
	v_mul_f32_e32 v238, v246, v238
	v_mul_f32_e32 v239, v247, v239
	v_mul_f32_e32 v240, v248, v240
	v_mul_f32_e32 v241, v249, v241
	v_mul_f32_e32 v238, v250, v238
	v_mul_f32_e32 v239, v251, v239
	v_mul_f32_e32 v240, v252, v240
	v_mul_f32_e32 v241, v253, v241
	v_max_f32_e32 v246, 0, v254
	v_max_f32_e32 v247, 0, v255
	v_max_f32_e32 v248, 0, v148
	v_max_f32_e32 v249, 0, v149
	v_fma_f32 v238, -|v254|, v238, v246
	v_fma_f32 v239, -|v255|, v239, v247
	v_fma_f32 v240, -|v148|, v240, v248
	v_fma_f32 v241, -|v149|, v241, v249
	v_mov_b32_dpp v112, v108 quad_perm:[0,1,2,3] row_mask:0xf bank_mask:0x8
	v_mov_b32_dpp v113, v109 quad_perm:[0,1,2,3] row_mask:0xf bank_mask:0x8
	v_mov_b32_dpp v114, v110 quad_perm:[0,1,2,3] row_mask:0xf bank_mask:0x8
	v_mov_b32_dpp v115, v111 quad_perm:[0,1,2,3] row_mask:0xf bank_mask:0x8
	v_pk_fma_f32 v[254:255], v[210:211], v[104:105], v[140:141]
	v_pk_fma_f32 v[148:149], v[212:213], v[106:107], v[142:143]
	v_fmac_f32_dpp v254, v104, v194 row_shr:1 row_mask:0xf bank_mask:0xf
	v_fmac_f32_dpp v255, v105, v195 row_shr:1 row_mask:0xf bank_mask:0xf
	v_fmac_f32_dpp v148, v106, v196 row_shr:1 row_mask:0xf bank_mask:0xf
	v_fmac_f32_dpp v149, v107, v197 row_shr:1 row_mask:0xf bank_mask:0xf
	v_fmac_f32_dpp v254, v104, v178 row_shr:2 row_mask:0xf bank_mask:0xf
	v_fmac_f32_dpp v255, v105, v179 row_shr:2 row_mask:0xf bank_mask:0xf
	v_fmac_f32_dpp v148, v106, v180 row_shr:2 row_mask:0xf bank_mask:0xf
	v_fmac_f32_dpp v149, v107, v181 row_shr:2 row_mask:0xf bank_mask:0xf
	v_fmac_f32_dpp v254, v112, v194 row_ror:1 row_mask:0xf bank_mask:0x1
	v_fmac_f32_dpp v255, v113, v195 row_ror:1 row_mask:0xf bank_mask:0x1
	v_fmac_f32_dpp v148, v114, v196 row_ror:1 row_mask:0xf bank_mask:0x1
	v_fmac_f32_dpp v149, v115, v197 row_ror:1 row_mask:0xf bank_mask:0x1
	v_fmac_f32_dpp v254, v112, v178 row_ror:2 row_mask:0xf bank_mask:0x1
	v_fmac_f32_dpp v255, v113, v179 row_ror:2 row_mask:0xf bank_mask:0x1
	v_fmac_f32_dpp v148, v114, v180 row_ror:2 row_mask:0xf bank_mask:0x1
	v_fmac_f32_dpp v149, v115, v181 row_ror:2 row_mask:0xf bank_mask:0x1
	v_pk_mul_f32 v[254:255], v[238:239], v[254:255]
	v_pk_mul_f32 v[148:149], v[240:241], v[148:149]
	v_cvt_pk_bf16_f32 v242, v254, v255
	v_cvt_pk_bf16_f32 v243, v148, v149
	v_mov_b32_dpp v112, v92 quad_perm:[0,1,2,3] row_mask:0xf bank_mask:0x8
	v_mov_b32_dpp v113, v93 quad_perm:[0,1,2,3] row_mask:0xf bank_mask:0x8
;     __device__ __forceinline__ void operator()(const f32x4 (&acc)[2][2][4][2], const Unit& u, int wr, int wc, int fr, int fq) const {
;     ...
;         if (!halo_ok) {
;             if (threadIdx.x < 64) { unsigned sp = 0;
;     ...
; #pragma unroll
;                     for (int m = 0; m < 4; ++m) {
;                         f32x4 cv;
;                         if (!samp) {
;                             const f32x4 prev = m ? v[m - 1] : hv;
; #pragma unroll
;                             for (int e = 0; e < 4; ++e) {
;                                 const int vi = __float_as_int(v[m][e]), pi = __float_as_int(prev[e]);
;                                 const int o1 = __builtin_amdgcn_mov_dpp(pi, 0x121, 0xf, 0xf, false);
;                                 const int o2 = __builtin_amdgcn_mov_dpp(pi, 0x122, 0xf, 0xf, false);
;                                 const float p1 = __int_as_float(__builtin_amdgcn_update_dpp(o1, vi, 0x111, 0xf, 0xf, false));
;                                 const float p2 = __int_as_float(__builtin_amdgcn_update_dpp(o2, vi, 0x112, 0xf, 0xf, false));
;                                 cv[e] = cb[e] + cw0[e] * p2 + cw1[e] * p1 + cw2[e] * v[m][e];
;                             }
;                         } else {
;                             const int ns = rowb + 16 * m + fr - MP;
;                             f32x4 s0 = (f32x4){0.f, 0.f, 0.f, 0.f}, s1 = s0;
;                             if (ns < NS) {
;                                 s0 = *(const f32x4*)(state + (size_t)(ns * 2 + 0) * FF2 + oc); s1 = *(const f32x4*)(state + (size_t)(ns * 2 + 1) * FF2 + oc);
;                                 *(f32x4*)(ncs + (size_t)(ns * 2 + 0) * FF2 + oc) = s1; *(f32x4*)(ncs + (size_t)(ns * 2 + 1) * FF2 + oc) = v[m];
;                             }
;                             cv = cb + cw0 * s0 + cw1 * s1 + cw2 * v[m];
;                         }
;                         if (bj == 0) cg[m] = gelu4(cv);
;                         else {
;                             const f32x4 r = cg[m] * cv;
;                             v2u w; w.x = cvt_pk_bf16(r[0], r[1]); w.y = cvt_pk_bf16(r[2], r[3]);
;                             *(v2u*)(ACT + (size_t)(rowb + 16 * m + fr) * FF + 128 * u.pn + 32 * wc + 8 * fq + 4 * n) = w;
;                         }
;                     }
	v_mov_b32_dpp v114, v94 quad_perm:[0,1,2,3] row_mask:0xf bank_mask:0x8
	v_mov_b32_dpp v115, v95 quad_perm:[0,1,2,3] row_mask:0xf bank_mask:0x8
	v_pk_fma_f32 v[254:255], v[206:207], v[88:89], v[136:137]
	v_pk_fma_f32 v[148:149], v[208:209], v[90:91], v[138:139]
	v_fmac_f32_dpp v254, v88, v190 row_shr:1 row_mask:0xf bank_mask:0xf
	v_fmac_f32_dpp v255, v89, v191 row_shr:1 row_mask:0xf bank_mask:0xf
	v_fmac_f32_dpp v148, v90, v192 row_shr:1 row_mask:0xf bank_mask:0xf
	v_fmac_f32_dpp v149, v91, v193 row_shr:1 row_mask:0xf bank_mask:0xf
	v_fmac_f32_dpp v254, v88, v174 row_shr:2 row_mask:0xf bank_mask:0xf
	v_fmac_f32_dpp v255, v89, v175 row_shr:2 row_mask:0xf bank_mask:0xf
	v_fmac_f32_dpp v148, v90, v176 row_shr:2 row_mask:0xf bank_mask:0xf
	v_fmac_f32_dpp v149, v91, v177 row_shr:2 row_mask:0xf bank_mask:0xf
	v_fmac_f32_dpp v254, v112, v190 row_ror:1 row_mask:0xf bank_mask:0x1
	v_fmac_f32_dpp v255, v113, v191 row_ror:1 row_mask:0xf bank_mask:0x1
	v_fmac_f32_dpp v148, v114, v192 row_ror:1 row_mask:0xf bank_mask:0x1
	v_fmac_f32_dpp v149, v115, v193 row_ror:1 row_mask:0xf bank_mask:0x1
	v_fmac_f32_dpp v254, v112, v174 row_ror:2 row_mask:0xf bank_mask:0x1
	v_fmac_f32_dpp v255, v113, v175 row_ror:2 row_mask:0xf bank_mask:0x1
	v_fmac_f32_dpp v148, v114, v176 row_ror:2 row_mask:0xf bank_mask:0x1
	v_fmac_f32_dpp v149, v115, v177 row_ror:2 row_mask:0xf bank_mask:0x1
	v_fma_f32 v246, |v254|, s38, 1.0
	v_fma_f32 v247, |v255|, s38, 1.0
	v_fma_f32 v248, |v148|, s38, 1.0
	v_fma_f32 v249, |v149|, s38, 1.0
	v_mul_f32_e32 v250, v254, v254
	v_mul_f32_e32 v251, v255, v255
	v_mul_f32_e32 v252, v148, v148
	v_mul_f32_e32 v253, v149, v149
	v_rcp_f32_e32 v246, v246
	v_rcp_f32_e32 v247, v247
	v_rcp_f32_e32 v248, v248
	v_rcp_f32_e32 v249, v249
	v_mul_f32_e32 v250, s72, v250
	v_mul_f32_e32 v251, s72, v251
	v_mul_f32_e32 v252, s72, v252
	v_mul_f32_e32 v253, s72, v253
	v_exp_f32_e32 v250, v250
	v_exp_f32_e32 v251, v251
	v_exp_f32_e32 v252, v252
	v_exp_f32_e32 v253, v253
	v_fmamk_f32 v238, v246, 0x3f07dc22, v219
	v_fmamk_f32 v239, v247, 0x3f07dc22, v219
	v_fmamk_f32 v240, v248, 0x3f07dc22, v219
	v_fmamk_f32 v241, v249, 0x3f07dc22, v219
	v_fma_f32 v238, v246, v238, s66
	v_fma_f32 v239, v247, v239, s66
	v_fma_f32 v240, v248, v240, s66
	v_fma_f32 v241, v249, v241, s66
	v_fma_f32 v238, v246, v238, s68
	v_fma_f32 v239, v247, v239, s68
	v_fma_f32 v240, v248, v240, s68
	v_fma_f32 v241, v249, v241, s68
	v_fma_f32 v238, v246, v238, s70
	v_fma_f32 v239, v247, v239, s70
	v_fma_f32 v240, v248, v240, s70
	v_fma_f32 v241, v249, v241, s70
	v_mul_f32_e32 v238, v246, v238
	v_mul_f32_e32 v239, v247, v239
	v_mul_f32_e32 v240, v248, v240
	v_mul_f32_e32 v241, v249, v241
	v_mul_f32_e32 v238, v250, v238
	v_mul_f32_e32 v239, v251, v239
	v_mul_f32_e32 v240, v252, v240
	v_mul_f32_e32 v241, v253, v241
	v_max_f32_e32 v246, 0, v254
	v_max_f32_e32 v247, 0, v255
	v_max_f32_e32 v248, 0, v148
	v_max_f32_e32 v249, 0, v149
	v_fma_f32 v238, -|v254|, v238, v246
	v_fma_f32 v239, -|v255|, v239, v247
	v_fma_f32 v240, -|v148|, v240, v248
	v_fma_f32 v241, -|v149|, v241, v249
	v_mov_b32_dpp v112, v76 quad_perm:[0,1,2,3] row_mask:0xf bank_mask:0x8
	v_mov_b32_dpp v113, v77 quad_perm:[0,1,2,3] row_mask:0xf bank_mask:0x8
	v_mov_b32_dpp v114, v78 quad_perm:[0,1,2,3] row_mask:0xf bank_mask:0x8
	v_mov_b32_dpp v115, v79 quad_perm:[0,1,2,3] row_mask:0xf bank_mask:0x8
	v_pk_fma_f32 v[254:255], v[128:129], v[72:73], v[144:145]
	v_pk_fma_f32 v[148:149], v[130:131], v[74:75], v[146:147]
	v_fmac_f32_dpp v254, v72, v198 row_shr:1 row_mask:0xf bank_mask:0xf
	v_fmac_f32_dpp v255, v73, v199 row_shr:1 row_mask:0xf bank_mask:0xf
	v_fmac_f32_dpp v148, v74, v200 row_shr:1 row_mask:0xf bank_mask:0xf
	v_fmac_f32_dpp v149, v75, v201 row_shr:1 row_mask:0xf bank_mask:0xf
	v_fmac_f32_dpp v254, v72, v182 row_shr:2 row_mask:0xf bank_mask:0xf
	v_fmac_f32_dpp v255, v73, v183 row_shr:2 row_mask:0xf bank_mask:0xf
	v_fmac_f32_dpp v148, v74, v184 row_shr:2 row_mask:0xf bank_mask:0xf
	v_fmac_f32_dpp v149, v75, v185 row_shr:2 row_mask:0xf bank_mask:0xf
	v_fmac_f32_dpp v254, v112, v198 row_ror:1 row_mask:0xf bank_mask:0x1
	v_fmac_f32_dpp v255, v113, v199 row_ror:1 row_mask:0xf bank_mask:0x1
	v_fmac_f32_dpp v148, v114, v200 row_ror:1 row_mask:0xf bank_mask:0x1
	v_fmac_f32_dpp v149, v115, v201 row_ror:1 row_mask:0xf bank_mask:0x1
	v_fmac_f32_dpp v254, v112, v182 row_ror:2 row_mask:0xf bank_mask:0x1
	v_fmac_f32_dpp v255, v113, v183 row_ror:2 row_mask:0xf bank_mask:0x1
	v_fmac_f32_dpp v148, v114, v184 row_ror:2 row_mask:0xf bank_mask:0x1
	v_fmac_f32_dpp v149, v115, v185 row_ror:2 row_mask:0xf bank_mask:0x1
	v_pk_mul_f32 v[254:255], v[238:239], v[254:255]
	v_pk_mul_f32 v[148:149], v[240:241], v[148:149]
	v_cvt_pk_bf16_f32 v244, v254, v255
	v_cvt_pk_bf16_f32 v245, v148, v149
	s_add_u32 s56, s46, 0x16000
	s_addc_u32 s57, s47, 0
	global_store_dwordx4 v151, v[242:245], s[56:57]
	s_and_b64 vcc, exec, s[86:87]
	s_cbranch_vccz .Lfe_h0b
	s_and_saveexec_b64 s[14:15], s[8:9]
	s_cbranch_execz .Lfe_hw3
	s_mov_b32 s13, 0x100001
	s_branch .Lfe_hw1

;     __device__ __forceinline__ void operator()(const f32x4 (&acc)[2][2][4][2], const Unit& u, int wr, int wc, int fr, int fq) const {
;     ...
;             if (threadIdx.x < 64) { unsigned sp = 0;
;                 while ((unsigned)__builtin_amdgcn_readfirstlane(__hip_atomic_load(halo_ctr, __ATOMIC_RELAXED, __HIP_MEMORY_SCOPE_AGENT)) < halo_need) { __builtin_amdgcn_s_sleep(8); if (++sp > (1u << 20)) break; }
;                 __builtin_amdgcn_fence(__ATOMIC_ACQUIRE, "agent"); asm volatile("s_waitcnt vmcnt(0)" ::: "memory"); }
.Lfe_hw1:
	global_load_dword v246, v169, s[40:41] sc1
	s_mov_b64 s[84:85], -1
	s_waitcnt vmcnt(0)
	v_readfirstlane_b32 s48, v246
	s_cmp_gt_u32 s48, 43
	s_cbranch_scc1 .Lfe_hw0
	s_add_i32 s13, s13, -1
	s_cmp_eq_u32 s13, 0
	s_cselect_b64 s[84:85], -1, 0
	s_sleep 8
	s_branch .Lfe_hw0

;     __device__ __forceinline__ void operator()(const f32x4 (&acc)[2][2][4][2], const Unit& u, int wr, int wc, int fr, int fq) const {
;     ...
;                     if (!samp) {
;                         if ((blk & 31) != 0 && fr >= 14) hv = *(const f32x4*)(HALO + (size_t)(2 * blk + fr - 14) * FF2 + cgc);
;                         if ((u.pm & 7) == 7 && ai == 1 && wr == 1 && fr >= 14) *(f32x4*)(ncp + (size_t)((u.pm >> 3) * 2 + (fr - 14)) * FF2 + oc) = v[3];
;                     }
; #pragma unroll
;                     for (int m = 0; m < 4; ++m) {
;                         f32x4 cv;
;                         if (!samp) {
;                             const f32x4 prev = m ? v[m - 1] : hv;
; #pragma unroll
;                             for (int e = 0; e < 4; ++e) {
;                                 const int vi = __float_as_int(v[m][e]), pi = __float_as_int(prev[e]);
;                                 const int o1 = __builtin_amdgcn_mov_dpp(pi, 0x121, 0xf, 0xf, false);
;                                 const int o2 = __builtin_amdgcn_mov_dpp(pi, 0x122, 0xf, 0xf, false);
;                                 const float p1 = __int_as_float(__builtin_amdgcn_update_dpp(o1, vi, 0x111, 0xf, 0xf, false));
;                                 const float p2 = __int_as_float(__builtin_amdgcn_update_dpp(o2, vi, 0x112, 0xf, 0xf, false));
;                                 cv[e] = cb[e] + cw0[e] * p2 + cw1[e] * p1 + cw2[e] * v[m][e];
;                             }
;                         } else {
;                             const int ns = rowb + 16 * m + fr - MP;
;                             f32x4 s0 = (f32x4){0.f, 0.f, 0.f, 0.f}, s1 = s0;
;                             if (ns < NS) {
;                                 s0 = *(const f32x4*)(state + (size_t)(ns * 2 + 0) * FF2 + oc); s1 = *(const f32x4*)(state + (size_t)(ns * 2 + 1) * FF2 + oc);
;                                 *(f32x4*)(ncs + (size_t)(ns * 2 + 0) * FF2 + oc) = s1; *(f32x4*)(ncs + (size_t)(ns * 2 + 1) * FF2 + oc) = v[m];
;                             }
;                             cv = cb + cw0 * s0 + cw1 * s1 + cw2 * v[m];
;                         }
;                         if (bj == 0) cg[m] = gelu4(cv);
;                         else {
;                             const f32x4 r = cg[m] * cv;
;                             v2u w; w.x = cvt_pk_bf16(r[0], r[1]); w.y = cvt_pk_bf16(r[2], r[3]);
.Lfe_hw3:
	s_or_b64 exec, exec, s[14:15]
	s_barrier
	s_and_b64 vcc, exec, s[92:93]
	s_cbranch_vccz .Lfe_h0b
	s_mov_b64 s[14:15], exec
	s_mov_b64 exec, s[10:11]
	global_load_dwordx4 v[220:223], v150, s[44:45]
	global_load_dwordx4 v[224:227], v150, s[44:45] offset:16
	global_load_dwordx4 v[228:231], v150, s[44:45] offset:512
	global_load_dwordx4 v[232:235], v150, s[44:45] offset:528
	s_mov_b64 exec, s[14:15]
	s_waitcnt vmcnt(0)
.Lfe_h0b:
	s_waitcnt vmcnt(1)
	v_pk_fma_f32 v[254:255], v[202:203], v[124:125], v[132:133]
	v_pk_fma_f32 v[148:149], v[204:205], v[126:127], v[134:135]
	v_fmac_f32_dpp v254, v124, v186 row_shr:1 row_mask:0xf bank_mask:0xf
	v_fmac_f32_dpp v255, v125, v187 row_shr:1 row_mask:0xf bank_mask:0xf
	v_fmac_f32_dpp v148, v126, v188 row_shr:1 row_mask:0xf bank_mask:0xf
	v_fmac_f32_dpp v149, v127, v189 row_shr:1 row_mask:0xf bank_mask:0xf
	v_fmac_f32_dpp v254, v124, v170 row_shr:2 row_mask:0xf bank_mask:0xf
	v_fmac_f32_dpp v255, v125, v171 row_shr:2 row_mask:0xf bank_mask:0xf
	v_fmac_f32_dpp v148, v126, v172 row_shr:2 row_mask:0xf bank_mask:0xf
	v_fmac_f32_dpp v149, v127, v173 row_shr:2 row_mask:0xf bank_mask:0xf
	v_fmac_f32_dpp v254, v220, v186 row_ror:1 row_mask:0xf bank_mask:0x1
	v_fmac_f32_dpp v255, v221, v187 row_ror:1 row_mask:0xf bank_mask:0x1
	v_fmac_f32_dpp v148, v222, v188 row_ror:1 row_mask:0xf bank_mask:0x1
	v_fmac_f32_dpp v149, v223, v189 row_ror:1 row_mask:0xf bank_mask:0x1
	v_fmac_f32_dpp v254, v220, v170 row_ror:2 row_mask:0xf bank_mask:0x1
	v_fmac_f32_dpp v255, v221, v171 row_ror:2 row_mask:0xf bank_mask:0x1
	v_fmac_f32_dpp v148, v222, v172 row_ror:2 row_mask:0xf bank_mask:0x1
	v_fmac_f32_dpp v149, v223, v173 row_ror:2 row_mask:0xf bank_mask:0x1
	v_fma_f32 v246, |v254|, s38, 1.0
	v_fma_f32 v247, |v255|, s38, 1.0
	v_fma_f32 v248, |v148|, s38, 1.0
	v_fma_f32 v249, |v149|, s38, 1.0
	v_mul_f32_e32 v250, v254, v254
	v_mul_f32_e32 v251, v255, v255
	v_mul_f32_e32 v252, v148, v148
	v_mul_f32_e32 v253, v149, v149
	v_rcp_f32_e32 v246, v246
	v_rcp_f32_e32 v247, v247
	v_rcp_f32_e32 v248, v248
	v_rcp_f32_e32 v249, v249
	v_mul_f32_e32 v250, s72, v250
	v_mul_f32_e32 v251, s72, v251
	v_mul_f32_e32 v252, s72, v252
	v_mul_f32_e32 v253, s72, v253
	v_exp_f32_e32 v250, v250
	v_exp_f32_e32 v251, v251
	v_exp_f32_e32 v252, v252
	v_exp_f32_e32 v253, v253
	v_fmamk_f32 v238, v246, 0x3f07dc22, v219
	v_fmamk_f32 v239, v247, 0x3f07dc22, v219
	v_fmamk_f32 v240, v248, 0x3f07dc22, v219
	v_fmamk_f32 v241, v249, 0x3f07dc22, v219
	v_fma_f32 v238, v246, v238, s66
	v_fma_f32 v239, v247, v239, s66
	v_fma_f32 v240, v248, v240, s66
	v_fma_f32 v241, v249, v241, s66
	v_fma_f32 v238, v246, v238, s68
	v_fma_f32 v239, v247, v239, s68
	v_fma_f32 v240, v248, v240, s68
	v_fma_f32 v241, v249, v241, s68
	v_fma_f32 v238, v246, v238, s70
	v_fma_f32 v239, v247, v239, s70
	v_fma_f32 v240, v248, v240, s70
	v_fma_f32 v241, v249, v241, s70
	v_mul_f32_e32 v238, v246, v238
	v_mul_f32_e32 v239, v247, v239
	v_mul_f32_e32 v240, v248, v240
	v_mul_f32_e32 v241, v249, v241
	v_mul_f32_e32 v238, v250, v238
	v_mul_f32_e32 v239, v251, v239
	v_mul_f32_e32 v240, v252, v240
	v_mul_f32_e32 v241, v253, v241
	v_max_f32_e32 v246, 0, v254
	v_max_f32_e32 v247, 0, v255
	v_max_f32_e32 v248, 0, v148
	v_max_f32_e32 v249, 0, v149
	v_fma_f32 v238, -|v254|, v238, v246
	v_fma_f32 v239, -|v255|, v239, v247
	v_fma_f32 v240, -|v148|, v240, v248
	v_fma_f32 v241, -|v149|, v241, v249
	v_pk_fma_f32 v[254:255], v[210:211], v[108:109], v[140:141]
	v_pk_fma_f32 v[148:149], v[212:213], v[110:111], v[142:143]
	v_fmac_f32_dpp v254, v108, v194 row_shr:1 row_mask:0xf bank_mask:0xf
	v_fmac_f32_dpp v255, v109, v195 row_shr:1 row_mask:0xf bank_mask:0xf
	v_fmac_f32_dpp v148, v110, v196 row_shr:1 row_mask:0xf bank_mask:0xf
	v_fmac_f32_dpp v149, v111, v197 row_shr:1 row_mask:0xf bank_mask:0xf
	v_fmac_f32_dpp v254, v108, v178 row_shr:2 row_mask:0xf bank_mask:0xf
	v_fmac_f32_dpp v255, v109, v179 row_shr:2 row_mask:0xf bank_mask:0xf
	v_fmac_f32_dpp v148, v110, v180 row_shr:2 row_mask:0xf bank_mask:0xf
	v_fmac_f32_dpp v149, v111, v181 row_shr:2 row_mask:0xf bank_mask:0xf
	v_fmac_f32_dpp v254, v228, v194 row_ror:1 row_mask:0xf bank_mask:0x1
	v_fmac_f32_dpp v255, v229, v195 row_ror:1 row_mask:0xf bank_mask:0x1
	v_fmac_f32_dpp v148, v230, v196 row_ror:1 row_mask:0xf bank_mask:0x1
	v_fmac_f32_dpp v149, v231, v197 row_ror:1 row_mask:0xf bank_mask:0x1
	v_fmac_f32_dpp v254, v228, v178 row_ror:2 row_mask:0xf bank_mask:0x1
	v_fmac_f32_dpp v255, v229, v179 row_ror:2 row_mask:0xf bank_mask:0x1
	v_fmac_f32_dpp v148, v230, v180 row_ror:2 row_mask:0xf bank_mask:0x1
	v_fmac_f32_dpp v149, v231, v181 row_ror:2 row_mask:0xf bank_mask:0x1
	v_pk_mul_f32 v[254:255], v[238:239], v[254:255]
	v_pk_mul_f32 v[148:149], v[240:241], v[148:149]
	v_cvt_pk_bf16_f32 v242, v254, v255
	v_cvt_pk_bf16_f32 v243, v148, v149
	v_pk_fma_f32 v[254:255], v[206:207], v[92:93], v[136:137]
	v_pk_fma_f32 v[148:149], v[208:209], v[94:95], v[138:139]
	v_fmac_f32_dpp v254, v92, v190 row_shr:1 row_mask:0xf bank_mask:0xf
	v_fmac_f32_dpp v255, v93, v191 row_shr:1 row_mask:0xf bank_mask:0xf
	v_fmac_f32_dpp v148, v94, v192 row_shr:1 row_mask:0xf bank_mask:0xf
	v_fmac_f32_dpp v149, v95, v193 row_shr:1 row_mask:0xf bank_mask:0xf
	v_fmac_f32_dpp v254, v92, v174 row_shr:2 row_mask:0xf bank_mask:0xf
	v_fmac_f32_dpp v255, v93, v175 row_shr:2 row_mask:0xf bank_mask:0xf
	v_fmac_f32_dpp v148, v94, v176 row_shr:2 row_mask:0xf bank_mask:0xf
	v_fmac_f32_dpp v149, v95, v177 row_shr:2 row_mask:0xf bank_mask:0xf
	v_fmac_f32_dpp v254, v224, v190 row_ror:1 row_mask:0xf bank_mask:0x1
	v_fmac_f32_dpp v255, v225, v191 row_ror:1 row_mask:0xf bank_mask:0x1
	v_fmac_f32_dpp v148, v226, v192 row_ror:1 row_mask:0xf bank_mask:0x1
; __device__ __forceinline__ unsigned cvt_pk_bf16(float lo, float hi) { unsigned r; asm volatile("v_cvt_pk_bf16_f32 %0, %1, %2" : "=v"(r) : "v"(lo), "v"(hi)); return r; }
;     __device__ __forceinline__ void operator()(const f32x4 (&acc)[2][2][4][2], const Unit& u, int wr, int wc, int fr, int fq) const {
;     ...
; #pragma unroll
;                     for (int m = 0; m < 4; ++m) {
;                         f32x4 cv;
;                         if (!samp) {
;                             const f32x4 prev = m ? v[m - 1] : hv;
; #pragma unroll
;                             for (int e = 0; e < 4; ++e) {
;                                 const int vi = __float_as_int(v[m][e]), pi = __float_as_int(prev[e]);
;                                 const int o1 = __builtin_amdgcn_mov_dpp(pi, 0x121, 0xf, 0xf, false);
;                                 const int o2 = __builtin_amdgcn_mov_dpp(pi, 0x122, 0xf, 0xf, false);
;                                 const float p1 = __int_as_float(__builtin_amdgcn_update_dpp(o1, vi, 0x111, 0xf, 0xf, false));
;                                 const float p2 = __int_as_float(__builtin_amdgcn_update_dpp(o2, vi, 0x112, 0xf, 0xf, false));
;                                 cv[e] = cb[e] + cw0[e] * p2 + cw1[e] * p1 + cw2[e] * v[m][e];
;                             }
;                         } else {
;                             const int ns = rowb + 16 * m + fr - MP;
;                             f32x4 s0 = (f32x4){0.f, 0.f, 0.f, 0.f}, s1 = s0;
;                             if (ns < NS) {
;                                 s0 = *(const f32x4*)(state + (size_t)(ns * 2 + 0) * FF2 + oc); s1 = *(const f32x4*)(state + (size_t)(ns * 2 + 1) * FF2 + oc);
;                                 *(f32x4*)(ncs + (size_t)(ns * 2 + 0) * FF2 + oc) = s1; *(f32x4*)(ncs + (size_t)(ns * 2 + 1) * FF2 + oc) = v[m];
;                             }
;                             cv = cb + cw0 * s0 + cw1 * s1 + cw2 * v[m];
;                         }
;                         if (bj == 0) cg[m] = gelu4(cv);
;                         else {
;                             const f32x4 r = cg[m] * cv;
;                             v2u w; w.x = cvt_pk_bf16(r[0], r[1]); w.y = cvt_pk_bf16(r[2], r[3]);
;                             *(v2u*)(ACT + (size_t)(rowb + 16 * m + fr) * FF + 128 * u.pn + 32 * wc + 8 * fq + 4 * n) = w;
	v_fmac_f32_dpp v149, v227, v193 row_ror:1 row_mask:0xf bank_mask:0x1
	v_fmac_f32_dpp v254, v224, v174 row_ror:2 row_mask:0xf bank_mask:0x1
	v_fmac_f32_dpp v255, v225, v175 row_ror:2 row_mask:0xf bank_mask:0x1
	v_fmac_f32_dpp v148, v226, v176 row_ror:2 row_mask:0xf bank_mask:0x1
	v_fmac_f32_dpp v149, v227, v177 row_ror:2 row_mask:0xf bank_mask:0x1
	v_fma_f32 v246, |v254|, s38, 1.0
	v_fma_f32 v247, |v255|, s38, 1.0
	v_fma_f32 v248, |v148|, s38, 1.0
	v_fma_f32 v249, |v149|, s38, 1.0
	v_mul_f32_e32 v250, v254, v254
	v_mul_f32_e32 v251, v255, v255
	v_mul_f32_e32 v252, v148, v148
	v_mul_f32_e32 v253, v149, v149
	v_rcp_f32_e32 v246, v246
	v_rcp_f32_e32 v247, v247
	v_rcp_f32_e32 v248, v248
	v_rcp_f32_e32 v249, v249
	v_mul_f32_e32 v250, s72, v250
	v_mul_f32_e32 v251, s72, v251
	v_mul_f32_e32 v252, s72, v252
	v_mul_f32_e32 v253, s72, v253
	v_exp_f32_e32 v250, v250
	v_exp_f32_e32 v251, v251
	v_exp_f32_e32 v252, v252
	v_exp_f32_e32 v253, v253
	v_fmamk_f32 v238, v246, 0x3f07dc22, v219
	v_fmamk_f32 v239, v247, 0x3f07dc22, v219
	v_fmamk_f32 v240, v248, 0x3f07dc22, v219
	v_fmamk_f32 v241, v249, 0x3f07dc22, v219
	v_fma_f32 v238, v246, v238, s66
	v_fma_f32 v239, v247, v239, s66
	v_fma_f32 v240, v248, v240, s66
	v_fma_f32 v241, v249, v241, s66
	v_fma_f32 v238, v246, v238, s68
	v_fma_f32 v239, v247, v239, s68
	v_fma_f32 v240, v248, v240, s68
	v_fma_f32 v241, v249, v241, s68
	v_fma_f32 v238, v246, v238, s70
	v_fma_f32 v239, v247, v239, s70
	v_fma_f32 v240, v248, v240, s70
	v_fma_f32 v241, v249, v241, s70
	v_mul_f32_e32 v238, v246, v238
	v_mul_f32_e32 v239, v247, v239
	v_mul_f32_e32 v240, v248, v240
	v_mul_f32_e32 v241, v249, v241
	v_mul_f32_e32 v238, v250, v238
	v_mul_f32_e32 v239, v251, v239
	v_mul_f32_e32 v240, v252, v240
	v_mul_f32_e32 v241, v253, v241
	v_max_f32_e32 v246, 0, v254
	v_max_f32_e32 v247, 0, v255
	v_max_f32_e32 v248, 0, v148
	v_max_f32_e32 v249, 0, v149
	v_fma_f32 v238, -|v254|, v238, v246
	v_fma_f32 v239, -|v255|, v239, v247
	v_fma_f32 v240, -|v148|, v240, v248
	v_fma_f32 v241, -|v149|, v241, v249
	v_pk_fma_f32 v[254:255], v[128:129], v[76:77], v[144:145]
	v_pk_fma_f32 v[148:149], v[130:131], v[78:79], v[146:147]
	v_fmac_f32_dpp v254, v76, v198 row_shr:1 row_mask:0xf bank_mask:0xf
	v_fmac_f32_dpp v255, v77, v199 row_shr:1 row_mask:0xf bank_mask:0xf
	v_fmac_f32_dpp v148, v78, v200 row_shr:1 row_mask:0xf bank_mask:0xf
	v_fmac_f32_dpp v149, v79, v201 row_shr:1 row_mask:0xf bank_mask:0xf
	v_fmac_f32_dpp v254, v76, v182 row_shr:2 row_mask:0xf bank_mask:0xf
	v_fmac_f32_dpp v255, v77, v183 row_shr:2 row_mask:0xf bank_mask:0xf
	v_fmac_f32_dpp v148, v78, v184 row_shr:2 row_mask:0xf bank_mask:0xf
	v_fmac_f32_dpp v149, v79, v185 row_shr:2 row_mask:0xf bank_mask:0xf
	v_fmac_f32_dpp v254, v232, v198 row_ror:1 row_mask:0xf bank_mask:0x1
	v_fmac_f32_dpp v255, v233, v199 row_ror:1 row_mask:0xf bank_mask:0x1
	v_fmac_f32_dpp v148, v234, v200 row_ror:1 row_mask:0xf bank_mask:0x1
	v_fmac_f32_dpp v149, v235, v201 row_ror:1 row_mask:0xf bank_mask:0x1
	v_fmac_f32_dpp v254, v232, v182 row_ror:2 row_mask:0xf bank_mask:0x1
	v_fmac_f32_dpp v255, v233, v183 row_ror:2 row_mask:0xf bank_mask:0x1
	v_fmac_f32_dpp v148, v234, v184 row_ror:2 row_mask:0xf bank_mask:0x1
	v_fmac_f32_dpp v149, v235, v185 row_ror:2 row_mask:0xf bank_mask:0x1
	v_pk_mul_f32 v[254:255], v[238:239], v[254:255]
	v_pk_mul_f32 v[148:149], v[240:241], v[148:149]
	v_cvt_pk_bf16_f32 v244, v254, v255
	v_cvt_pk_bf16_f32 v245, v148, v149
	global_store_dwordx4 v151, v[242:245], s[46:47]
	v_add_u32_e32 v150, 0x16000, v150
	s_mov_b64 s[14:15], exec
	s_mov_b64 exec, s[10:11]
	global_load_dwordx4 v[220:223], v150, s[44:45]
	global_load_dwordx4 v[224:227], v150, s[44:45] offset:16
	global_load_dwordx4 v[228:231], v150, s[44:45] offset:512
	global_load_dwordx4 v[232:235], v150, s[44:45] offset:528
	s_mov_b64 exec, s[14:15]
	v_mov_b32_dpp v112, v48 quad_perm:[0,1,2,3] row_mask:0xf bank_mask:0x8
	v_mov_b32_dpp v113, v49 quad_perm:[0,1,2,3] row_mask:0xf bank_mask:0x8
	v_mov_b32_dpp v114, v50 quad_perm:[0,1,2,3] row_mask:0xf bank_mask:0x8
	v_mov_b32_dpp v115, v51 quad_perm:[0,1,2,3] row_mask:0xf bank_mask:0x8
	v_pk_fma_f32 v[254:255], v[202:203], v[56:57], v[132:133]
	v_pk_fma_f32 v[148:149], v[204:205], v[58:59], v[134:135]
	v_fmac_f32_dpp v254, v56, v186 row_shr:1 row_mask:0xf bank_mask:0xf
	v_fmac_f32_dpp v255, v57, v187 row_shr:1 row_mask:0xf bank_mask:0xf
	v_fmac_f32_dpp v148, v58, v188 row_shr:1 row_mask:0xf bank_mask:0xf
	v_fmac_f32_dpp v149, v59, v189 row_shr:1 row_mask:0xf bank_mask:0xf
	v_fmac_f32_dpp v254, v56, v170 row_shr:2 row_mask:0xf bank_mask:0xf
	v_fmac_f32_dpp v255, v57, v171 row_shr:2 row_mask:0xf bank_mask:0xf
	v_fmac_f32_dpp v148, v58, v172 row_shr:2 row_mask:0xf bank_mask:0xf
	v_fmac_f32_dpp v149, v59, v173 row_shr:2 row_mask:0xf bank_mask:0xf
	v_fmac_f32_dpp v254, v112, v186 row_ror:1 row_mask:0xf bank_mask:0x1
	v_fmac_f32_dpp v255, v113, v187 row_ror:1 row_mask:0xf bank_mask:0x1
	v_fmac_f32_dpp v148, v114, v188 row_ror:1 row_mask:0xf bank_mask:0x1
	v_fmac_f32_dpp v149, v115, v189 row_ror:1 row_mask:0xf bank_mask:0x1
	v_fmac_f32_dpp v254, v112, v170 row_ror:2 row_mask:0xf bank_mask:0x1
	v_fmac_f32_dpp v255, v113, v171 row_ror:2 row_mask:0xf bank_mask:0x1
	v_fmac_f32_dpp v148, v114, v172 row_ror:2 row_mask:0xf bank_mask:0x1
	v_fmac_f32_dpp v149, v115, v173 row_ror:2 row_mask:0xf bank_mask:0x1
	v_fma_f32 v246, |v254|, s38, 1.0
	v_fma_f32 v247, |v255|, s38, 1.0
	v_fma_f32 v248, |v148|, s38, 1.0
	v_fma_f32 v249, |v149|, s38, 1.0
	v_mul_f32_e32 v250, v254, v254
	v_mul_f32_e32 v251, v255, v255
	v_mul_f32_e32 v252, v148, v148
	v_mul_f32_e32 v253, v149, v149
	v_rcp_f32_e32 v246, v246
	v_rcp_f32_e32 v247, v247
; __device__ __forceinline__ unsigned cvt_pk_bf16(float lo, float hi) { unsigned r; asm volatile("v_cvt_pk_bf16_f32 %0, %1, %2" : "=v"(r) : "v"(lo), "v"(hi)); return r; }
;     __device__ __forceinline__ void operator()(const f32x4 (&acc)[2][2][4][2], const Unit& u, int wr, int wc, int fr, int fq) const {
;     ...
; #pragma unroll
;                     for (int m = 0; m < 4; ++m) {
;                         f32x4 cv;
;                         if (!samp) {
;                             const f32x4 prev = m ? v[m - 1] : hv;
; #pragma unroll
;                             for (int e = 0; e < 4; ++e) {
;                                 const int vi = __float_as_int(v[m][e]), pi = __float_as_int(prev[e]);
;                                 const int o1 = __builtin_amdgcn_mov_dpp(pi, 0x121, 0xf, 0xf, false);
;                                 const int o2 = __builtin_amdgcn_mov_dpp(pi, 0x122, 0xf, 0xf, false);
;                                 const float p1 = __int_as_float(__builtin_amdgcn_update_dpp(o1, vi, 0x111, 0xf, 0xf, false));
;                                 const float p2 = __int_as_float(__builtin_amdgcn_update_dpp(o2, vi, 0x112, 0xf, 0xf, false));
;                                 cv[e] = cb[e] + cw0[e] * p2 + cw1[e] * p1 + cw2[e] * v[m][e];
;                             }
;                         } else {
;                             const int ns = rowb + 16 * m + fr - MP;
;                             f32x4 s0 = (f32x4){0.f, 0.f, 0.f, 0.f}, s1 = s0;
;                             if (ns < NS) {
;                                 s0 = *(const f32x4*)(state + (size_t)(ns * 2 + 0) * FF2 + oc); s1 = *(const f32x4*)(state + (size_t)(ns * 2 + 1) * FF2 + oc);
;                                 *(f32x4*)(ncs + (size_t)(ns * 2 + 0) * FF2 + oc) = s1; *(f32x4*)(ncs + (size_t)(ns * 2 + 1) * FF2 + oc) = v[m];
;                             }
;                             cv = cb + cw0 * s0 + cw1 * s1 + cw2 * v[m];
;                         }
;                         if (bj == 0) cg[m] = gelu4(cv);
;                         else {
;                             const f32x4 r = cg[m] * cv;
;                             v2u w; w.x = cvt_pk_bf16(r[0], r[1]); w.y = cvt_pk_bf16(r[2], r[3]);
;                             *(v2u*)(ACT + (size_t)(rowb + 16 * m + fr) * FF + 128 * u.pn + 32 * wc + 8 * fq + 4 * n) = w;
	v_rcp_f32_e32 v248, v248
	v_rcp_f32_e32 v249, v249
	v_mul_f32_e32 v250, s72, v250
	v_mul_f32_e32 v251, s72, v251
	v_mul_f32_e32 v252, s72, v252
	v_mul_f32_e32 v253, s72, v253
	v_exp_f32_e32 v250, v250
	v_exp_f32_e32 v251, v251
	v_exp_f32_e32 v252, v252
	v_exp_f32_e32 v253, v253
	v_fmamk_f32 v238, v246, 0x3f07dc22, v219
	v_fmamk_f32 v239, v247, 0x3f07dc22, v219
	v_fmamk_f32 v240, v248, 0x3f07dc22, v219
	v_fmamk_f32 v241, v249, 0x3f07dc22, v219
	v_fma_f32 v238, v246, v238, s66
	v_fma_f32 v239, v247, v239, s66
	v_fma_f32 v240, v248, v240, s66
	v_fma_f32 v241, v249, v241, s66
	v_fma_f32 v238, v246, v238, s68
	v_fma_f32 v239, v247, v239, s68
	v_fma_f32 v240, v248, v240, s68
	v_fma_f32 v241, v249, v241, s68
	v_fma_f32 v238, v246, v238, s70
	v_fma_f32 v239, v247, v239, s70
	v_fma_f32 v240, v248, v240, s70
	v_fma_f32 v241, v249, v241, s70
	v_mul_f32_e32 v238, v246, v238
	v_mul_f32_e32 v239, v247, v239
	v_mul_f32_e32 v240, v248, v240
	v_mul_f32_e32 v241, v249, v241
	v_mul_f32_e32 v238, v250, v238
	v_mul_f32_e32 v239, v251, v239
	v_mul_f32_e32 v240, v252, v240
	v_mul_f32_e32 v241, v253, v241
	v_max_f32_e32 v246, 0, v254
	v_max_f32_e32 v247, 0, v255
	v_max_f32_e32 v248, 0, v148
	v_max_f32_e32 v249, 0, v149
	v_fma_f32 v238, -|v254|, v238, v246
	v_fma_f32 v239, -|v255|, v239, v247
	v_fma_f32 v240, -|v148|, v240, v248
	v_fma_f32 v241, -|v149|, v241, v249
	v_mov_b32_dpp v112, v32 quad_perm:[0,1,2,3] row_mask:0xf bank_mask:0x8
	v_mov_b32_dpp v113, v33 quad_perm:[0,1,2,3] row_mask:0xf bank_mask:0x8
	v_mov_b32_dpp v114, v34 quad_perm:[0,1,2,3] row_mask:0xf bank_mask:0x8
	v_mov_b32_dpp v115, v35 quad_perm:[0,1,2,3] row_mask:0xf bank_mask:0x8
	v_pk_fma_f32 v[254:255], v[210:211], v[40:41], v[140:141]
	v_pk_fma_f32 v[148:149], v[212:213], v[42:43], v[142:143]
	v_fmac_f32_dpp v254, v40, v194 row_shr:1 row_mask:0xf bank_mask:0xf
	v_fmac_f32_dpp v255, v41, v195 row_shr:1 row_mask:0xf bank_mask:0xf
	v_fmac_f32_dpp v148, v42, v196 row_shr:1 row_mask:0xf bank_mask:0xf
	v_fmac_f32_dpp v149, v43, v197 row_shr:1 row_mask:0xf bank_mask:0xf
	v_fmac_f32_dpp v254, v40, v178 row_shr:2 row_mask:0xf bank_mask:0xf
	v_fmac_f32_dpp v255, v41, v179 row_shr:2 row_mask:0xf bank_mask:0xf
	v_fmac_f32_dpp v148, v42, v180 row_shr:2 row_mask:0xf bank_mask:0xf
	v_fmac_f32_dpp v149, v43, v181 row_shr:2 row_mask:0xf bank_mask:0xf
	v_fmac_f32_dpp v254, v112, v194 row_ror:1 row_mask:0xf bank_mask:0x1
	v_fmac_f32_dpp v255, v113, v195 row_ror:1 row_mask:0xf bank_mask:0x1
	v_fmac_f32_dpp v148, v114, v196 row_ror:1 row_mask:0xf bank_mask:0x1
	v_fmac_f32_dpp v149, v115, v197 row_ror:1 row_mask:0xf bank_mask:0x1
	v_fmac_f32_dpp v254, v112, v178 row_ror:2 row_mask:0xf bank_mask:0x1
	v_fmac_f32_dpp v255, v113, v179 row_ror:2 row_mask:0xf bank_mask:0x1
	v_fmac_f32_dpp v148, v114, v180 row_ror:2 row_mask:0xf bank_mask:0x1
	v_fmac_f32_dpp v149, v115, v181 row_ror:2 row_mask:0xf bank_mask:0x1
	v_pk_mul_f32 v[254:255], v[238:239], v[254:255]
	v_pk_mul_f32 v[148:149], v[240:241], v[148:149]
	v_cvt_pk_bf16_f32 v242, v254, v255
	v_cvt_pk_bf16_f32 v243, v148, v149
	v_mov_b32_dpp v112, v16 quad_perm:[0,1,2,3] row_mask:0xf bank_mask:0x8
	v_mov_b32_dpp v113, v17 quad_perm:[0,1,2,3] row_mask:0xf bank_mask:0x8
	v_mov_b32_dpp v114, v18 quad_perm:[0,1,2,3] row_mask:0xf bank_mask:0x8
	v_mov_b32_dpp v115, v19 quad_perm:[0,1,2,3] row_mask:0xf bank_mask:0x8
	v_pk_fma_f32 v[254:255], v[206:207], v[24:25], v[136:137]
	v_pk_fma_f32 v[148:149], v[208:209], v[26:27], v[138:139]
	v_fmac_f32_dpp v254, v24, v190 row_shr:1 row_mask:0xf bank_mask:0xf
	v_fmac_f32_dpp v255, v25, v191 row_shr:1 row_mask:0xf bank_mask:0xf
	v_fmac_f32_dpp v148, v26, v192 row_shr:1 row_mask:0xf bank_mask:0xf
	v_fmac_f32_dpp v149, v27, v193 row_shr:1 row_mask:0xf bank_mask:0xf
	v_fmac_f32_dpp v254, v24, v174 row_shr:2 row_mask:0xf bank_mask:0xf
	v_fmac_f32_dpp v255, v25, v175 row_shr:2 row_mask:0xf bank_mask:0xf
	v_fmac_f32_dpp v148, v26, v176 row_shr:2 row_mask:0xf bank_mask:0xf
	v_fmac_f32_dpp v149, v27, v177 row_shr:2 row_mask:0xf bank_mask:0xf
	v_fmac_f32_dpp v254, v112, v190 row_ror:1 row_mask:0xf bank_mask:0x1
	v_fmac_f32_dpp v255, v113, v191 row_ror:1 row_mask:0xf bank_mask:0x1
	v_fmac_f32_dpp v148, v114, v192 row_ror:1 row_mask:0xf bank_mask:0x1
	v_fmac_f32_dpp v149, v115, v193 row_ror:1 row_mask:0xf bank_mask:0x1
	v_fmac_f32_dpp v254, v112, v174 row_ror:2 row_mask:0xf bank_mask:0x1
	v_fmac_f32_dpp v255, v113, v175 row_ror:2 row_mask:0xf bank_mask:0x1
	v_fmac_f32_dpp v148, v114, v176 row_ror:2 row_mask:0xf bank_mask:0x1
	v_fmac_f32_dpp v149, v115, v177 row_ror:2 row_mask:0xf bank_mask:0x1
	v_fma_f32 v246, |v254|, s38, 1.0
	v_fma_f32 v247, |v255|, s38, 1.0
	v_fma_f32 v248, |v148|, s38, 1.0
	v_fma_f32 v249, |v149|, s38, 1.0
	v_mul_f32_e32 v250, v254, v254
	v_mul_f32_e32 v251, v255, v255
	v_mul_f32_e32 v252, v148, v148
	v_mul_f32_e32 v253, v149, v149
	v_rcp_f32_e32 v246, v246
	v_rcp_f32_e32 v247, v247
	v_rcp_f32_e32 v248, v248
	v_rcp_f32_e32 v249, v249
	v_mul_f32_e32 v250, s72, v250
	v_mul_f32_e32 v251, s72, v251
	v_mul_f32_e32 v252, s72, v252
	v_mul_f32_e32 v253, s72, v253
	v_exp_f32_e32 v250, v250
	v_exp_f32_e32 v251, v251
	v_exp_f32_e32 v252, v252
	v_exp_f32_e32 v253, v253
	v_fmamk_f32 v238, v246, 0x3f07dc22, v219
	v_fmamk_f32 v239, v247, 0x3f07dc22, v219
	v_fmamk_f32 v240, v248, 0x3f07dc22, v219
	v_fmamk_f32 v241, v249, 0x3f07dc22, v219
	v_fma_f32 v238, v246, v238, s66
	v_fma_f32 v239, v247, v239, s66
	v_fma_f32 v240, v248, v240, s66
	v_fma_f32 v241, v249, v241, s66
	v_fma_f32 v238, v246, v238, s68
	v_fma_f32 v239, v247, v239, s68
	v_fma_f32 v240, v248, v240, s68
	v_fma_f32 v241, v249, v241, s68
	v_fma_f32 v238, v246, v238, s70
; __device__ __forceinline__ unsigned cvt_pk_bf16(float lo, float hi) { unsigned r; asm volatile("v_cvt_pk_bf16_f32 %0, %1, %2" : "=v"(r) : "v"(lo), "v"(hi)); return r; }
;     __device__ __forceinline__ void operator()(const f32x4 (&acc)[2][2][4][2], const Unit& u, int wr, int wc, int fr, int fq) const {
;     ...
; #pragma unroll
;                     for (int m = 0; m < 4; ++m) {
;                         f32x4 cv;
;                         if (!samp) {
;                             const f32x4 prev = m ? v[m - 1] : hv;
; #pragma unroll
;                             for (int e = 0; e < 4; ++e) {
;                                 const int vi = __float_as_int(v[m][e]), pi = __float_as_int(prev[e]);
;                                 const int o1 = __builtin_amdgcn_mov_dpp(pi, 0x121, 0xf, 0xf, false);
;                                 const int o2 = __builtin_amdgcn_mov_dpp(pi, 0x122, 0xf, 0xf, false);
;                                 const float p1 = __int_as_float(__builtin_amdgcn_update_dpp(o1, vi, 0x111, 0xf, 0xf, false));
;                                 const float p2 = __int_as_float(__builtin_amdgcn_update_dpp(o2, vi, 0x112, 0xf, 0xf, false));
;                                 cv[e] = cb[e] + cw0[e] * p2 + cw1[e] * p1 + cw2[e] * v[m][e];
;                             }
;                         } else {
;                             const int ns = rowb + 16 * m + fr - MP;
;                             f32x4 s0 = (f32x4){0.f, 0.f, 0.f, 0.f}, s1 = s0;
;                             if (ns < NS) {
;                                 s0 = *(const f32x4*)(state + (size_t)(ns * 2 + 0) * FF2 + oc); s1 = *(const f32x4*)(state + (size_t)(ns * 2 + 1) * FF2 + oc);
;                                 *(f32x4*)(ncs + (size_t)(ns * 2 + 0) * FF2 + oc) = s1; *(f32x4*)(ncs + (size_t)(ns * 2 + 1) * FF2 + oc) = v[m];
;                             }
;                             cv = cb + cw0 * s0 + cw1 * s1 + cw2 * v[m];
;                         }
;                         if (bj == 0) cg[m] = gelu4(cv);
;                         else {
;                             const f32x4 r = cg[m] * cv;
;                             v2u w; w.x = cvt_pk_bf16(r[0], r[1]); w.y = cvt_pk_bf16(r[2], r[3]);
;                             *(v2u*)(ACT + (size_t)(rowb + 16 * m + fr) * FF + 128 * u.pn + 32 * wc + 8 * fq + 4 * n) = w;
	v_fma_f32 v239, v247, v239, s70
	v_fma_f32 v240, v248, v240, s70
	v_fma_f32 v241, v249, v241, s70
	v_mul_f32_e32 v238, v246, v238
	v_mul_f32_e32 v239, v247, v239
	v_mul_f32_e32 v240, v248, v240
	v_mul_f32_e32 v241, v249, v241
	v_mul_f32_e32 v238, v250, v238
	v_mul_f32_e32 v239, v251, v239
	v_mul_f32_e32 v240, v252, v240
	v_mul_f32_e32 v241, v253, v241
	v_max_f32_e32 v246, 0, v254
	v_max_f32_e32 v247, 0, v255
	v_max_f32_e32 v248, 0, v148
	v_max_f32_e32 v249, 0, v149
	v_fma_f32 v238, -|v254|, v238, v246
	v_fma_f32 v239, -|v255|, v239, v247
	v_fma_f32 v240, -|v148|, v240, v248
	v_fma_f32 v241, -|v149|, v241, v249
	v_mov_b32_dpp v112, v0 quad_perm:[0,1,2,3] row_mask:0xf bank_mask:0x8
	v_mov_b32_dpp v113, v1 quad_perm:[0,1,2,3] row_mask:0xf bank_mask:0x8
	v_mov_b32_dpp v114, v2 quad_perm:[0,1,2,3] row_mask:0xf bank_mask:0x8
	v_mov_b32_dpp v115, v3 quad_perm:[0,1,2,3] row_mask:0xf bank_mask:0x8
	v_pk_fma_f32 v[254:255], v[128:129], v[8:9], v[144:145]
	v_pk_fma_f32 v[148:149], v[130:131], v[10:11], v[146:147]
	v_fmac_f32_dpp v254, v8, v198 row_shr:1 row_mask:0xf bank_mask:0xf
	v_fmac_f32_dpp v255, v9, v199 row_shr:1 row_mask:0xf bank_mask:0xf
	v_fmac_f32_dpp v148, v10, v200 row_shr:1 row_mask:0xf bank_mask:0xf
	v_fmac_f32_dpp v149, v11, v201 row_shr:1 row_mask:0xf bank_mask:0xf
	v_fmac_f32_dpp v254, v8, v182 row_shr:2 row_mask:0xf bank_mask:0xf
	v_fmac_f32_dpp v255, v9, v183 row_shr:2 row_mask:0xf bank_mask:0xf
	v_fmac_f32_dpp v148, v10, v184 row_shr:2 row_mask:0xf bank_mask:0xf
	v_fmac_f32_dpp v149, v11, v185 row_shr:2 row_mask:0xf bank_mask:0xf
	v_fmac_f32_dpp v254, v112, v198 row_ror:1 row_mask:0xf bank_mask:0x1
	v_fmac_f32_dpp v255, v113, v199 row_ror:1 row_mask:0xf bank_mask:0x1
	v_fmac_f32_dpp v148, v114, v200 row_ror:1 row_mask:0xf bank_mask:0x1
	v_fmac_f32_dpp v149, v115, v201 row_ror:1 row_mask:0xf bank_mask:0x1
	v_fmac_f32_dpp v254, v112, v182 row_ror:2 row_mask:0xf bank_mask:0x1
	v_fmac_f32_dpp v255, v113, v183 row_ror:2 row_mask:0xf bank_mask:0x1
	v_fmac_f32_dpp v148, v114, v184 row_ror:2 row_mask:0xf bank_mask:0x1
	v_fmac_f32_dpp v149, v115, v185 row_ror:2 row_mask:0xf bank_mask:0x1
	v_pk_mul_f32 v[254:255], v[238:239], v[254:255]
	v_pk_mul_f32 v[148:149], v[240:241], v[148:149]
	v_cvt_pk_bf16_f32 v244, v254, v255
	v_cvt_pk_bf16_f32 v245, v148, v149
	s_add_u32 s56, s46, 0xf2000
	s_addc_u32 s57, s47, 0
	global_store_dwordx4 v151, v[242:245], s[56:57]
	v_mov_b32_dpp v112, v52 quad_perm:[0,1,2,3] row_mask:0xf bank_mask:0x8
	v_mov_b32_dpp v113, v53 quad_perm:[0,1,2,3] row_mask:0xf bank_mask:0x8
	v_mov_b32_dpp v114, v54 quad_perm:[0,1,2,3] row_mask:0xf bank_mask:0x8
	v_mov_b32_dpp v115, v55 quad_perm:[0,1,2,3] row_mask:0xf bank_mask:0x8
	v_pk_fma_f32 v[254:255], v[202:203], v[48:49], v[132:133]
	v_pk_fma_f32 v[148:149], v[204:205], v[50:51], v[134:135]
	v_fmac_f32_dpp v254, v48, v186 row_shr:1 row_mask:0xf bank_mask:0xf
	v_fmac_f32_dpp v255, v49, v187 row_shr:1 row_mask:0xf bank_mask:0xf
	v_fmac_f32_dpp v148, v50, v188 row_shr:1 row_mask:0xf bank_mask:0xf
	v_fmac_f32_dpp v149, v51, v189 row_shr:1 row_mask:0xf bank_mask:0xf
	v_fmac_f32_dpp v254, v48, v170 row_shr:2 row_mask:0xf bank_mask:0xf
	v_fmac_f32_dpp v255, v49, v171 row_shr:2 row_mask:0xf bank_mask:0xf
	v_fmac_f32_dpp v148, v50, v172 row_shr:2 row_mask:0xf bank_mask:0xf
	v_fmac_f32_dpp v149, v51, v173 row_shr:2 row_mask:0xf bank_mask:0xf
	v_fmac_f32_dpp v254, v112, v186 row_ror:1 row_mask:0xf bank_mask:0x1
	v_fmac_f32_dpp v255, v113, v187 row_ror:1 row_mask:0xf bank_mask:0x1
	v_fmac_f32_dpp v148, v114, v188 row_ror:1 row_mask:0xf bank_mask:0x1
	v_fmac_f32_dpp v149, v115, v189 row_ror:1 row_mask:0xf bank_mask:0x1
	v_fmac_f32_dpp v254, v112, v170 row_ror:2 row_mask:0xf bank_mask:0x1
	v_fmac_f32_dpp v255, v113, v171 row_ror:2 row_mask:0xf bank_mask:0x1
	v_fmac_f32_dpp v148, v114, v172 row_ror:2 row_mask:0xf bank_mask:0x1
	v_fmac_f32_dpp v149, v115, v173 row_ror:2 row_mask:0xf bank_mask:0x1
	v_fma_f32 v246, |v254|, s38, 1.0
	v_fma_f32 v247, |v255|, s38, 1.0
	v_fma_f32 v248, |v148|, s38, 1.0
	v_fma_f32 v249, |v149|, s38, 1.0
	v_mul_f32_e32 v250, v254, v254
	v_mul_f32_e32 v251, v255, v255
	v_mul_f32_e32 v252, v148, v148
	v_mul_f32_e32 v253, v149, v149
	v_rcp_f32_e32 v246, v246
	v_rcp_f32_e32 v247, v247
	v_rcp_f32_e32 v248, v248
	v_rcp_f32_e32 v249, v249
	v_mul_f32_e32 v250, s72, v250
	v_mul_f32_e32 v251, s72, v251
	v_mul_f32_e32 v252, s72, v252
	v_mul_f32_e32 v253, s72, v253
	v_exp_f32_e32 v250, v250
	v_exp_f32_e32 v251, v251
	v_exp_f32_e32 v252, v252
	v_exp_f32_e32 v253, v253
	v_fmamk_f32 v238, v246, 0x3f07dc22, v219
	v_fmamk_f32 v239, v247, 0x3f07dc22, v219
	v_fmamk_f32 v240, v248, 0x3f07dc22, v219
	v_fmamk_f32 v241, v249, 0x3f07dc22, v219
	v_fma_f32 v238, v246, v238, s66
	v_fma_f32 v239, v247, v239, s66
	v_fma_f32 v240, v248, v240, s66
	v_fma_f32 v241, v249, v241, s66
	v_fma_f32 v238, v246, v238, s68
	v_fma_f32 v239, v247, v239, s68
	v_fma_f32 v240, v248, v240, s68
	v_fma_f32 v241, v249, v241, s68
	v_fma_f32 v238, v246, v238, s70
	v_fma_f32 v239, v247, v239, s70
	v_fma_f32 v240, v248, v240, s70
	v_fma_f32 v241, v249, v241, s70
	v_mul_f32_e32 v238, v246, v238
	v_mul_f32_e32 v239, v247, v239
	v_mul_f32_e32 v240, v248, v240
	v_mul_f32_e32 v241, v249, v241
	v_mul_f32_e32 v238, v250, v238
	v_mul_f32_e32 v239, v251, v239
	v_mul_f32_e32 v240, v252, v240
	v_mul_f32_e32 v241, v253, v241
	v_max_f32_e32 v246, 0, v254
	v_max_f32_e32 v247, 0, v255
	v_max_f32_e32 v248, 0, v148
	v_max_f32_e32 v249, 0, v149
	v_fma_f32 v238, -|v254|, v238, v246
	v_fma_f32 v239, -|v255|, v239, v247
	v_fma_f32 v240, -|v148|, v240, v248
	v_fma_f32 v241, -|v149|, v241, v249
	v_mov_b32_dpp v112, v36 quad_perm:[0,1,2,3] row_mask:0xf bank_mask:0x8
; __device__ __forceinline__ unsigned cvt_pk_bf16(float lo, float hi) { unsigned r; asm volatile("v_cvt_pk_bf16_f32 %0, %1, %2" : "=v"(r) : "v"(lo), "v"(hi)); return r; }
;     __device__ __forceinline__ void operator()(const f32x4 (&acc)[2][2][4][2], const Unit& u, int wr, int wc, int fr, int fq) const {
;     ...
; #pragma unroll
;                     for (int m = 0; m < 4; ++m) {
;                         f32x4 cv;
;                         if (!samp) {
;                             const f32x4 prev = m ? v[m - 1] : hv;
; #pragma unroll
;                             for (int e = 0; e < 4; ++e) {
;                                 const int vi = __float_as_int(v[m][e]), pi = __float_as_int(prev[e]);
;                                 const int o1 = __builtin_amdgcn_mov_dpp(pi, 0x121, 0xf, 0xf, false);
;                                 const int o2 = __builtin_amdgcn_mov_dpp(pi, 0x122, 0xf, 0xf, false);
;                                 const float p1 = __int_as_float(__builtin_amdgcn_update_dpp(o1, vi, 0x111, 0xf, 0xf, false));
;                                 const float p2 = __int_as_float(__builtin_amdgcn_update_dpp(o2, vi, 0x112, 0xf, 0xf, false));
;                                 cv[e] = cb[e] + cw0[e] * p2 + cw1[e] * p1 + cw2[e] * v[m][e];
;                             }
;                         } else {
;                             const int ns = rowb + 16 * m + fr - MP;
;                             f32x4 s0 = (f32x4){0.f, 0.f, 0.f, 0.f}, s1 = s0;
;                             if (ns < NS) {
;                                 s0 = *(const f32x4*)(state + (size_t)(ns * 2 + 0) * FF2 + oc); s1 = *(const f32x4*)(state + (size_t)(ns * 2 + 1) * FF2 + oc);
;                                 *(f32x4*)(ncs + (size_t)(ns * 2 + 0) * FF2 + oc) = s1; *(f32x4*)(ncs + (size_t)(ns * 2 + 1) * FF2 + oc) = v[m];
;                             }
;                             cv = cb + cw0 * s0 + cw1 * s1 + cw2 * v[m];
;                         }
;                         if (bj == 0) cg[m] = gelu4(cv);
;                         else {
;                             const f32x4 r = cg[m] * cv;
;                             v2u w; w.x = cvt_pk_bf16(r[0], r[1]); w.y = cvt_pk_bf16(r[2], r[3]);
;                             *(v2u*)(ACT + (size_t)(rowb + 16 * m + fr) * FF + 128 * u.pn + 32 * wc + 8 * fq + 4 * n) = w;
	v_mov_b32_dpp v113, v37 quad_perm:[0,1,2,3] row_mask:0xf bank_mask:0x8
	v_mov_b32_dpp v114, v38 quad_perm:[0,1,2,3] row_mask:0xf bank_mask:0x8
	v_mov_b32_dpp v115, v39 quad_perm:[0,1,2,3] row_mask:0xf bank_mask:0x8
	v_pk_fma_f32 v[254:255], v[210:211], v[32:33], v[140:141]
	v_pk_fma_f32 v[148:149], v[212:213], v[34:35], v[142:143]
	v_fmac_f32_dpp v254, v32, v194 row_shr:1 row_mask:0xf bank_mask:0xf
	v_fmac_f32_dpp v255, v33, v195 row_shr:1 row_mask:0xf bank_mask:0xf
	v_fmac_f32_dpp v148, v34, v196 row_shr:1 row_mask:0xf bank_mask:0xf
	v_fmac_f32_dpp v149, v35, v197 row_shr:1 row_mask:0xf bank_mask:0xf
	v_fmac_f32_dpp v254, v32, v178 row_shr:2 row_mask:0xf bank_mask:0xf
	v_fmac_f32_dpp v255, v33, v179 row_shr:2 row_mask:0xf bank_mask:0xf
	v_fmac_f32_dpp v148, v34, v180 row_shr:2 row_mask:0xf bank_mask:0xf
	v_fmac_f32_dpp v149, v35, v181 row_shr:2 row_mask:0xf bank_mask:0xf
	v_fmac_f32_dpp v254, v112, v194 row_ror:1 row_mask:0xf bank_mask:0x1
	v_fmac_f32_dpp v255, v113, v195 row_ror:1 row_mask:0xf bank_mask:0x1
	v_fmac_f32_dpp v148, v114, v196 row_ror:1 row_mask:0xf bank_mask:0x1
	v_fmac_f32_dpp v149, v115, v197 row_ror:1 row_mask:0xf bank_mask:0x1
	v_fmac_f32_dpp v254, v112, v178 row_ror:2 row_mask:0xf bank_mask:0x1
	v_fmac_f32_dpp v255, v113, v179 row_ror:2 row_mask:0xf bank_mask:0x1
	v_fmac_f32_dpp v148, v114, v180 row_ror:2 row_mask:0xf bank_mask:0x1
	v_fmac_f32_dpp v149, v115, v181 row_ror:2 row_mask:0xf bank_mask:0x1
	v_pk_mul_f32 v[254:255], v[238:239], v[254:255]
	v_pk_mul_f32 v[148:149], v[240:241], v[148:149]
	v_cvt_pk_bf16_f32 v242, v254, v255
	v_cvt_pk_bf16_f32 v243, v148, v149
	v_mov_b32_dpp v112, v20 quad_perm:[0,1,2,3] row_mask:0xf bank_mask:0x8
	v_mov_b32_dpp v113, v21 quad_perm:[0,1,2,3] row_mask:0xf bank_mask:0x8
	v_mov_b32_dpp v114, v22 quad_perm:[0,1,2,3] row_mask:0xf bank_mask:0x8
	v_mov_b32_dpp v115, v23 quad_perm:[0,1,2,3] row_mask:0xf bank_mask:0x8
	v_pk_fma_f32 v[254:255], v[206:207], v[16:17], v[136:137]
	v_pk_fma_f32 v[148:149], v[208:209], v[18:19], v[138:139]
	v_fmac_f32_dpp v254, v16, v190 row_shr:1 row_mask:0xf bank_mask:0xf
	v_fmac_f32_dpp v255, v17, v191 row_shr:1 row_mask:0xf bank_mask:0xf
	v_fmac_f32_dpp v148, v18, v192 row_shr:1 row_mask:0xf bank_mask:0xf
	v_fmac_f32_dpp v149, v19, v193 row_shr:1 row_mask:0xf bank_mask:0xf
	v_fmac_f32_dpp v254, v16, v174 row_shr:2 row_mask:0xf bank_mask:0xf
	v_fmac_f32_dpp v255, v17, v175 row_shr:2 row_mask:0xf bank_mask:0xf
	v_fmac_f32_dpp v148, v18, v176 row_shr:2 row_mask:0xf bank_mask:0xf
	v_fmac_f32_dpp v149, v19, v177 row_shr:2 row_mask:0xf bank_mask:0xf
	v_fmac_f32_dpp v254, v112, v190 row_ror:1 row_mask:0xf bank_mask:0x1
	v_fmac_f32_dpp v255, v113, v191 row_ror:1 row_mask:0xf bank_mask:0x1
	v_fmac_f32_dpp v148, v114, v192 row_ror:1 row_mask:0xf bank_mask:0x1
	v_fmac_f32_dpp v149, v115, v193 row_ror:1 row_mask:0xf bank_mask:0x1
	v_fmac_f32_dpp v254, v112, v174 row_ror:2 row_mask:0xf bank_mask:0x1
	v_fmac_f32_dpp v255, v113, v175 row_ror:2 row_mask:0xf bank_mask:0x1
	v_fmac_f32_dpp v148, v114, v176 row_ror:2 row_mask:0xf bank_mask:0x1
	v_fmac_f32_dpp v149, v115, v177 row_ror:2 row_mask:0xf bank_mask:0x1
	v_fma_f32 v246, |v254|, s38, 1.0
	v_fma_f32 v247, |v255|, s38, 1.0
	v_fma_f32 v248, |v148|, s38, 1.0
	v_fma_f32 v249, |v149|, s38, 1.0
	v_mul_f32_e32 v250, v254, v254
	v_mul_f32_e32 v251, v255, v255
	v_mul_f32_e32 v252, v148, v148
	v_mul_f32_e32 v253, v149, v149
	v_rcp_f32_e32 v246, v246
	v_rcp_f32_e32 v247, v247
	v_rcp_f32_e32 v248, v248
	v_rcp_f32_e32 v249, v249
	v_mul_f32_e32 v250, s72, v250
	v_mul_f32_e32 v251, s72, v251
	v_mul_f32_e32 v252, s72, v252
	v_mul_f32_e32 v253, s72, v253
	v_exp_f32_e32 v250, v250
	v_exp_f32_e32 v251, v251
	v_exp_f32_e32 v252, v252
	v_exp_f32_e32 v253, v253
	v_fmamk_f32 v238, v246, 0x3f07dc22, v219
	v_fmamk_f32 v239, v247, 0x3f07dc22, v219
	v_fmamk_f32 v240, v248, 0x3f07dc22, v219
	v_fmamk_f32 v241, v249, 0x3f07dc22, v219
	v_fma_f32 v238, v246, v238, s66
	v_fma_f32 v239, v247, v239, s66
	v_fma_f32 v240, v248, v240, s66
	v_fma_f32 v241, v249, v241, s66
	v_fma_f32 v238, v246, v238, s68
	v_fma_f32 v239, v247, v239, s68
	v_fma_f32 v240, v248, v240, s68
	v_fma_f32 v241, v249, v241, s68
	v_fma_f32 v238, v246, v238, s70
	v_fma_f32 v239, v247, v239, s70
	v_fma_f32 v240, v248, v240, s70
	v_fma_f32 v241, v249, v241, s70
	v_mul_f32_e32 v238, v246, v238
	v_mul_f32_e32 v239, v247, v239
	v_mul_f32_e32 v240, v248, v240
	v_mul_f32_e32 v241, v249, v241
	v_mul_f32_e32 v238, v250, v238
	v_mul_f32_e32 v239, v251, v239
	v_mul_f32_e32 v240, v252, v240
	v_mul_f32_e32 v241, v253, v241
	v_max_f32_e32 v246, 0, v254
	v_max_f32_e32 v247, 0, v255
	v_max_f32_e32 v248, 0, v148
	v_max_f32_e32 v249, 0, v149
	v_fma_f32 v238, -|v254|, v238, v246
	v_fma_f32 v239, -|v255|, v239, v247
	v_fma_f32 v240, -|v148|, v240, v248
	v_fma_f32 v241, -|v149|, v241, v249
	v_mov_b32_dpp v112, v4 quad_perm:[0,1,2,3] row_mask:0xf bank_mask:0x8
	v_mov_b32_dpp v113, v5 quad_perm:[0,1,2,3] row_mask:0xf bank_mask:0x8
	v_mov_b32_dpp v114, v6 quad_perm:[0,1,2,3] row_mask:0xf bank_mask:0x8
	v_mov_b32_dpp v115, v7 quad_perm:[0,1,2,3] row_mask:0xf bank_mask:0x8
	v_pk_fma_f32 v[254:255], v[128:129], v[0:1], v[144:145]
	v_pk_fma_f32 v[148:149], v[130:131], v[2:3], v[146:147]
	v_fmac_f32_dpp v254, v0, v198 row_shr:1 row_mask:0xf bank_mask:0xf
	v_fmac_f32_dpp v255, v1, v199 row_shr:1 row_mask:0xf bank_mask:0xf
	v_fmac_f32_dpp v148, v2, v200 row_shr:1 row_mask:0xf bank_mask:0xf
	v_fmac_f32_dpp v149, v3, v201 row_shr:1 row_mask:0xf bank_mask:0xf
	v_fmac_f32_dpp v254, v0, v182 row_shr:2 row_mask:0xf bank_mask:0xf
	v_fmac_f32_dpp v255, v1, v183 row_shr:2 row_mask:0xf bank_mask:0xf
; __device__ __forceinline__ unsigned cvt_pk_bf16(float lo, float hi) { unsigned r; asm volatile("v_cvt_pk_bf16_f32 %0, %1, %2" : "=v"(r) : "v"(lo), "v"(hi)); return r; }
;     __device__ __forceinline__ void operator()(const f32x4 (&acc)[2][2][4][2], const Unit& u, int wr, int wc, int fr, int fq) const {
;     ...
; #pragma unroll
;                     for (int m = 0; m < 4; ++m) {
;                         f32x4 cv;
;                         if (!samp) {
;                             const f32x4 prev = m ? v[m - 1] : hv;
; #pragma unroll
;                             for (int e = 0; e < 4; ++e) {
;                                 const int vi = __float_as_int(v[m][e]), pi = __float_as_int(prev[e]);
;                                 const int o1 = __builtin_amdgcn_mov_dpp(pi, 0x121, 0xf, 0xf, false);
;                                 const int o2 = __builtin_amdgcn_mov_dpp(pi, 0x122, 0xf, 0xf, false);
;                                 const float p1 = __int_as_float(__builtin_amdgcn_update_dpp(o1, vi, 0x111, 0xf, 0xf, false));
;                                 const float p2 = __int_as_float(__builtin_amdgcn_update_dpp(o2, vi, 0x112, 0xf, 0xf, false));
;                                 cv[e] = cb[e] + cw0[e] * p2 + cw1[e] * p1 + cw2[e] * v[m][e];
;                             }
;                         } else {
;                             const int ns = rowb + 16 * m + fr - MP;
;                             f32x4 s0 = (f32x4){0.f, 0.f, 0.f, 0.f}, s1 = s0;
;                             if (ns < NS) {
;                                 s0 = *(const f32x4*)(state + (size_t)(ns * 2 + 0) * FF2 + oc); s1 = *(const f32x4*)(state + (size_t)(ns * 2 + 1) * FF2 + oc);
;                                 *(f32x4*)(ncs + (size_t)(ns * 2 + 0) * FF2 + oc) = s1; *(f32x4*)(ncs + (size_t)(ns * 2 + 1) * FF2 + oc) = v[m];
;                             }
;                             cv = cb + cw0 * s0 + cw1 * s1 + cw2 * v[m];
;                         }
;                         if (bj == 0) cg[m] = gelu4(cv);
;                         else {
;                             const f32x4 r = cg[m] * cv;
;                             v2u w; w.x = cvt_pk_bf16(r[0], r[1]); w.y = cvt_pk_bf16(r[2], r[3]);
;                             *(v2u*)(ACT + (size_t)(rowb + 16 * m + fr) * FF + 128 * u.pn + 32 * wc + 8 * fq + 4 * n) = w;
	v_fmac_f32_dpp v148, v2, v184 row_shr:2 row_mask:0xf bank_mask:0xf
	v_fmac_f32_dpp v149, v3, v185 row_shr:2 row_mask:0xf bank_mask:0xf
	v_fmac_f32_dpp v254, v112, v198 row_ror:1 row_mask:0xf bank_mask:0x1
	v_fmac_f32_dpp v255, v113, v199 row_ror:1 row_mask:0xf bank_mask:0x1
	v_fmac_f32_dpp v148, v114, v200 row_ror:1 row_mask:0xf bank_mask:0x1
	v_fmac_f32_dpp v149, v115, v201 row_ror:1 row_mask:0xf bank_mask:0x1
	v_fmac_f32_dpp v254, v112, v182 row_ror:2 row_mask:0xf bank_mask:0x1
	v_fmac_f32_dpp v255, v113, v183 row_ror:2 row_mask:0xf bank_mask:0x1
	v_fmac_f32_dpp v148, v114, v184 row_ror:2 row_mask:0xf bank_mask:0x1
	v_fmac_f32_dpp v149, v115, v185 row_ror:2 row_mask:0xf bank_mask:0x1
	v_pk_mul_f32 v[254:255], v[238:239], v[254:255]
	v_pk_mul_f32 v[148:149], v[240:241], v[148:149]
	v_cvt_pk_bf16_f32 v244, v254, v255
	v_cvt_pk_bf16_f32 v245, v148, v149
	s_add_u32 s56, s46, 0xdc000
	s_addc_u32 s57, s47, 0
	global_store_dwordx4 v151, v[242:245], s[56:57]
	v_mov_b32_dpp v112, v60 quad_perm:[0,1,2,3] row_mask:0xf bank_mask:0x8
	v_mov_b32_dpp v113, v61 quad_perm:[0,1,2,3] row_mask:0xf bank_mask:0x8
	v_mov_b32_dpp v114, v62 quad_perm:[0,1,2,3] row_mask:0xf bank_mask:0x8
	v_mov_b32_dpp v115, v63 quad_perm:[0,1,2,3] row_mask:0xf bank_mask:0x8
	v_pk_fma_f32 v[254:255], v[202:203], v[52:53], v[132:133]
	v_pk_fma_f32 v[148:149], v[204:205], v[54:55], v[134:135]
	v_fmac_f32_dpp v254, v52, v186 row_shr:1 row_mask:0xf bank_mask:0xf
	v_fmac_f32_dpp v255, v53, v187 row_shr:1 row_mask:0xf bank_mask:0xf
	v_fmac_f32_dpp v148, v54, v188 row_shr:1 row_mask:0xf bank_mask:0xf
	v_fmac_f32_dpp v149, v55, v189 row_shr:1 row_mask:0xf bank_mask:0xf
	v_fmac_f32_dpp v254, v52, v170 row_shr:2 row_mask:0xf bank_mask:0xf
	v_fmac_f32_dpp v255, v53, v171 row_shr:2 row_mask:0xf bank_mask:0xf
	v_fmac_f32_dpp v148, v54, v172 row_shr:2 row_mask:0xf bank_mask:0xf
	v_fmac_f32_dpp v149, v55, v173 row_shr:2 row_mask:0xf bank_mask:0xf
	v_fmac_f32_dpp v254, v112, v186 row_ror:1 row_mask:0xf bank_mask:0x1
	v_fmac_f32_dpp v255, v113, v187 row_ror:1 row_mask:0xf bank_mask:0x1
	v_fmac_f32_dpp v148, v114, v188 row_ror:1 row_mask:0xf bank_mask:0x1
	v_fmac_f32_dpp v149, v115, v189 row_ror:1 row_mask:0xf bank_mask:0x1
	v_fmac_f32_dpp v254, v112, v170 row_ror:2 row_mask:0xf bank_mask:0x1
	v_fmac_f32_dpp v255, v113, v171 row_ror:2 row_mask:0xf bank_mask:0x1
	v_fmac_f32_dpp v148, v114, v172 row_ror:2 row_mask:0xf bank_mask:0x1
	v_fmac_f32_dpp v149, v115, v173 row_ror:2 row_mask:0xf bank_mask:0x1
	v_fma_f32 v246, |v254|, s38, 1.0
	v_fma_f32 v247, |v255|, s38, 1.0
	v_fma_f32 v248, |v148|, s38, 1.0
	v_fma_f32 v249, |v149|, s38, 1.0
	v_mul_f32_e32 v250, v254, v254
	v_mul_f32_e32 v251, v255, v255
	v_mul_f32_e32 v252, v148, v148
	v_mul_f32_e32 v253, v149, v149
	v_rcp_f32_e32 v246, v246
	v_rcp_f32_e32 v247, v247
	v_rcp_f32_e32 v248, v248
	v_rcp_f32_e32 v249, v249
	v_mul_f32_e32 v250, s72, v250
	v_mul_f32_e32 v251, s72, v251
	v_mul_f32_e32 v252, s72, v252
	v_mul_f32_e32 v253, s72, v253
	v_exp_f32_e32 v250, v250
	v_exp_f32_e32 v251, v251
	v_exp_f32_e32 v252, v252
	v_exp_f32_e32 v253, v253
	v_fmamk_f32 v238, v246, 0x3f07dc22, v219
	v_fmamk_f32 v239, v247, 0x3f07dc22, v219
	v_fmamk_f32 v240, v248, 0x3f07dc22, v219
	v_fmamk_f32 v241, v249, 0x3f07dc22, v219
	v_fma_f32 v238, v246, v238, s66
	v_fma_f32 v239, v247, v239, s66
	v_fma_f32 v240, v248, v240, s66
	v_fma_f32 v241, v249, v241, s66
	v_fma_f32 v238, v246, v238, s68
	v_fma_f32 v239, v247, v239, s68
	v_fma_f32 v240, v248, v240, s68
	v_fma_f32 v241, v249, v241, s68
	v_fma_f32 v238, v246, v238, s70
	v_fma_f32 v239, v247, v239, s70
	v_fma_f32 v240, v248, v240, s70
	v_fma_f32 v241, v249, v241, s70
	v_mul_f32_e32 v238, v246, v238
	v_mul_f32_e32 v239, v247, v239
	v_mul_f32_e32 v240, v248, v240
	v_mul_f32_e32 v241, v249, v241
	v_mul_f32_e32 v238, v250, v238
	v_mul_f32_e32 v239, v251, v239
	v_mul_f32_e32 v240, v252, v240
	v_mul_f32_e32 v241, v253, v241
	v_max_f32_e32 v246, 0, v254
	v_max_f32_e32 v247, 0, v255
	v_max_f32_e32 v248, 0, v148
	v_max_f32_e32 v249, 0, v149
	v_fma_f32 v238, -|v254|, v238, v246
	v_fma_f32 v239, -|v255|, v239, v247
	v_fma_f32 v240, -|v148|, v240, v248
	v_fma_f32 v241, -|v149|, v241, v249
	v_mov_b32_dpp v112, v44 quad_perm:[0,1,2,3] row_mask:0xf bank_mask:0x8
	v_mov_b32_dpp v113, v45 quad_perm:[0,1,2,3] row_mask:0xf bank_mask:0x8
	v_mov_b32_dpp v114, v46 quad_perm:[0,1,2,3] row_mask:0xf bank_mask:0x8
	v_mov_b32_dpp v115, v47 quad_perm:[0,1,2,3] row_mask:0xf bank_mask:0x8
	v_pk_fma_f32 v[254:255], v[210:211], v[36:37], v[140:141]
	v_pk_fma_f32 v[148:149], v[212:213], v[38:39], v[142:143]
	v_fmac_f32_dpp v254, v36, v194 row_shr:1 row_mask:0xf bank_mask:0xf
	v_fmac_f32_dpp v255, v37, v195 row_shr:1 row_mask:0xf bank_mask:0xf
	v_fmac_f32_dpp v148, v38, v196 row_shr:1 row_mask:0xf bank_mask:0xf
	v_fmac_f32_dpp v149, v39, v197 row_shr:1 row_mask:0xf bank_mask:0xf
	v_fmac_f32_dpp v254, v36, v178 row_shr:2 row_mask:0xf bank_mask:0xf
	v_fmac_f32_dpp v255, v37, v179 row_shr:2 row_mask:0xf bank_mask:0xf
	v_fmac_f32_dpp v148, v38, v180 row_shr:2 row_mask:0xf bank_mask:0xf
	v_fmac_f32_dpp v149, v39, v181 row_shr:2 row_mask:0xf bank_mask:0xf
	v_fmac_f32_dpp v254, v112, v194 row_ror:1 row_mask:0xf bank_mask:0x1
	v_fmac_f32_dpp v255, v113, v195 row_ror:1 row_mask:0xf bank_mask:0x1
	v_fmac_f32_dpp v148, v114, v196 row_ror:1 row_mask:0xf bank_mask:0x1
	v_fmac_f32_dpp v149, v115, v197 row_ror:1 row_mask:0xf bank_mask:0x1
	v_fmac_f32_dpp v254, v112, v178 row_ror:2 row_mask:0xf bank_mask:0x1
	v_fmac_f32_dpp v255, v113, v179 row_ror:2 row_mask:0xf bank_mask:0x1
	v_fmac_f32_dpp v148, v114, v180 row_ror:2 row_mask:0xf bank_mask:0x1
; __device__ __forceinline__ unsigned cvt_pk_bf16(float lo, float hi) { unsigned r; asm volatile("v_cvt_pk_bf16_f32 %0, %1, %2" : "=v"(r) : "v"(lo), "v"(hi)); return r; }
;     __device__ __forceinline__ void operator()(const f32x4 (&acc)[2][2][4][2], const Unit& u, int wr, int wc, int fr, int fq) const {
;     ...
; #pragma unroll
;                     for (int m = 0; m < 4; ++m) {
;                         f32x4 cv;
;                         if (!samp) {
;                             const f32x4 prev = m ? v[m - 1] : hv;
; #pragma unroll
;                             for (int e = 0; e < 4; ++e) {
;                                 const int vi = __float_as_int(v[m][e]), pi = __float_as_int(prev[e]);
;                                 const int o1 = __builtin_amdgcn_mov_dpp(pi, 0x121, 0xf, 0xf, false);
;                                 const int o2 = __builtin_amdgcn_mov_dpp(pi, 0x122, 0xf, 0xf, false);
;                                 const float p1 = __int_as_float(__builtin_amdgcn_update_dpp(o1, vi, 0x111, 0xf, 0xf, false));
;                                 const float p2 = __int_as_float(__builtin_amdgcn_update_dpp(o2, vi, 0x112, 0xf, 0xf, false));
;                                 cv[e] = cb[e] + cw0[e] * p2 + cw1[e] * p1 + cw2[e] * v[m][e];
;                             }
;                         } else {
;                             const int ns = rowb + 16 * m + fr - MP;
;                             f32x4 s0 = (f32x4){0.f, 0.f, 0.f, 0.f}, s1 = s0;
;                             if (ns < NS) {
;                                 s0 = *(const f32x4*)(state + (size_t)(ns * 2 + 0) * FF2 + oc); s1 = *(const f32x4*)(state + (size_t)(ns * 2 + 1) * FF2 + oc);
;                                 *(f32x4*)(ncs + (size_t)(ns * 2 + 0) * FF2 + oc) = s1; *(f32x4*)(ncs + (size_t)(ns * 2 + 1) * FF2 + oc) = v[m];
;                             }
;                             cv = cb + cw0 * s0 + cw1 * s1 + cw2 * v[m];
;                         }
;                         if (bj == 0) cg[m] = gelu4(cv);
;                         else {
;                             const f32x4 r = cg[m] * cv;
;                             v2u w; w.x = cvt_pk_bf16(r[0], r[1]); w.y = cvt_pk_bf16(r[2], r[3]);
;                             *(v2u*)(ACT + (size_t)(rowb + 16 * m + fr) * FF + 128 * u.pn + 32 * wc + 8 * fq + 4 * n) = w;
	v_fmac_f32_dpp v149, v115, v181 row_ror:2 row_mask:0xf bank_mask:0x1
	v_pk_mul_f32 v[254:255], v[238:239], v[254:255]
	v_pk_mul_f32 v[148:149], v[240:241], v[148:149]
	v_cvt_pk_bf16_f32 v242, v254, v255
	v_cvt_pk_bf16_f32 v243, v148, v149
	v_mov_b32_dpp v112, v28 quad_perm:[0,1,2,3] row_mask:0xf bank_mask:0x8
	v_mov_b32_dpp v113, v29 quad_perm:[0,1,2,3] row_mask:0xf bank_mask:0x8
	v_mov_b32_dpp v114, v30 quad_perm:[0,1,2,3] row_mask:0xf bank_mask:0x8
	v_mov_b32_dpp v115, v31 quad_perm:[0,1,2,3] row_mask:0xf bank_mask:0x8
	v_pk_fma_f32 v[254:255], v[206:207], v[20:21], v[136:137]
	v_pk_fma_f32 v[148:149], v[208:209], v[22:23], v[138:139]
	v_fmac_f32_dpp v254, v20, v190 row_shr:1 row_mask:0xf bank_mask:0xf
	v_fmac_f32_dpp v255, v21, v191 row_shr:1 row_mask:0xf bank_mask:0xf
	v_fmac_f32_dpp v148, v22, v192 row_shr:1 row_mask:0xf bank_mask:0xf
	v_fmac_f32_dpp v149, v23, v193 row_shr:1 row_mask:0xf bank_mask:0xf
	v_fmac_f32_dpp v254, v20, v174 row_shr:2 row_mask:0xf bank_mask:0xf
	v_fmac_f32_dpp v255, v21, v175 row_shr:2 row_mask:0xf bank_mask:0xf
	v_fmac_f32_dpp v148, v22, v176 row_shr:2 row_mask:0xf bank_mask:0xf
	v_fmac_f32_dpp v149, v23, v177 row_shr:2 row_mask:0xf bank_mask:0xf
	v_fmac_f32_dpp v254, v112, v190 row_ror:1 row_mask:0xf bank_mask:0x1
	v_fmac_f32_dpp v255, v113, v191 row_ror:1 row_mask:0xf bank_mask:0x1
	v_fmac_f32_dpp v148, v114, v192 row_ror:1 row_mask:0xf bank_mask:0x1
	v_fmac_f32_dpp v149, v115, v193 row_ror:1 row_mask:0xf bank_mask:0x1
	v_fmac_f32_dpp v254, v112, v174 row_ror:2 row_mask:0xf bank_mask:0x1
	v_fmac_f32_dpp v255, v113, v175 row_ror:2 row_mask:0xf bank_mask:0x1
	v_fmac_f32_dpp v148, v114, v176 row_ror:2 row_mask:0xf bank_mask:0x1
	v_fmac_f32_dpp v149, v115, v177 row_ror:2 row_mask:0xf bank_mask:0x1
	v_fma_f32 v246, |v254|, s38, 1.0
	v_fma_f32 v247, |v255|, s38, 1.0
	v_fma_f32 v248, |v148|, s38, 1.0
	v_fma_f32 v249, |v149|, s38, 1.0
	v_mul_f32_e32 v250, v254, v254
	v_mul_f32_e32 v251, v255, v255
	v_mul_f32_e32 v252, v148, v148
	v_mul_f32_e32 v253, v149, v149
	v_rcp_f32_e32 v246, v246
	v_rcp_f32_e32 v247, v247
	v_rcp_f32_e32 v248, v248
	v_rcp_f32_e32 v249, v249
	v_mul_f32_e32 v250, s72, v250
	v_mul_f32_e32 v251, s72, v251
	v_mul_f32_e32 v252, s72, v252
	v_mul_f32_e32 v253, s72, v253
	v_exp_f32_e32 v250, v250
	v_exp_f32_e32 v251, v251
	v_exp_f32_e32 v252, v252
	v_exp_f32_e32 v253, v253
	v_fmamk_f32 v238, v246, 0x3f07dc22, v219
	v_fmamk_f32 v239, v247, 0x3f07dc22, v219
	v_fmamk_f32 v240, v248, 0x3f07dc22, v219
	v_fmamk_f32 v241, v249, 0x3f07dc22, v219
	v_fma_f32 v238, v246, v238, s66
	v_fma_f32 v239, v247, v239, s66
	v_fma_f32 v240, v248, v240, s66
	v_fma_f32 v241, v249, v241, s66
	v_fma_f32 v238, v246, v238, s68
	v_fma_f32 v239, v247, v239, s68
	v_fma_f32 v240, v248, v240, s68
	v_fma_f32 v241, v249, v241, s68
	v_fma_f32 v238, v246, v238, s70
	v_fma_f32 v239, v247, v239, s70
	v_fma_f32 v240, v248, v240, s70
	v_fma_f32 v241, v249, v241, s70
	v_mul_f32_e32 v238, v246, v238
	v_mul_f32_e32 v239, v247, v239
	v_mul_f32_e32 v240, v248, v240
	v_mul_f32_e32 v241, v249, v241
	v_mul_f32_e32 v238, v250, v238
	v_mul_f32_e32 v239, v251, v239
	v_mul_f32_e32 v240, v252, v240
	v_mul_f32_e32 v241, v253, v241
	v_max_f32_e32 v246, 0, v254
	v_max_f32_e32 v247, 0, v255
	v_max_f32_e32 v248, 0, v148
	v_max_f32_e32 v249, 0, v149
	v_fma_f32 v238, -|v254|, v238, v246
	v_fma_f32 v239, -|v255|, v239, v247
	v_fma_f32 v240, -|v148|, v240, v248
	v_fma_f32 v241, -|v149|, v241, v249
	v_mov_b32_dpp v112, v12 quad_perm:[0,1,2,3] row_mask:0xf bank_mask:0x8
	v_mov_b32_dpp v113, v13 quad_perm:[0,1,2,3] row_mask:0xf bank_mask:0x8
	v_mov_b32_dpp v114, v14 quad_perm:[0,1,2,3] row_mask:0xf bank_mask:0x8
	v_mov_b32_dpp v115, v15 quad_perm:[0,1,2,3] row_mask:0xf bank_mask:0x8
	v_pk_fma_f32 v[254:255], v[128:129], v[4:5], v[144:145]
	v_pk_fma_f32 v[148:149], v[130:131], v[6:7], v[146:147]
	v_fmac_f32_dpp v254, v4, v198 row_shr:1 row_mask:0xf bank_mask:0xf
	v_fmac_f32_dpp v255, v5, v199 row_shr:1 row_mask:0xf bank_mask:0xf
	v_fmac_f32_dpp v148, v6, v200 row_shr:1 row_mask:0xf bank_mask:0xf
	v_fmac_f32_dpp v149, v7, v201 row_shr:1 row_mask:0xf bank_mask:0xf
	v_fmac_f32_dpp v254, v4, v182 row_shr:2 row_mask:0xf bank_mask:0xf
	v_fmac_f32_dpp v255, v5, v183 row_shr:2 row_mask:0xf bank_mask:0xf
	v_fmac_f32_dpp v148, v6, v184 row_shr:2 row_mask:0xf bank_mask:0xf
	v_fmac_f32_dpp v149, v7, v185 row_shr:2 row_mask:0xf bank_mask:0xf
	v_fmac_f32_dpp v254, v112, v198 row_ror:1 row_mask:0xf bank_mask:0x1
	v_fmac_f32_dpp v255, v113, v199 row_ror:1 row_mask:0xf bank_mask:0x1
	v_fmac_f32_dpp v148, v114, v200 row_ror:1 row_mask:0xf bank_mask:0x1
	v_fmac_f32_dpp v149, v115, v201 row_ror:1 row_mask:0xf bank_mask:0x1
	v_fmac_f32_dpp v254, v112, v182 row_ror:2 row_mask:0xf bank_mask:0x1
	v_fmac_f32_dpp v255, v113, v183 row_ror:2 row_mask:0xf bank_mask:0x1
	v_fmac_f32_dpp v148, v114, v184 row_ror:2 row_mask:0xf bank_mask:0x1
	v_fmac_f32_dpp v149, v115, v185 row_ror:2 row_mask:0xf bank_mask:0x1
	v_pk_mul_f32 v[254:255], v[238:239], v[254:255]
	v_pk_mul_f32 v[148:149], v[240:241], v[148:149]
	v_cvt_pk_bf16_f32 v244, v254, v255
	v_cvt_pk_bf16_f32 v245, v148, v149
	s_add_u32 s56, s46, 0xc6000
	s_addc_u32 s57, s47, 0
	global_store_dwordx4 v151, v[242:245], s[56:57]
	s_waitcnt vmcnt(3)
; __device__ __forceinline__ unsigned cvt_pk_bf16(float lo, float hi) { unsigned r; asm volatile("v_cvt_pk_bf16_f32 %0, %1, %2" : "=v"(r) : "v"(lo), "v"(hi)); return r; }
;     __device__ __forceinline__ void operator()(const f32x4 (&acc)[2][2][4][2], const Unit& u, int wr, int wc, int fr, int fq) const {
;     ...
; #pragma unroll
;                     for (int m = 0; m < 4; ++m) {
;                         f32x4 cv;
;                         if (!samp) {
;                             const f32x4 prev = m ? v[m - 1] : hv;
; #pragma unroll
;                             for (int e = 0; e < 4; ++e) {
;                                 const int vi = __float_as_int(v[m][e]), pi = __float_as_int(prev[e]);
;                                 const int o1 = __builtin_amdgcn_mov_dpp(pi, 0x121, 0xf, 0xf, false);
;                                 const int o2 = __builtin_amdgcn_mov_dpp(pi, 0x122, 0xf, 0xf, false);
;                                 const float p1 = __int_as_float(__builtin_amdgcn_update_dpp(o1, vi, 0x111, 0xf, 0xf, false));
;                                 const float p2 = __int_as_float(__builtin_amdgcn_update_dpp(o2, vi, 0x112, 0xf, 0xf, false));
;                                 cv[e] = cb[e] + cw0[e] * p2 + cw1[e] * p1 + cw2[e] * v[m][e];
;                             }
;                         } else {
;                             const int ns = rowb + 16 * m + fr - MP;
;                             f32x4 s0 = (f32x4){0.f, 0.f, 0.f, 0.f}, s1 = s0;
;                             if (ns < NS) {
;                                 s0 = *(const f32x4*)(state + (size_t)(ns * 2 + 0) * FF2 + oc); s1 = *(const f32x4*)(state + (size_t)(ns * 2 + 1) * FF2 + oc);
;                                 *(f32x4*)(ncs + (size_t)(ns * 2 + 0) * FF2 + oc) = s1; *(f32x4*)(ncs + (size_t)(ns * 2 + 1) * FF2 + oc) = v[m];
;                             }
;                             cv = cb + cw0 * s0 + cw1 * s1 + cw2 * v[m];
;                         }
;                         if (bj == 0) cg[m] = gelu4(cv);
;                         else {
;                             const f32x4 r = cg[m] * cv;
;                             v2u w; w.x = cvt_pk_bf16(r[0], r[1]); w.y = cvt_pk_bf16(r[2], r[3]);
;                             *(v2u*)(ACT + (size_t)(rowb + 16 * m + fr) * FF + 128 * u.pn + 32 * wc + 8 * fq + 4 * n) = w;
	v_pk_fma_f32 v[254:255], v[202:203], v[60:61], v[132:133]
	v_pk_fma_f32 v[148:149], v[204:205], v[62:63], v[134:135]
	v_fmac_f32_dpp v254, v60, v186 row_shr:1 row_mask:0xf bank_mask:0xf
	v_fmac_f32_dpp v255, v61, v187 row_shr:1 row_mask:0xf bank_mask:0xf
	v_fmac_f32_dpp v148, v62, v188 row_shr:1 row_mask:0xf bank_mask:0xf
	v_fmac_f32_dpp v149, v63, v189 row_shr:1 row_mask:0xf bank_mask:0xf
	v_fmac_f32_dpp v254, v60, v170 row_shr:2 row_mask:0xf bank_mask:0xf
	v_fmac_f32_dpp v255, v61, v171 row_shr:2 row_mask:0xf bank_mask:0xf
	v_fmac_f32_dpp v148, v62, v172 row_shr:2 row_mask:0xf bank_mask:0xf
	v_fmac_f32_dpp v149, v63, v173 row_shr:2 row_mask:0xf bank_mask:0xf
	v_fmac_f32_dpp v254, v220, v186 row_ror:1 row_mask:0xf bank_mask:0x1
	v_fmac_f32_dpp v255, v221, v187 row_ror:1 row_mask:0xf bank_mask:0x1
	v_fmac_f32_dpp v148, v222, v188 row_ror:1 row_mask:0xf bank_mask:0x1
	v_fmac_f32_dpp v149, v223, v189 row_ror:1 row_mask:0xf bank_mask:0x1
	v_fmac_f32_dpp v254, v220, v170 row_ror:2 row_mask:0xf bank_mask:0x1
	v_fmac_f32_dpp v255, v221, v171 row_ror:2 row_mask:0xf bank_mask:0x1
	v_fmac_f32_dpp v148, v222, v172 row_ror:2 row_mask:0xf bank_mask:0x1
	v_fmac_f32_dpp v149, v223, v173 row_ror:2 row_mask:0xf bank_mask:0x1
	v_fma_f32 v246, |v254|, s38, 1.0
	v_fma_f32 v247, |v255|, s38, 1.0
	v_fma_f32 v248, |v148|, s38, 1.0
	v_fma_f32 v249, |v149|, s38, 1.0
	v_mul_f32_e32 v250, v254, v254
	v_mul_f32_e32 v251, v255, v255
	v_mul_f32_e32 v252, v148, v148
	v_mul_f32_e32 v253, v149, v149
	v_rcp_f32_e32 v246, v246
	v_rcp_f32_e32 v247, v247
	v_rcp_f32_e32 v248, v248
	v_rcp_f32_e32 v249, v249
	v_mul_f32_e32 v250, s72, v250
	v_mul_f32_e32 v251, s72, v251
	v_mul_f32_e32 v252, s72, v252
	v_mul_f32_e32 v253, s72, v253
	v_exp_f32_e32 v250, v250
	v_exp_f32_e32 v251, v251
	v_exp_f32_e32 v252, v252
	v_exp_f32_e32 v253, v253
	v_fmamk_f32 v238, v246, 0x3f07dc22, v219
	v_fmamk_f32 v239, v247, 0x3f07dc22, v219
	v_fmamk_f32 v240, v248, 0x3f07dc22, v219
	v_fmamk_f32 v241, v249, 0x3f07dc22, v219
	v_fma_f32 v238, v246, v238, s66
	v_fma_f32 v239, v247, v239, s66
	v_fma_f32 v240, v248, v240, s66
	v_fma_f32 v241, v249, v241, s66
	v_fma_f32 v238, v246, v238, s68
	v_fma_f32 v239, v247, v239, s68
	v_fma_f32 v240, v248, v240, s68
	v_fma_f32 v241, v249, v241, s68
	v_fma_f32 v238, v246, v238, s70
	v_fma_f32 v239, v247, v239, s70
	v_fma_f32 v240, v248, v240, s70
	v_fma_f32 v241, v249, v241, s70
	v_mul_f32_e32 v238, v246, v238
	v_mul_f32_e32 v239, v247, v239
	v_mul_f32_e32 v240, v248, v240
	v_mul_f32_e32 v241, v249, v241
	v_mul_f32_e32 v238, v250, v238
	v_mul_f32_e32 v239, v251, v239
	v_mul_f32_e32 v240, v252, v240
	v_mul_f32_e32 v241, v253, v241
	v_max_f32_e32 v246, 0, v254
	v_max_f32_e32 v247, 0, v255
	v_max_f32_e32 v248, 0, v148
	v_max_f32_e32 v249, 0, v149
	v_fma_f32 v238, -|v254|, v238, v246
	v_fma_f32 v239, -|v255|, v239, v247
	v_fma_f32 v240, -|v148|, v240, v248
	v_fma_f32 v241, -|v149|, v241, v249
	v_pk_fma_f32 v[254:255], v[210:211], v[44:45], v[140:141]
	v_pk_fma_f32 v[148:149], v[212:213], v[46:47], v[142:143]
	v_fmac_f32_dpp v254, v44, v194 row_shr:1 row_mask:0xf bank_mask:0xf
	v_fmac_f32_dpp v255, v45, v195 row_shr:1 row_mask:0xf bank_mask:0xf
	v_fmac_f32_dpp v148, v46, v196 row_shr:1 row_mask:0xf bank_mask:0xf
	v_fmac_f32_dpp v149, v47, v197 row_shr:1 row_mask:0xf bank_mask:0xf
	v_fmac_f32_dpp v254, v44, v178 row_shr:2 row_mask:0xf bank_mask:0xf
	v_fmac_f32_dpp v255, v45, v179 row_shr:2 row_mask:0xf bank_mask:0xf
	v_fmac_f32_dpp v148, v46, v180 row_shr:2 row_mask:0xf bank_mask:0xf
	v_fmac_f32_dpp v149, v47, v181 row_shr:2 row_mask:0xf bank_mask:0xf
	v_fmac_f32_dpp v254, v228, v194 row_ror:1 row_mask:0xf bank_mask:0x1
	v_fmac_f32_dpp v255, v229, v195 row_ror:1 row_mask:0xf bank_mask:0x1
	v_fmac_f32_dpp v148, v230, v196 row_ror:1 row_mask:0xf bank_mask:0x1
	v_fmac_f32_dpp v149, v231, v197 row_ror:1 row_mask:0xf bank_mask:0x1
	v_fmac_f32_dpp v254, v228, v178 row_ror:2 row_mask:0xf bank_mask:0x1
	v_fmac_f32_dpp v255, v229, v179 row_ror:2 row_mask:0xf bank_mask:0x1
	v_fmac_f32_dpp v148, v230, v180 row_ror:2 row_mask:0xf bank_mask:0x1
	v_fmac_f32_dpp v149, v231, v181 row_ror:2 row_mask:0xf bank_mask:0x1
	v_pk_mul_f32 v[254:255], v[238:239], v[254:255]
	v_pk_mul_f32 v[148:149], v[240:241], v[148:149]
	v_cvt_pk_bf16_f32 v242, v254, v255
	v_cvt_pk_bf16_f32 v243, v148, v149
	v_pk_fma_f32 v[254:255], v[206:207], v[28:29], v[136:137]
	v_pk_fma_f32 v[148:149], v[208:209], v[30:31], v[138:139]
	v_fmac_f32_dpp v254, v28, v190 row_shr:1 row_mask:0xf bank_mask:0xf
	v_fmac_f32_dpp v255, v29, v191 row_shr:1 row_mask:0xf bank_mask:0xf
	v_fmac_f32_dpp v148, v30, v192 row_shr:1 row_mask:0xf bank_mask:0xf
;     __device__ __forceinline__ void operator()(const f32x4 (&acc)[2][2][4][2], const Unit& u, int wr, int wc, int fr, int fq) const {
;     ...
;                         if ((u.pm & 7) == 7 && ai == 1 && wr == 1 && fr >= 14) *(f32x4*)(ncp + (size_t)((u.pm >> 3) * 2 + (fr - 14)) * FF2 + oc) = v[3];
;     ...
; #pragma unroll
;                     for (int m = 0; m < 4; ++m) {
;                         f32x4 cv;
;                         if (!samp) {
;                             const f32x4 prev = m ? v[m - 1] : hv;
; #pragma unroll
;                             for (int e = 0; e < 4; ++e) {
;                                 const int vi = __float_as_int(v[m][e]), pi = __float_as_int(prev[e]);
;                                 const int o1 = __builtin_amdgcn_mov_dpp(pi, 0x121, 0xf, 0xf, false);
;                                 const int o2 = __builtin_amdgcn_mov_dpp(pi, 0x122, 0xf, 0xf, false);
;                                 const float p1 = __int_as_float(__builtin_amdgcn_update_dpp(o1, vi, 0x111, 0xf, 0xf, false));
;                                 const float p2 = __int_as_float(__builtin_amdgcn_update_dpp(o2, vi, 0x112, 0xf, 0xf, false));
;                                 cv[e] = cb[e] + cw0[e] * p2 + cw1[e] * p1 + cw2[e] * v[m][e];
;                             }
;                         } else {
;                             const int ns = rowb + 16 * m + fr - MP;
;                             f32x4 s0 = (f32x4){0.f, 0.f, 0.f, 0.f}, s1 = s0;
;                             if (ns < NS) {
;                                 s0 = *(const f32x4*)(state + (size_t)(ns * 2 + 0) * FF2 + oc); s1 = *(const f32x4*)(state + (size_t)(ns * 2 + 1) * FF2 + oc);
;                                 *(f32x4*)(ncs + (size_t)(ns * 2 + 0) * FF2 + oc) = s1; *(f32x4*)(ncs + (size_t)(ns * 2 + 1) * FF2 + oc) = v[m];
;                             }
;                             cv = cb + cw0 * s0 + cw1 * s1 + cw2 * v[m];
;                         }
;                         if (bj == 0) cg[m] = gelu4(cv);
;                         else {
;                             const f32x4 r = cg[m] * cv;
;                             v2u w; w.x = cvt_pk_bf16(r[0], r[1]); w.y = cvt_pk_bf16(r[2], r[3]);
;                             *(v2u*)(ACT + (size_t)(rowb + 16 * m + fr) * FF + 128 * u.pn + 32 * wc + 8 * fq + 4 * n) = w;
	v_fmac_f32_dpp v149, v31, v193 row_shr:1 row_mask:0xf bank_mask:0xf
	v_fmac_f32_dpp v254, v28, v174 row_shr:2 row_mask:0xf bank_mask:0xf
	v_fmac_f32_dpp v255, v29, v175 row_shr:2 row_mask:0xf bank_mask:0xf
	v_fmac_f32_dpp v148, v30, v176 row_shr:2 row_mask:0xf bank_mask:0xf
	v_fmac_f32_dpp v149, v31, v177 row_shr:2 row_mask:0xf bank_mask:0xf
	v_fmac_f32_dpp v254, v224, v190 row_ror:1 row_mask:0xf bank_mask:0x1
	v_fmac_f32_dpp v255, v225, v191 row_ror:1 row_mask:0xf bank_mask:0x1
	v_fmac_f32_dpp v148, v226, v192 row_ror:1 row_mask:0xf bank_mask:0x1
	v_fmac_f32_dpp v149, v227, v193 row_ror:1 row_mask:0xf bank_mask:0x1
	v_fmac_f32_dpp v254, v224, v174 row_ror:2 row_mask:0xf bank_mask:0x1
	v_fmac_f32_dpp v255, v225, v175 row_ror:2 row_mask:0xf bank_mask:0x1
	v_fmac_f32_dpp v148, v226, v176 row_ror:2 row_mask:0xf bank_mask:0x1
	v_fmac_f32_dpp v149, v227, v177 row_ror:2 row_mask:0xf bank_mask:0x1
	v_fma_f32 v246, |v254|, s38, 1.0
	v_fma_f32 v247, |v255|, s38, 1.0
	v_fma_f32 v248, |v148|, s38, 1.0
	v_fma_f32 v249, |v149|, s38, 1.0
	v_mul_f32_e32 v250, v254, v254
	v_mul_f32_e32 v251, v255, v255
	v_mul_f32_e32 v252, v148, v148
	v_mul_f32_e32 v253, v149, v149
	v_rcp_f32_e32 v246, v246
	v_rcp_f32_e32 v247, v247
	v_rcp_f32_e32 v248, v248
	v_rcp_f32_e32 v249, v249
	v_mul_f32_e32 v250, s72, v250
	v_mul_f32_e32 v251, s72, v251
	v_mul_f32_e32 v252, s72, v252
	v_mul_f32_e32 v253, s72, v253
	v_exp_f32_e32 v250, v250
	v_exp_f32_e32 v251, v251
	v_exp_f32_e32 v252, v252
	v_exp_f32_e32 v253, v253
	v_fmamk_f32 v238, v246, 0x3f07dc22, v219
	v_fmamk_f32 v239, v247, 0x3f07dc22, v219
	v_fmamk_f32 v240, v248, 0x3f07dc22, v219
	v_fmamk_f32 v241, v249, 0x3f07dc22, v219
	v_fma_f32 v238, v246, v238, s66
	v_fma_f32 v239, v247, v239, s66
	v_fma_f32 v240, v248, v240, s66
	v_fma_f32 v241, v249, v241, s66
	v_fma_f32 v238, v246, v238, s68
	v_fma_f32 v239, v247, v239, s68
	v_fma_f32 v240, v248, v240, s68
	v_fma_f32 v241, v249, v241, s68
	v_fma_f32 v238, v246, v238, s70
	v_fma_f32 v239, v247, v239, s70
	v_fma_f32 v240, v248, v240, s70
	v_fma_f32 v241, v249, v241, s70
	v_mul_f32_e32 v238, v246, v238
	v_mul_f32_e32 v239, v247, v239
	v_mul_f32_e32 v240, v248, v240
	v_mul_f32_e32 v241, v249, v241
	v_mul_f32_e32 v238, v250, v238
	v_mul_f32_e32 v239, v251, v239
	v_mul_f32_e32 v240, v252, v240
	v_mul_f32_e32 v241, v253, v241
	v_max_f32_e32 v246, 0, v254
	v_max_f32_e32 v247, 0, v255
	v_max_f32_e32 v248, 0, v148
	v_max_f32_e32 v249, 0, v149
	v_fma_f32 v238, -|v254|, v238, v246
	v_fma_f32 v239, -|v255|, v239, v247
	v_fma_f32 v240, -|v148|, v240, v248
	v_fma_f32 v241, -|v149|, v241, v249
	v_pk_fma_f32 v[254:255], v[128:129], v[12:13], v[144:145]
	v_pk_fma_f32 v[148:149], v[130:131], v[14:15], v[146:147]
	v_fmac_f32_dpp v254, v12, v198 row_shr:1 row_mask:0xf bank_mask:0xf
	v_fmac_f32_dpp v255, v13, v199 row_shr:1 row_mask:0xf bank_mask:0xf
	v_fmac_f32_dpp v148, v14, v200 row_shr:1 row_mask:0xf bank_mask:0xf
	v_fmac_f32_dpp v149, v15, v201 row_shr:1 row_mask:0xf bank_mask:0xf
	v_fmac_f32_dpp v254, v12, v182 row_shr:2 row_mask:0xf bank_mask:0xf
	v_fmac_f32_dpp v255, v13, v183 row_shr:2 row_mask:0xf bank_mask:0xf
	v_fmac_f32_dpp v148, v14, v184 row_shr:2 row_mask:0xf bank_mask:0xf
	v_fmac_f32_dpp v149, v15, v185 row_shr:2 row_mask:0xf bank_mask:0xf
	v_fmac_f32_dpp v254, v232, v198 row_ror:1 row_mask:0xf bank_mask:0x1
	v_fmac_f32_dpp v255, v233, v199 row_ror:1 row_mask:0xf bank_mask:0x1
	v_fmac_f32_dpp v148, v234, v200 row_ror:1 row_mask:0xf bank_mask:0x1
	v_fmac_f32_dpp v149, v235, v201 row_ror:1 row_mask:0xf bank_mask:0x1
	v_fmac_f32_dpp v254, v232, v182 row_ror:2 row_mask:0xf bank_mask:0x1
	v_fmac_f32_dpp v255, v233, v183 row_ror:2 row_mask:0xf bank_mask:0x1
	v_fmac_f32_dpp v148, v234, v184 row_ror:2 row_mask:0xf bank_mask:0x1
	v_fmac_f32_dpp v149, v235, v185 row_ror:2 row_mask:0xf bank_mask:0x1
	v_pk_mul_f32 v[254:255], v[238:239], v[254:255]
	v_pk_mul_f32 v[148:149], v[240:241], v[148:149]
	v_cvt_pk_bf16_f32 v244, v254, v255
	v_cvt_pk_bf16_f32 v245, v148, v149
	s_add_u32 s56, s46, 0xb0000
	s_addc_u32 s57, s47, 0
	global_store_dwordx4 v151, v[242:245], s[56:57]
	s_and_b32 s14, s88, 7
	s_cmp_eq_u32 s14, 7
	s_cselect_b32 s14, s73, 0
	s_cmp_eq_u32 s14, 1
	s_cbranch_scc0 .Lfe_done
	s_lshr_b32 s14, s88, 3
	s_mul_i32 s14, s14, 0xb000
	v_mul_i32_i24_e32 v246, 0x5800, v216
	v_add_u32_e32 v246, s14, v246
	v_add_u32_e32 v246, v246, v237
	v_add_u32_e32 v247, 0x2c00, v246
	s_mov_b64 s[14:15], exec
	s_mov_b64 exec, s[10:11]
	global_store_dwordx4 v246, v[56:59], s[50:51]
	global_store_dwordx4 v246, v[24:27], s[50:51] offset:16
	global_store_dwordx4 v247, v[40:43], s[50:51]
	global_store_dwordx4 v247, v[8:11], s[50:51] offset:16
	s_mov_b64 exec, s[14:15]

; __device__ __forceinline__ unsigned xb_ld(unsigned* p)              { return __hip_atomic_load(p, __ATOMIC_RELAXED, __HIP_MEMORY_SCOPE_AGENT); }
; __device__ __forceinline__ unsigned xb_add(unsigned* p, unsigned v) { return __hip_atomic_fetch_add(p, v, __ATOMIC_RELAXED, __HIP_MEMORY_SCOPE_AGENT); }
; #define XB_SPIN(cond, bar) do { unsigned _sp = 0; while (cond) { __builtin_amdgcn_s_sleep(1); \
;     if ((++_sp & 255u) == 0u) { if (xb_ld(&(bar)[XB_TMO])) break; if (_sp > XB_SPIN_CAP) { atomicAdd(&(bar)[XB_TMO], 1u); break; } } } } while (0)
; __device__ __forceinline__ void xcd_barrier(const XcdBarrier& b) {
;     ...
;         if (nloc == 0u) { xcd_barrier_complete(bar, b.x, nloc, nx); b.st[0] = nloc; b.st[1] = nx; }
;         const unsigned old = xb_add(&bar[XB_XSUB(b.x)], 1u);
;         const unsigned gen = old / nloc;
;         if (old + 1u == (gen + 1u) * nloc) {
;             __builtin_amdgcn_fence(__ATOMIC_RELEASE, "agent");
;             asm volatile("s_waitcnt vmcnt(0)" ::: "memory");
;             const unsigned og = xb_add(&bar[XB_TOP], 1u);
;             const unsigned tg = og / nx;
;             if (og + 1u == (tg + 1u) * nx) xb_add(&bar[XB_TOPGEN], 1u);
;             else XB_SPIN(xb_ld(&bar[XB_TOPGEN]) == tg, bar);
;             __builtin_amdgcn_fence(__ATOMIC_ACQUIRE, "agent");
;             xb_add(&bar[XB_XGEN(b.x)], 1u);
;             asm volatile("s_waitcnt vmcnt(0)" ::: "memory");
;         } else {
;             XB_SPIN(xb_ld(&bar[XB_XGEN(b.x)]) == gen, bar);
.LBB0_1144:
	s_or_b64 exec, exec, s[12:13]
	v_cvt_f32_u32_e32 v4, v2
	s_waitcnt vmcnt(0)
	v_readfirstlane_b32 s0, v3
	v_sub_u32_e32 v3, 0, v2
	v_rcp_iflag_f32_e32 v4, v4
	v_add_u32_e32 v5, s0, v1
	v_mul_f32_e32 v4, 0x4f7ffffe, v4
	v_cvt_u32_f32_e32 v4, v4
	v_mul_lo_u32 v1, v3, v4
	v_mul_hi_u32 v1, v4, v1
	v_add_u32_e32 v1, v4, v1
	v_mul_hi_u32 v1, v5, v1
	v_mul_lo_u32 v3, v1, v2
	v_sub_u32_e32 v3, v5, v3
	v_add_u32_e32 v4, 1, v1
	v_cmp_ge_u32_e32 vcc, v3, v2
	s_nop 1
	v_cndmask_b32_e32 v1, v1, v4, vcc
	v_sub_u32_e32 v4, v3, v2
	v_cndmask_b32_e32 v3, v3, v4, vcc
	v_add_u32_e32 v4, 1, v1
	v_cmp_ge_u32_e32 vcc, v3, v2
	v_add_u32_e32 v3, 1, v5
	s_nop 0
	v_cndmask_b32_e32 v1, v1, v4, vcc
	v_mul_lo_u32 v4, v2, v1
	v_add_u32_e32 v2, v4, v2
	v_cmp_ne_u32_e32 vcc, v3, v2
	s_and_saveexec_b64 s[0:1], vcc
	s_xor_b64 s[10:11], exec, s[0:1]
	s_cbranch_execz .LBB0_1158
	s_waitcnt lgkmcnt(0)
	buffer_inv sc1
	v_mov_b32_e32 v0, 0x2000
	global_load_dword v0, v0, s[4:5] offset:1024 sc1
	s_add_u32 s16, s4, 0x2400
	s_addc_u32 s17, s5, 0
	s_waitcnt vmcnt(0)
	v_cmp_eq_u32_e32 vcc, v0, v1
	s_and_saveexec_b64 s[12:13], vcc
	s_cbranch_execz .LBB0_1157
	s_add_u32 s14, s80, 0x1a20200
	s_addc_u32 s15, s81, 0
	s_mov_b32 s0, 1
	s_mov_b64 s[18:19], 0
	v_mov_b32_e32 v0, 0
	s_branch .LBB0_1148

; __device__ __forceinline__ unsigned xb_ld(unsigned* p)              { return __hip_atomic_load(p, __ATOMIC_RELAXED, __HIP_MEMORY_SCOPE_AGENT); }
; #define XB_SPIN(cond, bar) do { unsigned _sp = 0; while (cond) { __builtin_amdgcn_s_sleep(1); \
;     if ((++_sp & 255u) == 0u) { if (xb_ld(&(bar)[XB_TMO])) break; if (_sp > XB_SPIN_CAP) { atomicAdd(&(bar)[XB_TMO], 1u); break; } } } } while (0)
; __device__ __forceinline__ void xcd_barrier(const XcdBarrier& b) {
;     ...
;             XB_SPIN(xb_ld(&bar[XB_XGEN(b.x)]) == gen, bar);
;             __builtin_amdgcn_fence(__ATOMIC_ACQUIRE, "agent");
;             asm volatile("s_waitcnt vmcnt(0)" ::: "memory");
.LBB0_1157:
	s_or_b64 exec, exec, s[12:13]
	s_waitcnt vmcnt(0)
	s_waitcnt vmcnt(0)
